# batched PEER tails + counted GEMM waits + phase-12 epilogue reload removal
# speedup vs baseline: 1.1261x; 1.0022x over previous
; DEV int tidx() { int t = threadIdx.x; asm volatile("" : "+v"(t)); return t; }
; #define G_LOAD(RA, RB, KT) { _Pragma("unroll") for (int i = 0; i < 4; i++) { \
;       RA[i] = *(const u32x4*)(Ap + (size_t)(i * 32) * lda + (KT) * 64); RB[i] = *(const u32x4*)(Bp + (size_t)(i * 32) * ldb + (KT) * 64); } }
; template <class Epi>
; DEV void gemm_tile(const bf16_t* __restrict__ A, int lda, const bf16_t* __restrict__ Bt, int ldb, int K, int m0, int n0,
;                    Epi& epi, char* smem) {
;   bf16_t* As = (bf16_t*)smem;
;   bf16_t* Bs = As + 128 * GLD;
;   const int tid = tidx(), lane = tid & 63, w = tid >> 6, wm = w >> 1, wn = w & 1;
;   const int l15 = lane & 15, quad = lane >> 4;
;   f32x4 acc[4][4];
; #pragma unroll
;   for (int i = 0; i < 4; i++)
; #pragma unroll
;     for (int j = 0; j < 4; j++) acc[i][j] = (f32x4){0.f, 0.f, 0.f, 0.f};
;   u32x4 ra0[4], rb0[4], ra1[4], rb1[4];
;   const int nk = K >> 6;
;   const int lrow = tid >> 3, lcc = tid & 7;
;   const bf16_t* Ap = A + (size_t)(m0 + lrow) * lda + lcc * 8;
;   const bf16_t* Bp = Bt + (size_t)(n0 + lrow) * ldb + lcc * 8;
;     ...
;   G_LOAD(ra0, rb0, 0);
;   G_LOAD(ra1, rb1, 1);
.LBB0_179:
	s_ashr_i32 s13, s1, 6
	s_and_b32 s2, s1, 7
	s_and_b32 s3, s13, -8
	s_or_b32 s2, s3, s2
	s_lshr_b32 s3, s1, 31
	s_add_i32 s3, s2, s3
	s_ashr_i32 s12, s3, 1
	s_lshl_b32 s3, s12, 3
	s_bfe_u32 s14, s1, 0x30006
	s_or_b32 s3, s3, s14
	s_cmpk_gt_i32 s3, 0x7f
	s_cbranch_scc1 .LBB0_178
	v_mov_b32_e32 v145, v195
	s_lshr_b32 s14, s1, 6
	s_lshl_b32 s2, s2, 3
	s_lshl_b32 s18, s12, 4
	s_lshl_b32 s3, s3, 7
	s_and_b32 s15, s0, 7
	v_ashrrev_i32_e32 v66, 3, v145
	s_and_b32 s14, s14, 7
	s_sub_i32 s2, s2, s18
	s_movk_i32 s20, 0x880
	s_bfe_u32 s19, s1, 0x30003
	v_add_u32_e32 v0, s3, v66
	v_mov_b64_e32 v[2:3], s[10:11]
	s_lshl_b32 s16, s15, 3
	s_lshl_b32 s17, s14, 7
	s_or_b32 s2, s2, s19
	v_mad_i64_i32 v[2:3], s[14:15], v0, s20, v[2:3]
	v_lshlrev_b32_e32 v0, 4, v145
	s_lshl_b32 s2, s2, 7
	v_and_b32_e32 v0, 0x70, v0
	v_lshl_add_u64 v[6:7], v[2:3], 0, v[0:1]
	v_add_u32_e32 v4, s2, v66
	v_mov_b64_e32 v[2:3], s[8:9]
	v_mad_i64_i32 v[2:3], s[14:15], v4, s20, v[2:3]
	s_mov_b32 s14, 0x11000
	s_waitcnt vmcnt(21)
	v_add_co_u32_e32 v22, vcc, s14, v6
	v_lshl_add_u64 v[14:15], v[2:3], 0, v[0:1]
	s_nop 0
	v_addc_co_u32_e32 v23, vcc, 0, v7, vcc
	s_waitcnt vmcnt(20)
	v_add_co_u32_e32 v30, vcc, s14, v14
	s_mov_b32 s14, 0x22000
	s_nop 0
	v_addc_co_u32_e32 v31, vcc, 0, v15, vcc
	s_waitcnt vmcnt(19)
	v_add_co_u32_e32 v38, vcc, s14, v6
	s_lshl_b32 s13, s13, 3
	s_nop 0
	v_addc_co_u32_e32 v39, vcc, 0, v7, vcc
	s_waitcnt vmcnt(18)
	v_add_co_u32_e32 v46, vcc, s14, v14
	s_mov_b32 s14, 0x33000
	s_nop 0
	v_addc_co_u32_e32 v47, vcc, 0, v15, vcc
	s_waitcnt vmcnt(17)
	v_add_co_u32_e32 v54, vcc, s14, v6
	s_and_b32 s13, s13, 0x1ffffc0
	s_nop 0
	v_addc_co_u32_e32 v55, vcc, 0, v7, vcc
	s_waitcnt vmcnt(16)
	v_add_co_u32_e32 v62, vcc, s14, v14
	s_or_b32 s13, s13, s16
	s_nop 0
	v_addc_co_u32_e32 v63, vcc, 0, v15, vcc
	global_load_dwordx4 v[2:5], v[6:7], off
	s_nop 0
	global_load_dwordx4 v[10:13], v[14:15], off
	s_nop 0
	global_load_dwordx4 v[18:21], v[22:23], off
	s_nop 0
	global_load_dwordx4 v[26:29], v[30:31], off
	s_nop 0
	global_load_dwordx4 v[34:37], v[38:39], off
	s_nop 0
	global_load_dwordx4 v[42:45], v[46:47], off
	s_nop 0
	global_load_dwordx4 v[50:53], v[54:55], off
	s_nop 0
	global_load_dwordx4 v[58:61], v[62:63], off
	s_nop 0
	global_load_dwordx4 v[6:9], v[6:7], off offset:128
	s_nop 0
	global_load_dwordx4 v[14:17], v[14:15], off offset:128
	s_nop 0
	global_load_dwordx4 v[22:25], v[22:23], off offset:128
	s_nop 0
	global_load_dwordx4 v[30:33], v[30:31], off offset:128
	s_nop 0
	global_load_dwordx4 v[38:41], v[38:39], off offset:128
	s_nop 0
	global_load_dwordx4 v[46:49], v[46:47], off offset:128
	s_nop 0
	global_load_dwordx4 v[54:57], v[54:55], off offset:128
	s_nop 0
	global_load_dwordx4 v[62:65], v[62:63], off offset:128
	s_or_b32 s13, s13, s19
	v_mad_u64_u32 v[134:135], s[14:15], v66, s36, v[0:1]
	s_sub_i32 s13, s13, s18
	v_ashrrev_i32_e32 v67, 1, v145
	s_lshl_b32 s14, s13, 7
	s_lshl_b32 s12, s12, 10
	v_and_b32_e32 v146, 0xffffffc0, v67
	v_ashrrev_i32_e32 v67, 31, v66
	s_ashr_i32 s15, s14, 31
	s_or_b32 s12, s17, s12
	s_movk_i32 s19, 0x880
	v_lshl_add_u64 v[68:69], v[66:67], 0, s[14:15]
	v_mov_b64_e32 v[70:71], s[28:29]
	v_add_u32_e32 v66, s12, v66
	v_and_b32_e32 v0, 7, v145
	v_mad_u64_u32 v[136:137], s[14:15], v68, s19, v[70:71]
	v_mad_i64_i32 v[138:139], s[12:13], v66, s19, v[70:71]
	v_mov_b32_e32 v118, 0
	v_and_b32_e32 v144, 64, v145
	v_lshlrev_b32_e32 v0, 4, v0
	v_mad_i32_i24 v137, v69, s19, v137
	s_mov_b32 s12, -2
	v_mov_b32_e32 v119, v118
	v_mov_b32_e32 v120, v118
	v_mov_b32_e32 v121, v118
	v_mov_b32_e32 v126, v118
	v_mov_b32_e32 v127, v118
	v_mov_b32_e32 v128, v118
	v_mov_b32_e32 v129, v118
	v_mov_b32_e32 v90, v118
	v_mov_b32_e32 v91, v118
	v_mov_b32_e32 v92, v118
	v_mov_b32_e32 v93, v118
	v_mov_b32_e32 v98, v118
	v_mov_b32_e32 v99, v118
	v_mov_b32_e32 v100, v118
	v_mov_b32_e32 v101, v118
	v_mov_b32_e32 v66, v118
	v_mov_b32_e32 v67, v118
	v_mov_b32_e32 v68, v118
	v_mov_b32_e32 v69, v118
	v_mov_b32_e32 v70, v118
	v_mov_b32_e32 v71, v118
	v_mov_b32_e32 v72, v118
	v_mov_b32_e32 v73, v118
	v_mov_b32_e32 v74, v118
	v_mov_b32_e32 v75, v118
	v_mov_b32_e32 v76, v118
	v_mov_b32_e32 v77, v118
	v_mov_b32_e32 v82, v118
	v_mov_b32_e32 v83, v118
	v_mov_b32_e32 v84, v118
	v_mov_b32_e32 v85, v118
	v_mov_b32_e32 v78, v118
	v_mov_b32_e32 v79, v118
	v_mov_b32_e32 v80, v118
	v_mov_b32_e32 v81, v118
	v_mov_b32_e32 v86, v118
	v_mov_b32_e32 v87, v118
	v_mov_b32_e32 v88, v118
	v_mov_b32_e32 v89, v118
	v_mov_b32_e32 v94, v118
	v_mov_b32_e32 v95, v118
	v_mov_b32_e32 v96, v118
	v_mov_b32_e32 v97, v118
	v_mov_b32_e32 v102, v118
	v_mov_b32_e32 v103, v118
	v_mov_b32_e32 v104, v118
	v_mov_b32_e32 v105, v118
	v_mov_b32_e32 v110, v118
	v_mov_b32_e32 v111, v118
	v_mov_b32_e32 v112, v118
	v_mov_b32_e32 v113, v118
	v_mov_b32_e32 v114, v118
	v_mov_b32_e32 v115, v118
	v_mov_b32_e32 v116, v118
	v_mov_b32_e32 v117, v118
	v_mov_b32_e32 v122, v118
	v_mov_b32_e32 v123, v118
	v_mov_b32_e32 v124, v118
	v_mov_b32_e32 v125, v118
	v_mov_b32_e32 v106, v118
	v_mov_b32_e32 v107, v118
	v_mov_b32_e32 v108, v118
	v_mov_b32_e32 v109, v118
	s_branch .LBB0_182

; #define G_LOAD(RA, RB, KT) { _Pragma("unroll") for (int i = 0; i < 4; i++) { \
;       RA[i] = *(const u32x4*)(Ap + (size_t)(i * 32) * lda + (KT) * 64); RB[i] = *(const u32x4*)(Bp + (size_t)(i * 32) * ldb + (KT) * 64); } }
; #define G_STORE(RA, RB) { _Pragma("unroll") for (int i = 0; i < 4; i++) { \
;       *(u32x4*)(As + (lrow + i * 32) * GLD + lcc * 8) = RA[i]; *(u32x4*)(Bs + (lrow + i * 32) * GLD + lcc * 8) = RB[i]; } }
; template <class Epi>
; DEV void gemm_tile(const bf16_t* __restrict__ A, int lda, const bf16_t* __restrict__ Bt, int ldb, int K, int m0, int n0,
;                    Epi& epi, char* smem) {
;     ...
;   G_LOAD(ra0, rb0, 0);
;   G_LOAD(ra1, rb1, 1);
;   for (int kt = 0; kt < nk; kt += 2) {
;     __syncthreads();
;     G_STORE(ra0, rb0);
;     __syncthreads();
;     if (kt + 2 < nk) G_LOAD(ra0, rb0, kt + 2);
.LBB0_182:
	s_add_i32 s12, s12, 2
	s_cmp_gt_u32 s12, 13
	s_cselect_b64 s[14:15], -1, 0
	s_and_b64 vcc, exec, s[14:15]
	v_lshl_add_u64 v[142:143], v[138:139], 0, v[0:1]
	v_lshl_add_u64 v[140:141], v[136:137], 0, v[0:1]
	s_waitcnt lgkmcnt(0)
	s_barrier
	s_waitcnt vmcnt(8)
	ds_write_b128 v134, v[2:5]
	ds_write_b128 v134, v[10:13] offset:20480
	ds_write_b128 v134, v[18:21] offset:5120
	ds_write_b128 v134, v[26:29] offset:25600
	ds_write_b128 v134, v[34:37] offset:10240
	ds_write_b128 v134, v[42:45] offset:30720
	ds_write_b128 v134, v[50:53] offset:15360
	ds_write_b128 v134, v[58:61] offset:35840
	s_waitcnt lgkmcnt(0)
	s_barrier
	s_cbranch_vccnz .Lgw_skip_0
	v_add_co_u32_e32 v2, vcc, 0x4200000, v142
	s_nop 1
	v_addc_co_u32_e32 v3, vcc, 0, v143, vcc
	v_add_co_u32_e32 v10, vcc, 0xba00000, v140
	global_load_dwordx4 v[2:5], v[2:3], off offset:256
	s_nop 0
	v_addc_co_u32_e32 v11, vcc, 0, v141, vcc
	v_add_co_u32_e32 v18, vcc, 0x4211000, v142
	global_load_dwordx4 v[10:13], v[10:11], off offset:256
	s_nop 0
	v_addc_co_u32_e32 v19, vcc, 0, v143, vcc
	v_add_co_u32_e32 v26, vcc, 0xba11000, v140
	global_load_dwordx4 v[18:21], v[18:19], off offset:256
	s_nop 0
	v_addc_co_u32_e32 v27, vcc, 0, v141, vcc
	v_add_co_u32_e32 v34, vcc, 0x4222000, v142
	global_load_dwordx4 v[26:29], v[26:27], off offset:256
	s_nop 0
	v_addc_co_u32_e32 v35, vcc, 0, v143, vcc
	v_add_co_u32_e32 v42, vcc, 0xba22000, v140
	global_load_dwordx4 v[34:37], v[34:35], off offset:256
	s_nop 0
	v_addc_co_u32_e32 v43, vcc, 0, v141, vcc
	v_add_co_u32_e32 v50, vcc, 0x4233000, v142
	global_load_dwordx4 v[42:45], v[42:43], off offset:256
	s_nop 0
	v_addc_co_u32_e32 v51, vcc, 0, v143, vcc
	v_add_co_u32_e32 v58, vcc, 0xba33000, v140
	global_load_dwordx4 v[50:53], v[50:51], off offset:256
	s_nop 0
	v_addc_co_u32_e32 v59, vcc, 0, v141, vcc
	global_load_dwordx4 v[58:61], v[58:59], off offset:256
; DEV int tidx() { int t = threadIdx.x; asm volatile("" : "+v"(t)); return t; }
; DEV f32x4 mfma16(bf16x8 a, bf16x8 b, f32x4 c) { return __builtin_amdgcn_mfma_f32_16x16x32_bf16(a, b, c, 0, 0, 0); }
; #define G_LOAD(RA, RB, KT) { _Pragma("unroll") for (int i = 0; i < 4; i++) { \
;       RA[i] = *(const u32x4*)(Ap + (size_t)(i * 32) * lda + (KT) * 64); RB[i] = *(const u32x4*)(Bp + (size_t)(i * 32) * ldb + (KT) * 64); } }
; #define G_STORE(RA, RB) { _Pragma("unroll") for (int i = 0; i < 4; i++) { \
;       *(u32x4*)(As + (lrow + i * 32) * GLD + lcc * 8) = RA[i]; *(u32x4*)(Bs + (lrow + i * 32) * GLD + lcc * 8) = RB[i]; } }
; template <int TI, int TJ, int KS>
; DEV void mfma_lds(const bf16_t* Arows, int lda, const bf16_t* Brows, int ldb, int i0, int j0, f32x4 (&acc)[TI][TJ]) {
;   const int lane = tidx() & 63, l15 = lane & 15, quad = lane >> 4;
; #pragma unroll
;   for (int ks = 0; ks < KS; ks++) {
;     bf16x8 af[TI], bfr[TJ];
; #pragma unroll
;     for (int i = 0; i < TI; i++) af[i] = *(const bf16x8*)(Arows + (i0 + i * 16 + l15) * lda + ks * 32 + quad * 8);
; #pragma unroll
;     for (int j = 0; j < TJ; j++) bfr[j] = *(const bf16x8*)(Brows + (j0 + j * 16 + l15) * ldb + ks * 32 + quad * 8);
; #pragma unroll
;     for (int i = 0; i < TI; i++)
; #pragma unroll
;       for (int j = 0; j < TJ; j++) acc[i][j] = mfma16(af[i], bfr[j], acc[i][j]);
;   }
; template <class Epi>
; DEV void gemm_tile(const bf16_t* __restrict__ A, int lda, const bf16_t* __restrict__ Bt, int ldb, int K, int m0, int n0,
;                    Epi& epi, char* smem) {
;     ...
;     mfma_lds<4, 4, 2>(Bs, GLD, As, GLD, wn * 64, wm * 64, acc);
;     __syncthreads();
;     G_STORE(ra1, rb1);
;     __syncthreads();
;     if (kt + 3 < nk) G_LOAD(ra1, rb1, kt + 3);
;     mfma_lds<4, 4, 2>(Bs, GLD, As, GLD, wn * 64, wm * 64, acc);
.LBB0_184:
	v_mov_b32_e32 v130, v195
	s_cmp_gt_u32 s12, 12
	v_and_b32_e32 v135, 15, v130
	v_or_b32_e32 v131, v135, v144
	v_and_b32_e32 v148, 48, v130
	v_mul_u32_u24_e32 v130, 0x50, v131
	v_lshl_add_u32 v147, v130, 1, v148
	ds_read_b128 v[130:133], v147 offset:20480
	v_or_b32_e32 v135, v135, v146
	v_mad_u64_u32 v[184:185], s[16:17], v135, s36, v[148:149]
	ds_read_b128 v[148:151], v184
	ds_read_b128 v[152:155], v184 offset:2560
	ds_read_b128 v[156:159], v184 offset:5120
	ds_read_b128 v[160:163], v184 offset:7680
	s_waitcnt lgkmcnt(3)
	v_mfma_f32_16x16x32_bf16 v[106:109], v[130:133], v[148:151], v[106:109]
	s_waitcnt lgkmcnt(2)
	v_mfma_f32_16x16x32_bf16 v[122:125], v[130:133], v[152:155], v[122:125]
	s_waitcnt lgkmcnt(1)
	v_mfma_f32_16x16x32_bf16 v[114:117], v[130:133], v[156:159], v[114:117]
	s_waitcnt lgkmcnt(0)
	v_mfma_f32_16x16x32_bf16 v[110:113], v[130:133], v[160:163], v[110:113]
	ds_read_b128 v[130:133], v147 offset:23040
	s_waitcnt lgkmcnt(0)
	v_mfma_f32_16x16x32_bf16 v[102:105], v[130:133], v[148:151], v[102:105]
	v_mfma_f32_16x16x32_bf16 v[94:97], v[130:133], v[152:155], v[94:97]
	v_mfma_f32_16x16x32_bf16 v[164:167], v[130:133], v[156:159], v[86:89]
	v_mfma_f32_16x16x32_bf16 v[130:133], v[130:133], v[160:163], v[78:81]
	s_nop 2
	ds_read_b128 v[78:81], v147 offset:25600
	s_waitcnt lgkmcnt(0)
	v_mfma_f32_16x16x32_bf16 v[180:183], v[78:81], v[160:163], v[66:69]
	s_nop 2
	ds_read_b128 v[66:69], v147 offset:28160
	v_mfma_f32_16x16x32_bf16 v[168:171], v[78:81], v[148:151], v[82:85]
	v_mfma_f32_16x16x32_bf16 v[172:175], v[78:81], v[152:155], v[74:77]
	v_mfma_f32_16x16x32_bf16 v[176:179], v[78:81], v[156:159], v[70:73]
	ds_read_b128 v[78:81], v147 offset:20544
	s_waitcnt lgkmcnt(1)
	v_mfma_f32_16x16x32_bf16 v[126:129], v[66:69], v[156:159], v[126:129]
	v_mfma_f32_16x16x32_bf16 v[156:159], v[66:69], v[160:163], v[118:121]
	ds_read_b128 v[160:163], v184 offset:2624
	s_nop 1
	ds_read_b128 v[118:121], v184 offset:64
	v_mfma_f32_16x16x32_bf16 v[148:151], v[66:69], v[148:151], v[98:101]
	s_nop 2
	ds_read_b128 v[98:101], v147 offset:23104
	s_waitcnt lgkmcnt(2)
	v_mfma_f32_16x16x32_bf16 v[70:73], v[78:81], v[160:163], v[122:125]
	s_nop 2
	ds_read_b128 v[122:125], v184 offset:5184
	ds_read_b128 v[184:187], v184 offset:7744
	v_mfma_f32_16x16x32_bf16 v[152:155], v[66:69], v[152:155], v[90:93]
	s_waitcnt lgkmcnt(3)
	v_mfma_f32_16x16x32_bf16 v[66:69], v[78:81], v[118:121], v[106:109]
	s_waitcnt lgkmcnt(1)
	v_mfma_f32_16x16x32_bf16 v[74:77], v[78:81], v[122:125], v[114:117]
	s_waitcnt lgkmcnt(0)
	v_mfma_f32_16x16x32_bf16 v[78:81], v[78:81], v[184:187], v[110:113]
	v_mfma_f32_16x16x32_bf16 v[86:89], v[98:101], v[160:163], v[94:97]
	s_nop 1
	ds_read_b128 v[110:113], v147 offset:25664
	v_mfma_f32_16x16x32_bf16 v[94:97], v[98:101], v[184:187], v[130:133]
	s_nop 2
	ds_read_b128 v[130:133], v147 offset:28224
	v_mfma_f32_16x16x32_bf16 v[82:85], v[98:101], v[118:121], v[102:105]
	s_waitcnt lgkmcnt(0)
	s_barrier
	v_mfma_f32_16x16x32_bf16 v[90:93], v[98:101], v[122:125], v[164:167]
	s_waitcnt vmcnt(8)
	ds_write_b128 v134, v[6:9]
	ds_write_b128 v134, v[14:17] offset:20480
	ds_write_b128 v134, v[22:25] offset:5120
	ds_write_b128 v134, v[30:33] offset:25600
	ds_write_b128 v134, v[38:41] offset:10240
	ds_write_b128 v134, v[46:49] offset:30720
	ds_write_b128 v134, v[54:57] offset:15360
	ds_write_b128 v134, v[62:65] offset:35840
	v_mfma_f32_16x16x32_bf16 v[98:101], v[110:113], v[118:121], v[168:171]
	s_waitcnt lgkmcnt(0)
	s_barrier
	v_mfma_f32_16x16x32_bf16 v[102:105], v[110:113], v[160:163], v[172:175]
	v_mfma_f32_16x16x32_bf16 v[106:109], v[110:113], v[122:125], v[176:179]
	v_mfma_f32_16x16x32_bf16 v[110:113], v[110:113], v[184:187], v[180:183]
	v_mfma_f32_16x16x32_bf16 v[114:117], v[130:133], v[118:121], v[148:151]
	v_mfma_f32_16x16x32_bf16 v[118:121], v[130:133], v[160:163], v[152:155]
	v_mfma_f32_16x16x32_bf16 v[122:125], v[130:133], v[122:125], v[126:129]
	v_mfma_f32_16x16x32_bf16 v[130:133], v[130:133], v[184:187], v[156:159]
	s_cbranch_scc1 .LBB0_181
	v_add_co_u32_e32 v6, vcc, 0x4200000, v142
	s_nop 1
	v_addc_co_u32_e32 v7, vcc, 0, v143, vcc
	v_add_co_u32_e32 v14, vcc, 0xba00000, v140
	global_load_dwordx4 v[6:9], v[6:7], off offset:384
	s_nop 0
	v_addc_co_u32_e32 v15, vcc, 0, v141, vcc
	v_add_co_u32_e32 v22, vcc, 0x4211000, v142
	global_load_dwordx4 v[14:17], v[14:15], off offset:384
	s_nop 0
	v_addc_co_u32_e32 v23, vcc, 0, v143, vcc
	v_add_co_u32_e32 v30, vcc, 0xba11000, v140
	global_load_dwordx4 v[22:25], v[22:23], off offset:384
	s_nop 0
	v_addc_co_u32_e32 v31, vcc, 0, v141, vcc
	v_add_co_u32_e32 v38, vcc, 0x4222000, v142
	global_load_dwordx4 v[30:33], v[30:31], off offset:384
	s_nop 0
	v_addc_co_u32_e32 v39, vcc, 0, v143, vcc
	v_add_co_u32_e32 v46, vcc, 0xba22000, v140
	global_load_dwordx4 v[38:41], v[38:39], off offset:384
	s_nop 0
	v_addc_co_u32_e32 v47, vcc, 0, v141, vcc
	v_add_co_u32_e32 v54, vcc, 0x4233000, v142
	global_load_dwordx4 v[46:49], v[46:47], off offset:384
	s_nop 0
	v_addc_co_u32_e32 v55, vcc, 0, v143, vcc
	v_add_co_u32_e32 v62, vcc, 0xba33000, v140
	global_load_dwordx4 v[54:57], v[54:55], off offset:384
	s_nop 0
	v_addc_co_u32_e32 v63, vcc, 0, v141, vcc
	global_load_dwordx4 v[62:65], v[62:63], off offset:384
	s_branch .LBB0_181
.Lgw_skip_0:
	s_waitcnt vmcnt(0)
	s_branch .LBB0_184

; DEV int tidx() { int t = threadIdx.x; asm volatile("" : "+v"(t)); return t; }
; #define G_LOAD(RA, RB, KT) { _Pragma("unroll") for (int i = 0; i < 4; i++) { \
;       RA[i] = *(const u32x4*)(Ap + (size_t)(i * 32) * lda + (KT) * 64); RB[i] = *(const u32x4*)(Bp + (size_t)(i * 32) * ldb + (KT) * 64); } }
; template <class Epi>
; DEV void gemm_tile(const bf16_t* __restrict__ A, int lda, const bf16_t* __restrict__ Bt, int ldb, int K, int m0, int n0,
;                    Epi& epi, char* smem) {
;   bf16_t* As = (bf16_t*)smem;
;   bf16_t* Bs = As + 128 * GLD;
;   const int tid = tidx(), lane = tid & 63, w = tid >> 6, wm = w >> 1, wn = w & 1;
;   const int l15 = lane & 15, quad = lane >> 4;
;   f32x4 acc[4][4];
; #pragma unroll
;   for (int i = 0; i < 4; i++)
; #pragma unroll
;     for (int j = 0; j < 4; j++) acc[i][j] = (f32x4){0.f, 0.f, 0.f, 0.f};
;   u32x4 ra0[4], rb0[4], ra1[4], rb1[4];
;   const int nk = K >> 6;
;   const int lrow = tid >> 3, lcc = tid & 7;
;   const bf16_t* Ap = A + (size_t)(m0 + lrow) * lda + lcc * 8;
;   const bf16_t* Bp = Bt + (size_t)(n0 + lrow) * ldb + lcc * 8;
;     ...
;   G_LOAD(ra0, rb0, 0);
;   G_LOAD(ra1, rb1, 1);
.LBB0_198:
	s_ashr_i32 s1, s12, 6
	s_and_b32 s0, s12, 7
	s_and_b32 s13, s1, 0x1ffffff8
	s_or_b32 s0, s13, s0
	s_lshl_b32 s0, s0, 3
	s_bfe_u32 s13, s12, 0x30006
	s_or_b32 s0, s0, s13
	s_cmpk_gt_i32 s0, 0x7f
	s_cbranch_scc1 .LBB0_197
	s_lshr_b32 s13, s12, 6
	v_mov_b32_e32 v141, v195
	s_bfe_u32 s16, s3, 0x30007
	s_and_b32 s20, s13, 7
	s_lshl_b32 s0, s0, 7
	s_lshl_b32 s13, s12, 4
	s_mul_i32 s18, s16, 0x44000
	v_ashrrev_i32_e32 v2, 3, v141
	s_and_b32 s16, s2, 7
	s_movk_i32 s21, 0x880
	s_and_b32 s13, s13, 0x380
	v_add_u32_e32 v0, s0, v2
	v_mov_b64_e32 v[4:5], s[14:15]
	s_lshl_b32 s19, s16, 3
	v_mad_i64_i32 v[4:5], s[16:17], v0, s21, v[4:5]
	v_lshlrev_b32_e32 v0, 4, v141
	v_add_u32_e32 v3, s13, v2
	v_mov_b64_e32 v[6:7], s[10:11]
	v_and_b32_e32 v0, 0x70, v0
	v_mad_i64_i32 v[6:7], s[16:17], v3, s21, v[6:7]
	v_lshl_add_u64 v[4:5], v[4:5], 0, v[0:1]
	s_mov_b32 s16, 0x11000
	v_add_co_u32_e32 v8, vcc, s16, v4
	v_lshl_add_u64 v[6:7], v[6:7], 0, v[0:1]
	s_nop 0
	v_addc_co_u32_e32 v9, vcc, 0, v5, vcc
	v_add_co_u32_e32 v10, vcc, s16, v6
	s_mov_b32 s16, 0x22000
	s_nop 0
	v_addc_co_u32_e32 v11, vcc, 0, v7, vcc
	v_add_co_u32_e32 v12, vcc, s16, v4
	v_ashrrev_i32_e32 v3, 1, v141
	s_nop 0
	v_addc_co_u32_e32 v13, vcc, 0, v5, vcc
	s_waitcnt vmcnt(22)
	v_add_co_u32_e32 v14, vcc, s16, v6
	s_mov_b32 s16, 0x33000
	s_nop 0
	v_addc_co_u32_e32 v15, vcc, 0, v7, vcc
	v_add_co_u32_e32 v16, vcc, s16, v4
	v_and_b32_e32 v142, 0xffffffc0, v3
	s_nop 0
	v_addc_co_u32_e32 v17, vcc, 0, v5, vcc
	v_add_co_u32_e32 v18, vcc, s16, v6
	v_mad_u64_u32 v[130:131], s[16:17], v2, s36, v[0:1]
	s_nop 0
	v_addc_co_u32_e32 v19, vcc, 0, v7, vcc
	global_load_dwordx4 v[42:45], v[4:5], off
	global_load_dwordx4 v[50:53], v[6:7], off
	global_load_dwordx4 v[58:61], v[8:9], off
	global_load_dwordx4 v[66:69], v[10:11], off
	global_load_dwordx4 v[78:81], v[12:13], off
	global_load_dwordx4 v[86:89], v[14:15], off
	global_load_dwordx4 v[94:97], v[16:17], off
	global_load_dwordx4 v[102:105], v[18:19], off
	global_load_dwordx4 v[46:49], v[4:5], off offset:128
	global_load_dwordx4 v[54:57], v[6:7], off offset:128
	global_load_dwordx4 v[62:65], v[8:9], off offset:128
	global_load_dwordx4 v[70:73], v[10:11], off offset:128
	global_load_dwordx4 v[82:85], v[12:13], off offset:128
	global_load_dwordx4 v[90:93], v[14:15], off offset:128
	global_load_dwordx4 v[98:101], v[16:17], off offset:128
	global_load_dwordx4 v[106:109], v[18:19], off offset:128
	s_add_u32 s16, s28, s18
	s_addc_u32 s17, s29, 0
	s_lshl_b32 s1, s1, 3
	s_and_b32 s1, s1, 0x1ffffc0
	v_mov_b64_e32 v[4:5], s[16:17]
	s_or_b32 s1, s1, s19
	v_mad_i64_i32 v[132:133], s[16:17], v2, s21, v[4:5]
	s_or_b32 s1, s1, s20
	s_lshl_b32 s16, s1, 7
	v_ashrrev_i32_e32 v3, 31, v2
	s_ashr_i32 s17, s16, 31
	v_lshl_add_u64 v[2:3], v[2:3], 0, s[16:17]
	v_mov_b64_e32 v[4:5], s[28:29]
	v_and_b32_e32 v0, 7, v141
	v_mad_u64_u32 v[134:135], s[16:17], v2, s21, v[4:5]
	v_mov_b32_e32 v2, 0
	v_and_b32_e32 v140, 64, v141
	v_lshlrev_b32_e32 v0, 4, v0
	v_mad_i32_i24 v135, v3, s21, v135
	s_movk_i32 s21, 0x2000
	s_mov_b32 s1, -2
	v_mov_b32_e32 v3, v2
	v_mov_b32_e32 v4, v2
	v_mov_b32_e32 v5, v2
	v_mov_b32_e32 v6, v2
	v_mov_b32_e32 v7, v2
	v_mov_b32_e32 v8, v2
	v_mov_b32_e32 v9, v2
	v_mov_b32_e32 v10, v2
	v_mov_b32_e32 v11, v2
	v_mov_b32_e32 v12, v2
	v_mov_b32_e32 v13, v2
	v_mov_b32_e32 v14, v2
	v_mov_b32_e32 v15, v2
	v_mov_b32_e32 v16, v2
	v_mov_b32_e32 v17, v2
	v_mov_b32_e32 v18, v2
	v_mov_b32_e32 v19, v2
	v_mov_b32_e32 v20, v2
	v_mov_b32_e32 v21, v2
	s_waitcnt vmcnt(37)
	v_mov_b32_e32 v22, v2
	v_mov_b32_e32 v23, v2
	v_mov_b32_e32 v24, v2
	v_mov_b32_e32 v25, v2
	v_mov_b32_e32 v26, v2
	v_mov_b32_e32 v27, v2
	v_mov_b32_e32 v28, v2
	v_mov_b32_e32 v29, v2
	s_waitcnt vmcnt(36)
	v_mov_b32_e32 v30, v2
	v_mov_b32_e32 v31, v2
	v_mov_b32_e32 v32, v2
	v_mov_b32_e32 v33, v2
	v_mov_b32_e32 v34, v2
	v_mov_b32_e32 v35, v2
	v_mov_b32_e32 v36, v2
	v_mov_b32_e32 v37, v2
	s_waitcnt vmcnt(35)
	v_mov_b32_e32 v38, v2
	v_mov_b32_e32 v39, v2
	v_mov_b32_e32 v40, v2
	v_mov_b32_e32 v41, v2
	v_mov_b32_e32 v74, v2
	v_mov_b32_e32 v75, v2
	v_mov_b32_e32 v76, v2
	v_mov_b32_e32 v77, v2
	v_mov_b32_e32 v110, v2
	v_mov_b32_e32 v111, v2
	v_mov_b32_e32 v112, v2
	v_mov_b32_e32 v113, v2
	v_mov_b32_e32 v114, v2
	v_mov_b32_e32 v115, v2
	v_mov_b32_e32 v116, v2
	v_mov_b32_e32 v117, v2
	v_mov_b32_e32 v118, v2
	v_mov_b32_e32 v119, v2
	v_mov_b32_e32 v120, v2
	v_mov_b32_e32 v121, v2
	v_mov_b32_e32 v122, v2
	v_mov_b32_e32 v123, v2
	v_mov_b32_e32 v124, v2
	v_mov_b32_e32 v125, v2
	v_mov_b32_e32 v126, v2
	v_mov_b32_e32 v127, v2
	v_mov_b32_e32 v128, v2
	v_mov_b32_e32 v129, v2
	s_branch .LBB0_201

; #define G_LOAD(RA, RB, KT) { _Pragma("unroll") for (int i = 0; i < 4; i++) { \
;       RA[i] = *(const u32x4*)(Ap + (size_t)(i * 32) * lda + (KT) * 64); RB[i] = *(const u32x4*)(Bp + (size_t)(i * 32) * ldb + (KT) * 64); } }
; #define G_STORE(RA, RB) { _Pragma("unroll") for (int i = 0; i < 4; i++) { \
;       *(u32x4*)(As + (lrow + i * 32) * GLD + lcc * 8) = RA[i]; *(u32x4*)(Bs + (lrow + i * 32) * GLD + lcc * 8) = RB[i]; } }
; template <class Epi>
; DEV void gemm_tile(const bf16_t* __restrict__ A, int lda, const bf16_t* __restrict__ Bt, int ldb, int K, int m0, int n0,
;                    Epi& epi, char* smem) {
;     ...
;   G_LOAD(ra0, rb0, 0);
;   G_LOAD(ra1, rb1, 1);
;   for (int kt = 0; kt < nk; kt += 2) {
;     __syncthreads();
;     G_STORE(ra0, rb0);
;     __syncthreads();
;     if (kt + 2 < nk) G_LOAD(ra0, rb0, kt + 2);
.LBB0_201:
	s_add_i32 s1, s1, 2
	s_cmp_gt_u32 s1, 13
	s_cselect_b64 s[16:17], -1, 0
	s_and_b64 vcc, exec, s[16:17]
	v_lshl_add_u64 v[138:139], v[134:135], 0, v[0:1]
	v_lshl_add_u64 v[136:137], v[132:133], 0, v[0:1]
	s_waitcnt lgkmcnt(0)
	s_barrier
	s_waitcnt vmcnt(8)
	ds_write_b128 v130, v[42:45]
	ds_write_b128 v130, v[50:53] offset:20480
	ds_write_b128 v130, v[58:61] offset:5120
	ds_write_b128 v130, v[66:69] offset:25600
	ds_write_b128 v130, v[78:81] offset:10240
	ds_write_b128 v130, v[86:89] offset:30720
	ds_write_b128 v130, v[94:97] offset:15360
	ds_write_b128 v130, v[102:105] offset:35840
	s_waitcnt lgkmcnt(0)
	s_barrier
	s_cbranch_vccnz .Lgw_skip_1
	v_add_co_u32_e32 v42, vcc, 0x4200000, v138
	s_nop 1
	v_addc_co_u32_e32 v43, vcc, 0, v139, vcc
	v_add_co_u32_e32 v50, vcc, 0xb3a0000, v136
	global_load_dwordx4 v[42:45], v[42:43], off offset:256
	s_nop 0
	v_addc_co_u32_e32 v51, vcc, 0, v137, vcc
	v_add_co_u32_e32 v58, vcc, 0x4211000, v138
	global_load_dwordx4 v[50:53], v[50:51], off offset:256
	s_nop 0
	v_addc_co_u32_e32 v59, vcc, 0, v139, vcc
	v_add_co_u32_e32 v66, vcc, 0xb3b1000, v136
	global_load_dwordx4 v[58:61], v[58:59], off offset:256
	s_nop 0
	v_addc_co_u32_e32 v67, vcc, 0, v137, vcc
	v_add_co_u32_e32 v78, vcc, 0x4222000, v138
	global_load_dwordx4 v[66:69], v[66:67], off offset:256
	s_nop 0
	v_addc_co_u32_e32 v79, vcc, 0, v139, vcc
	v_add_co_u32_e32 v86, vcc, 0xb3c2000, v136
	global_load_dwordx4 v[78:81], v[78:79], off offset:256
	s_nop 0
	v_addc_co_u32_e32 v87, vcc, 0, v137, vcc
	v_add_co_u32_e32 v94, vcc, 0x4233000, v138
	global_load_dwordx4 v[86:89], v[86:87], off offset:256
	s_nop 0
	v_addc_co_u32_e32 v95, vcc, 0, v139, vcc
	v_add_co_u32_e32 v102, vcc, 0xb3d3000, v136
	global_load_dwordx4 v[94:97], v[94:95], off offset:256
	s_nop 0
	v_addc_co_u32_e32 v103, vcc, 0, v137, vcc
	global_load_dwordx4 v[102:105], v[102:103], off offset:256
; DEV int tidx() { int t = threadIdx.x; asm volatile("" : "+v"(t)); return t; }
; DEV f32x4 mfma16(bf16x8 a, bf16x8 b, f32x4 c) { return __builtin_amdgcn_mfma_f32_16x16x32_bf16(a, b, c, 0, 0, 0); }
; #define G_LOAD(RA, RB, KT) { _Pragma("unroll") for (int i = 0; i < 4; i++) { \
;       RA[i] = *(const u32x4*)(Ap + (size_t)(i * 32) * lda + (KT) * 64); RB[i] = *(const u32x4*)(Bp + (size_t)(i * 32) * ldb + (KT) * 64); } }
; #define G_STORE(RA, RB) { _Pragma("unroll") for (int i = 0; i < 4; i++) { \
;       *(u32x4*)(As + (lrow + i * 32) * GLD + lcc * 8) = RA[i]; *(u32x4*)(Bs + (lrow + i * 32) * GLD + lcc * 8) = RB[i]; } }
; template <int TI, int TJ, int KS>
; DEV void mfma_lds(const bf16_t* Arows, int lda, const bf16_t* Brows, int ldb, int i0, int j0, f32x4 (&acc)[TI][TJ]) {
;   const int lane = tidx() & 63, l15 = lane & 15, quad = lane >> 4;
; #pragma unroll
;   for (int ks = 0; ks < KS; ks++) {
;     bf16x8 af[TI], bfr[TJ];
; #pragma unroll
;     for (int i = 0; i < TI; i++) af[i] = *(const bf16x8*)(Arows + (i0 + i * 16 + l15) * lda + ks * 32 + quad * 8);
; #pragma unroll
;     for (int j = 0; j < TJ; j++) bfr[j] = *(const bf16x8*)(Brows + (j0 + j * 16 + l15) * ldb + ks * 32 + quad * 8);
; #pragma unroll
;     for (int i = 0; i < TI; i++)
; #pragma unroll
;       for (int j = 0; j < TJ; j++) acc[i][j] = mfma16(af[i], bfr[j], acc[i][j]);
;   }
; template <class Epi>
; DEV void gemm_tile(const bf16_t* __restrict__ A, int lda, const bf16_t* __restrict__ Bt, int ldb, int K, int m0, int n0,
;                    Epi& epi, char* smem) {
;     ...
;     mfma_lds<4, 4, 2>(Bs, GLD, As, GLD, wn * 64, wm * 64, acc);
;     __syncthreads();
;     G_STORE(ra1, rb1);
;     __syncthreads();
;     if (kt + 3 < nk) G_LOAD(ra1, rb1, kt + 3);
;     mfma_lds<4, 4, 2>(Bs, GLD, As, GLD, wn * 64, wm * 64, acc);
.LBB0_203:
	v_mov_b32_e32 v131, v195
	s_cmp_gt_u32 s1, 12
	v_and_b32_e32 v143, 15, v131
	v_or_b32_e32 v144, v143, v140
	v_and_b32_e32 v148, 48, v131
	v_mul_u32_u24_e32 v131, 0x50, v144
	v_lshl_add_u32 v131, v131, 1, v148
	ds_read_b128 v[144:147], v131 offset:20480
	v_or_b32_e32 v143, v143, v142
	v_mad_u64_u32 v[180:181], s[18:19], v143, s36, v[148:149]
	ds_read_b128 v[148:151], v180
	ds_read_b128 v[152:155], v180 offset:2560
	ds_read_b128 v[156:159], v180 offset:5120
	ds_read_b128 v[160:163], v180 offset:7680
	s_waitcnt lgkmcnt(3)
	v_mfma_f32_16x16x32_bf16 v[126:129], v[144:147], v[148:151], v[126:129]
	ds_read_b128 v[176:179], v180 offset:64
	s_waitcnt lgkmcnt(3)
	v_mfma_f32_16x16x32_bf16 v[122:125], v[144:147], v[152:155], v[122:125]
	s_waitcnt lgkmcnt(2)
	v_mfma_f32_16x16x32_bf16 v[118:121], v[144:147], v[156:159], v[118:121]
	s_waitcnt lgkmcnt(1)
	v_mfma_f32_16x16x32_bf16 v[114:117], v[144:147], v[160:163], v[114:117]
	ds_read_b128 v[144:147], v131 offset:23040
	s_waitcnt lgkmcnt(0)
	v_mfma_f32_16x16x32_bf16 v[110:113], v[144:147], v[148:151], v[110:113]
	v_mfma_f32_16x16x32_bf16 v[74:77], v[144:147], v[152:155], v[74:77]
	v_mfma_f32_16x16x32_bf16 v[38:41], v[144:147], v[156:159], v[38:41]
	v_mfma_f32_16x16x32_bf16 v[34:37], v[144:147], v[160:163], v[34:37]
	ds_read_b128 v[144:147], v131 offset:25600
	s_waitcnt lgkmcnt(0)
	v_mfma_f32_16x16x32_bf16 v[164:167], v[144:147], v[148:151], v[30:33]
	s_nop 2
	ds_read_b128 v[30:33], v131 offset:23104
	v_mfma_f32_16x16x32_bf16 v[168:171], v[144:147], v[152:155], v[26:29]
	v_mfma_f32_16x16x32_bf16 v[172:175], v[144:147], v[156:159], v[22:25]
	v_mfma_f32_16x16x32_bf16 v[144:147], v[144:147], v[160:163], v[18:21]
	s_nop 2
	ds_read_b128 v[18:21], v131 offset:28160
	s_waitcnt lgkmcnt(0)
	v_mfma_f32_16x16x32_bf16 v[148:151], v[18:21], v[148:151], v[14:17]
	s_nop 2
	ds_read_b128 v[14:17], v131 offset:20544
	v_mfma_f32_16x16x32_bf16 v[160:163], v[18:21], v[160:163], v[2:5]
	s_waitcnt lgkmcnt(0)
	v_mfma_f32_16x16x32_bf16 v[2:5], v[14:17], v[176:179], v[126:129]
	s_nop 2
	ds_read_b128 v[126:129], v180 offset:2624
	v_mfma_f32_16x16x32_bf16 v[152:155], v[18:21], v[152:155], v[10:13]
	v_mfma_f32_16x16x32_bf16 v[156:159], v[18:21], v[156:159], v[6:9]
	v_mfma_f32_16x16x32_bf16 v[18:21], v[30:33], v[176:179], v[110:113]
	s_nop 2
	ds_read_b128 v[110:113], v131 offset:25664
	s_waitcnt lgkmcnt(1)
	v_mfma_f32_16x16x32_bf16 v[6:9], v[14:17], v[126:129], v[122:125]
	s_nop 2
	ds_read_b128 v[122:125], v180 offset:5184
	ds_read_b128 v[180:183], v180 offset:7744
	v_mfma_f32_16x16x32_bf16 v[22:25], v[30:33], v[126:129], v[74:77]
	s_waitcnt lgkmcnt(1)
	v_mfma_f32_16x16x32_bf16 v[26:29], v[30:33], v[122:125], v[38:41]
	s_waitcnt lgkmcnt(0)
	v_mfma_f32_16x16x32_bf16 v[30:33], v[30:33], v[180:183], v[34:37]
	v_mfma_f32_16x16x32_bf16 v[34:37], v[110:113], v[176:179], v[164:167]
	s_nop 2
	ds_read_b128 v[164:167], v131 offset:28224
	v_mfma_f32_16x16x32_bf16 v[10:13], v[14:17], v[122:125], v[118:121]
	s_waitcnt lgkmcnt(0)
	s_barrier
	v_mfma_f32_16x16x32_bf16 v[14:17], v[14:17], v[180:183], v[114:117]
	s_waitcnt vmcnt(8)
	ds_write_b128 v130, v[46:49]
	ds_write_b128 v130, v[54:57] offset:20480
	ds_write_b128 v130, v[62:65] offset:5120
	ds_write_b128 v130, v[70:73] offset:25600
	ds_write_b128 v130, v[82:85] offset:10240
	ds_write_b128 v130, v[90:93] offset:30720
	ds_write_b128 v130, v[98:101] offset:15360
	ds_write_b128 v130, v[106:109] offset:35840
	v_mfma_f32_16x16x32_bf16 v[38:41], v[110:113], v[126:129], v[168:171]
	s_waitcnt lgkmcnt(0)
	s_barrier
	v_mfma_f32_16x16x32_bf16 v[74:77], v[110:113], v[122:125], v[172:175]
	v_mfma_f32_16x16x32_bf16 v[110:113], v[110:113], v[180:183], v[144:147]
	v_mfma_f32_16x16x32_bf16 v[114:117], v[164:167], v[176:179], v[148:151]
	v_mfma_f32_16x16x32_bf16 v[118:121], v[164:167], v[126:129], v[152:155]
	v_mfma_f32_16x16x32_bf16 v[122:125], v[164:167], v[122:125], v[156:159]
	v_mfma_f32_16x16x32_bf16 v[126:129], v[164:167], v[180:183], v[160:163]
	s_cbranch_scc1 .LBB0_200
	v_add_co_u32_e32 v46, vcc, 0x4200000, v138
	s_nop 1
	v_addc_co_u32_e32 v47, vcc, 0, v139, vcc
	v_add_co_u32_e32 v54, vcc, 0xb3a0000, v136
	global_load_dwordx4 v[46:49], v[46:47], off offset:384
	s_nop 0
	v_addc_co_u32_e32 v55, vcc, 0, v137, vcc
	v_add_co_u32_e32 v62, vcc, 0x4211000, v138
	global_load_dwordx4 v[54:57], v[54:55], off offset:384
	s_nop 0
	v_addc_co_u32_e32 v63, vcc, 0, v139, vcc
	v_add_co_u32_e32 v70, vcc, 0xb3b1000, v136
	global_load_dwordx4 v[62:65], v[62:63], off offset:384
	s_nop 0
	v_addc_co_u32_e32 v71, vcc, 0, v137, vcc
	v_add_co_u32_e32 v82, vcc, 0x4222000, v138
	global_load_dwordx4 v[70:73], v[70:71], off offset:384
	s_nop 0
	v_addc_co_u32_e32 v83, vcc, 0, v139, vcc
	v_add_co_u32_e32 v90, vcc, 0xb3c2000, v136
	global_load_dwordx4 v[82:85], v[82:83], off offset:384
	s_nop 0
	v_addc_co_u32_e32 v91, vcc, 0, v137, vcc
	v_add_co_u32_e32 v98, vcc, 0x4233000, v138
	global_load_dwordx4 v[90:93], v[90:91], off offset:384
	s_nop 0
	v_addc_co_u32_e32 v99, vcc, 0, v139, vcc
	v_add_co_u32_e32 v106, vcc, 0xb3d3000, v136
	global_load_dwordx4 v[98:101], v[98:99], off offset:384
	s_nop 0
	v_addc_co_u32_e32 v107, vcc, 0, v137, vcc
	global_load_dwordx4 v[106:109], v[106:107], off offset:384
	s_branch .LBB0_200

; DEV int tidx() { int t = threadIdx.x; asm volatile("" : "+v"(t)); return t; }
; #define G_LOAD(RA, RB, KT) { _Pragma("unroll") for (int i = 0; i < 4; i++) { \
;       RA[i] = *(const u32x4*)(Ap + (size_t)(i * 32) * lda + (KT) * 64); RB[i] = *(const u32x4*)(Bp + (size_t)(i * 32) * ldb + (KT) * 64); } }
; template <class Epi>
; DEV void gemm_tile(const bf16_t* __restrict__ A, int lda, const bf16_t* __restrict__ Bt, int ldb, int K, int m0, int n0,
;                    Epi& epi, char* smem) {
;   bf16_t* As = (bf16_t*)smem;
;   bf16_t* Bs = As + 128 * GLD;
;   const int tid = tidx(), lane = tid & 63, w = tid >> 6, wm = w >> 1, wn = w & 1;
;   const int l15 = lane & 15, quad = lane >> 4;
;   f32x4 acc[4][4];
; #pragma unroll
;   for (int i = 0; i < 4; i++)
; #pragma unroll
;     for (int j = 0; j < 4; j++) acc[i][j] = (f32x4){0.f, 0.f, 0.f, 0.f};
;   u32x4 ra0[4], rb0[4], ra1[4], rb1[4];
;   const int nk = K >> 6;
;   const int lrow = tid >> 3, lcc = tid & 7;
;   const bf16_t* Ap = A + (size_t)(m0 + lrow) * lda + lcc * 8;
;   const bf16_t* Bp = Bt + (size_t)(n0 + lrow) * ldb + lcc * 8;
;     ...
;   G_LOAD(ra0, rb0, 0);
;   G_LOAD(ra1, rb1, 1);
; DEV void phase_gemm_hgin(const Params& p, char* smem) {
;     ...
;   const int items = (MT / 128) * 40;
;   for (int item = blockIdx.x; item < items; item += gridDim.x) {
;     int mt = item / 40, nt = item - mt * 40;
;     gemm_tile(WSP(bf16_t, OFF_H), LDH, WSP(bf16_t, S_WHGIN), LDH, 1024, mt * 128, nt * 128, epi, smem);
.LBB0_323:
	s_mul_hi_i32 s0, s21, 0x66666667
	s_lshr_b32 s1, s0, 31
	s_ashr_i32 s0, s0, 4
	s_add_i32 s1, s0, s1
	s_mul_i32 s0, s1, 0xffffffd8
	s_add_i32 s0, s0, s21
	v_mov_b32_e32 v140, v195
	s_lshl_b32 s12, s1, 7
	s_lshl_b32 s13, s0, 7
	v_mov_b64_e32 v[2:3], s[28:29]
	v_ashrrev_i32_e32 v18, 3, v140
	v_add_u32_e32 v19, s12, v18
	s_movk_i32 s10, 0x880
	v_lshlrev_b32_e32 v0, 4, v140
	v_add_u32_e32 v6, s13, v18
	v_mov_b64_e32 v[4:5], s[18:19]
	v_mad_i64_i32 v[2:3], s[6:7], v19, s10, v[2:3]
	v_and_b32_e32 v0, 0x70, v0
	v_mad_i64_i32 v[4:5], s[6:7], v6, s10, v[4:5]
	v_lshl_add_u64 v[2:3], v[2:3], 0, v[0:1]
	s_mov_b32 s6, 0x11000
	v_add_co_u32_e32 v6, vcc, s6, v2
	v_lshl_add_u64 v[4:5], v[4:5], 0, v[0:1]
	s_nop 0
	v_addc_co_u32_e32 v7, vcc, 0, v3, vcc
	v_add_co_u32_e32 v8, vcc, s6, v4
	s_mov_b32 s6, 0x22000
	s_nop 0
	v_addc_co_u32_e32 v9, vcc, 0, v5, vcc
	v_add_co_u32_e32 v10, vcc, s6, v2
	s_mulk_i32 s1, 0x1400
	s_nop 0
	v_addc_co_u32_e32 v11, vcc, 0, v3, vcc
	v_add_co_u32_e32 v12, vcc, s6, v4
	s_mov_b32 s6, 0x33000
	s_nop 0
	v_addc_co_u32_e32 v13, vcc, 0, v5, vcc
	s_waitcnt vmcnt(22)
	v_add_co_u32_e32 v14, vcc, s6, v2
	v_and_b32_e32 v142, 64, v140
	s_nop 0
	v_addc_co_u32_e32 v15, vcc, 0, v3, vcc
	v_add_co_u32_e32 v16, vcc, s6, v4
	v_mad_u64_u32 v[130:131], s[6:7], v18, s36, v[0:1]
	s_nop 0
	v_addc_co_u32_e32 v17, vcc, 0, v5, vcc
	global_load_dwordx4 v[66:69], v[2:3], off
	global_load_dwordx4 v[74:77], v[4:5], off
	global_load_dwordx4 v[82:85], v[6:7], off
	global_load_dwordx4 v[90:93], v[8:9], off
	global_load_dwordx4 v[98:101], v[10:11], off
	global_load_dwordx4 v[106:109], v[12:13], off
	global_load_dwordx4 v[114:117], v[14:15], off
	global_load_dwordx4 v[122:125], v[16:17], off
	global_load_dwordx4 v[70:73], v[2:3], off offset:128
	global_load_dwordx4 v[78:81], v[4:5], off offset:128
	global_load_dwordx4 v[86:89], v[6:7], off offset:128
	global_load_dwordx4 v[94:97], v[8:9], off offset:128
	global_load_dwordx4 v[102:105], v[10:11], off offset:128
	global_load_dwordx4 v[110:113], v[12:13], off offset:128
	global_load_dwordx4 v[118:121], v[14:15], off offset:128
	global_load_dwordx4 v[126:129], v[16:17], off offset:128
	v_ashrrev_i32_e32 v2, 1, v140
	v_readlane_b32 s6, v254, 0
	v_and_b32_e32 v141, 0xffffffc0, v2
	v_add_u32_e32 v2, s20, v18
	v_readlane_b32 s7, v254, 1
	v_subrev_u32_e32 v4, s1, v2
	v_and_b32_e32 v0, 7, v140
	v_mov_b64_e32 v[2:3], s[6:7]
	v_mad_i64_i32 v[132:133], s[6:7], v4, s10, v[2:3]
	v_mad_i64_i32 v[134:135], s[6:7], v19, s10, v[2:3]
	v_mov_b32_e32 v2, 0
	v_lshlrev_b32_e32 v0, 4, v0
	s_mov_b32 s1, -2
	v_mov_b32_e32 v3, v2
	v_mov_b32_e32 v4, v2
	v_mov_b32_e32 v5, v2
	v_mov_b32_e32 v6, v2
	v_mov_b32_e32 v7, v2
	v_mov_b32_e32 v8, v2
	v_mov_b32_e32 v9, v2
	v_mov_b32_e32 v10, v2
	v_mov_b32_e32 v11, v2
	v_mov_b32_e32 v12, v2
	v_mov_b32_e32 v13, v2
	v_mov_b32_e32 v14, v2
	v_mov_b32_e32 v15, v2
	v_mov_b32_e32 v16, v2
	v_mov_b32_e32 v17, v2
	v_mov_b32_e32 v18, v2
	v_mov_b32_e32 v19, v2
	v_mov_b32_e32 v20, v2
	v_mov_b32_e32 v21, v2
	s_waitcnt vmcnt(37)
	v_mov_b32_e32 v22, v2
	v_mov_b32_e32 v23, v2
	v_mov_b32_e32 v24, v2
	v_mov_b32_e32 v25, v2
	v_mov_b32_e32 v26, v2
	v_mov_b32_e32 v27, v2
	v_mov_b32_e32 v28, v2
	v_mov_b32_e32 v29, v2
	s_waitcnt vmcnt(36)
	v_mov_b32_e32 v30, v2
	v_mov_b32_e32 v31, v2
	v_mov_b32_e32 v32, v2
	v_mov_b32_e32 v33, v2
	v_mov_b32_e32 v34, v2
	v_mov_b32_e32 v35, v2
	v_mov_b32_e32 v36, v2
	v_mov_b32_e32 v37, v2
	s_waitcnt vmcnt(35)
	v_mov_b32_e32 v38, v2
	v_mov_b32_e32 v39, v2
	v_mov_b32_e32 v40, v2
	v_mov_b32_e32 v41, v2
	v_mov_b32_e32 v42, v2
	v_mov_b32_e32 v43, v2
	v_mov_b32_e32 v44, v2
	v_mov_b32_e32 v45, v2
	s_waitcnt vmcnt(34)
	v_mov_b32_e32 v46, v2
	v_mov_b32_e32 v47, v2
	v_mov_b32_e32 v48, v2
	v_mov_b32_e32 v49, v2
	v_mov_b32_e32 v50, v2
	v_mov_b32_e32 v51, v2
	v_mov_b32_e32 v52, v2
	v_mov_b32_e32 v53, v2
	s_waitcnt vmcnt(33)
	v_mov_b32_e32 v54, v2
	v_mov_b32_e32 v55, v2
	v_mov_b32_e32 v56, v2
	v_mov_b32_e32 v57, v2
	v_mov_b32_e32 v58, v2
	v_mov_b32_e32 v59, v2
	v_mov_b32_e32 v60, v2
	v_mov_b32_e32 v61, v2
	s_waitcnt vmcnt(32)
	v_mov_b32_e32 v62, v2
	v_mov_b32_e32 v63, v2
	v_mov_b32_e32 v64, v2
	v_mov_b32_e32 v65, v2
	s_branch .LBB0_325

; #define G_LOAD(RA, RB, KT) { _Pragma("unroll") for (int i = 0; i < 4; i++) { \
;       RA[i] = *(const u32x4*)(Ap + (size_t)(i * 32) * lda + (KT) * 64); RB[i] = *(const u32x4*)(Bp + (size_t)(i * 32) * ldb + (KT) * 64); } }
; #define G_STORE(RA, RB) { _Pragma("unroll") for (int i = 0; i < 4; i++) { \
;       *(u32x4*)(As + (lrow + i * 32) * GLD + lcc * 8) = RA[i]; *(u32x4*)(Bs + (lrow + i * 32) * GLD + lcc * 8) = RB[i]; } }
; template <class Epi>
; DEV void gemm_tile(const bf16_t* __restrict__ A, int lda, const bf16_t* __restrict__ Bt, int ldb, int K, int m0, int n0,
;                    Epi& epi, char* smem) {
;     ...
;   G_LOAD(ra0, rb0, 0);
;   G_LOAD(ra1, rb1, 1);
;   for (int kt = 0; kt < nk; kt += 2) {
;     __syncthreads();
;     G_STORE(ra0, rb0);
;     __syncthreads();
;     if (kt + 2 < nk) G_LOAD(ra0, rb0, kt + 2);
.LBB0_325:
	s_add_i32 s1, s1, 2
	s_cmp_gt_u32 s1, 13
	s_cselect_b64 s[6:7], -1, 0
	s_and_b64 vcc, exec, s[6:7]
	v_lshl_add_u64 v[138:139], v[134:135], 0, v[0:1]
	v_lshl_add_u64 v[136:137], v[132:133], 0, v[0:1]
	s_waitcnt lgkmcnt(0)
	s_barrier
	s_waitcnt vmcnt(8)
	ds_write_b128 v130, v[66:69]
	ds_write_b128 v130, v[74:77] offset:20480
	ds_write_b128 v130, v[82:85] offset:5120
	ds_write_b128 v130, v[90:93] offset:25600
	ds_write_b128 v130, v[98:101] offset:10240
	ds_write_b128 v130, v[106:109] offset:30720
	ds_write_b128 v130, v[114:117] offset:15360
	ds_write_b128 v130, v[122:125] offset:35840
	s_waitcnt lgkmcnt(0)
	s_barrier
	s_cbranch_vccnz .Lgw_skip_2
	v_add_co_u32_e32 v66, vcc, 0x4200000, v138
	s_nop 1
	v_addc_co_u32_e32 v67, vcc, 0, v139, vcc
	v_add_co_u32_e32 v74, vcc, 0xa900000, v136
	global_load_dwordx4 v[66:69], v[66:67], off offset:256
	s_nop 0
	v_addc_co_u32_e32 v75, vcc, 0, v137, vcc
	v_add_co_u32_e32 v82, vcc, 0x4211000, v138
	global_load_dwordx4 v[74:77], v[74:75], off offset:256
	s_nop 0
	v_addc_co_u32_e32 v83, vcc, 0, v139, vcc
	v_add_co_u32_e32 v90, vcc, 0xa911000, v136
	global_load_dwordx4 v[82:85], v[82:83], off offset:256
	s_nop 0
	v_addc_co_u32_e32 v91, vcc, 0, v137, vcc
	v_add_co_u32_e32 v98, vcc, 0x4222000, v138
	global_load_dwordx4 v[90:93], v[90:91], off offset:256
	s_nop 0
	v_addc_co_u32_e32 v99, vcc, 0, v139, vcc
	v_add_co_u32_e32 v106, vcc, 0xa922000, v136
	global_load_dwordx4 v[98:101], v[98:99], off offset:256
	s_nop 0
	v_addc_co_u32_e32 v107, vcc, 0, v137, vcc
	v_add_co_u32_e32 v114, vcc, 0x4233000, v138
	global_load_dwordx4 v[106:109], v[106:107], off offset:256
	s_nop 0
	v_addc_co_u32_e32 v115, vcc, 0, v139, vcc
	v_add_co_u32_e32 v122, vcc, 0xa933000, v136
	global_load_dwordx4 v[114:117], v[114:115], off offset:256
	s_nop 0
	v_addc_co_u32_e32 v123, vcc, 0, v137, vcc
	global_load_dwordx4 v[122:125], v[122:123], off offset:256
; DEV int tidx() { int t = threadIdx.x; asm volatile("" : "+v"(t)); return t; }
; DEV f32x4 mfma16(bf16x8 a, bf16x8 b, f32x4 c) { return __builtin_amdgcn_mfma_f32_16x16x32_bf16(a, b, c, 0, 0, 0); }
; #define G_LOAD(RA, RB, KT) { _Pragma("unroll") for (int i = 0; i < 4; i++) { \
;       RA[i] = *(const u32x4*)(Ap + (size_t)(i * 32) * lda + (KT) * 64); RB[i] = *(const u32x4*)(Bp + (size_t)(i * 32) * ldb + (KT) * 64); } }
; #define G_STORE(RA, RB) { _Pragma("unroll") for (int i = 0; i < 4; i++) { \
;       *(u32x4*)(As + (lrow + i * 32) * GLD + lcc * 8) = RA[i]; *(u32x4*)(Bs + (lrow + i * 32) * GLD + lcc * 8) = RB[i]; } }
; template <int TI, int TJ, int KS>
; DEV void mfma_lds(const bf16_t* Arows, int lda, const bf16_t* Brows, int ldb, int i0, int j0, f32x4 (&acc)[TI][TJ]) {
;   const int lane = tidx() & 63, l15 = lane & 15, quad = lane >> 4;
; #pragma unroll
;   for (int ks = 0; ks < KS; ks++) {
;     bf16x8 af[TI], bfr[TJ];
; #pragma unroll
;     for (int i = 0; i < TI; i++) af[i] = *(const bf16x8*)(Arows + (i0 + i * 16 + l15) * lda + ks * 32 + quad * 8);
; #pragma unroll
;     for (int j = 0; j < TJ; j++) bfr[j] = *(const bf16x8*)(Brows + (j0 + j * 16 + l15) * ldb + ks * 32 + quad * 8);
; #pragma unroll
;     for (int i = 0; i < TI; i++)
; #pragma unroll
;       for (int j = 0; j < TJ; j++) acc[i][j] = mfma16(af[i], bfr[j], acc[i][j]);
;   }
; template <class Epi>
; DEV void gemm_tile(const bf16_t* __restrict__ A, int lda, const bf16_t* __restrict__ Bt, int ldb, int K, int m0, int n0,
;                    Epi& epi, char* smem) {
;     ...
;     mfma_lds<4, 4, 2>(Bs, GLD, As, GLD, wn * 64, wm * 64, acc);
;     __syncthreads();
;     G_STORE(ra1, rb1);
;     __syncthreads();
;     if (kt + 3 < nk) G_LOAD(ra1, rb1, kt + 3);
;     mfma_lds<4, 4, 2>(Bs, GLD, As, GLD, wn * 64, wm * 64, acc);
.LBB0_327:
	v_mov_b32_e32 v131, v195
	s_cmp_gt_u32 s1, 12
	v_and_b32_e32 v143, 15, v131
	v_or_b32_e32 v144, v143, v142
	v_and_b32_e32 v148, 48, v131
	v_mul_u32_u24_e32 v131, 0x50, v144
	v_lshl_add_u32 v131, v131, 1, v148
	ds_read_b128 v[144:147], v131 offset:20480
	v_or_b32_e32 v143, v143, v141
	v_mad_u64_u32 v[180:181], s[10:11], v143, s36, v[148:149]
	ds_read_b128 v[148:151], v180
	ds_read_b128 v[152:155], v180 offset:2560
	ds_read_b128 v[156:159], v180 offset:5120
	ds_read_b128 v[160:163], v180 offset:7680
	s_waitcnt lgkmcnt(3)
	v_mfma_f32_16x16x32_bf16 v[62:65], v[144:147], v[148:151], v[62:65]
	ds_read_b128 v[176:179], v180 offset:64
	s_waitcnt lgkmcnt(3)
	v_mfma_f32_16x16x32_bf16 v[58:61], v[144:147], v[152:155], v[58:61]
	s_waitcnt lgkmcnt(2)
	v_mfma_f32_16x16x32_bf16 v[54:57], v[144:147], v[156:159], v[54:57]
	s_waitcnt lgkmcnt(1)
	v_mfma_f32_16x16x32_bf16 v[50:53], v[144:147], v[160:163], v[50:53]
	ds_read_b128 v[144:147], v131 offset:23040
	s_waitcnt lgkmcnt(0)
	v_mfma_f32_16x16x32_bf16 v[46:49], v[144:147], v[148:151], v[46:49]
	v_mfma_f32_16x16x32_bf16 v[42:45], v[144:147], v[152:155], v[42:45]
	v_mfma_f32_16x16x32_bf16 v[38:41], v[144:147], v[156:159], v[38:41]
	v_mfma_f32_16x16x32_bf16 v[34:37], v[144:147], v[160:163], v[34:37]
	ds_read_b128 v[144:147], v131 offset:25600
	s_waitcnt lgkmcnt(0)
	v_mfma_f32_16x16x32_bf16 v[164:167], v[144:147], v[148:151], v[30:33]
	s_nop 2
	ds_read_b128 v[30:33], v131 offset:23104
	v_mfma_f32_16x16x32_bf16 v[168:171], v[144:147], v[152:155], v[26:29]
	v_mfma_f32_16x16x32_bf16 v[172:175], v[144:147], v[156:159], v[22:25]
	v_mfma_f32_16x16x32_bf16 v[144:147], v[144:147], v[160:163], v[18:21]
	s_nop 2
	ds_read_b128 v[18:21], v131 offset:28160
	s_waitcnt lgkmcnt(0)
	v_mfma_f32_16x16x32_bf16 v[148:151], v[18:21], v[148:151], v[14:17]
	s_nop 2
	ds_read_b128 v[14:17], v131 offset:20544
	v_mfma_f32_16x16x32_bf16 v[160:163], v[18:21], v[160:163], v[2:5]
	s_waitcnt lgkmcnt(0)
	v_mfma_f32_16x16x32_bf16 v[2:5], v[14:17], v[176:179], v[62:65]
	s_nop 2
	ds_read_b128 v[62:65], v180 offset:2624
	v_mfma_f32_16x16x32_bf16 v[152:155], v[18:21], v[152:155], v[10:13]
	v_mfma_f32_16x16x32_bf16 v[156:159], v[18:21], v[156:159], v[6:9]
	v_mfma_f32_16x16x32_bf16 v[18:21], v[30:33], v[176:179], v[46:49]
	s_nop 2
	ds_read_b128 v[46:49], v131 offset:25664
	s_waitcnt lgkmcnt(1)
	v_mfma_f32_16x16x32_bf16 v[6:9], v[14:17], v[62:65], v[58:61]
	s_nop 2
	ds_read_b128 v[58:61], v180 offset:5184
	ds_read_b128 v[180:183], v180 offset:7744
	v_mfma_f32_16x16x32_bf16 v[22:25], v[30:33], v[62:65], v[42:45]
	s_waitcnt lgkmcnt(1)
	v_mfma_f32_16x16x32_bf16 v[26:29], v[30:33], v[58:61], v[38:41]
	s_waitcnt lgkmcnt(0)
	v_mfma_f32_16x16x32_bf16 v[30:33], v[30:33], v[180:183], v[34:37]
	v_mfma_f32_16x16x32_bf16 v[34:37], v[46:49], v[176:179], v[164:167]
	s_nop 2
	ds_read_b128 v[164:167], v131 offset:28224
	v_mfma_f32_16x16x32_bf16 v[10:13], v[14:17], v[58:61], v[54:57]
	s_waitcnt lgkmcnt(0)
	s_barrier
	v_mfma_f32_16x16x32_bf16 v[14:17], v[14:17], v[180:183], v[50:53]
	s_waitcnt vmcnt(8)
	ds_write_b128 v130, v[70:73]
	ds_write_b128 v130, v[78:81] offset:20480
	ds_write_b128 v130, v[86:89] offset:5120
	ds_write_b128 v130, v[94:97] offset:25600
	ds_write_b128 v130, v[102:105] offset:10240
	ds_write_b128 v130, v[110:113] offset:30720
	ds_write_b128 v130, v[118:121] offset:15360
	ds_write_b128 v130, v[126:129] offset:35840
	v_mfma_f32_16x16x32_bf16 v[38:41], v[46:49], v[62:65], v[168:171]
	s_waitcnt lgkmcnt(0)
	s_barrier
	v_mfma_f32_16x16x32_bf16 v[42:45], v[46:49], v[58:61], v[172:175]
	v_mfma_f32_16x16x32_bf16 v[46:49], v[46:49], v[180:183], v[144:147]
	v_mfma_f32_16x16x32_bf16 v[50:53], v[164:167], v[176:179], v[148:151]
	v_mfma_f32_16x16x32_bf16 v[54:57], v[164:167], v[62:65], v[152:155]
	v_mfma_f32_16x16x32_bf16 v[58:61], v[164:167], v[58:61], v[156:159]
	v_mfma_f32_16x16x32_bf16 v[62:65], v[164:167], v[180:183], v[160:163]
	s_cbranch_scc1 .LBB0_324
	v_add_co_u32_e32 v70, vcc, 0x4200000, v138
	s_nop 1
	v_addc_co_u32_e32 v71, vcc, 0, v139, vcc
	v_add_co_u32_e32 v78, vcc, 0xa900000, v136
	global_load_dwordx4 v[70:73], v[70:71], off offset:384
	s_nop 0
	v_addc_co_u32_e32 v79, vcc, 0, v137, vcc
	v_add_co_u32_e32 v86, vcc, 0x4211000, v138
	global_load_dwordx4 v[78:81], v[78:79], off offset:384
	s_nop 0
	v_addc_co_u32_e32 v87, vcc, 0, v139, vcc
	v_add_co_u32_e32 v94, vcc, 0xa911000, v136
	global_load_dwordx4 v[86:89], v[86:87], off offset:384
	s_nop 0
	v_addc_co_u32_e32 v95, vcc, 0, v137, vcc
	v_add_co_u32_e32 v102, vcc, 0x4222000, v138
	global_load_dwordx4 v[94:97], v[94:95], off offset:384
	s_nop 0
	v_addc_co_u32_e32 v103, vcc, 0, v139, vcc
	v_add_co_u32_e32 v110, vcc, 0xa922000, v136
	global_load_dwordx4 v[102:105], v[102:103], off offset:384
	s_nop 0
	v_addc_co_u32_e32 v111, vcc, 0, v137, vcc
	v_add_co_u32_e32 v118, vcc, 0x4233000, v138
	global_load_dwordx4 v[110:113], v[110:111], off offset:384
	s_nop 0
	v_addc_co_u32_e32 v119, vcc, 0, v139, vcc
	v_add_co_u32_e32 v126, vcc, 0xa933000, v136
	global_load_dwordx4 v[118:121], v[118:119], off offset:384
	s_nop 0
	v_addc_co_u32_e32 v127, vcc, 0, v137, vcc
	global_load_dwordx4 v[126:129], v[126:127], off offset:384
	s_branch .LBB0_324

; DEV float sigm(float x) { return 1.f / (1.f + __expf(-x)); }
;   DEV void operator()(int m, int n, f32x4 v) {
;     ...
;     if (seg == 1 || seg == 2) {
;       const int dir = seg - 1;
; #pragma unroll
;       for (int r = 0; r < 4; r++) {
;         float lb = sigm(lbp[(2 + dir) * 1024 + c + r] - lbp[dir * 1024 + c + r]);
;         float ff = lb + (1.f - lb) * sigm(v[r]);
;         v[r] = __logf(ff);
.LBB0_344:
	v_lshrrev_b32_e32 v0, 2, v140
	v_and_or_b32 v0, v0, 12, s13
	s_movk_i32 s23, 0x3cc
	s_waitcnt vmcnt(6)
	v_bitop3_b32 v79, v0, s23, v142 bitop3:0xc8
	s_and_b32 s23, s13, 0xfffffc00
	v_or_b32_e32 v78, v0, v142
	s_add_i32 s13, s23, 0x400
	v_or_b32_e32 v66, s13, v79
	v_add_u32_e32 v68, 0xfffffc00, v78
	v_ashrrev_i32_e32 v67, 31, v66
	v_ashrrev_i32_e32 v69, 31, v68
	s_andn2_b64 vcc, exec, s[0:1]
	v_lshl_add_u64 v[74:75], v[66:67], 2, s[46:47]
	v_lshl_add_u64 v[76:77], v[68:69], 2, s[46:47]
	s_cbranch_vccnz .LBB0_346
	global_load_dwordx4 v[66:69], v[74:75], off
	global_load_dwordx4 v[70:73], v[76:77], off
	s_mov_b32 s34, 0x800000
	s_mov_b32 s13, 0x7f800000
	s_waitcnt vmcnt(0)
	v_mov_b32_e32 v84, v66
	v_mov_b32_e32 v85, v67
	v_mov_b32_e32 v86, v68
	v_mov_b32_e32 v87, v69
	v_mov_b32_e32 v88, v70
	v_mov_b32_e32 v89, v71
	v_mov_b32_e32 v90, v72
	v_mov_b32_e32 v91, v73
	v_sub_f32_e32 v0, v66, v70
	v_mul_f32_e32 v0, 0xbfb8aa3b, v0
	v_exp_f32_e32 v80, v0
	v_mul_f32_e32 v0, 0xbfb8aa3b, v62
	v_exp_f32_e32 v81, v0
	s_nop 0
	v_pk_add_f32 v[80:81], v[80:81], 1.0 op_sel_hi:[1,0]
	s_nop 0
	v_div_scale_f32 v0, s[0:1], v81, v81, 1.0
	v_rcp_f32_e32 v62, v0
	s_nop 0
	v_fma_f32 v66, -v0, v62, 1.0
	v_fmac_f32_e32 v62, v66, v62
	v_div_scale_f32 v66, vcc, 1.0, v81, 1.0
	v_mul_f32_e32 v70, v66, v62
	v_fma_f32 v82, -v0, v70, v66
	v_fmac_f32_e32 v70, v82, v62
	v_fma_f32 v0, -v0, v70, v66
	v_div_fmas_f32 v0, v0, v62, v70
	v_div_scale_f32 v62, s[0:1], v80, v80, 1.0
	v_rcp_f32_e32 v66, v62
	v_div_fixup_f32 v0, v0, v81, 1.0
	v_fma_f32 v70, -v62, v66, 1.0
	v_fmac_f32_e32 v66, v70, v66
	v_div_scale_f32 v70, vcc, 1.0, v80, 1.0
	v_mul_f32_e32 v81, v70, v66
	v_fma_f32 v82, -v62, v81, v70
	v_fmac_f32_e32 v81, v82, v66
	v_fma_f32 v62, -v62, v81, v70
	v_div_fmas_f32 v62, v62, v66, v81
	v_div_fixup_f32 v62, v62, v80, 1.0
	v_sub_f32_e32 v66, 1.0, v62
	v_fmac_f32_e32 v62, v0, v66
	v_cmp_gt_f32_e32 vcc, s34, v62
	s_nop 1
	v_cndmask_b32_e64 v0, 0, 32, vcc
	v_ldexp_f32 v0, v62, v0
	v_log_f32_e32 v0, v0
	s_nop 0
	v_mul_f32_e32 v62, 0x3f317217, v0
	v_fma_f32 v62, v0, s37, -v62
	v_fmac_f32_e32 v62, 0x3377d1cf, v0
	v_fmac_f32_e32 v62, 0x3f317217, v0
	v_cmp_lt_f32_e64 s[38:39], |v0|, s13
	s_nop 1
	v_cndmask_b32_e64 v0, v0, v62, s[38:39]
	v_cndmask_b32_e32 v62, 0, v225, vcc
	v_sub_f32_e32 v62, v0, v62
	v_sub_f32_e32 v0, v67, v71
	v_mul_f32_e32 v0, 0xbfb8aa3b, v0
	v_exp_f32_e32 v66, v0
	v_mul_f32_e32 v0, 0xbfb8aa3b, v63
	v_exp_f32_e32 v67, v0
	s_nop 0
	v_pk_add_f32 v[66:67], v[66:67], 1.0 op_sel_hi:[1,0]
	s_nop 0
	v_div_scale_f32 v0, s[0:1], v67, v67, 1.0
	v_rcp_f32_e32 v63, v0
	s_nop 0
	v_fma_f32 v70, -v0, v63, 1.0
	v_fmac_f32_e32 v63, v70, v63
	v_div_scale_f32 v70, vcc, 1.0, v67, 1.0
	v_mul_f32_e32 v71, v70, v63
	v_fma_f32 v80, -v0, v71, v70
	v_fmac_f32_e32 v71, v80, v63
	v_fma_f32 v0, -v0, v71, v70
	v_div_fmas_f32 v0, v0, v63, v71
	v_div_scale_f32 v63, s[0:1], v66, v66, 1.0
	v_div_fixup_f32 v0, v0, v67, 1.0
	v_rcp_f32_e32 v67, v63
	s_nop 0
	v_fma_f32 v70, -v63, v67, 1.0
	v_fmac_f32_e32 v67, v70, v67
	v_div_scale_f32 v70, vcc, 1.0, v66, 1.0
	v_mul_f32_e32 v71, v70, v67
	v_fma_f32 v80, -v63, v71, v70
	v_fmac_f32_e32 v71, v80, v67
	v_fma_f32 v63, -v63, v71, v70
	v_div_fmas_f32 v63, v63, v67, v71
	v_div_fixup_f32 v63, v63, v66, 1.0
	v_sub_f32_e32 v66, 1.0, v63
	v_fmac_f32_e32 v63, v0, v66
	v_cmp_gt_f32_e32 vcc, s34, v63
	s_nop 1
	v_cndmask_b32_e64 v0, 0, 32, vcc
	v_ldexp_f32 v0, v63, v0
	v_log_f32_e32 v0, v0
	s_nop 0
	v_mul_f32_e32 v63, 0x3f317217, v0
	v_fma_f32 v63, v0, s37, -v63
	v_fmac_f32_e32 v63, 0x3377d1cf, v0
	v_fmac_f32_e32 v63, 0x3f317217, v0
	v_cmp_lt_f32_e64 s[38:39], |v0|, s13
	s_nop 1
	v_cndmask_b32_e64 v0, v0, v63, s[38:39]
	v_cndmask_b32_e32 v63, 0, v225, vcc
	v_sub_f32_e32 v63, v0, v63
	v_sub_f32_e32 v0, v68, v72
	v_mul_f32_e32 v0, 0xbfb8aa3b, v0
	v_exp_f32_e32 v66, v0
	v_mul_f32_e32 v0, 0xbfb8aa3b, v64
	v_exp_f32_e32 v67, v0
	s_nop 0
	v_pk_add_f32 v[66:67], v[66:67], 1.0 op_sel_hi:[1,0]
	s_nop 0
	v_div_scale_f32 v0, s[0:1], v67, v67, 1.0
	v_rcp_f32_e32 v64, v0
	s_nop 0
	v_fma_f32 v68, -v0, v64, 1.0
	v_fmac_f32_e32 v64, v68, v64
	v_div_scale_f32 v68, vcc, 1.0, v67, 1.0
	v_mul_f32_e32 v70, v68, v64
	v_fma_f32 v71, -v0, v70, v68
	v_fmac_f32_e32 v70, v71, v64
	v_fma_f32 v0, -v0, v70, v68
	v_div_fmas_f32 v0, v0, v64, v70
	v_div_scale_f32 v64, s[0:1], v66, v66, 1.0
	v_div_fixup_f32 v0, v0, v67, 1.0
	v_rcp_f32_e32 v67, v64
	s_nop 0
	v_fma_f32 v68, -v64, v67, 1.0
	v_fmac_f32_e32 v67, v68, v67
	v_div_scale_f32 v68, vcc, 1.0, v66, 1.0
	v_mul_f32_e32 v70, v68, v67
	v_fma_f32 v71, -v64, v70, v68
	v_fmac_f32_e32 v70, v71, v67
	v_fma_f32 v64, -v64, v70, v68
	v_div_fmas_f32 v64, v64, v67, v70
	v_div_fixup_f32 v64, v64, v66, 1.0
	v_sub_f32_e32 v66, 1.0, v64
	v_fmac_f32_e32 v64, v0, v66
	v_cmp_gt_f32_e32 vcc, s34, v64
	s_nop 1
	v_cndmask_b32_e64 v0, 0, 32, vcc
	v_ldexp_f32 v0, v64, v0
	v_log_f32_e32 v0, v0
	s_nop 0
	v_mul_f32_e32 v64, 0x3f317217, v0
	v_fma_f32 v64, v0, s37, -v64
	v_fmac_f32_e32 v64, 0x3377d1cf, v0
	v_fmac_f32_e32 v64, 0x3f317217, v0
	v_cmp_lt_f32_e64 s[38:39], |v0|, s13
	s_nop 1
	v_cndmask_b32_e64 v0, v0, v64, s[38:39]
	v_cndmask_b32_e32 v64, 0, v225, vcc
	v_sub_f32_e32 v64, v0, v64
	v_sub_f32_e32 v0, v69, v73
	v_mul_f32_e32 v0, 0xbfb8aa3b, v0
	v_exp_f32_e32 v66, v0
	v_mul_f32_e32 v0, 0xbfb8aa3b, v65
	v_exp_f32_e32 v67, v0
	s_nop 0
	v_pk_add_f32 v[66:67], v[66:67], 1.0 op_sel_hi:[1,0]
	s_nop 0
	v_div_scale_f32 v0, s[0:1], v67, v67, 1.0
	v_rcp_f32_e32 v65, v0
	s_nop 0
	v_fma_f32 v68, -v0, v65, 1.0
	v_fmac_f32_e32 v65, v68, v65
	v_div_scale_f32 v68, vcc, 1.0, v67, 1.0
	v_mul_f32_e32 v69, v68, v65
	v_fma_f32 v70, -v0, v69, v68
	v_fmac_f32_e32 v69, v70, v65
	v_fma_f32 v0, -v0, v69, v68
	v_div_fmas_f32 v0, v0, v65, v69
	v_div_scale_f32 v65, s[0:1], v66, v66, 1.0
	v_div_fixup_f32 v0, v0, v67, 1.0
	v_rcp_f32_e32 v67, v65
	s_nop 0
	v_fma_f32 v68, -v65, v67, 1.0
	v_fmac_f32_e32 v67, v68, v67
	v_div_scale_f32 v68, vcc, 1.0, v66, 1.0
	v_mul_f32_e32 v69, v68, v67
	v_fma_f32 v70, -v65, v69, v68
	v_fmac_f32_e32 v69, v70, v67
	v_fma_f32 v65, -v65, v69, v68
	v_div_fmas_f32 v65, v65, v67, v69
	v_div_fixup_f32 v65, v65, v66, 1.0
	v_sub_f32_e32 v66, 1.0, v65
	v_fmac_f32_e32 v65, v0, v66
	v_cmp_gt_f32_e32 vcc, s34, v65
	s_mov_b64 s[34:35], 0x100
	s_nop 0
	v_cndmask_b32_e64 v0, 0, 32, vcc
	v_ldexp_f32 v0, v65, v0
	v_log_f32_e32 v0, v0
	s_nop 0
	v_mul_f32_e32 v65, 0x3f317217, v0
	v_fma_f32 v65, v0, s37, -v65
	v_fmac_f32_e32 v65, 0x3377d1cf, v0
	v_fmac_f32_e32 v65, 0x3f317217, v0
	v_cmp_lt_f32_e64 s[38:39], |v0|, s13
	s_nop 1
	v_cndmask_b32_e64 v0, v0, v65, s[38:39]
	v_cndmask_b32_e32 v65, 0, v225, vcc
	v_sub_f32_e32 v65, v0, v65

; DEV float sigm(float x) { return 1.f / (1.f + __expf(-x)); }
;   DEV void operator()(int m, int n, f32x4 v) {
;     ...
;     if (seg == 1 || seg == 2) {
;       const int dir = seg - 1;
; #pragma unroll
;       for (int r = 0; r < 4; r++) {
;         float lb = sigm(lbp[(2 + dir) * 1024 + c + r] - lbp[dir * 1024 + c + r]);
;         float ff = lb + (1.f - lb) * sigm(v[r]);
;         v[r] = __logf(ff);
.LBB0_361:
	s_andn2_b64 vcc, exec, s[0:1]
	s_cbranch_vccnz .LBB0_363
	v_mul_f32_e32 v58, 0xbfb8aa3b, v58
	v_exp_f32_e32 v81, v58
	s_mov_b32 s11, 0x800000
	s_mov_b32 s10, 0x7f800000
	v_mul_f32_e32 v59, 0xbfb8aa3b, v59
	v_mul_f32_e32 v60, 0xbfb8aa3b, v60
	v_mul_f32_e32 v61, 0xbfb8aa3b, v61
	v_mov_b32_e32 v62, v84
	v_mov_b32_e32 v63, v85
	v_mov_b32_e32 v64, v86
	v_mov_b32_e32 v65, v87
	v_mov_b32_e32 v66, v88
	v_mov_b32_e32 v67, v89
	v_mov_b32_e32 v68, v90
	v_mov_b32_e32 v69, v91
	v_sub_f32_e32 v62, v62, v66
	v_mul_f32_e32 v62, 0xbfb8aa3b, v62
	v_exp_f32_e32 v80, v62
	s_nop 0
	v_pk_add_f32 v[80:81], v[80:81], 1.0 op_sel_hi:[1,0]
	s_nop 0
	v_div_scale_f32 v58, s[0:1], v81, v81, 1.0
	v_rcp_f32_e32 v62, v58
	s_nop 0
	v_fma_f32 v66, -v58, v62, 1.0
	v_fmac_f32_e32 v62, v66, v62
	v_div_scale_f32 v66, vcc, 1.0, v81, 1.0
	v_mul_f32_e32 v73, v66, v62
	v_fma_f32 v82, -v58, v73, v66
	v_fmac_f32_e32 v73, v82, v62
	v_fma_f32 v58, -v58, v73, v66
	v_div_fmas_f32 v58, v58, v62, v73
	v_div_scale_f32 v62, s[0:1], v80, v80, 1.0
	v_rcp_f32_e32 v66, v62
	v_div_fixup_f32 v58, v58, v81, 1.0
	v_fma_f32 v73, -v62, v66, 1.0
	v_fmac_f32_e32 v66, v73, v66
	v_div_scale_f32 v73, vcc, 1.0, v80, 1.0
	v_mul_f32_e32 v81, v73, v66
	v_fma_f32 v82, -v62, v81, v73
	v_fmac_f32_e32 v81, v82, v66
	v_fma_f32 v62, -v62, v81, v73
	v_div_fmas_f32 v62, v62, v66, v81
	v_div_fixup_f32 v62, v62, v80, 1.0
	v_sub_f32_e32 v66, 1.0, v62
	v_fmac_f32_e32 v62, v58, v66
	v_cmp_gt_f32_e32 vcc, s11, v62
	s_nop 1
	v_cndmask_b32_e64 v58, 0, 32, vcc
	v_ldexp_f32 v58, v62, v58
	v_log_f32_e32 v58, v58
	s_nop 0
	v_mul_f32_e32 v62, 0x3f317217, v58
	v_fma_f32 v62, v58, s37, -v62
	v_fmac_f32_e32 v62, 0x3377d1cf, v58
	v_fmac_f32_e32 v62, 0x3f317217, v58
	v_cmp_lt_f32_e64 s[42:43], |v58|, s10
	s_nop 1
	v_cndmask_b32_e64 v58, v58, v62, s[42:43]
	v_cndmask_b32_e32 v62, 0, v225, vcc
	v_sub_f32_e32 v58, v58, v62
	v_sub_f32_e32 v62, v63, v67
	v_mul_f32_e32 v62, 0xbfb8aa3b, v62
	v_exp_f32_e32 v62, v62
	v_exp_f32_e32 v63, v59
	s_nop 0
	v_pk_add_f32 v[62:63], v[62:63], 1.0 op_sel_hi:[1,0]
	s_nop 0
	v_div_scale_f32 v59, s[0:1], v63, v63, 1.0
	v_rcp_f32_e32 v66, v59
	s_nop 0
	v_fma_f32 v67, -v59, v66, 1.0
	v_fmac_f32_e32 v66, v67, v66
	v_div_scale_f32 v67, vcc, 1.0, v63, 1.0
	v_mul_f32_e32 v73, v67, v66
	v_fma_f32 v80, -v59, v73, v67
	v_fmac_f32_e32 v73, v80, v66
	v_fma_f32 v59, -v59, v73, v67
	v_div_fmas_f32 v59, v59, v66, v73
	v_div_fixup_f32 v59, v59, v63, 1.0
	v_div_scale_f32 v63, s[0:1], v62, v62, 1.0
	v_rcp_f32_e32 v66, v63
	s_nop 0
	v_fma_f32 v67, -v63, v66, 1.0
	v_fmac_f32_e32 v66, v67, v66
	v_div_scale_f32 v67, vcc, 1.0, v62, 1.0
	v_mul_f32_e32 v73, v67, v66
	v_fma_f32 v80, -v63, v73, v67
	v_fmac_f32_e32 v73, v80, v66
	v_fma_f32 v63, -v63, v73, v67
	v_div_fmas_f32 v63, v63, v66, v73
	v_div_fixup_f32 v62, v63, v62, 1.0
	v_sub_f32_e32 v63, 1.0, v62
	v_fmac_f32_e32 v62, v59, v63
	v_cmp_gt_f32_e32 vcc, s11, v62
	v_exp_f32_e32 v63, v60
	s_nop 0
	v_cndmask_b32_e64 v59, 0, 32, vcc
	v_ldexp_f32 v59, v62, v59
	v_log_f32_e32 v59, v59
	s_nop 0
	v_mul_f32_e32 v62, 0x3f317217, v59
	v_fma_f32 v62, v59, s37, -v62
	v_fmac_f32_e32 v62, 0x3377d1cf, v59
	v_fmac_f32_e32 v62, 0x3f317217, v59
	v_cmp_lt_f32_e64 s[42:43], |v59|, s10
	s_nop 1
	v_cndmask_b32_e64 v59, v59, v62, s[42:43]
	v_cndmask_b32_e32 v62, 0, v225, vcc
	v_sub_f32_e32 v59, v59, v62
	v_sub_f32_e32 v62, v64, v68
	v_mul_f32_e32 v62, 0xbfb8aa3b, v62
	v_exp_f32_e32 v62, v62
	s_nop 0
	v_pk_add_f32 v[62:63], v[62:63], 1.0 op_sel_hi:[1,0]
	s_nop 0
	v_div_scale_f32 v60, s[0:1], v63, v63, 1.0
	v_rcp_f32_e32 v64, v60
	s_nop 0
	v_fma_f32 v66, -v60, v64, 1.0
	v_fmac_f32_e32 v64, v66, v64
	v_div_scale_f32 v66, vcc, 1.0, v63, 1.0
	v_mul_f32_e32 v67, v66, v64
	v_fma_f32 v68, -v60, v67, v66
	v_fmac_f32_e32 v67, v68, v64
	v_fma_f32 v60, -v60, v67, v66
	v_div_fmas_f32 v60, v60, v64, v67
	v_div_fixup_f32 v60, v60, v63, 1.0
	v_div_scale_f32 v63, s[0:1], v62, v62, 1.0
	v_rcp_f32_e32 v64, v63
	s_nop 0
	v_fma_f32 v66, -v63, v64, 1.0
	v_fmac_f32_e32 v64, v66, v64
	v_div_scale_f32 v66, vcc, 1.0, v62, 1.0
	v_mul_f32_e32 v67, v66, v64
	v_fma_f32 v68, -v63, v67, v66
	v_fmac_f32_e32 v67, v68, v64
	v_fma_f32 v63, -v63, v67, v66
	v_div_fmas_f32 v63, v63, v64, v67
	v_div_fixup_f32 v62, v63, v62, 1.0
	v_sub_f32_e32 v63, 1.0, v62
	v_fmac_f32_e32 v62, v60, v63
	v_cmp_gt_f32_e32 vcc, s11, v62
	v_exp_f32_e32 v63, v61
	s_nop 0
	v_cndmask_b32_e64 v60, 0, 32, vcc
	v_ldexp_f32 v60, v62, v60
	v_log_f32_e32 v60, v60
	s_nop 0
	v_mul_f32_e32 v62, 0x3f317217, v60
	v_fma_f32 v62, v60, s37, -v62
	v_fmac_f32_e32 v62, 0x3377d1cf, v60
	v_fmac_f32_e32 v62, 0x3f317217, v60
	v_cmp_lt_f32_e64 s[42:43], |v60|, s10
	s_nop 1
	v_cndmask_b32_e64 v60, v60, v62, s[42:43]
	v_cndmask_b32_e32 v62, 0, v225, vcc
	v_sub_f32_e32 v60, v60, v62
	v_sub_f32_e32 v62, v65, v69
	v_mul_f32_e32 v62, 0xbfb8aa3b, v62
	v_exp_f32_e32 v62, v62
	s_nop 0
	v_pk_add_f32 v[62:63], v[62:63], 1.0 op_sel_hi:[1,0]
	s_nop 0
	v_div_scale_f32 v61, s[0:1], v63, v63, 1.0
	v_rcp_f32_e32 v64, v61
	s_nop 0
	v_fma_f32 v65, -v61, v64, 1.0
	v_fmac_f32_e32 v64, v65, v64
	v_div_scale_f32 v65, vcc, 1.0, v63, 1.0
	v_mul_f32_e32 v66, v65, v64
	v_fma_f32 v67, -v61, v66, v65
	v_fmac_f32_e32 v66, v67, v64
	v_fma_f32 v61, -v61, v66, v65
	v_div_fmas_f32 v61, v61, v64, v66
	v_div_fixup_f32 v61, v61, v63, 1.0
	v_div_scale_f32 v63, s[0:1], v62, v62, 1.0
	v_rcp_f32_e32 v64, v63
	s_nop 0
	v_fma_f32 v65, -v63, v64, 1.0
	v_fmac_f32_e32 v64, v65, v64
	v_div_scale_f32 v65, vcc, 1.0, v62, 1.0
	v_mul_f32_e32 v66, v65, v64
	v_fma_f32 v67, -v63, v66, v65
	v_fmac_f32_e32 v66, v67, v64
	v_fma_f32 v63, -v63, v66, v65
	v_div_fmas_f32 v63, v63, v64, v66
	v_div_fixup_f32 v62, v63, v62, 1.0
	v_sub_f32_e32 v63, 1.0, v62
	v_fmac_f32_e32 v62, v61, v63
	v_cmp_gt_f32_e32 vcc, s11, v62
	s_nop 1
	v_cndmask_b32_e64 v61, 0, 32, vcc
	v_ldexp_f32 v61, v62, v61
	v_log_f32_e32 v61, v61
	s_nop 0
	v_mul_f32_e32 v62, 0x3f317217, v61
	v_fma_f32 v62, v61, s37, -v62
	v_fmac_f32_e32 v62, 0x3377d1cf, v61
	v_fmac_f32_e32 v62, 0x3f317217, v61
	v_cmp_lt_f32_e64 s[42:43], |v61|, s10
	s_nop 1
	v_cndmask_b32_e64 v61, v61, v62, s[42:43]
	v_cndmask_b32_e32 v62, 0, v225, vcc
	v_sub_f32_e32 v61, v61, v62

; DEV float sigm(float x) { return 1.f / (1.f + __expf(-x)); }
;   DEV void operator()(int m, int n, f32x4 v) {
;     ...
;     if (seg == 1 || seg == 2) {
;       const int dir = seg - 1;
; #pragma unroll
;       for (int r = 0; r < 4; r++) {
;         float lb = sigm(lbp[(2 + dir) * 1024 + c + r] - lbp[dir * 1024 + c + r]);
;         float ff = lb + (1.f - lb) * sigm(v[r]);
;         v[r] = __logf(ff);
.LBB0_378:
	s_andn2_b64 vcc, exec, s[0:1]
	s_cbranch_vccnz .LBB0_380
	v_mul_f32_e32 v54, 0xbfb8aa3b, v54
	v_exp_f32_e32 v69, v54
	s_mov_b32 s11, 0x800000
	s_mov_b32 s10, 0x7f800000
	v_mul_f32_e32 v55, 0xbfb8aa3b, v55
	v_mul_f32_e32 v56, 0xbfb8aa3b, v56
	v_mul_f32_e32 v57, 0xbfb8aa3b, v57
	v_mov_b32_e32 v58, v84
	v_mov_b32_e32 v59, v85
	v_mov_b32_e32 v60, v86
	v_mov_b32_e32 v61, v87
	v_mov_b32_e32 v62, v88
	v_mov_b32_e32 v63, v89
	v_mov_b32_e32 v64, v90
	v_mov_b32_e32 v65, v91
	v_sub_f32_e32 v58, v58, v62
	v_mul_f32_e32 v58, 0xbfb8aa3b, v58
	v_exp_f32_e32 v68, v58
	s_nop 0
	v_pk_add_f32 v[68:69], v[68:69], 1.0 op_sel_hi:[1,0]
	s_nop 0
	v_div_scale_f32 v54, s[0:1], v69, v69, 1.0
	v_rcp_f32_e32 v58, v54
	s_nop 0
	v_fma_f32 v62, -v54, v58, 1.0
	v_fmac_f32_e32 v58, v62, v58
	v_div_scale_f32 v62, vcc, 1.0, v69, 1.0
	v_mul_f32_e32 v73, v62, v58
	v_fma_f32 v80, -v54, v73, v62
	v_fmac_f32_e32 v73, v80, v58
	v_fma_f32 v54, -v54, v73, v62
	v_div_fmas_f32 v54, v54, v58, v73
	v_div_scale_f32 v58, s[0:1], v68, v68, 1.0
	v_rcp_f32_e32 v62, v58
	v_div_fixup_f32 v54, v54, v69, 1.0
	v_fma_f32 v69, -v58, v62, 1.0
	v_fmac_f32_e32 v62, v69, v62
	v_div_scale_f32 v69, vcc, 1.0, v68, 1.0
	v_mul_f32_e32 v73, v69, v62
	v_fma_f32 v80, -v58, v73, v69
	v_fmac_f32_e32 v73, v80, v62
	v_fma_f32 v58, -v58, v73, v69
	v_div_fmas_f32 v58, v58, v62, v73
	v_div_fixup_f32 v58, v58, v68, 1.0
	v_sub_f32_e32 v62, 1.0, v58
	v_fmac_f32_e32 v58, v54, v62
	v_cmp_gt_f32_e32 vcc, s11, v58
	s_nop 1
	v_cndmask_b32_e64 v54, 0, 32, vcc
	v_ldexp_f32 v54, v58, v54
	v_log_f32_e32 v54, v54
	s_nop 0
	v_mul_f32_e32 v58, 0x3f317217, v54
	v_fma_f32 v58, v54, s37, -v58
	v_fmac_f32_e32 v58, 0x3377d1cf, v54
	v_fmac_f32_e32 v58, 0x3f317217, v54
	v_cmp_lt_f32_e64 s[42:43], |v54|, s10
	s_nop 1
	v_cndmask_b32_e64 v54, v54, v58, s[42:43]
	v_cndmask_b32_e32 v58, 0, v225, vcc
	v_sub_f32_e32 v54, v54, v58
	v_sub_f32_e32 v58, v59, v63
	v_mul_f32_e32 v58, 0xbfb8aa3b, v58
	v_exp_f32_e32 v58, v58
	v_exp_f32_e32 v59, v55
	s_nop 0
	v_pk_add_f32 v[58:59], v[58:59], 1.0 op_sel_hi:[1,0]
	s_nop 0
	v_div_scale_f32 v55, s[0:1], v59, v59, 1.0
	v_rcp_f32_e32 v62, v55
	s_nop 0
	v_fma_f32 v63, -v55, v62, 1.0
	v_fmac_f32_e32 v62, v63, v62
	v_div_scale_f32 v63, vcc, 1.0, v59, 1.0
	v_mul_f32_e32 v68, v63, v62
	v_fma_f32 v69, -v55, v68, v63
	v_fmac_f32_e32 v68, v69, v62
	v_fma_f32 v55, -v55, v68, v63
	v_div_fmas_f32 v55, v55, v62, v68
	v_div_fixup_f32 v55, v55, v59, 1.0
	v_div_scale_f32 v59, s[0:1], v58, v58, 1.0
	v_rcp_f32_e32 v62, v59
	s_nop 0
	v_fma_f32 v63, -v59, v62, 1.0
	v_fmac_f32_e32 v62, v63, v62
	v_div_scale_f32 v63, vcc, 1.0, v58, 1.0
	v_mul_f32_e32 v68, v63, v62
	v_fma_f32 v69, -v59, v68, v63
	v_fmac_f32_e32 v68, v69, v62
	v_fma_f32 v59, -v59, v68, v63
	v_div_fmas_f32 v59, v59, v62, v68
	v_div_fixup_f32 v58, v59, v58, 1.0
	v_sub_f32_e32 v59, 1.0, v58
	v_fmac_f32_e32 v58, v55, v59
	v_cmp_gt_f32_e32 vcc, s11, v58
	v_exp_f32_e32 v59, v56
	s_nop 0
	v_cndmask_b32_e64 v55, 0, 32, vcc
	v_ldexp_f32 v55, v58, v55
	v_log_f32_e32 v55, v55
	s_nop 0
	v_mul_f32_e32 v58, 0x3f317217, v55
	v_fma_f32 v58, v55, s37, -v58
	v_fmac_f32_e32 v58, 0x3377d1cf, v55
	v_fmac_f32_e32 v58, 0x3f317217, v55
	v_cmp_lt_f32_e64 s[42:43], |v55|, s10
	s_nop 1
	v_cndmask_b32_e64 v55, v55, v58, s[42:43]
	v_cndmask_b32_e32 v58, 0, v225, vcc
	v_sub_f32_e32 v55, v55, v58
	v_sub_f32_e32 v58, v60, v64
	v_mul_f32_e32 v58, 0xbfb8aa3b, v58
	v_exp_f32_e32 v58, v58
	s_nop 0
	v_pk_add_f32 v[58:59], v[58:59], 1.0 op_sel_hi:[1,0]
	s_nop 0
	v_div_scale_f32 v56, s[0:1], v59, v59, 1.0
	v_rcp_f32_e32 v60, v56
	s_nop 0
	v_fma_f32 v62, -v56, v60, 1.0
	v_fmac_f32_e32 v60, v62, v60
	v_div_scale_f32 v62, vcc, 1.0, v59, 1.0
	v_mul_f32_e32 v63, v62, v60
	v_fma_f32 v64, -v56, v63, v62
	v_fmac_f32_e32 v63, v64, v60
	v_fma_f32 v56, -v56, v63, v62
	v_div_fmas_f32 v56, v56, v60, v63
	v_div_fixup_f32 v56, v56, v59, 1.0
	v_div_scale_f32 v59, s[0:1], v58, v58, 1.0
	v_rcp_f32_e32 v60, v59
	s_nop 0
	v_fma_f32 v62, -v59, v60, 1.0
	v_fmac_f32_e32 v60, v62, v60
	v_div_scale_f32 v62, vcc, 1.0, v58, 1.0
	v_mul_f32_e32 v63, v62, v60
	v_fma_f32 v64, -v59, v63, v62
	v_fmac_f32_e32 v63, v64, v60
	v_fma_f32 v59, -v59, v63, v62
	v_div_fmas_f32 v59, v59, v60, v63
	v_div_fixup_f32 v58, v59, v58, 1.0
	v_sub_f32_e32 v59, 1.0, v58
	v_fmac_f32_e32 v58, v56, v59
	v_cmp_gt_f32_e32 vcc, s11, v58
	v_exp_f32_e32 v59, v57
	s_nop 0
	v_cndmask_b32_e64 v56, 0, 32, vcc
	v_ldexp_f32 v56, v58, v56
	v_log_f32_e32 v56, v56
	s_nop 0
	v_mul_f32_e32 v58, 0x3f317217, v56
	v_fma_f32 v58, v56, s37, -v58
	v_fmac_f32_e32 v58, 0x3377d1cf, v56
	v_fmac_f32_e32 v58, 0x3f317217, v56
	v_cmp_lt_f32_e64 s[42:43], |v56|, s10
	s_nop 1
	v_cndmask_b32_e64 v56, v56, v58, s[42:43]
	v_cndmask_b32_e32 v58, 0, v225, vcc
	v_sub_f32_e32 v56, v56, v58
	v_sub_f32_e32 v58, v61, v65
	v_mul_f32_e32 v58, 0xbfb8aa3b, v58
	v_exp_f32_e32 v58, v58
	s_nop 0
	v_pk_add_f32 v[58:59], v[58:59], 1.0 op_sel_hi:[1,0]
	s_nop 0
	v_div_scale_f32 v57, s[0:1], v59, v59, 1.0
	v_rcp_f32_e32 v60, v57
	s_nop 0
	v_fma_f32 v61, -v57, v60, 1.0
	v_fmac_f32_e32 v60, v61, v60
	v_div_scale_f32 v61, vcc, 1.0, v59, 1.0
	v_mul_f32_e32 v62, v61, v60
	v_fma_f32 v63, -v57, v62, v61
	v_fmac_f32_e32 v62, v63, v60
	v_fma_f32 v57, -v57, v62, v61
	v_div_fmas_f32 v57, v57, v60, v62
	v_div_fixup_f32 v57, v57, v59, 1.0
	v_div_scale_f32 v59, s[0:1], v58, v58, 1.0
	v_rcp_f32_e32 v60, v59
	s_nop 0
	v_fma_f32 v61, -v59, v60, 1.0
	v_fmac_f32_e32 v60, v61, v60
	v_div_scale_f32 v61, vcc, 1.0, v58, 1.0
	v_mul_f32_e32 v62, v61, v60
	v_fma_f32 v63, -v59, v62, v61
	v_fmac_f32_e32 v62, v63, v60
	v_fma_f32 v59, -v59, v62, v61
	v_div_fmas_f32 v59, v59, v60, v62
	v_div_fixup_f32 v58, v59, v58, 1.0
	v_sub_f32_e32 v59, 1.0, v58
	v_fmac_f32_e32 v58, v57, v59
	v_cmp_gt_f32_e32 vcc, s11, v58
	s_nop 1
	v_cndmask_b32_e64 v57, 0, 32, vcc
	v_ldexp_f32 v57, v58, v57
	v_log_f32_e32 v57, v57
	s_nop 0
	v_mul_f32_e32 v58, 0x3f317217, v57
	v_fma_f32 v58, v57, s37, -v58
	v_fmac_f32_e32 v58, 0x3377d1cf, v57
	v_fmac_f32_e32 v58, 0x3f317217, v57
	v_cmp_lt_f32_e64 s[42:43], |v57|, s10
	s_nop 1
	v_cndmask_b32_e64 v57, v57, v58, s[42:43]
	v_cndmask_b32_e32 v58, 0, v225, vcc
	v_sub_f32_e32 v57, v57, v58

; DEV float sigm(float x) { return 1.f / (1.f + __expf(-x)); }
;   DEV void operator()(int m, int n, f32x4 v) {
;     ...
;     if (seg == 1 || seg == 2) {
;       const int dir = seg - 1;
; #pragma unroll
;       for (int r = 0; r < 4; r++) {
;         float lb = sigm(lbp[(2 + dir) * 1024 + c + r] - lbp[dir * 1024 + c + r]);
;         float ff = lb + (1.f - lb) * sigm(v[r]);
;         v[r] = __logf(ff);
.LBB0_395:
	s_andn2_b64 vcc, exec, s[0:1]
	s_cbranch_vccnz .LBB0_397
	v_mul_f32_e32 v50, 0xbfb8aa3b, v50
	v_exp_f32_e32 v65, v50
	s_mov_b32 s11, 0x800000
	s_mov_b32 s10, 0x7f800000
	v_mul_f32_e32 v51, 0xbfb8aa3b, v51
	v_mul_f32_e32 v52, 0xbfb8aa3b, v52
	v_mul_f32_e32 v53, 0xbfb8aa3b, v53
	v_mov_b32_e32 v54, v84
	v_mov_b32_e32 v55, v85
	v_mov_b32_e32 v56, v86
	v_mov_b32_e32 v57, v87
	v_mov_b32_e32 v58, v88
	v_mov_b32_e32 v59, v89
	v_mov_b32_e32 v60, v90
	v_mov_b32_e32 v61, v91
	v_sub_f32_e32 v54, v54, v58
	v_mul_f32_e32 v54, 0xbfb8aa3b, v54
	v_exp_f32_e32 v64, v54
	s_nop 0
	v_pk_add_f32 v[64:65], v[64:65], 1.0 op_sel_hi:[1,0]
	s_nop 0
	v_div_scale_f32 v50, s[0:1], v65, v65, 1.0
	v_rcp_f32_e32 v54, v50
	s_nop 0
	v_fma_f32 v58, -v50, v54, 1.0
	v_fmac_f32_e32 v54, v58, v54
	v_div_scale_f32 v58, vcc, 1.0, v65, 1.0
	v_mul_f32_e32 v68, v58, v54
	v_fma_f32 v69, -v50, v68, v58
	v_fmac_f32_e32 v68, v69, v54
	v_fma_f32 v50, -v50, v68, v58
	v_div_fmas_f32 v50, v50, v54, v68
	v_div_scale_f32 v54, s[0:1], v64, v64, 1.0
	v_rcp_f32_e32 v58, v54
	v_div_fixup_f32 v50, v50, v65, 1.0
	v_fma_f32 v65, -v54, v58, 1.0
	v_fmac_f32_e32 v58, v65, v58
	v_div_scale_f32 v65, vcc, 1.0, v64, 1.0
	v_mul_f32_e32 v68, v65, v58
	v_fma_f32 v69, -v54, v68, v65
	v_fmac_f32_e32 v68, v69, v58
	v_fma_f32 v54, -v54, v68, v65
	v_div_fmas_f32 v54, v54, v58, v68
	v_div_fixup_f32 v54, v54, v64, 1.0
	v_sub_f32_e32 v58, 1.0, v54
	v_fmac_f32_e32 v54, v50, v58
	v_cmp_gt_f32_e32 vcc, s11, v54
	s_nop 1
	v_cndmask_b32_e64 v50, 0, 32, vcc
	v_ldexp_f32 v50, v54, v50
	v_log_f32_e32 v50, v50
	s_nop 0
	v_mul_f32_e32 v54, 0x3f317217, v50
	v_fma_f32 v54, v50, s37, -v54
	v_fmac_f32_e32 v54, 0x3377d1cf, v50
	v_fmac_f32_e32 v54, 0x3f317217, v50
	v_cmp_lt_f32_e64 s[42:43], |v50|, s10
	s_nop 1
	v_cndmask_b32_e64 v50, v50, v54, s[42:43]
	v_cndmask_b32_e32 v54, 0, v225, vcc
	v_sub_f32_e32 v50, v50, v54
	v_sub_f32_e32 v54, v55, v59
	v_mul_f32_e32 v54, 0xbfb8aa3b, v54
	v_exp_f32_e32 v54, v54
	v_exp_f32_e32 v55, v51
	s_nop 0
	v_pk_add_f32 v[54:55], v[54:55], 1.0 op_sel_hi:[1,0]
	s_nop 0
	v_div_scale_f32 v51, s[0:1], v55, v55, 1.0
	v_rcp_f32_e32 v58, v51
	s_nop 0
	v_fma_f32 v59, -v51, v58, 1.0
	v_fmac_f32_e32 v58, v59, v58
	v_div_scale_f32 v59, vcc, 1.0, v55, 1.0
	v_mul_f32_e32 v64, v59, v58
	v_fma_f32 v65, -v51, v64, v59
	v_fmac_f32_e32 v64, v65, v58
	v_fma_f32 v51, -v51, v64, v59
	v_div_fmas_f32 v51, v51, v58, v64
	v_div_fixup_f32 v51, v51, v55, 1.0
	v_div_scale_f32 v55, s[0:1], v54, v54, 1.0
	v_rcp_f32_e32 v58, v55
	s_nop 0
	v_fma_f32 v59, -v55, v58, 1.0
	v_fmac_f32_e32 v58, v59, v58
	v_div_scale_f32 v59, vcc, 1.0, v54, 1.0
	v_mul_f32_e32 v64, v59, v58
	v_fma_f32 v65, -v55, v64, v59
	v_fmac_f32_e32 v64, v65, v58
	v_fma_f32 v55, -v55, v64, v59
	v_div_fmas_f32 v55, v55, v58, v64
	v_div_fixup_f32 v54, v55, v54, 1.0
	v_sub_f32_e32 v55, 1.0, v54
	v_fmac_f32_e32 v54, v51, v55
	v_cmp_gt_f32_e32 vcc, s11, v54
	v_exp_f32_e32 v55, v52
	s_nop 0
	v_cndmask_b32_e64 v51, 0, 32, vcc
	v_ldexp_f32 v51, v54, v51
	v_log_f32_e32 v51, v51
	s_nop 0
	v_mul_f32_e32 v54, 0x3f317217, v51
	v_fma_f32 v54, v51, s37, -v54
	v_fmac_f32_e32 v54, 0x3377d1cf, v51
	v_fmac_f32_e32 v54, 0x3f317217, v51
	v_cmp_lt_f32_e64 s[42:43], |v51|, s10
	s_nop 1
	v_cndmask_b32_e64 v51, v51, v54, s[42:43]
	v_cndmask_b32_e32 v54, 0, v225, vcc
	v_sub_f32_e32 v51, v51, v54
	v_sub_f32_e32 v54, v56, v60
	v_mul_f32_e32 v54, 0xbfb8aa3b, v54
	v_exp_f32_e32 v54, v54
	s_nop 0
	v_pk_add_f32 v[54:55], v[54:55], 1.0 op_sel_hi:[1,0]
	s_nop 0
	v_div_scale_f32 v52, s[0:1], v55, v55, 1.0
	v_rcp_f32_e32 v56, v52
	s_nop 0
	v_fma_f32 v58, -v52, v56, 1.0
	v_fmac_f32_e32 v56, v58, v56
	v_div_scale_f32 v58, vcc, 1.0, v55, 1.0
	v_mul_f32_e32 v59, v58, v56
	v_fma_f32 v60, -v52, v59, v58
	v_fmac_f32_e32 v59, v60, v56
	v_fma_f32 v52, -v52, v59, v58
	v_div_fmas_f32 v52, v52, v56, v59
	v_div_fixup_f32 v52, v52, v55, 1.0
	v_div_scale_f32 v55, s[0:1], v54, v54, 1.0
	v_rcp_f32_e32 v56, v55
	s_nop 0
	v_fma_f32 v58, -v55, v56, 1.0
	v_fmac_f32_e32 v56, v58, v56
	v_div_scale_f32 v58, vcc, 1.0, v54, 1.0
	v_mul_f32_e32 v59, v58, v56
	v_fma_f32 v60, -v55, v59, v58
	v_fmac_f32_e32 v59, v60, v56
	v_fma_f32 v55, -v55, v59, v58
	v_div_fmas_f32 v55, v55, v56, v59
	v_div_fixup_f32 v54, v55, v54, 1.0
	v_sub_f32_e32 v55, 1.0, v54
	v_fmac_f32_e32 v54, v52, v55
	v_cmp_gt_f32_e32 vcc, s11, v54
	v_exp_f32_e32 v55, v53
	s_nop 0
	v_cndmask_b32_e64 v52, 0, 32, vcc
	v_ldexp_f32 v52, v54, v52
	v_log_f32_e32 v52, v52
	s_nop 0
	v_mul_f32_e32 v54, 0x3f317217, v52
	v_fma_f32 v54, v52, s37, -v54
	v_fmac_f32_e32 v54, 0x3377d1cf, v52
	v_fmac_f32_e32 v54, 0x3f317217, v52
	v_cmp_lt_f32_e64 s[42:43], |v52|, s10
	s_nop 1
	v_cndmask_b32_e64 v52, v52, v54, s[42:43]
	v_cndmask_b32_e32 v54, 0, v225, vcc
	v_sub_f32_e32 v52, v52, v54
	v_sub_f32_e32 v54, v57, v61
	v_mul_f32_e32 v54, 0xbfb8aa3b, v54
	v_exp_f32_e32 v54, v54
	s_nop 0
	v_pk_add_f32 v[54:55], v[54:55], 1.0 op_sel_hi:[1,0]
	s_nop 0
	v_div_scale_f32 v53, s[0:1], v55, v55, 1.0
	v_rcp_f32_e32 v56, v53
	s_nop 0
	v_fma_f32 v57, -v53, v56, 1.0
	v_fmac_f32_e32 v56, v57, v56
	v_div_scale_f32 v57, vcc, 1.0, v55, 1.0
	v_mul_f32_e32 v58, v57, v56
	v_fma_f32 v59, -v53, v58, v57
	v_fmac_f32_e32 v58, v59, v56
	v_fma_f32 v53, -v53, v58, v57
	v_div_fmas_f32 v53, v53, v56, v58
	v_div_fixup_f32 v53, v53, v55, 1.0
	v_div_scale_f32 v55, s[0:1], v54, v54, 1.0
	v_rcp_f32_e32 v56, v55
	s_nop 0
	v_fma_f32 v57, -v55, v56, 1.0
	v_fmac_f32_e32 v56, v57, v56
	v_div_scale_f32 v57, vcc, 1.0, v54, 1.0
	v_mul_f32_e32 v58, v57, v56
	v_fma_f32 v59, -v55, v58, v57
	v_fmac_f32_e32 v58, v59, v56
	v_fma_f32 v55, -v55, v58, v57
	v_div_fmas_f32 v55, v55, v56, v58
	v_div_fixup_f32 v54, v55, v54, 1.0
	v_sub_f32_e32 v55, 1.0, v54
	v_fmac_f32_e32 v54, v53, v55
	v_cmp_gt_f32_e32 vcc, s11, v54
	s_nop 1
	v_cndmask_b32_e64 v53, 0, 32, vcc
	v_ldexp_f32 v53, v54, v53
	v_log_f32_e32 v53, v53
	s_nop 0
	v_mul_f32_e32 v54, 0x3f317217, v53
	v_fma_f32 v54, v53, s37, -v54
	v_fmac_f32_e32 v54, 0x3377d1cf, v53
	v_fmac_f32_e32 v54, 0x3f317217, v53
	v_cmp_lt_f32_e64 s[42:43], |v53|, s10
	s_nop 1
	v_cndmask_b32_e64 v53, v53, v54, s[42:43]
	v_cndmask_b32_e32 v54, 0, v225, vcc
	v_sub_f32_e32 v53, v53, v54

; DEV float sigm(float x) { return 1.f / (1.f + __expf(-x)); }
;   DEV void operator()(int m, int n, f32x4 v) {
;     ...
;     if (seg == 1 || seg == 2) {
;       const int dir = seg - 1;
; #pragma unroll
;       for (int r = 0; r < 4; r++) {
;         float lb = sigm(lbp[(2 + dir) * 1024 + c + r] - lbp[dir * 1024 + c + r]);
;         float ff = lb + (1.f - lb) * sigm(v[r]);
;         v[r] = __logf(ff);
.LBB0_412:
	s_add_i32 s10, s23, 0x410
	v_or_b32_e32 v50, s10, v79
	v_add_u32_e32 v52, 0xfffffc10, v78
	v_ashrrev_i32_e32 v51, 31, v50
	v_ashrrev_i32_e32 v53, 31, v52
	s_andn2_b64 vcc, exec, s[0:1]
	v_lshl_add_u64 v[60:61], v[50:51], 2, s[46:47]
	v_lshl_add_u64 v[64:65], v[52:53], 2, s[46:47]
	s_cbranch_vccnz .LBB0_414
	global_load_dwordx4 v[50:53], v[60:61], off
	global_load_dwordx4 v[54:57], v[64:65], off
	v_mul_f32_e32 v46, 0xbfb8aa3b, v46
	v_exp_f32_e32 v69, v46
	s_mov_b32 s11, 0x800000
	s_mov_b32 s10, 0x7f800000
	v_mul_f32_e32 v47, 0xbfb8aa3b, v47
	v_mul_f32_e32 v48, 0xbfb8aa3b, v48
	v_mul_f32_e32 v49, 0xbfb8aa3b, v49
	s_waitcnt vmcnt(0)
	v_mov_b32_e32 v84, v50
	v_mov_b32_e32 v85, v51
	v_mov_b32_e32 v86, v52
	v_mov_b32_e32 v87, v53
	v_mov_b32_e32 v88, v54
	v_mov_b32_e32 v89, v55
	v_mov_b32_e32 v90, v56
	v_mov_b32_e32 v91, v57
	v_sub_f32_e32 v50, v50, v54
	v_mul_f32_e32 v50, 0xbfb8aa3b, v50
	v_exp_f32_e32 v68, v50
	s_nop 0
	v_pk_add_f32 v[68:69], v[68:69], 1.0 op_sel_hi:[1,0]
	s_nop 0
	v_div_scale_f32 v46, s[0:1], v69, v69, 1.0
	v_rcp_f32_e32 v50, v46
	s_nop 0
	v_fma_f32 v54, -v46, v50, 1.0
	v_fmac_f32_e32 v50, v54, v50
	v_div_scale_f32 v54, vcc, 1.0, v69, 1.0
	v_mul_f32_e32 v72, v54, v50
	v_fma_f32 v73, -v46, v72, v54
	v_fmac_f32_e32 v72, v73, v50
	v_fma_f32 v46, -v46, v72, v54
	v_div_fmas_f32 v46, v46, v50, v72
	v_div_scale_f32 v50, s[0:1], v68, v68, 1.0
	v_rcp_f32_e32 v54, v50
	v_div_fixup_f32 v46, v46, v69, 1.0
	v_fma_f32 v69, -v50, v54, 1.0
	v_fmac_f32_e32 v54, v69, v54
	v_div_scale_f32 v69, vcc, 1.0, v68, 1.0
	v_mul_f32_e32 v72, v69, v54
	v_fma_f32 v73, -v50, v72, v69
	v_fmac_f32_e32 v72, v73, v54
	v_fma_f32 v50, -v50, v72, v69
	v_div_fmas_f32 v50, v50, v54, v72
	v_div_fixup_f32 v50, v50, v68, 1.0
	v_sub_f32_e32 v54, 1.0, v50
	v_fmac_f32_e32 v50, v46, v54
	v_cmp_gt_f32_e32 vcc, s11, v50
	s_nop 1
	v_cndmask_b32_e64 v46, 0, 32, vcc
	v_ldexp_f32 v46, v50, v46
	v_log_f32_e32 v46, v46
	s_nop 0
	v_mul_f32_e32 v50, 0x3f317217, v46
	v_fma_f32 v50, v46, s37, -v50
	v_fmac_f32_e32 v50, 0x3377d1cf, v46
	v_fmac_f32_e32 v50, 0x3f317217, v46
	v_cmp_lt_f32_e64 s[42:43], |v46|, s10
	s_nop 1
	v_cndmask_b32_e64 v46, v46, v50, s[42:43]
	v_cndmask_b32_e32 v50, 0, v225, vcc
	v_sub_f32_e32 v46, v46, v50
	v_sub_f32_e32 v50, v51, v55
	v_mul_f32_e32 v50, 0xbfb8aa3b, v50
	v_exp_f32_e32 v50, v50
	v_exp_f32_e32 v51, v47
	s_nop 0
	v_pk_add_f32 v[50:51], v[50:51], 1.0 op_sel_hi:[1,0]
	s_nop 0
	v_div_scale_f32 v47, s[0:1], v51, v51, 1.0
	v_rcp_f32_e32 v54, v47
	s_nop 0
	v_fma_f32 v55, -v47, v54, 1.0
	v_fmac_f32_e32 v54, v55, v54
	v_div_scale_f32 v55, vcc, 1.0, v51, 1.0
	v_mul_f32_e32 v68, v55, v54
	v_fma_f32 v69, -v47, v68, v55
	v_fmac_f32_e32 v68, v69, v54
	v_fma_f32 v47, -v47, v68, v55
	v_div_fmas_f32 v47, v47, v54, v68
	v_div_fixup_f32 v47, v47, v51, 1.0
	v_div_scale_f32 v51, s[0:1], v50, v50, 1.0
	v_rcp_f32_e32 v54, v51
	s_nop 0
	v_fma_f32 v55, -v51, v54, 1.0
	v_fmac_f32_e32 v54, v55, v54
	v_div_scale_f32 v55, vcc, 1.0, v50, 1.0
	v_mul_f32_e32 v68, v55, v54
	v_fma_f32 v69, -v51, v68, v55
	v_fmac_f32_e32 v68, v69, v54
	v_fma_f32 v51, -v51, v68, v55
	v_div_fmas_f32 v51, v51, v54, v68
	v_div_fixup_f32 v50, v51, v50, 1.0
	v_sub_f32_e32 v51, 1.0, v50
	v_fmac_f32_e32 v50, v47, v51
	v_cmp_gt_f32_e32 vcc, s11, v50
	v_exp_f32_e32 v51, v48
	s_nop 0
	v_cndmask_b32_e64 v47, 0, 32, vcc
	v_ldexp_f32 v47, v50, v47
	v_log_f32_e32 v47, v47
	s_nop 0
	v_mul_f32_e32 v50, 0x3f317217, v47
	v_fma_f32 v50, v47, s37, -v50
	v_fmac_f32_e32 v50, 0x3377d1cf, v47
	v_fmac_f32_e32 v50, 0x3f317217, v47
	v_cmp_lt_f32_e64 s[42:43], |v47|, s10
	s_nop 1
	v_cndmask_b32_e64 v47, v47, v50, s[42:43]
	v_cndmask_b32_e32 v50, 0, v225, vcc
	v_sub_f32_e32 v47, v47, v50
	v_sub_f32_e32 v50, v52, v56
	v_mul_f32_e32 v50, 0xbfb8aa3b, v50
	v_exp_f32_e32 v50, v50
	s_nop 0
	v_pk_add_f32 v[50:51], v[50:51], 1.0 op_sel_hi:[1,0]
	s_nop 0
	v_div_scale_f32 v48, s[0:1], v51, v51, 1.0
	v_rcp_f32_e32 v52, v48
	s_nop 0
	v_fma_f32 v54, -v48, v52, 1.0
	v_fmac_f32_e32 v52, v54, v52
	v_div_scale_f32 v54, vcc, 1.0, v51, 1.0
	v_mul_f32_e32 v55, v54, v52
	v_fma_f32 v56, -v48, v55, v54
	v_fmac_f32_e32 v55, v56, v52
	v_fma_f32 v48, -v48, v55, v54
	v_div_fmas_f32 v48, v48, v52, v55
	v_div_fixup_f32 v48, v48, v51, 1.0
	v_div_scale_f32 v51, s[0:1], v50, v50, 1.0
	v_rcp_f32_e32 v52, v51
	s_nop 0
	v_fma_f32 v54, -v51, v52, 1.0
	v_fmac_f32_e32 v52, v54, v52
	v_div_scale_f32 v54, vcc, 1.0, v50, 1.0
	v_mul_f32_e32 v55, v54, v52
	v_fma_f32 v56, -v51, v55, v54
	v_fmac_f32_e32 v55, v56, v52
	v_fma_f32 v51, -v51, v55, v54
	v_div_fmas_f32 v51, v51, v52, v55
	v_div_fixup_f32 v50, v51, v50, 1.0
	v_sub_f32_e32 v51, 1.0, v50
	v_fmac_f32_e32 v50, v48, v51
	v_cmp_gt_f32_e32 vcc, s11, v50
	v_exp_f32_e32 v51, v49
	s_nop 0
	v_cndmask_b32_e64 v48, 0, 32, vcc
	v_ldexp_f32 v48, v50, v48
	v_log_f32_e32 v48, v48
	s_nop 0
	v_mul_f32_e32 v50, 0x3f317217, v48
	v_fma_f32 v50, v48, s37, -v50
	v_fmac_f32_e32 v50, 0x3377d1cf, v48
	v_fmac_f32_e32 v50, 0x3f317217, v48
	v_cmp_lt_f32_e64 s[42:43], |v48|, s10
	s_nop 1
	v_cndmask_b32_e64 v48, v48, v50, s[42:43]
	v_cndmask_b32_e32 v50, 0, v225, vcc
	v_sub_f32_e32 v48, v48, v50
	v_sub_f32_e32 v50, v53, v57
	v_mul_f32_e32 v50, 0xbfb8aa3b, v50
	v_exp_f32_e32 v50, v50
	s_nop 0
	v_pk_add_f32 v[50:51], v[50:51], 1.0 op_sel_hi:[1,0]
	s_nop 0
	v_div_scale_f32 v49, s[0:1], v51, v51, 1.0
	v_rcp_f32_e32 v52, v49
	s_nop 0
	v_fma_f32 v53, -v49, v52, 1.0
	v_fmac_f32_e32 v52, v53, v52
	v_div_scale_f32 v53, vcc, 1.0, v51, 1.0
	v_mul_f32_e32 v54, v53, v52
	v_fma_f32 v55, -v49, v54, v53
	v_fmac_f32_e32 v54, v55, v52
	v_fma_f32 v49, -v49, v54, v53
	v_div_fmas_f32 v49, v49, v52, v54
	v_div_fixup_f32 v49, v49, v51, 1.0
	v_div_scale_f32 v51, s[0:1], v50, v50, 1.0
	v_rcp_f32_e32 v52, v51
	s_nop 0
	v_fma_f32 v53, -v51, v52, 1.0
	v_fmac_f32_e32 v52, v53, v52
	v_div_scale_f32 v53, vcc, 1.0, v50, 1.0
	v_mul_f32_e32 v54, v53, v52
	v_fma_f32 v55, -v51, v54, v53
	v_fmac_f32_e32 v54, v55, v52
	v_fma_f32 v51, -v51, v54, v53
	v_div_fmas_f32 v51, v51, v52, v54
	v_div_fixup_f32 v50, v51, v50, 1.0
	v_sub_f32_e32 v51, 1.0, v50
	v_fmac_f32_e32 v50, v49, v51
	v_cmp_gt_f32_e32 vcc, s11, v50
	s_nop 1
	v_cndmask_b32_e64 v49, 0, 32, vcc
	v_ldexp_f32 v49, v50, v49
	v_log_f32_e32 v49, v49
	s_nop 0
	v_mul_f32_e32 v50, 0x3f317217, v49
	v_fma_f32 v50, v49, s37, -v50
	v_fmac_f32_e32 v50, 0x3377d1cf, v49
	v_fmac_f32_e32 v50, 0x3f317217, v49
	v_cmp_lt_f32_e64 s[42:43], |v49|, s10
	s_nop 1
	v_cndmask_b32_e64 v49, v49, v50, s[42:43]
	v_cndmask_b32_e32 v50, 0, v225, vcc
	v_sub_f32_e32 v49, v49, v50

; DEV float sigm(float x) { return 1.f / (1.f + __expf(-x)); }
;   DEV void operator()(int m, int n, f32x4 v) {
;     ...
;     if (seg == 1 || seg == 2) {
;       const int dir = seg - 1;
; #pragma unroll
;       for (int r = 0; r < 4; r++) {
;         float lb = sigm(lbp[(2 + dir) * 1024 + c + r] - lbp[dir * 1024 + c + r]);
;         float ff = lb + (1.f - lb) * sigm(v[r]);
;         v[r] = __logf(ff);
.LBB0_429:
	s_andn2_b64 vcc, exec, s[0:1]
	s_cbranch_vccnz .LBB0_431
	v_mul_f32_e32 v42, 0xbfb8aa3b, v42
	v_exp_f32_e32 v55, v42
	s_mov_b32 s11, 0x800000
	s_mov_b32 s10, 0x7f800000
	v_mul_f32_e32 v43, 0xbfb8aa3b, v43
	v_mul_f32_e32 v44, 0xbfb8aa3b, v44
	v_mul_f32_e32 v45, 0xbfb8aa3b, v45
	v_mov_b32_e32 v46, v84
	v_mov_b32_e32 v47, v85
	v_mov_b32_e32 v48, v86
	v_mov_b32_e32 v49, v87
	v_mov_b32_e32 v50, v88
	v_mov_b32_e32 v51, v89
	v_mov_b32_e32 v52, v90
	v_mov_b32_e32 v53, v91
	v_sub_f32_e32 v46, v46, v50
	v_mul_f32_e32 v46, 0xbfb8aa3b, v46
	v_exp_f32_e32 v54, v46
	s_nop 0
	v_pk_add_f32 v[54:55], v[54:55], 1.0 op_sel_hi:[1,0]
	s_nop 0
	v_div_scale_f32 v42, s[0:1], v55, v55, 1.0
	v_rcp_f32_e32 v46, v42
	s_nop 0
	v_fma_f32 v50, -v42, v46, 1.0
	v_fmac_f32_e32 v46, v50, v46
	v_div_scale_f32 v50, vcc, 1.0, v55, 1.0
	v_mul_f32_e32 v56, v50, v46
	v_fma_f32 v57, -v42, v56, v50
	v_fmac_f32_e32 v56, v57, v46
	v_fma_f32 v42, -v42, v56, v50
	v_div_fmas_f32 v42, v42, v46, v56
	v_div_scale_f32 v46, s[0:1], v54, v54, 1.0
	v_rcp_f32_e32 v50, v46
	v_div_fixup_f32 v42, v42, v55, 1.0
	v_fma_f32 v55, -v46, v50, 1.0
	v_fmac_f32_e32 v50, v55, v50
	v_div_scale_f32 v55, vcc, 1.0, v54, 1.0
	v_mul_f32_e32 v56, v55, v50
	v_fma_f32 v57, -v46, v56, v55
	v_fmac_f32_e32 v56, v57, v50
	v_fma_f32 v46, -v46, v56, v55
	v_div_fmas_f32 v46, v46, v50, v56
	v_div_fixup_f32 v46, v46, v54, 1.0
	v_sub_f32_e32 v50, 1.0, v46
	v_fmac_f32_e32 v46, v42, v50
	v_cmp_gt_f32_e32 vcc, s11, v46
	s_nop 1
	v_cndmask_b32_e64 v42, 0, 32, vcc
	v_ldexp_f32 v42, v46, v42
	v_log_f32_e32 v42, v42
	s_nop 0
	v_mul_f32_e32 v46, 0x3f317217, v42
	v_fma_f32 v46, v42, s37, -v46
	v_fmac_f32_e32 v46, 0x3377d1cf, v42
	v_fmac_f32_e32 v46, 0x3f317217, v42
	v_cmp_lt_f32_e64 s[42:43], |v42|, s10
	s_nop 1
	v_cndmask_b32_e64 v42, v42, v46, s[42:43]
	v_cndmask_b32_e32 v46, 0, v225, vcc
	v_sub_f32_e32 v42, v42, v46
	v_sub_f32_e32 v46, v47, v51
	v_mul_f32_e32 v46, 0xbfb8aa3b, v46
	v_exp_f32_e32 v46, v46
	v_exp_f32_e32 v47, v43
	s_nop 0
	v_pk_add_f32 v[46:47], v[46:47], 1.0 op_sel_hi:[1,0]
	s_nop 0
	v_div_scale_f32 v43, s[0:1], v47, v47, 1.0
	v_rcp_f32_e32 v50, v43
	s_nop 0
	v_fma_f32 v51, -v43, v50, 1.0
	v_fmac_f32_e32 v50, v51, v50
	v_div_scale_f32 v51, vcc, 1.0, v47, 1.0
	v_mul_f32_e32 v54, v51, v50
	v_fma_f32 v55, -v43, v54, v51
	v_fmac_f32_e32 v54, v55, v50
	v_fma_f32 v43, -v43, v54, v51
	v_div_fmas_f32 v43, v43, v50, v54
	v_div_fixup_f32 v43, v43, v47, 1.0
	v_div_scale_f32 v47, s[0:1], v46, v46, 1.0
	v_rcp_f32_e32 v50, v47
	s_nop 0
	v_fma_f32 v51, -v47, v50, 1.0
	v_fmac_f32_e32 v50, v51, v50
	v_div_scale_f32 v51, vcc, 1.0, v46, 1.0
	v_mul_f32_e32 v54, v51, v50
	v_fma_f32 v55, -v47, v54, v51
	v_fmac_f32_e32 v54, v55, v50
	v_fma_f32 v47, -v47, v54, v51
	v_div_fmas_f32 v47, v47, v50, v54
	v_div_fixup_f32 v46, v47, v46, 1.0
	v_sub_f32_e32 v47, 1.0, v46
	v_fmac_f32_e32 v46, v43, v47
	v_cmp_gt_f32_e32 vcc, s11, v46
	v_exp_f32_e32 v47, v44
	s_nop 0
	v_cndmask_b32_e64 v43, 0, 32, vcc
	v_ldexp_f32 v43, v46, v43
	v_log_f32_e32 v43, v43
	s_nop 0
	v_mul_f32_e32 v46, 0x3f317217, v43
	v_fma_f32 v46, v43, s37, -v46
	v_fmac_f32_e32 v46, 0x3377d1cf, v43
	v_fmac_f32_e32 v46, 0x3f317217, v43
	v_cmp_lt_f32_e64 s[42:43], |v43|, s10
	s_nop 1
	v_cndmask_b32_e64 v43, v43, v46, s[42:43]
	v_cndmask_b32_e32 v46, 0, v225, vcc
	v_sub_f32_e32 v43, v43, v46
	v_sub_f32_e32 v46, v48, v52
	v_mul_f32_e32 v46, 0xbfb8aa3b, v46
	v_exp_f32_e32 v46, v46
	s_nop 0
	v_pk_add_f32 v[46:47], v[46:47], 1.0 op_sel_hi:[1,0]
	s_nop 0
	v_div_scale_f32 v44, s[0:1], v47, v47, 1.0
	v_rcp_f32_e32 v48, v44
	s_nop 0
	v_fma_f32 v50, -v44, v48, 1.0
	v_fmac_f32_e32 v48, v50, v48
	v_div_scale_f32 v50, vcc, 1.0, v47, 1.0
	v_mul_f32_e32 v51, v50, v48
	v_fma_f32 v52, -v44, v51, v50
	v_fmac_f32_e32 v51, v52, v48
	v_fma_f32 v44, -v44, v51, v50
	v_div_fmas_f32 v44, v44, v48, v51
	v_div_fixup_f32 v44, v44, v47, 1.0
	v_div_scale_f32 v47, s[0:1], v46, v46, 1.0
	v_rcp_f32_e32 v48, v47
	s_nop 0
	v_fma_f32 v50, -v47, v48, 1.0
	v_fmac_f32_e32 v48, v50, v48
	v_div_scale_f32 v50, vcc, 1.0, v46, 1.0
	v_mul_f32_e32 v51, v50, v48
	v_fma_f32 v52, -v47, v51, v50
	v_fmac_f32_e32 v51, v52, v48
	v_fma_f32 v47, -v47, v51, v50
	v_div_fmas_f32 v47, v47, v48, v51
	v_div_fixup_f32 v46, v47, v46, 1.0
	v_sub_f32_e32 v47, 1.0, v46
	v_fmac_f32_e32 v46, v44, v47
	v_cmp_gt_f32_e32 vcc, s11, v46
	v_exp_f32_e32 v47, v45
	s_nop 0
	v_cndmask_b32_e64 v44, 0, 32, vcc
	v_ldexp_f32 v44, v46, v44
	v_log_f32_e32 v44, v44
	s_nop 0
	v_mul_f32_e32 v46, 0x3f317217, v44
	v_fma_f32 v46, v44, s37, -v46
	v_fmac_f32_e32 v46, 0x3377d1cf, v44
	v_fmac_f32_e32 v46, 0x3f317217, v44
	v_cmp_lt_f32_e64 s[42:43], |v44|, s10
	s_nop 1
	v_cndmask_b32_e64 v44, v44, v46, s[42:43]
	v_cndmask_b32_e32 v46, 0, v225, vcc
	v_sub_f32_e32 v44, v44, v46
	v_sub_f32_e32 v46, v49, v53
	v_mul_f32_e32 v46, 0xbfb8aa3b, v46
	v_exp_f32_e32 v46, v46
	s_nop 0
	v_pk_add_f32 v[46:47], v[46:47], 1.0 op_sel_hi:[1,0]
	s_nop 0
	v_div_scale_f32 v45, s[0:1], v47, v47, 1.0
	v_rcp_f32_e32 v48, v45
	s_nop 0
	v_fma_f32 v49, -v45, v48, 1.0
	v_fmac_f32_e32 v48, v49, v48
	v_div_scale_f32 v49, vcc, 1.0, v47, 1.0
	v_mul_f32_e32 v50, v49, v48
	v_fma_f32 v51, -v45, v50, v49
	v_fmac_f32_e32 v50, v51, v48
	v_fma_f32 v45, -v45, v50, v49
	v_div_fmas_f32 v45, v45, v48, v50
	v_div_fixup_f32 v45, v45, v47, 1.0
	v_div_scale_f32 v47, s[0:1], v46, v46, 1.0
	v_rcp_f32_e32 v48, v47
	s_nop 0
	v_fma_f32 v49, -v47, v48, 1.0
	v_fmac_f32_e32 v48, v49, v48
	v_div_scale_f32 v49, vcc, 1.0, v46, 1.0
	v_mul_f32_e32 v50, v49, v48
	v_fma_f32 v51, -v47, v50, v49
	v_fmac_f32_e32 v50, v51, v48
	v_fma_f32 v47, -v47, v50, v49
	v_div_fmas_f32 v47, v47, v48, v50
	v_div_fixup_f32 v46, v47, v46, 1.0
	v_sub_f32_e32 v47, 1.0, v46
	v_fmac_f32_e32 v46, v45, v47
	v_cmp_gt_f32_e32 vcc, s11, v46
	s_nop 1
	v_cndmask_b32_e64 v45, 0, 32, vcc
	v_ldexp_f32 v45, v46, v45
	v_log_f32_e32 v45, v45
	s_nop 0
	v_mul_f32_e32 v46, 0x3f317217, v45
	v_fma_f32 v46, v45, s37, -v46
	v_fmac_f32_e32 v46, 0x3377d1cf, v45
	v_fmac_f32_e32 v46, 0x3f317217, v45
	v_cmp_lt_f32_e64 s[42:43], |v45|, s10
	s_nop 1
	v_cndmask_b32_e64 v45, v45, v46, s[42:43]
	v_cndmask_b32_e32 v46, 0, v225, vcc
	v_sub_f32_e32 v45, v45, v46

; DEV float sigm(float x) { return 1.f / (1.f + __expf(-x)); }
;   DEV void operator()(int m, int n, f32x4 v) {
;     ...
;     if (seg == 1 || seg == 2) {
;       const int dir = seg - 1;
; #pragma unroll
;       for (int r = 0; r < 4; r++) {
;         float lb = sigm(lbp[(2 + dir) * 1024 + c + r] - lbp[dir * 1024 + c + r]);
;         float ff = lb + (1.f - lb) * sigm(v[r]);
;         v[r] = __logf(ff);
.LBB0_446:
	s_andn2_b64 vcc, exec, s[0:1]
	s_cbranch_vccnz .LBB0_448
	v_mul_f32_e32 v38, 0xbfb8aa3b, v38
	v_exp_f32_e32 v51, v38
	s_mov_b32 s11, 0x800000
	s_mov_b32 s10, 0x7f800000
	v_mul_f32_e32 v39, 0xbfb8aa3b, v39
	v_mul_f32_e32 v40, 0xbfb8aa3b, v40
	v_mul_f32_e32 v41, 0xbfb8aa3b, v41
	v_mov_b32_e32 v42, v84
	v_mov_b32_e32 v43, v85
	v_mov_b32_e32 v44, v86
	v_mov_b32_e32 v45, v87
	v_mov_b32_e32 v46, v88
	v_mov_b32_e32 v47, v89
	v_mov_b32_e32 v48, v90
	v_mov_b32_e32 v49, v91
	v_sub_f32_e32 v42, v42, v46
	v_mul_f32_e32 v42, 0xbfb8aa3b, v42
	v_exp_f32_e32 v50, v42
	s_nop 0
	v_pk_add_f32 v[50:51], v[50:51], 1.0 op_sel_hi:[1,0]
	s_nop 0
	v_div_scale_f32 v38, s[0:1], v51, v51, 1.0
	v_rcp_f32_e32 v42, v38
	s_nop 0
	v_fma_f32 v46, -v38, v42, 1.0
	v_fmac_f32_e32 v42, v46, v42
	v_div_scale_f32 v46, vcc, 1.0, v51, 1.0
	v_mul_f32_e32 v52, v46, v42
	v_fma_f32 v53, -v38, v52, v46
	v_fmac_f32_e32 v52, v53, v42
	v_fma_f32 v38, -v38, v52, v46
	v_div_fmas_f32 v38, v38, v42, v52
	v_div_scale_f32 v42, s[0:1], v50, v50, 1.0
	v_rcp_f32_e32 v46, v42
	v_div_fixup_f32 v38, v38, v51, 1.0
	v_fma_f32 v51, -v42, v46, 1.0
	v_fmac_f32_e32 v46, v51, v46
	v_div_scale_f32 v51, vcc, 1.0, v50, 1.0
	v_mul_f32_e32 v52, v51, v46
	v_fma_f32 v53, -v42, v52, v51
	v_fmac_f32_e32 v52, v53, v46
	v_fma_f32 v42, -v42, v52, v51
	v_div_fmas_f32 v42, v42, v46, v52
	v_div_fixup_f32 v42, v42, v50, 1.0
	v_sub_f32_e32 v46, 1.0, v42
	v_fmac_f32_e32 v42, v38, v46
	v_cmp_gt_f32_e32 vcc, s11, v42
	s_nop 1
	v_cndmask_b32_e64 v38, 0, 32, vcc
	v_ldexp_f32 v38, v42, v38
	v_log_f32_e32 v38, v38
	s_nop 0
	v_mul_f32_e32 v42, 0x3f317217, v38
	v_fma_f32 v42, v38, s37, -v42
	v_fmac_f32_e32 v42, 0x3377d1cf, v38
	v_fmac_f32_e32 v42, 0x3f317217, v38
	v_cmp_lt_f32_e64 s[42:43], |v38|, s10
	s_nop 1
	v_cndmask_b32_e64 v38, v38, v42, s[42:43]
	v_cndmask_b32_e32 v42, 0, v225, vcc
	v_sub_f32_e32 v38, v38, v42
	v_sub_f32_e32 v42, v43, v47
	v_mul_f32_e32 v42, 0xbfb8aa3b, v42
	v_exp_f32_e32 v42, v42
	v_exp_f32_e32 v43, v39
	s_nop 0
	v_pk_add_f32 v[42:43], v[42:43], 1.0 op_sel_hi:[1,0]
	s_nop 0
	v_div_scale_f32 v39, s[0:1], v43, v43, 1.0
	v_rcp_f32_e32 v46, v39
	s_nop 0
	v_fma_f32 v47, -v39, v46, 1.0
	v_fmac_f32_e32 v46, v47, v46
	v_div_scale_f32 v47, vcc, 1.0, v43, 1.0
	v_mul_f32_e32 v50, v47, v46
	v_fma_f32 v51, -v39, v50, v47
	v_fmac_f32_e32 v50, v51, v46
	v_fma_f32 v39, -v39, v50, v47
	v_div_fmas_f32 v39, v39, v46, v50
	v_div_fixup_f32 v39, v39, v43, 1.0
	v_div_scale_f32 v43, s[0:1], v42, v42, 1.0
	v_rcp_f32_e32 v46, v43
	s_nop 0
	v_fma_f32 v47, -v43, v46, 1.0
	v_fmac_f32_e32 v46, v47, v46
	v_div_scale_f32 v47, vcc, 1.0, v42, 1.0
	v_mul_f32_e32 v50, v47, v46
	v_fma_f32 v51, -v43, v50, v47
	v_fmac_f32_e32 v50, v51, v46
	v_fma_f32 v43, -v43, v50, v47
	v_div_fmas_f32 v43, v43, v46, v50
	v_div_fixup_f32 v42, v43, v42, 1.0
	v_sub_f32_e32 v43, 1.0, v42
	v_fmac_f32_e32 v42, v39, v43
	v_cmp_gt_f32_e32 vcc, s11, v42
	v_exp_f32_e32 v43, v40
	s_nop 0
	v_cndmask_b32_e64 v39, 0, 32, vcc
	v_ldexp_f32 v39, v42, v39
	v_log_f32_e32 v39, v39
	s_nop 0
	v_mul_f32_e32 v42, 0x3f317217, v39
	v_fma_f32 v42, v39, s37, -v42
	v_fmac_f32_e32 v42, 0x3377d1cf, v39
	v_fmac_f32_e32 v42, 0x3f317217, v39
	v_cmp_lt_f32_e64 s[42:43], |v39|, s10
	s_nop 1
	v_cndmask_b32_e64 v39, v39, v42, s[42:43]
	v_cndmask_b32_e32 v42, 0, v225, vcc
	v_sub_f32_e32 v39, v39, v42
	v_sub_f32_e32 v42, v44, v48
	v_mul_f32_e32 v42, 0xbfb8aa3b, v42
	v_exp_f32_e32 v42, v42
	s_nop 0
	v_pk_add_f32 v[42:43], v[42:43], 1.0 op_sel_hi:[1,0]
	s_nop 0
	v_div_scale_f32 v40, s[0:1], v43, v43, 1.0
	v_rcp_f32_e32 v44, v40
	s_nop 0
	v_fma_f32 v46, -v40, v44, 1.0
	v_fmac_f32_e32 v44, v46, v44
	v_div_scale_f32 v46, vcc, 1.0, v43, 1.0
	v_mul_f32_e32 v47, v46, v44
	v_fma_f32 v48, -v40, v47, v46
	v_fmac_f32_e32 v47, v48, v44
	v_fma_f32 v40, -v40, v47, v46
	v_div_fmas_f32 v40, v40, v44, v47
	v_div_fixup_f32 v40, v40, v43, 1.0
	v_div_scale_f32 v43, s[0:1], v42, v42, 1.0
	v_rcp_f32_e32 v44, v43
	s_nop 0
	v_fma_f32 v46, -v43, v44, 1.0
	v_fmac_f32_e32 v44, v46, v44
	v_div_scale_f32 v46, vcc, 1.0, v42, 1.0
	v_mul_f32_e32 v47, v46, v44
	v_fma_f32 v48, -v43, v47, v46
	v_fmac_f32_e32 v47, v48, v44
	v_fma_f32 v43, -v43, v47, v46
	v_div_fmas_f32 v43, v43, v44, v47
	v_div_fixup_f32 v42, v43, v42, 1.0
	v_sub_f32_e32 v43, 1.0, v42
	v_fmac_f32_e32 v42, v40, v43
	v_cmp_gt_f32_e32 vcc, s11, v42
	v_exp_f32_e32 v43, v41
	s_nop 0
	v_cndmask_b32_e64 v40, 0, 32, vcc
	v_ldexp_f32 v40, v42, v40
	v_log_f32_e32 v40, v40
	s_nop 0
	v_mul_f32_e32 v42, 0x3f317217, v40
	v_fma_f32 v42, v40, s37, -v42
	v_fmac_f32_e32 v42, 0x3377d1cf, v40
	v_fmac_f32_e32 v42, 0x3f317217, v40
	v_cmp_lt_f32_e64 s[42:43], |v40|, s10
	s_nop 1
	v_cndmask_b32_e64 v40, v40, v42, s[42:43]
	v_cndmask_b32_e32 v42, 0, v225, vcc
	v_sub_f32_e32 v40, v40, v42
	v_sub_f32_e32 v42, v45, v49
	v_mul_f32_e32 v42, 0xbfb8aa3b, v42
	v_exp_f32_e32 v42, v42
	s_nop 0
	v_pk_add_f32 v[42:43], v[42:43], 1.0 op_sel_hi:[1,0]
	s_nop 0
	v_div_scale_f32 v41, s[0:1], v43, v43, 1.0
	v_rcp_f32_e32 v44, v41
	s_nop 0
	v_fma_f32 v45, -v41, v44, 1.0
	v_fmac_f32_e32 v44, v45, v44
	v_div_scale_f32 v45, vcc, 1.0, v43, 1.0
	v_mul_f32_e32 v46, v45, v44
	v_fma_f32 v47, -v41, v46, v45
	v_fmac_f32_e32 v46, v47, v44
	v_fma_f32 v41, -v41, v46, v45
	v_div_fmas_f32 v41, v41, v44, v46
	v_div_fixup_f32 v41, v41, v43, 1.0
	v_div_scale_f32 v43, s[0:1], v42, v42, 1.0
	v_rcp_f32_e32 v44, v43
	s_nop 0
	v_fma_f32 v45, -v43, v44, 1.0
	v_fmac_f32_e32 v44, v45, v44
	v_div_scale_f32 v45, vcc, 1.0, v42, 1.0
	v_mul_f32_e32 v46, v45, v44
	v_fma_f32 v47, -v43, v46, v45
	v_fmac_f32_e32 v46, v47, v44
	v_fma_f32 v43, -v43, v46, v45
	v_div_fmas_f32 v43, v43, v44, v46
	v_div_fixup_f32 v42, v43, v42, 1.0
	v_sub_f32_e32 v43, 1.0, v42
	v_fmac_f32_e32 v42, v41, v43
	v_cmp_gt_f32_e32 vcc, s11, v42
	s_nop 1
	v_cndmask_b32_e64 v41, 0, 32, vcc
	v_ldexp_f32 v41, v42, v41
	v_log_f32_e32 v41, v41
	s_nop 0
	v_mul_f32_e32 v42, 0x3f317217, v41
	v_fma_f32 v42, v41, s37, -v42
	v_fmac_f32_e32 v42, 0x3377d1cf, v41
	v_fmac_f32_e32 v42, 0x3f317217, v41
	v_cmp_lt_f32_e64 s[42:43], |v41|, s10
	s_nop 1
	v_cndmask_b32_e64 v41, v41, v42, s[42:43]
	v_cndmask_b32_e32 v42, 0, v225, vcc
	v_sub_f32_e32 v41, v41, v42

; DEV float sigm(float x) { return 1.f / (1.f + __expf(-x)); }
;   DEV void operator()(int m, int n, f32x4 v) {
;     ...
;     if (seg == 1 || seg == 2) {
;       const int dir = seg - 1;
; #pragma unroll
;       for (int r = 0; r < 4; r++) {
;         float lb = sigm(lbp[(2 + dir) * 1024 + c + r] - lbp[dir * 1024 + c + r]);
;         float ff = lb + (1.f - lb) * sigm(v[r]);
;         v[r] = __logf(ff);
.LBB0_463:
	s_andn2_b64 vcc, exec, s[0:1]
	s_cbranch_vccnz .LBB0_465
	v_mul_f32_e32 v34, 0xbfb8aa3b, v34
	v_exp_f32_e32 v47, v34
	s_mov_b32 s11, 0x800000
	s_mov_b32 s10, 0x7f800000
	v_mul_f32_e32 v35, 0xbfb8aa3b, v35
	v_mul_f32_e32 v36, 0xbfb8aa3b, v36
	v_mul_f32_e32 v37, 0xbfb8aa3b, v37
	v_mov_b32_e32 v38, v84
	v_mov_b32_e32 v39, v85
	v_mov_b32_e32 v40, v86
	v_mov_b32_e32 v41, v87
	v_mov_b32_e32 v42, v88
	v_mov_b32_e32 v43, v89
	v_mov_b32_e32 v44, v90
	v_mov_b32_e32 v45, v91
	v_sub_f32_e32 v38, v38, v42
	v_mul_f32_e32 v38, 0xbfb8aa3b, v38
	v_exp_f32_e32 v46, v38
	s_nop 0
	v_pk_add_f32 v[46:47], v[46:47], 1.0 op_sel_hi:[1,0]
	s_nop 0
	v_div_scale_f32 v34, s[0:1], v47, v47, 1.0
	v_rcp_f32_e32 v38, v34
	s_nop 0
	v_fma_f32 v42, -v34, v38, 1.0
	v_fmac_f32_e32 v38, v42, v38
	v_div_scale_f32 v42, vcc, 1.0, v47, 1.0
	v_mul_f32_e32 v48, v42, v38
	v_fma_f32 v49, -v34, v48, v42
	v_fmac_f32_e32 v48, v49, v38
	v_fma_f32 v34, -v34, v48, v42
	v_div_fmas_f32 v34, v34, v38, v48
	v_div_scale_f32 v38, s[0:1], v46, v46, 1.0
	v_rcp_f32_e32 v42, v38
	v_div_fixup_f32 v34, v34, v47, 1.0
	v_fma_f32 v47, -v38, v42, 1.0
	v_fmac_f32_e32 v42, v47, v42
	v_div_scale_f32 v47, vcc, 1.0, v46, 1.0
	v_mul_f32_e32 v48, v47, v42
	v_fma_f32 v49, -v38, v48, v47
	v_fmac_f32_e32 v48, v49, v42
	v_fma_f32 v38, -v38, v48, v47
	v_div_fmas_f32 v38, v38, v42, v48
	v_div_fixup_f32 v38, v38, v46, 1.0
	v_sub_f32_e32 v42, 1.0, v38
	v_fmac_f32_e32 v38, v34, v42
	v_cmp_gt_f32_e32 vcc, s11, v38
	s_nop 1
	v_cndmask_b32_e64 v34, 0, 32, vcc
	v_ldexp_f32 v34, v38, v34
	v_log_f32_e32 v34, v34
	s_nop 0
	v_mul_f32_e32 v38, 0x3f317217, v34
	v_fma_f32 v38, v34, s37, -v38
	v_fmac_f32_e32 v38, 0x3377d1cf, v34
	v_fmac_f32_e32 v38, 0x3f317217, v34
	v_cmp_lt_f32_e64 s[42:43], |v34|, s10
	s_nop 1
	v_cndmask_b32_e64 v34, v34, v38, s[42:43]
	v_cndmask_b32_e32 v38, 0, v225, vcc
	v_sub_f32_e32 v34, v34, v38
	v_sub_f32_e32 v38, v39, v43
	v_mul_f32_e32 v38, 0xbfb8aa3b, v38
	v_exp_f32_e32 v38, v38
	v_exp_f32_e32 v39, v35
	s_nop 0
	v_pk_add_f32 v[38:39], v[38:39], 1.0 op_sel_hi:[1,0]
	s_nop 0
	v_div_scale_f32 v35, s[0:1], v39, v39, 1.0
	v_rcp_f32_e32 v42, v35
	s_nop 0
	v_fma_f32 v43, -v35, v42, 1.0
	v_fmac_f32_e32 v42, v43, v42
	v_div_scale_f32 v43, vcc, 1.0, v39, 1.0
	v_mul_f32_e32 v46, v43, v42
	v_fma_f32 v47, -v35, v46, v43
	v_fmac_f32_e32 v46, v47, v42
	v_fma_f32 v35, -v35, v46, v43
	v_div_fmas_f32 v35, v35, v42, v46
	v_div_fixup_f32 v35, v35, v39, 1.0
	v_div_scale_f32 v39, s[0:1], v38, v38, 1.0
	v_rcp_f32_e32 v42, v39
	s_nop 0
	v_fma_f32 v43, -v39, v42, 1.0
	v_fmac_f32_e32 v42, v43, v42
	v_div_scale_f32 v43, vcc, 1.0, v38, 1.0
	v_mul_f32_e32 v46, v43, v42
	v_fma_f32 v47, -v39, v46, v43
	v_fmac_f32_e32 v46, v47, v42
	v_fma_f32 v39, -v39, v46, v43
	v_div_fmas_f32 v39, v39, v42, v46
	v_div_fixup_f32 v38, v39, v38, 1.0
	v_sub_f32_e32 v39, 1.0, v38
	v_fmac_f32_e32 v38, v35, v39
	v_cmp_gt_f32_e32 vcc, s11, v38
	v_exp_f32_e32 v39, v36
	s_nop 0
	v_cndmask_b32_e64 v35, 0, 32, vcc
	v_ldexp_f32 v35, v38, v35
	v_log_f32_e32 v35, v35
	s_nop 0
	v_mul_f32_e32 v38, 0x3f317217, v35
	v_fma_f32 v38, v35, s37, -v38
	v_fmac_f32_e32 v38, 0x3377d1cf, v35
	v_fmac_f32_e32 v38, 0x3f317217, v35
	v_cmp_lt_f32_e64 s[42:43], |v35|, s10
	s_nop 1
	v_cndmask_b32_e64 v35, v35, v38, s[42:43]
	v_cndmask_b32_e32 v38, 0, v225, vcc
	v_sub_f32_e32 v35, v35, v38
	v_sub_f32_e32 v38, v40, v44
	v_mul_f32_e32 v38, 0xbfb8aa3b, v38
	v_exp_f32_e32 v38, v38
	s_nop 0
	v_pk_add_f32 v[38:39], v[38:39], 1.0 op_sel_hi:[1,0]
	s_nop 0
	v_div_scale_f32 v36, s[0:1], v39, v39, 1.0
	v_rcp_f32_e32 v40, v36
	s_nop 0
	v_fma_f32 v42, -v36, v40, 1.0
	v_fmac_f32_e32 v40, v42, v40
	v_div_scale_f32 v42, vcc, 1.0, v39, 1.0
	v_mul_f32_e32 v43, v42, v40
	v_fma_f32 v44, -v36, v43, v42
	v_fmac_f32_e32 v43, v44, v40
	v_fma_f32 v36, -v36, v43, v42
	v_div_fmas_f32 v36, v36, v40, v43
	v_div_fixup_f32 v36, v36, v39, 1.0
	v_div_scale_f32 v39, s[0:1], v38, v38, 1.0
	v_rcp_f32_e32 v40, v39
	s_nop 0
	v_fma_f32 v42, -v39, v40, 1.0
	v_fmac_f32_e32 v40, v42, v40
	v_div_scale_f32 v42, vcc, 1.0, v38, 1.0
	v_mul_f32_e32 v43, v42, v40
	v_fma_f32 v44, -v39, v43, v42
	v_fmac_f32_e32 v43, v44, v40
	v_fma_f32 v39, -v39, v43, v42
	v_div_fmas_f32 v39, v39, v40, v43
	v_div_fixup_f32 v38, v39, v38, 1.0
	v_sub_f32_e32 v39, 1.0, v38
	v_fmac_f32_e32 v38, v36, v39
	v_cmp_gt_f32_e32 vcc, s11, v38
	v_exp_f32_e32 v39, v37
	s_nop 0
	v_cndmask_b32_e64 v36, 0, 32, vcc
	v_ldexp_f32 v36, v38, v36
	v_log_f32_e32 v36, v36
	s_nop 0
	v_mul_f32_e32 v38, 0x3f317217, v36
	v_fma_f32 v38, v36, s37, -v38
	v_fmac_f32_e32 v38, 0x3377d1cf, v36
	v_fmac_f32_e32 v38, 0x3f317217, v36
	v_cmp_lt_f32_e64 s[42:43], |v36|, s10
	s_nop 1
	v_cndmask_b32_e64 v36, v36, v38, s[42:43]
	v_cndmask_b32_e32 v38, 0, v225, vcc
	v_sub_f32_e32 v36, v36, v38
	v_sub_f32_e32 v38, v41, v45
	v_mul_f32_e32 v38, 0xbfb8aa3b, v38
	v_exp_f32_e32 v38, v38
	s_nop 0
	v_pk_add_f32 v[38:39], v[38:39], 1.0 op_sel_hi:[1,0]
	s_nop 0
	v_div_scale_f32 v37, s[0:1], v39, v39, 1.0
	v_rcp_f32_e32 v40, v37
	s_nop 0
	v_fma_f32 v41, -v37, v40, 1.0
	v_fmac_f32_e32 v40, v41, v40
	v_div_scale_f32 v41, vcc, 1.0, v39, 1.0
	v_mul_f32_e32 v42, v41, v40
	v_fma_f32 v43, -v37, v42, v41
	v_fmac_f32_e32 v42, v43, v40
	v_fma_f32 v37, -v37, v42, v41
	v_div_fmas_f32 v37, v37, v40, v42
	v_div_fixup_f32 v37, v37, v39, 1.0
	v_div_scale_f32 v39, s[0:1], v38, v38, 1.0
	v_rcp_f32_e32 v40, v39
	s_nop 0
	v_fma_f32 v41, -v39, v40, 1.0
	v_fmac_f32_e32 v40, v41, v40
	v_div_scale_f32 v41, vcc, 1.0, v38, 1.0
	v_mul_f32_e32 v42, v41, v40
	v_fma_f32 v43, -v39, v42, v41
	v_fmac_f32_e32 v42, v43, v40
	v_fma_f32 v39, -v39, v42, v41
	v_div_fmas_f32 v39, v39, v40, v42
	v_div_fixup_f32 v38, v39, v38, 1.0
	v_sub_f32_e32 v39, 1.0, v38
	v_fmac_f32_e32 v38, v37, v39
	v_cmp_gt_f32_e32 vcc, s11, v38
	s_nop 1
	v_cndmask_b32_e64 v37, 0, 32, vcc
	v_ldexp_f32 v37, v38, v37
	v_log_f32_e32 v37, v37
	s_nop 0
	v_mul_f32_e32 v38, 0x3f317217, v37
	v_fma_f32 v38, v37, s37, -v38
	v_fmac_f32_e32 v38, 0x3377d1cf, v37
	v_fmac_f32_e32 v38, 0x3f317217, v37
	v_cmp_lt_f32_e64 s[42:43], |v37|, s10
	s_nop 1
	v_cndmask_b32_e64 v37, v37, v38, s[42:43]
	v_cndmask_b32_e32 v38, 0, v225, vcc
	v_sub_f32_e32 v37, v37, v38

; DEV float sigm(float x) { return 1.f / (1.f + __expf(-x)); }
;   DEV void operator()(int m, int n, f32x4 v) {
;     ...
;     if (seg == 1 || seg == 2) {
;       const int dir = seg - 1;
; #pragma unroll
;       for (int r = 0; r < 4; r++) {
;         float lb = sigm(lbp[(2 + dir) * 1024 + c + r] - lbp[dir * 1024 + c + r]);
;         float ff = lb + (1.f - lb) * sigm(v[r]);
;         v[r] = __logf(ff);
.LBB0_480:
	s_add_i32 s10, s23, 0x420
	v_or_b32_e32 v34, s10, v79
	v_add_u32_e32 v36, 0xfffffc20, v78
	v_ashrrev_i32_e32 v35, 31, v34
	v_ashrrev_i32_e32 v37, 31, v36
	s_andn2_b64 vcc, exec, s[0:1]
	v_lshl_add_u64 v[42:43], v[34:35], 2, s[46:47]
	v_lshl_add_u64 v[44:45], v[36:37], 2, s[46:47]
	s_cbranch_vccnz .LBB0_482
	global_load_dwordx4 v[34:37], v[42:43], off
	global_load_dwordx4 v[38:41], v[44:45], off
	v_mul_f32_e32 v30, 0xbfb8aa3b, v30
	v_exp_f32_e32 v47, v30
	s_mov_b32 s11, 0x800000
	s_mov_b32 s10, 0x7f800000
	v_mul_f32_e32 v31, 0xbfb8aa3b, v31
	v_mul_f32_e32 v32, 0xbfb8aa3b, v32
	v_mul_f32_e32 v33, 0xbfb8aa3b, v33
	s_waitcnt vmcnt(0)
	v_mov_b32_e32 v84, v34
	v_mov_b32_e32 v85, v35
	v_mov_b32_e32 v86, v36
	v_mov_b32_e32 v87, v37
	v_mov_b32_e32 v88, v38
	v_mov_b32_e32 v89, v39
	v_mov_b32_e32 v90, v40
	v_mov_b32_e32 v91, v41
	v_sub_f32_e32 v34, v34, v38
	v_mul_f32_e32 v34, 0xbfb8aa3b, v34
	v_exp_f32_e32 v46, v34
	s_nop 0
	v_pk_add_f32 v[46:47], v[46:47], 1.0 op_sel_hi:[1,0]
	s_nop 0
	v_div_scale_f32 v30, s[0:1], v47, v47, 1.0
	v_rcp_f32_e32 v34, v30
	s_nop 0
	v_fma_f32 v38, -v30, v34, 1.0
	v_fmac_f32_e32 v34, v38, v34
	v_div_scale_f32 v38, vcc, 1.0, v47, 1.0
	v_mul_f32_e32 v48, v38, v34
	v_fma_f32 v49, -v30, v48, v38
	v_fmac_f32_e32 v48, v49, v34
	v_fma_f32 v30, -v30, v48, v38
	v_div_fmas_f32 v30, v30, v34, v48
	v_div_scale_f32 v34, s[0:1], v46, v46, 1.0
	v_rcp_f32_e32 v38, v34
	v_div_fixup_f32 v30, v30, v47, 1.0
	v_fma_f32 v47, -v34, v38, 1.0
	v_fmac_f32_e32 v38, v47, v38
	v_div_scale_f32 v47, vcc, 1.0, v46, 1.0
	v_mul_f32_e32 v48, v47, v38
	v_fma_f32 v49, -v34, v48, v47
	v_fmac_f32_e32 v48, v49, v38
	v_fma_f32 v34, -v34, v48, v47
	v_div_fmas_f32 v34, v34, v38, v48
	v_div_fixup_f32 v34, v34, v46, 1.0
	v_sub_f32_e32 v38, 1.0, v34
	v_fmac_f32_e32 v34, v30, v38
	v_cmp_gt_f32_e32 vcc, s11, v34
	s_nop 1
	v_cndmask_b32_e64 v30, 0, 32, vcc
	v_ldexp_f32 v30, v34, v30
	v_log_f32_e32 v30, v30
	s_nop 0
	v_mul_f32_e32 v34, 0x3f317217, v30
	v_fma_f32 v34, v30, s37, -v34
	v_fmac_f32_e32 v34, 0x3377d1cf, v30
	v_fmac_f32_e32 v34, 0x3f317217, v30
	v_cmp_lt_f32_e64 s[42:43], |v30|, s10
	s_nop 1
	v_cndmask_b32_e64 v30, v30, v34, s[42:43]
	v_cndmask_b32_e32 v34, 0, v225, vcc
	v_sub_f32_e32 v30, v30, v34
	v_sub_f32_e32 v34, v35, v39
	v_mul_f32_e32 v34, 0xbfb8aa3b, v34
	v_exp_f32_e32 v34, v34
	v_exp_f32_e32 v35, v31
	s_nop 0
	v_pk_add_f32 v[34:35], v[34:35], 1.0 op_sel_hi:[1,0]
	s_nop 0
	v_div_scale_f32 v31, s[0:1], v35, v35, 1.0
	v_rcp_f32_e32 v38, v31
	s_nop 0
	v_fma_f32 v39, -v31, v38, 1.0
	v_fmac_f32_e32 v38, v39, v38
	v_div_scale_f32 v39, vcc, 1.0, v35, 1.0
	v_mul_f32_e32 v46, v39, v38
	v_fma_f32 v47, -v31, v46, v39
	v_fmac_f32_e32 v46, v47, v38
	v_fma_f32 v31, -v31, v46, v39
	v_div_fmas_f32 v31, v31, v38, v46
	v_div_fixup_f32 v31, v31, v35, 1.0
	v_div_scale_f32 v35, s[0:1], v34, v34, 1.0
	v_rcp_f32_e32 v38, v35
	s_nop 0
	v_fma_f32 v39, -v35, v38, 1.0
	v_fmac_f32_e32 v38, v39, v38
	v_div_scale_f32 v39, vcc, 1.0, v34, 1.0
	v_mul_f32_e32 v46, v39, v38
	v_fma_f32 v47, -v35, v46, v39
	v_fmac_f32_e32 v46, v47, v38
	v_fma_f32 v35, -v35, v46, v39
	v_div_fmas_f32 v35, v35, v38, v46
	v_div_fixup_f32 v34, v35, v34, 1.0
	v_sub_f32_e32 v35, 1.0, v34
	v_fmac_f32_e32 v34, v31, v35
	v_cmp_gt_f32_e32 vcc, s11, v34
	v_exp_f32_e32 v35, v32
	s_nop 0
	v_cndmask_b32_e64 v31, 0, 32, vcc
	v_ldexp_f32 v31, v34, v31
	v_log_f32_e32 v31, v31
	s_nop 0
	v_mul_f32_e32 v34, 0x3f317217, v31
	v_fma_f32 v34, v31, s37, -v34
	v_fmac_f32_e32 v34, 0x3377d1cf, v31
	v_fmac_f32_e32 v34, 0x3f317217, v31
	v_cmp_lt_f32_e64 s[42:43], |v31|, s10
	s_nop 1
	v_cndmask_b32_e64 v31, v31, v34, s[42:43]
	v_cndmask_b32_e32 v34, 0, v225, vcc
	v_sub_f32_e32 v31, v31, v34
	v_sub_f32_e32 v34, v36, v40
	v_mul_f32_e32 v34, 0xbfb8aa3b, v34
	v_exp_f32_e32 v34, v34
	s_nop 0
	v_pk_add_f32 v[34:35], v[34:35], 1.0 op_sel_hi:[1,0]
	s_nop 0
	v_div_scale_f32 v32, s[0:1], v35, v35, 1.0
	v_rcp_f32_e32 v36, v32
	s_nop 0
	v_fma_f32 v38, -v32, v36, 1.0
	v_fmac_f32_e32 v36, v38, v36
	v_div_scale_f32 v38, vcc, 1.0, v35, 1.0
	v_mul_f32_e32 v39, v38, v36
	v_fma_f32 v40, -v32, v39, v38
	v_fmac_f32_e32 v39, v40, v36
	v_fma_f32 v32, -v32, v39, v38
	v_div_fmas_f32 v32, v32, v36, v39
	v_div_fixup_f32 v32, v32, v35, 1.0
	v_div_scale_f32 v35, s[0:1], v34, v34, 1.0
	v_rcp_f32_e32 v36, v35
	s_nop 0
	v_fma_f32 v38, -v35, v36, 1.0
	v_fmac_f32_e32 v36, v38, v36
	v_div_scale_f32 v38, vcc, 1.0, v34, 1.0
	v_mul_f32_e32 v39, v38, v36
	v_fma_f32 v40, -v35, v39, v38
	v_fmac_f32_e32 v39, v40, v36
	v_fma_f32 v35, -v35, v39, v38
	v_div_fmas_f32 v35, v35, v36, v39
	v_div_fixup_f32 v34, v35, v34, 1.0
	v_sub_f32_e32 v35, 1.0, v34
	v_fmac_f32_e32 v34, v32, v35
	v_cmp_gt_f32_e32 vcc, s11, v34
	v_exp_f32_e32 v35, v33
	s_nop 0
	v_cndmask_b32_e64 v32, 0, 32, vcc
	v_ldexp_f32 v32, v34, v32
	v_log_f32_e32 v32, v32
	s_nop 0
	v_mul_f32_e32 v34, 0x3f317217, v32
	v_fma_f32 v34, v32, s37, -v34
	v_fmac_f32_e32 v34, 0x3377d1cf, v32
	v_fmac_f32_e32 v34, 0x3f317217, v32
	v_cmp_lt_f32_e64 s[42:43], |v32|, s10
	s_nop 1
	v_cndmask_b32_e64 v32, v32, v34, s[42:43]
	v_cndmask_b32_e32 v34, 0, v225, vcc
	v_sub_f32_e32 v32, v32, v34
	v_sub_f32_e32 v34, v37, v41
	v_mul_f32_e32 v34, 0xbfb8aa3b, v34
	v_exp_f32_e32 v34, v34
	s_nop 0
	v_pk_add_f32 v[34:35], v[34:35], 1.0 op_sel_hi:[1,0]
	s_nop 0
	v_div_scale_f32 v33, s[0:1], v35, v35, 1.0
	v_rcp_f32_e32 v36, v33
	s_nop 0
	v_fma_f32 v37, -v33, v36, 1.0
	v_fmac_f32_e32 v36, v37, v36
	v_div_scale_f32 v37, vcc, 1.0, v35, 1.0
	v_mul_f32_e32 v38, v37, v36
	v_fma_f32 v39, -v33, v38, v37
	v_fmac_f32_e32 v38, v39, v36
	v_fma_f32 v33, -v33, v38, v37
	v_div_fmas_f32 v33, v33, v36, v38
	v_div_fixup_f32 v33, v33, v35, 1.0
	v_div_scale_f32 v35, s[0:1], v34, v34, 1.0
	v_rcp_f32_e32 v36, v35
	s_nop 0
	v_fma_f32 v37, -v35, v36, 1.0
	v_fmac_f32_e32 v36, v37, v36
	v_div_scale_f32 v37, vcc, 1.0, v34, 1.0
	v_mul_f32_e32 v38, v37, v36
	v_fma_f32 v39, -v35, v38, v37
	v_fmac_f32_e32 v38, v39, v36
	v_fma_f32 v35, -v35, v38, v37
	v_div_fmas_f32 v35, v35, v36, v38
	v_div_fixup_f32 v34, v35, v34, 1.0
	v_sub_f32_e32 v35, 1.0, v34
	v_fmac_f32_e32 v34, v33, v35
	v_cmp_gt_f32_e32 vcc, s11, v34
	s_nop 1
	v_cndmask_b32_e64 v33, 0, 32, vcc
	v_ldexp_f32 v33, v34, v33
	v_log_f32_e32 v33, v33
	s_nop 0
	v_mul_f32_e32 v34, 0x3f317217, v33
	v_fma_f32 v34, v33, s37, -v34
	v_fmac_f32_e32 v34, 0x3377d1cf, v33
	v_fmac_f32_e32 v34, 0x3f317217, v33
	v_cmp_lt_f32_e64 s[42:43], |v33|, s10
	s_nop 1
	v_cndmask_b32_e64 v33, v33, v34, s[42:43]
	v_cndmask_b32_e32 v34, 0, v225, vcc
	v_sub_f32_e32 v33, v33, v34

; DEV float sigm(float x) { return 1.f / (1.f + __expf(-x)); }
;   DEV void operator()(int m, int n, f32x4 v) {
;     ...
;     if (seg == 1 || seg == 2) {
;       const int dir = seg - 1;
; #pragma unroll
;       for (int r = 0; r < 4; r++) {
;         float lb = sigm(lbp[(2 + dir) * 1024 + c + r] - lbp[dir * 1024 + c + r]);
;         float ff = lb + (1.f - lb) * sigm(v[r]);
;         v[r] = __logf(ff);
.LBB0_497:
	s_andn2_b64 vcc, exec, s[0:1]
	s_cbranch_vccnz .LBB0_499
	v_mul_f32_e32 v26, 0xbfb8aa3b, v26
	v_exp_f32_e32 v39, v26
	s_mov_b32 s11, 0x800000
	s_mov_b32 s10, 0x7f800000
	v_mul_f32_e32 v27, 0xbfb8aa3b, v27
	v_mul_f32_e32 v28, 0xbfb8aa3b, v28
	v_mul_f32_e32 v29, 0xbfb8aa3b, v29
	v_mov_b32_e32 v30, v84
	v_mov_b32_e32 v31, v85
	v_mov_b32_e32 v32, v86
	v_mov_b32_e32 v33, v87
	v_mov_b32_e32 v34, v88
	v_mov_b32_e32 v35, v89
	v_mov_b32_e32 v36, v90
	v_mov_b32_e32 v37, v91
	v_sub_f32_e32 v30, v30, v34
	v_mul_f32_e32 v30, 0xbfb8aa3b, v30
	v_exp_f32_e32 v38, v30
	s_nop 0
	v_pk_add_f32 v[38:39], v[38:39], 1.0 op_sel_hi:[1,0]
	s_nop 0
	v_div_scale_f32 v26, s[0:1], v39, v39, 1.0
	v_rcp_f32_e32 v30, v26
	s_nop 0
	v_fma_f32 v34, -v26, v30, 1.0
	v_fmac_f32_e32 v30, v34, v30
	v_div_scale_f32 v34, vcc, 1.0, v39, 1.0
	v_mul_f32_e32 v40, v34, v30
	v_fma_f32 v41, -v26, v40, v34
	v_fmac_f32_e32 v40, v41, v30
	v_fma_f32 v26, -v26, v40, v34
	v_div_fmas_f32 v26, v26, v30, v40
	v_div_scale_f32 v30, s[0:1], v38, v38, 1.0
	v_rcp_f32_e32 v34, v30
	v_div_fixup_f32 v26, v26, v39, 1.0
	v_fma_f32 v39, -v30, v34, 1.0
	v_fmac_f32_e32 v34, v39, v34
	v_div_scale_f32 v39, vcc, 1.0, v38, 1.0
	v_mul_f32_e32 v40, v39, v34
	v_fma_f32 v41, -v30, v40, v39
	v_fmac_f32_e32 v40, v41, v34
	v_fma_f32 v30, -v30, v40, v39
	v_div_fmas_f32 v30, v30, v34, v40
	v_div_fixup_f32 v30, v30, v38, 1.0
	v_sub_f32_e32 v34, 1.0, v30
	v_fmac_f32_e32 v30, v26, v34
	v_cmp_gt_f32_e32 vcc, s11, v30
	s_nop 1
	v_cndmask_b32_e64 v26, 0, 32, vcc
	v_ldexp_f32 v26, v30, v26
	v_log_f32_e32 v26, v26
	s_nop 0
	v_mul_f32_e32 v30, 0x3f317217, v26
	v_fma_f32 v30, v26, s37, -v30
	v_fmac_f32_e32 v30, 0x3377d1cf, v26
	v_fmac_f32_e32 v30, 0x3f317217, v26
	v_cmp_lt_f32_e64 s[42:43], |v26|, s10
	s_nop 1
	v_cndmask_b32_e64 v26, v26, v30, s[42:43]
	v_cndmask_b32_e32 v30, 0, v225, vcc
	v_sub_f32_e32 v26, v26, v30
	v_sub_f32_e32 v30, v31, v35
	v_mul_f32_e32 v30, 0xbfb8aa3b, v30
	v_exp_f32_e32 v30, v30
	v_exp_f32_e32 v31, v27
	s_nop 0
	v_pk_add_f32 v[30:31], v[30:31], 1.0 op_sel_hi:[1,0]
	s_nop 0
	v_div_scale_f32 v27, s[0:1], v31, v31, 1.0
	v_rcp_f32_e32 v34, v27
	s_nop 0
	v_fma_f32 v35, -v27, v34, 1.0
	v_fmac_f32_e32 v34, v35, v34
	v_div_scale_f32 v35, vcc, 1.0, v31, 1.0
	v_mul_f32_e32 v38, v35, v34
	v_fma_f32 v39, -v27, v38, v35
	v_fmac_f32_e32 v38, v39, v34
	v_fma_f32 v27, -v27, v38, v35
	v_div_fmas_f32 v27, v27, v34, v38
	v_div_fixup_f32 v27, v27, v31, 1.0
	v_div_scale_f32 v31, s[0:1], v30, v30, 1.0
	v_rcp_f32_e32 v34, v31
	s_nop 0
	v_fma_f32 v35, -v31, v34, 1.0
	v_fmac_f32_e32 v34, v35, v34
	v_div_scale_f32 v35, vcc, 1.0, v30, 1.0
	v_mul_f32_e32 v38, v35, v34
	v_fma_f32 v39, -v31, v38, v35
	v_fmac_f32_e32 v38, v39, v34
	v_fma_f32 v31, -v31, v38, v35
	v_div_fmas_f32 v31, v31, v34, v38
	v_div_fixup_f32 v30, v31, v30, 1.0
	v_sub_f32_e32 v31, 1.0, v30
	v_fmac_f32_e32 v30, v27, v31
	v_cmp_gt_f32_e32 vcc, s11, v30
	v_exp_f32_e32 v31, v28
	s_nop 0
	v_cndmask_b32_e64 v27, 0, 32, vcc
	v_ldexp_f32 v27, v30, v27
	v_log_f32_e32 v27, v27
	s_nop 0
	v_mul_f32_e32 v30, 0x3f317217, v27
	v_fma_f32 v30, v27, s37, -v30
	v_fmac_f32_e32 v30, 0x3377d1cf, v27
	v_fmac_f32_e32 v30, 0x3f317217, v27
	v_cmp_lt_f32_e64 s[42:43], |v27|, s10
	s_nop 1
	v_cndmask_b32_e64 v27, v27, v30, s[42:43]
	v_cndmask_b32_e32 v30, 0, v225, vcc
	v_sub_f32_e32 v27, v27, v30
	v_sub_f32_e32 v30, v32, v36
	v_mul_f32_e32 v30, 0xbfb8aa3b, v30
	v_exp_f32_e32 v30, v30
	s_nop 0
	v_pk_add_f32 v[30:31], v[30:31], 1.0 op_sel_hi:[1,0]
	s_nop 0
	v_div_scale_f32 v28, s[0:1], v31, v31, 1.0
	v_rcp_f32_e32 v32, v28
	s_nop 0
	v_fma_f32 v34, -v28, v32, 1.0
	v_fmac_f32_e32 v32, v34, v32
	v_div_scale_f32 v34, vcc, 1.0, v31, 1.0
	v_mul_f32_e32 v35, v34, v32
	v_fma_f32 v36, -v28, v35, v34
	v_fmac_f32_e32 v35, v36, v32
	v_fma_f32 v28, -v28, v35, v34
	v_div_fmas_f32 v28, v28, v32, v35
	v_div_fixup_f32 v28, v28, v31, 1.0
	v_div_scale_f32 v31, s[0:1], v30, v30, 1.0
	v_rcp_f32_e32 v32, v31
	s_nop 0
	v_fma_f32 v34, -v31, v32, 1.0
	v_fmac_f32_e32 v32, v34, v32
	v_div_scale_f32 v34, vcc, 1.0, v30, 1.0
	v_mul_f32_e32 v35, v34, v32
	v_fma_f32 v36, -v31, v35, v34
	v_fmac_f32_e32 v35, v36, v32
	v_fma_f32 v31, -v31, v35, v34
	v_div_fmas_f32 v31, v31, v32, v35
	v_div_fixup_f32 v30, v31, v30, 1.0
	v_sub_f32_e32 v31, 1.0, v30
	v_fmac_f32_e32 v30, v28, v31
	v_cmp_gt_f32_e32 vcc, s11, v30
	v_exp_f32_e32 v31, v29
	s_nop 0
	v_cndmask_b32_e64 v28, 0, 32, vcc
	v_ldexp_f32 v28, v30, v28
	v_log_f32_e32 v28, v28
	s_nop 0
	v_mul_f32_e32 v30, 0x3f317217, v28
	v_fma_f32 v30, v28, s37, -v30
	v_fmac_f32_e32 v30, 0x3377d1cf, v28
	v_fmac_f32_e32 v30, 0x3f317217, v28
	v_cmp_lt_f32_e64 s[42:43], |v28|, s10
	s_nop 1
	v_cndmask_b32_e64 v28, v28, v30, s[42:43]
	v_cndmask_b32_e32 v30, 0, v225, vcc
	v_sub_f32_e32 v28, v28, v30
	v_sub_f32_e32 v30, v33, v37
	v_mul_f32_e32 v30, 0xbfb8aa3b, v30
	v_exp_f32_e32 v30, v30
	s_nop 0
	v_pk_add_f32 v[30:31], v[30:31], 1.0 op_sel_hi:[1,0]
	s_nop 0
	v_div_scale_f32 v29, s[0:1], v31, v31, 1.0
	v_rcp_f32_e32 v32, v29
	s_nop 0
	v_fma_f32 v33, -v29, v32, 1.0
	v_fmac_f32_e32 v32, v33, v32
	v_div_scale_f32 v33, vcc, 1.0, v31, 1.0
	v_mul_f32_e32 v34, v33, v32
	v_fma_f32 v35, -v29, v34, v33
	v_fmac_f32_e32 v34, v35, v32
	v_fma_f32 v29, -v29, v34, v33
	v_div_fmas_f32 v29, v29, v32, v34
	v_div_fixup_f32 v29, v29, v31, 1.0
	v_div_scale_f32 v31, s[0:1], v30, v30, 1.0
	v_rcp_f32_e32 v32, v31
	s_nop 0
	v_fma_f32 v33, -v31, v32, 1.0
	v_fmac_f32_e32 v32, v33, v32
	v_div_scale_f32 v33, vcc, 1.0, v30, 1.0
	v_mul_f32_e32 v34, v33, v32
	v_fma_f32 v35, -v31, v34, v33
	v_fmac_f32_e32 v34, v35, v32
	v_fma_f32 v31, -v31, v34, v33
	v_div_fmas_f32 v31, v31, v32, v34
	v_div_fixup_f32 v30, v31, v30, 1.0
	v_sub_f32_e32 v31, 1.0, v30
	v_fmac_f32_e32 v30, v29, v31
	v_cmp_gt_f32_e32 vcc, s11, v30
	s_nop 1
	v_cndmask_b32_e64 v29, 0, 32, vcc
	v_ldexp_f32 v29, v30, v29
	v_log_f32_e32 v29, v29
	s_nop 0
	v_mul_f32_e32 v30, 0x3f317217, v29
	v_fma_f32 v30, v29, s37, -v30
	v_fmac_f32_e32 v30, 0x3377d1cf, v29
	v_fmac_f32_e32 v30, 0x3f317217, v29
	v_cmp_lt_f32_e64 s[42:43], |v29|, s10
	s_nop 1
	v_cndmask_b32_e64 v29, v29, v30, s[42:43]
	v_cndmask_b32_e32 v30, 0, v225, vcc
	v_sub_f32_e32 v29, v29, v30

; DEV float sigm(float x) { return 1.f / (1.f + __expf(-x)); }
;   DEV void operator()(int m, int n, f32x4 v) {
;     ...
;     if (seg == 1 || seg == 2) {
;       const int dir = seg - 1;
; #pragma unroll
;       for (int r = 0; r < 4; r++) {
;         float lb = sigm(lbp[(2 + dir) * 1024 + c + r] - lbp[dir * 1024 + c + r]);
;         float ff = lb + (1.f - lb) * sigm(v[r]);
;         v[r] = __logf(ff);
.LBB0_514:
	s_andn2_b64 vcc, exec, s[0:1]
	s_cbranch_vccnz .LBB0_516
	v_mul_f32_e32 v22, 0xbfb8aa3b, v22
	v_exp_f32_e32 v35, v22
	s_mov_b32 s11, 0x800000
	s_mov_b32 s10, 0x7f800000
	v_mul_f32_e32 v23, 0xbfb8aa3b, v23
	v_mul_f32_e32 v24, 0xbfb8aa3b, v24
	v_mul_f32_e32 v25, 0xbfb8aa3b, v25
	v_mov_b32_e32 v26, v84
	v_mov_b32_e32 v27, v85
	v_mov_b32_e32 v28, v86
	v_mov_b32_e32 v29, v87
	v_mov_b32_e32 v30, v88
	v_mov_b32_e32 v31, v89
	v_mov_b32_e32 v32, v90
	v_mov_b32_e32 v33, v91
	v_sub_f32_e32 v26, v26, v30
	v_mul_f32_e32 v26, 0xbfb8aa3b, v26
	v_exp_f32_e32 v34, v26
	s_nop 0
	v_pk_add_f32 v[34:35], v[34:35], 1.0 op_sel_hi:[1,0]
	s_nop 0
	v_div_scale_f32 v22, s[0:1], v35, v35, 1.0
	v_rcp_f32_e32 v26, v22
	s_nop 0
	v_fma_f32 v30, -v22, v26, 1.0
	v_fmac_f32_e32 v26, v30, v26
	v_div_scale_f32 v30, vcc, 1.0, v35, 1.0
	v_mul_f32_e32 v36, v30, v26
	v_fma_f32 v37, -v22, v36, v30
	v_fmac_f32_e32 v36, v37, v26
	v_fma_f32 v22, -v22, v36, v30
	v_div_fmas_f32 v22, v22, v26, v36
	v_div_scale_f32 v26, s[0:1], v34, v34, 1.0
	v_rcp_f32_e32 v30, v26
	v_div_fixup_f32 v22, v22, v35, 1.0
	v_fma_f32 v35, -v26, v30, 1.0
	v_fmac_f32_e32 v30, v35, v30
	v_div_scale_f32 v35, vcc, 1.0, v34, 1.0
	v_mul_f32_e32 v36, v35, v30
	v_fma_f32 v37, -v26, v36, v35
	v_fmac_f32_e32 v36, v37, v30
	v_fma_f32 v26, -v26, v36, v35
	v_div_fmas_f32 v26, v26, v30, v36
	v_div_fixup_f32 v26, v26, v34, 1.0
	v_sub_f32_e32 v30, 1.0, v26
	v_fmac_f32_e32 v26, v22, v30
	v_cmp_gt_f32_e32 vcc, s11, v26
	s_nop 1
	v_cndmask_b32_e64 v22, 0, 32, vcc
	v_ldexp_f32 v22, v26, v22
	v_log_f32_e32 v22, v22
	s_nop 0
	v_mul_f32_e32 v26, 0x3f317217, v22
	v_fma_f32 v26, v22, s37, -v26
	v_fmac_f32_e32 v26, 0x3377d1cf, v22
	v_fmac_f32_e32 v26, 0x3f317217, v22
	v_cmp_lt_f32_e64 s[42:43], |v22|, s10
	s_nop 1
	v_cndmask_b32_e64 v22, v22, v26, s[42:43]
	v_cndmask_b32_e32 v26, 0, v225, vcc
	v_sub_f32_e32 v22, v22, v26
	v_sub_f32_e32 v26, v27, v31
	v_mul_f32_e32 v26, 0xbfb8aa3b, v26
	v_exp_f32_e32 v26, v26
	v_exp_f32_e32 v27, v23
	s_nop 0
	v_pk_add_f32 v[26:27], v[26:27], 1.0 op_sel_hi:[1,0]
	s_nop 0
	v_div_scale_f32 v23, s[0:1], v27, v27, 1.0
	v_rcp_f32_e32 v30, v23
	s_nop 0
	v_fma_f32 v31, -v23, v30, 1.0
	v_fmac_f32_e32 v30, v31, v30
	v_div_scale_f32 v31, vcc, 1.0, v27, 1.0
	v_mul_f32_e32 v34, v31, v30
	v_fma_f32 v35, -v23, v34, v31
	v_fmac_f32_e32 v34, v35, v30
	v_fma_f32 v23, -v23, v34, v31
	v_div_fmas_f32 v23, v23, v30, v34
	v_div_fixup_f32 v23, v23, v27, 1.0
	v_div_scale_f32 v27, s[0:1], v26, v26, 1.0
	v_rcp_f32_e32 v30, v27
	s_nop 0
	v_fma_f32 v31, -v27, v30, 1.0
	v_fmac_f32_e32 v30, v31, v30
	v_div_scale_f32 v31, vcc, 1.0, v26, 1.0
	v_mul_f32_e32 v34, v31, v30
	v_fma_f32 v35, -v27, v34, v31
	v_fmac_f32_e32 v34, v35, v30
	v_fma_f32 v27, -v27, v34, v31
	v_div_fmas_f32 v27, v27, v30, v34
	v_div_fixup_f32 v26, v27, v26, 1.0
	v_sub_f32_e32 v27, 1.0, v26
	v_fmac_f32_e32 v26, v23, v27
	v_cmp_gt_f32_e32 vcc, s11, v26
	v_exp_f32_e32 v27, v24
	s_nop 0
	v_cndmask_b32_e64 v23, 0, 32, vcc
	v_ldexp_f32 v23, v26, v23
	v_log_f32_e32 v23, v23
	s_nop 0
	v_mul_f32_e32 v26, 0x3f317217, v23
	v_fma_f32 v26, v23, s37, -v26
	v_fmac_f32_e32 v26, 0x3377d1cf, v23
	v_fmac_f32_e32 v26, 0x3f317217, v23
	v_cmp_lt_f32_e64 s[42:43], |v23|, s10
	s_nop 1
	v_cndmask_b32_e64 v23, v23, v26, s[42:43]
	v_cndmask_b32_e32 v26, 0, v225, vcc
	v_sub_f32_e32 v23, v23, v26
	v_sub_f32_e32 v26, v28, v32
	v_mul_f32_e32 v26, 0xbfb8aa3b, v26
	v_exp_f32_e32 v26, v26
	s_nop 0
	v_pk_add_f32 v[26:27], v[26:27], 1.0 op_sel_hi:[1,0]
	s_nop 0
	v_div_scale_f32 v24, s[0:1], v27, v27, 1.0
	v_rcp_f32_e32 v28, v24
	s_nop 0
	v_fma_f32 v30, -v24, v28, 1.0
	v_fmac_f32_e32 v28, v30, v28
	v_div_scale_f32 v30, vcc, 1.0, v27, 1.0
	v_mul_f32_e32 v31, v30, v28
	v_fma_f32 v32, -v24, v31, v30
	v_fmac_f32_e32 v31, v32, v28
	v_fma_f32 v24, -v24, v31, v30
	v_div_fmas_f32 v24, v24, v28, v31
	v_div_fixup_f32 v24, v24, v27, 1.0
	v_div_scale_f32 v27, s[0:1], v26, v26, 1.0
	v_rcp_f32_e32 v28, v27
	s_nop 0
	v_fma_f32 v30, -v27, v28, 1.0
	v_fmac_f32_e32 v28, v30, v28
	v_div_scale_f32 v30, vcc, 1.0, v26, 1.0
	v_mul_f32_e32 v31, v30, v28
	v_fma_f32 v32, -v27, v31, v30
	v_fmac_f32_e32 v31, v32, v28
	v_fma_f32 v27, -v27, v31, v30
	v_div_fmas_f32 v27, v27, v28, v31
	v_div_fixup_f32 v26, v27, v26, 1.0
	v_sub_f32_e32 v27, 1.0, v26
	v_fmac_f32_e32 v26, v24, v27
	v_cmp_gt_f32_e32 vcc, s11, v26
	v_exp_f32_e32 v27, v25
	s_nop 0
	v_cndmask_b32_e64 v24, 0, 32, vcc
	v_ldexp_f32 v24, v26, v24
	v_log_f32_e32 v24, v24
	s_nop 0
	v_mul_f32_e32 v26, 0x3f317217, v24
	v_fma_f32 v26, v24, s37, -v26
	v_fmac_f32_e32 v26, 0x3377d1cf, v24
	v_fmac_f32_e32 v26, 0x3f317217, v24
	v_cmp_lt_f32_e64 s[42:43], |v24|, s10
	s_nop 1
	v_cndmask_b32_e64 v24, v24, v26, s[42:43]
	v_cndmask_b32_e32 v26, 0, v225, vcc
	v_sub_f32_e32 v24, v24, v26
	v_sub_f32_e32 v26, v29, v33
	v_mul_f32_e32 v26, 0xbfb8aa3b, v26
	v_exp_f32_e32 v26, v26
	s_nop 0
	v_pk_add_f32 v[26:27], v[26:27], 1.0 op_sel_hi:[1,0]
	s_nop 0
	v_div_scale_f32 v25, s[0:1], v27, v27, 1.0
	v_rcp_f32_e32 v28, v25
	s_nop 0
	v_fma_f32 v29, -v25, v28, 1.0
	v_fmac_f32_e32 v28, v29, v28
	v_div_scale_f32 v29, vcc, 1.0, v27, 1.0
	v_mul_f32_e32 v30, v29, v28
	v_fma_f32 v31, -v25, v30, v29
	v_fmac_f32_e32 v30, v31, v28
	v_fma_f32 v25, -v25, v30, v29
	v_div_fmas_f32 v25, v25, v28, v30
	v_div_fixup_f32 v25, v25, v27, 1.0
	v_div_scale_f32 v27, s[0:1], v26, v26, 1.0
	v_rcp_f32_e32 v28, v27
	s_nop 0
	v_fma_f32 v29, -v27, v28, 1.0
	v_fmac_f32_e32 v28, v29, v28
	v_div_scale_f32 v29, vcc, 1.0, v26, 1.0
	v_mul_f32_e32 v30, v29, v28
	v_fma_f32 v31, -v27, v30, v29
	v_fmac_f32_e32 v30, v31, v28
	v_fma_f32 v27, -v27, v30, v29
	v_div_fmas_f32 v27, v27, v28, v30
	v_div_fixup_f32 v26, v27, v26, 1.0
	v_sub_f32_e32 v27, 1.0, v26
	v_fmac_f32_e32 v26, v25, v27
	v_cmp_gt_f32_e32 vcc, s11, v26
	s_nop 1
	v_cndmask_b32_e64 v25, 0, 32, vcc
	v_ldexp_f32 v25, v26, v25
	v_log_f32_e32 v25, v25
	s_nop 0
	v_mul_f32_e32 v26, 0x3f317217, v25
	v_fma_f32 v26, v25, s37, -v26
	v_fmac_f32_e32 v26, 0x3377d1cf, v25
	v_fmac_f32_e32 v26, 0x3f317217, v25
	v_cmp_lt_f32_e64 s[42:43], |v25|, s10
	s_nop 1
	v_cndmask_b32_e64 v25, v25, v26, s[42:43]
	v_cndmask_b32_e32 v26, 0, v225, vcc
	v_sub_f32_e32 v25, v25, v26

; DEV float sigm(float x) { return 1.f / (1.f + __expf(-x)); }
;   DEV void operator()(int m, int n, f32x4 v) {
;     ...
;     if (seg == 1 || seg == 2) {
;       const int dir = seg - 1;
; #pragma unroll
;       for (int r = 0; r < 4; r++) {
;         float lb = sigm(lbp[(2 + dir) * 1024 + c + r] - lbp[dir * 1024 + c + r]);
;         float ff = lb + (1.f - lb) * sigm(v[r]);
;         v[r] = __logf(ff);
.LBB0_531:
	s_andn2_b64 vcc, exec, s[0:1]
	s_cbranch_vccnz .LBB0_533
	v_mul_f32_e32 v18, 0xbfb8aa3b, v18
	v_exp_f32_e32 v31, v18
	s_mov_b32 s11, 0x800000
	s_mov_b32 s10, 0x7f800000
	v_mul_f32_e32 v19, 0xbfb8aa3b, v19
	v_mul_f32_e32 v20, 0xbfb8aa3b, v20
	v_mul_f32_e32 v21, 0xbfb8aa3b, v21
	v_mov_b32_e32 v22, v84
	v_mov_b32_e32 v23, v85
	v_mov_b32_e32 v24, v86
	v_mov_b32_e32 v25, v87
	v_mov_b32_e32 v26, v88
	v_mov_b32_e32 v27, v89
	v_mov_b32_e32 v28, v90
	v_mov_b32_e32 v29, v91
	v_sub_f32_e32 v22, v22, v26
	v_mul_f32_e32 v22, 0xbfb8aa3b, v22
	v_exp_f32_e32 v30, v22
	s_nop 0
	v_pk_add_f32 v[30:31], v[30:31], 1.0 op_sel_hi:[1,0]
	s_nop 0
	v_div_scale_f32 v18, s[0:1], v31, v31, 1.0
	v_rcp_f32_e32 v22, v18
	s_nop 0
	v_fma_f32 v26, -v18, v22, 1.0
	v_fmac_f32_e32 v22, v26, v22
	v_div_scale_f32 v26, vcc, 1.0, v31, 1.0
	v_mul_f32_e32 v32, v26, v22
	v_fma_f32 v33, -v18, v32, v26
	v_fmac_f32_e32 v32, v33, v22
	v_fma_f32 v18, -v18, v32, v26
	v_div_fmas_f32 v18, v18, v22, v32
	v_div_scale_f32 v22, s[0:1], v30, v30, 1.0
	v_rcp_f32_e32 v26, v22
	v_div_fixup_f32 v18, v18, v31, 1.0
	v_fma_f32 v31, -v22, v26, 1.0
	v_fmac_f32_e32 v26, v31, v26
	v_div_scale_f32 v31, vcc, 1.0, v30, 1.0
	v_mul_f32_e32 v32, v31, v26
	v_fma_f32 v33, -v22, v32, v31
	v_fmac_f32_e32 v32, v33, v26
	v_fma_f32 v22, -v22, v32, v31
	v_div_fmas_f32 v22, v22, v26, v32
	v_div_fixup_f32 v22, v22, v30, 1.0
	v_sub_f32_e32 v26, 1.0, v22
	v_fmac_f32_e32 v22, v18, v26
	v_cmp_gt_f32_e32 vcc, s11, v22
	s_nop 1
	v_cndmask_b32_e64 v18, 0, 32, vcc
	v_ldexp_f32 v18, v22, v18
	v_log_f32_e32 v18, v18
	s_nop 0
	v_mul_f32_e32 v22, 0x3f317217, v18
	v_fma_f32 v22, v18, s37, -v22
	v_fmac_f32_e32 v22, 0x3377d1cf, v18
	v_fmac_f32_e32 v22, 0x3f317217, v18
	v_cmp_lt_f32_e64 s[42:43], |v18|, s10
	s_nop 1
	v_cndmask_b32_e64 v18, v18, v22, s[42:43]
	v_cndmask_b32_e32 v22, 0, v225, vcc
	v_sub_f32_e32 v18, v18, v22
	v_sub_f32_e32 v22, v23, v27
	v_mul_f32_e32 v22, 0xbfb8aa3b, v22
	v_exp_f32_e32 v22, v22
	v_exp_f32_e32 v23, v19
	s_nop 0
	v_pk_add_f32 v[22:23], v[22:23], 1.0 op_sel_hi:[1,0]
	s_nop 0
	v_div_scale_f32 v19, s[0:1], v23, v23, 1.0
	v_rcp_f32_e32 v26, v19
	s_nop 0
	v_fma_f32 v27, -v19, v26, 1.0
	v_fmac_f32_e32 v26, v27, v26
	v_div_scale_f32 v27, vcc, 1.0, v23, 1.0
	v_mul_f32_e32 v30, v27, v26
	v_fma_f32 v31, -v19, v30, v27
	v_fmac_f32_e32 v30, v31, v26
	v_fma_f32 v19, -v19, v30, v27
	v_div_fmas_f32 v19, v19, v26, v30
	v_div_fixup_f32 v19, v19, v23, 1.0
	v_div_scale_f32 v23, s[0:1], v22, v22, 1.0
	v_rcp_f32_e32 v26, v23
	s_nop 0
	v_fma_f32 v27, -v23, v26, 1.0
	v_fmac_f32_e32 v26, v27, v26
	v_div_scale_f32 v27, vcc, 1.0, v22, 1.0
	v_mul_f32_e32 v30, v27, v26
	v_fma_f32 v31, -v23, v30, v27
	v_fmac_f32_e32 v30, v31, v26
	v_fma_f32 v23, -v23, v30, v27
	v_div_fmas_f32 v23, v23, v26, v30
	v_div_fixup_f32 v22, v23, v22, 1.0
	v_sub_f32_e32 v23, 1.0, v22
	v_fmac_f32_e32 v22, v19, v23
	v_cmp_gt_f32_e32 vcc, s11, v22
	v_exp_f32_e32 v23, v20
	s_nop 0
	v_cndmask_b32_e64 v19, 0, 32, vcc
	v_ldexp_f32 v19, v22, v19
	v_log_f32_e32 v19, v19
	s_nop 0
	v_mul_f32_e32 v22, 0x3f317217, v19
	v_fma_f32 v22, v19, s37, -v22
	v_fmac_f32_e32 v22, 0x3377d1cf, v19
	v_fmac_f32_e32 v22, 0x3f317217, v19
	v_cmp_lt_f32_e64 s[42:43], |v19|, s10
	s_nop 1
	v_cndmask_b32_e64 v19, v19, v22, s[42:43]
	v_cndmask_b32_e32 v22, 0, v225, vcc
	v_sub_f32_e32 v19, v19, v22
	v_sub_f32_e32 v22, v24, v28
	v_mul_f32_e32 v22, 0xbfb8aa3b, v22
	v_exp_f32_e32 v22, v22
	s_nop 0
	v_pk_add_f32 v[22:23], v[22:23], 1.0 op_sel_hi:[1,0]
	s_nop 0
	v_div_scale_f32 v20, s[0:1], v23, v23, 1.0
	v_rcp_f32_e32 v24, v20
	s_nop 0
	v_fma_f32 v26, -v20, v24, 1.0
	v_fmac_f32_e32 v24, v26, v24
	v_div_scale_f32 v26, vcc, 1.0, v23, 1.0
	v_mul_f32_e32 v27, v26, v24
	v_fma_f32 v28, -v20, v27, v26
	v_fmac_f32_e32 v27, v28, v24
	v_fma_f32 v20, -v20, v27, v26
	v_div_fmas_f32 v20, v20, v24, v27
	v_div_fixup_f32 v20, v20, v23, 1.0
	v_div_scale_f32 v23, s[0:1], v22, v22, 1.0
	v_rcp_f32_e32 v24, v23
	s_nop 0
	v_fma_f32 v26, -v23, v24, 1.0
	v_fmac_f32_e32 v24, v26, v24
	v_div_scale_f32 v26, vcc, 1.0, v22, 1.0
	v_mul_f32_e32 v27, v26, v24
	v_fma_f32 v28, -v23, v27, v26
	v_fmac_f32_e32 v27, v28, v24
	v_fma_f32 v23, -v23, v27, v26
	v_div_fmas_f32 v23, v23, v24, v27
	v_div_fixup_f32 v22, v23, v22, 1.0
	v_sub_f32_e32 v23, 1.0, v22
	v_fmac_f32_e32 v22, v20, v23
	v_cmp_gt_f32_e32 vcc, s11, v22
	v_exp_f32_e32 v23, v21
	s_nop 0
	v_cndmask_b32_e64 v20, 0, 32, vcc
	v_ldexp_f32 v20, v22, v20
	v_log_f32_e32 v20, v20
	s_nop 0
	v_mul_f32_e32 v22, 0x3f317217, v20
	v_fma_f32 v22, v20, s37, -v22
	v_fmac_f32_e32 v22, 0x3377d1cf, v20
	v_fmac_f32_e32 v22, 0x3f317217, v20
	v_cmp_lt_f32_e64 s[42:43], |v20|, s10
	s_nop 1
	v_cndmask_b32_e64 v20, v20, v22, s[42:43]
	v_cndmask_b32_e32 v22, 0, v225, vcc
	v_sub_f32_e32 v20, v20, v22
	v_sub_f32_e32 v22, v25, v29
	v_mul_f32_e32 v22, 0xbfb8aa3b, v22
	v_exp_f32_e32 v22, v22
	s_nop 0
	v_pk_add_f32 v[22:23], v[22:23], 1.0 op_sel_hi:[1,0]
	s_nop 0
	v_div_scale_f32 v21, s[0:1], v23, v23, 1.0
	v_rcp_f32_e32 v24, v21
	s_nop 0
	v_fma_f32 v25, -v21, v24, 1.0
	v_fmac_f32_e32 v24, v25, v24
	v_div_scale_f32 v25, vcc, 1.0, v23, 1.0
	v_mul_f32_e32 v26, v25, v24
	v_fma_f32 v27, -v21, v26, v25
	v_fmac_f32_e32 v26, v27, v24
	v_fma_f32 v21, -v21, v26, v25
	v_div_fmas_f32 v21, v21, v24, v26
	v_div_fixup_f32 v21, v21, v23, 1.0
	v_div_scale_f32 v23, s[0:1], v22, v22, 1.0
	v_rcp_f32_e32 v24, v23
	s_nop 0
	v_fma_f32 v25, -v23, v24, 1.0
	v_fmac_f32_e32 v24, v25, v24
	v_div_scale_f32 v25, vcc, 1.0, v22, 1.0
	v_mul_f32_e32 v26, v25, v24
	v_fma_f32 v27, -v23, v26, v25
	v_fmac_f32_e32 v26, v27, v24
	v_fma_f32 v23, -v23, v26, v25
	v_div_fmas_f32 v23, v23, v24, v26
	v_div_fixup_f32 v22, v23, v22, 1.0
	v_sub_f32_e32 v23, 1.0, v22
	v_fmac_f32_e32 v22, v21, v23
	v_cmp_gt_f32_e32 vcc, s11, v22
	s_nop 1
	v_cndmask_b32_e64 v21, 0, 32, vcc
	v_ldexp_f32 v21, v22, v21
	v_log_f32_e32 v21, v21
	s_nop 0
	v_mul_f32_e32 v22, 0x3f317217, v21
	v_fma_f32 v22, v21, s37, -v22
	v_fmac_f32_e32 v22, 0x3377d1cf, v21
	v_fmac_f32_e32 v22, 0x3f317217, v21
	v_cmp_lt_f32_e64 s[42:43], |v21|, s10
	s_nop 1
	v_cndmask_b32_e64 v21, v21, v22, s[42:43]
	v_cndmask_b32_e32 v22, 0, v225, vcc
	v_sub_f32_e32 v21, v21, v22

; DEV float sigm(float x) { return 1.f / (1.f + __expf(-x)); }
;   DEV void operator()(int m, int n, f32x4 v) {
;     ...
;     if (seg == 1 || seg == 2) {
;       const int dir = seg - 1;
; #pragma unroll
;       for (int r = 0; r < 4; r++) {
;         float lb = sigm(lbp[(2 + dir) * 1024 + c + r] - lbp[dir * 1024 + c + r]);
;         float ff = lb + (1.f - lb) * sigm(v[r]);
;         v[r] = __logf(ff);
.LBB0_548:
	s_addk_i32 s23, 0x430
	v_or_b32_e32 v18, s23, v79
	v_add_u32_e32 v20, 0xfffffc30, v78
	v_ashrrev_i32_e32 v19, 31, v18
	v_ashrrev_i32_e32 v21, 31, v20
	s_andn2_b64 vcc, exec, s[0:1]
	v_lshl_add_u64 v[26:27], v[18:19], 2, s[46:47]
	v_lshl_add_u64 v[28:29], v[20:21], 2, s[46:47]
	s_cbranch_vccnz .LBB0_550
	global_load_dwordx4 v[18:21], v[26:27], off
	global_load_dwordx4 v[22:25], v[28:29], off
	v_mul_f32_e32 v14, 0xbfb8aa3b, v14
	v_exp_f32_e32 v31, v14
	s_mov_b32 s11, 0x800000
	s_mov_b32 s10, 0x7f800000
	v_mul_f32_e32 v15, 0xbfb8aa3b, v15
	v_mul_f32_e32 v16, 0xbfb8aa3b, v16
	v_mul_f32_e32 v17, 0xbfb8aa3b, v17
	s_waitcnt vmcnt(0)
	v_mov_b32_e32 v84, v18
	v_mov_b32_e32 v85, v19
	v_mov_b32_e32 v86, v20
	v_mov_b32_e32 v87, v21
	v_mov_b32_e32 v88, v22
	v_mov_b32_e32 v89, v23
	v_mov_b32_e32 v90, v24
	v_mov_b32_e32 v91, v25
	v_sub_f32_e32 v18, v18, v22
	v_mul_f32_e32 v18, 0xbfb8aa3b, v18
	v_exp_f32_e32 v30, v18
	s_nop 0
	v_pk_add_f32 v[30:31], v[30:31], 1.0 op_sel_hi:[1,0]
	s_nop 0
	v_div_scale_f32 v14, s[0:1], v31, v31, 1.0
	v_rcp_f32_e32 v18, v14
	s_nop 0
	v_fma_f32 v22, -v14, v18, 1.0
	v_fmac_f32_e32 v18, v22, v18
	v_div_scale_f32 v22, vcc, 1.0, v31, 1.0
	v_mul_f32_e32 v32, v22, v18
	v_fma_f32 v33, -v14, v32, v22
	v_fmac_f32_e32 v32, v33, v18
	v_fma_f32 v14, -v14, v32, v22
	v_div_fmas_f32 v14, v14, v18, v32
	v_div_scale_f32 v18, s[0:1], v30, v30, 1.0
	v_rcp_f32_e32 v22, v18
	v_div_fixup_f32 v14, v14, v31, 1.0
	v_fma_f32 v31, -v18, v22, 1.0
	v_fmac_f32_e32 v22, v31, v22
	v_div_scale_f32 v31, vcc, 1.0, v30, 1.0
	v_mul_f32_e32 v32, v31, v22
	v_fma_f32 v33, -v18, v32, v31
	v_fmac_f32_e32 v32, v33, v22
	v_fma_f32 v18, -v18, v32, v31
	v_div_fmas_f32 v18, v18, v22, v32
	v_div_fixup_f32 v18, v18, v30, 1.0
	v_sub_f32_e32 v22, 1.0, v18
	v_fmac_f32_e32 v18, v14, v22
	v_cmp_gt_f32_e32 vcc, s11, v18
	s_nop 1
	v_cndmask_b32_e64 v14, 0, 32, vcc
	v_ldexp_f32 v14, v18, v14
	v_log_f32_e32 v14, v14
	s_nop 0
	v_mul_f32_e32 v18, 0x3f317217, v14
	v_fma_f32 v18, v14, s37, -v18
	v_fmac_f32_e32 v18, 0x3377d1cf, v14
	v_fmac_f32_e32 v18, 0x3f317217, v14
	v_cmp_lt_f32_e64 s[42:43], |v14|, s10
	s_nop 1
	v_cndmask_b32_e64 v14, v14, v18, s[42:43]
	v_cndmask_b32_e32 v18, 0, v225, vcc
	v_sub_f32_e32 v14, v14, v18
	v_sub_f32_e32 v18, v19, v23
	v_mul_f32_e32 v18, 0xbfb8aa3b, v18
	v_exp_f32_e32 v18, v18
	v_exp_f32_e32 v19, v15
	s_nop 0
	v_pk_add_f32 v[18:19], v[18:19], 1.0 op_sel_hi:[1,0]
	s_nop 0
	v_div_scale_f32 v15, s[0:1], v19, v19, 1.0
	v_rcp_f32_e32 v22, v15
	s_nop 0
	v_fma_f32 v23, -v15, v22, 1.0
	v_fmac_f32_e32 v22, v23, v22
	v_div_scale_f32 v23, vcc, 1.0, v19, 1.0
	v_mul_f32_e32 v30, v23, v22
	v_fma_f32 v31, -v15, v30, v23
	v_fmac_f32_e32 v30, v31, v22
	v_fma_f32 v15, -v15, v30, v23
	v_div_fmas_f32 v15, v15, v22, v30
	v_div_fixup_f32 v15, v15, v19, 1.0
	v_div_scale_f32 v19, s[0:1], v18, v18, 1.0
	v_rcp_f32_e32 v22, v19
	s_nop 0
	v_fma_f32 v23, -v19, v22, 1.0
	v_fmac_f32_e32 v22, v23, v22
	v_div_scale_f32 v23, vcc, 1.0, v18, 1.0
	v_mul_f32_e32 v30, v23, v22
	v_fma_f32 v31, -v19, v30, v23
	v_fmac_f32_e32 v30, v31, v22
	v_fma_f32 v19, -v19, v30, v23
	v_div_fmas_f32 v19, v19, v22, v30
	v_div_fixup_f32 v18, v19, v18, 1.0
	v_sub_f32_e32 v19, 1.0, v18
	v_fmac_f32_e32 v18, v15, v19
	v_cmp_gt_f32_e32 vcc, s11, v18
	v_exp_f32_e32 v19, v16
	s_nop 0
	v_cndmask_b32_e64 v15, 0, 32, vcc
	v_ldexp_f32 v15, v18, v15
	v_log_f32_e32 v15, v15
	s_nop 0
	v_mul_f32_e32 v18, 0x3f317217, v15
	v_fma_f32 v18, v15, s37, -v18
	v_fmac_f32_e32 v18, 0x3377d1cf, v15
	v_fmac_f32_e32 v18, 0x3f317217, v15
	v_cmp_lt_f32_e64 s[42:43], |v15|, s10
	s_nop 1
	v_cndmask_b32_e64 v15, v15, v18, s[42:43]
	v_cndmask_b32_e32 v18, 0, v225, vcc
	v_sub_f32_e32 v15, v15, v18
	v_sub_f32_e32 v18, v20, v24
	v_mul_f32_e32 v18, 0xbfb8aa3b, v18
	v_exp_f32_e32 v18, v18
	s_nop 0
	v_pk_add_f32 v[18:19], v[18:19], 1.0 op_sel_hi:[1,0]
	s_nop 0
	v_div_scale_f32 v16, s[0:1], v19, v19, 1.0
	v_rcp_f32_e32 v20, v16
	s_nop 0
	v_fma_f32 v22, -v16, v20, 1.0
	v_fmac_f32_e32 v20, v22, v20
	v_div_scale_f32 v22, vcc, 1.0, v19, 1.0
	v_mul_f32_e32 v23, v22, v20
	v_fma_f32 v24, -v16, v23, v22
	v_fmac_f32_e32 v23, v24, v20
	v_fma_f32 v16, -v16, v23, v22
	v_div_fmas_f32 v16, v16, v20, v23
	v_div_fixup_f32 v16, v16, v19, 1.0
	v_div_scale_f32 v19, s[0:1], v18, v18, 1.0
	v_rcp_f32_e32 v20, v19
	s_nop 0
	v_fma_f32 v22, -v19, v20, 1.0
	v_fmac_f32_e32 v20, v22, v20
	v_div_scale_f32 v22, vcc, 1.0, v18, 1.0
	v_mul_f32_e32 v23, v22, v20
	v_fma_f32 v24, -v19, v23, v22
	v_fmac_f32_e32 v23, v24, v20
	v_fma_f32 v19, -v19, v23, v22
	v_div_fmas_f32 v19, v19, v20, v23
	v_div_fixup_f32 v18, v19, v18, 1.0
	v_sub_f32_e32 v19, 1.0, v18
	v_fmac_f32_e32 v18, v16, v19
	v_cmp_gt_f32_e32 vcc, s11, v18
	v_exp_f32_e32 v19, v17
	s_nop 0
	v_cndmask_b32_e64 v16, 0, 32, vcc
	v_ldexp_f32 v16, v18, v16
	v_log_f32_e32 v16, v16
	s_nop 0
	v_mul_f32_e32 v18, 0x3f317217, v16
	v_fma_f32 v18, v16, s37, -v18
	v_fmac_f32_e32 v18, 0x3377d1cf, v16
	v_fmac_f32_e32 v18, 0x3f317217, v16
	v_cmp_lt_f32_e64 s[42:43], |v16|, s10
	s_nop 1
	v_cndmask_b32_e64 v16, v16, v18, s[42:43]
	v_cndmask_b32_e32 v18, 0, v225, vcc
	v_sub_f32_e32 v16, v16, v18
	v_sub_f32_e32 v18, v21, v25
	v_mul_f32_e32 v18, 0xbfb8aa3b, v18
	v_exp_f32_e32 v18, v18
	s_nop 0
	v_pk_add_f32 v[18:19], v[18:19], 1.0 op_sel_hi:[1,0]
	s_nop 0
	v_div_scale_f32 v17, s[0:1], v19, v19, 1.0
	v_rcp_f32_e32 v20, v17
	s_nop 0
	v_fma_f32 v21, -v17, v20, 1.0
	v_fmac_f32_e32 v20, v21, v20
	v_div_scale_f32 v21, vcc, 1.0, v19, 1.0
	v_mul_f32_e32 v22, v21, v20
	v_fma_f32 v23, -v17, v22, v21
	v_fmac_f32_e32 v22, v23, v20
	v_fma_f32 v17, -v17, v22, v21
	v_div_fmas_f32 v17, v17, v20, v22
	v_div_fixup_f32 v17, v17, v19, 1.0
	v_div_scale_f32 v19, s[0:1], v18, v18, 1.0
	v_rcp_f32_e32 v20, v19
	s_nop 0
	v_fma_f32 v21, -v19, v20, 1.0
	v_fmac_f32_e32 v20, v21, v20
	v_div_scale_f32 v21, vcc, 1.0, v18, 1.0
	v_mul_f32_e32 v22, v21, v20
	v_fma_f32 v23, -v19, v22, v21
	v_fmac_f32_e32 v22, v23, v20
	v_fma_f32 v19, -v19, v22, v21
	v_div_fmas_f32 v19, v19, v20, v22
	v_div_fixup_f32 v18, v19, v18, 1.0
	v_sub_f32_e32 v19, 1.0, v18
	v_fmac_f32_e32 v18, v17, v19
	v_cmp_gt_f32_e32 vcc, s11, v18
	s_nop 1
	v_cndmask_b32_e64 v17, 0, 32, vcc
	v_ldexp_f32 v17, v18, v17
	v_log_f32_e32 v17, v17
	s_nop 0
	v_mul_f32_e32 v18, 0x3f317217, v17
	v_fma_f32 v18, v17, s37, -v18
	v_fmac_f32_e32 v18, 0x3377d1cf, v17
	v_fmac_f32_e32 v18, 0x3f317217, v17
	v_cmp_lt_f32_e64 s[42:43], |v17|, s10
	s_nop 1
	v_cndmask_b32_e64 v17, v17, v18, s[42:43]
	v_cndmask_b32_e32 v18, 0, v225, vcc
	v_sub_f32_e32 v17, v17, v18

; DEV float sigm(float x) { return 1.f / (1.f + __expf(-x)); }
;   DEV void operator()(int m, int n, f32x4 v) {
;     ...
;     if (seg == 1 || seg == 2) {
;       const int dir = seg - 1;
; #pragma unroll
;       for (int r = 0; r < 4; r++) {
;         float lb = sigm(lbp[(2 + dir) * 1024 + c + r] - lbp[dir * 1024 + c + r]);
;         float ff = lb + (1.f - lb) * sigm(v[r]);
;         v[r] = __logf(ff);
.LBB0_565:
	s_andn2_b64 vcc, exec, s[0:1]
	s_cbranch_vccnz .LBB0_567
	v_mul_f32_e32 v10, 0xbfb8aa3b, v10
	v_exp_f32_e32 v23, v10
	s_mov_b32 s11, 0x800000
	s_mov_b32 s10, 0x7f800000
	v_mul_f32_e32 v11, 0xbfb8aa3b, v11
	v_mul_f32_e32 v12, 0xbfb8aa3b, v12
	v_mul_f32_e32 v13, 0xbfb8aa3b, v13
	v_mov_b32_e32 v14, v84
	v_mov_b32_e32 v15, v85
	v_mov_b32_e32 v16, v86
	v_mov_b32_e32 v17, v87
	v_mov_b32_e32 v18, v88
	v_mov_b32_e32 v19, v89
	v_mov_b32_e32 v20, v90
	v_mov_b32_e32 v21, v91
	v_sub_f32_e32 v14, v14, v18
	v_mul_f32_e32 v14, 0xbfb8aa3b, v14
	v_exp_f32_e32 v22, v14
	s_nop 0
	v_pk_add_f32 v[22:23], v[22:23], 1.0 op_sel_hi:[1,0]
	s_nop 0
	v_div_scale_f32 v10, s[0:1], v23, v23, 1.0
	v_rcp_f32_e32 v14, v10
	s_nop 0
	v_fma_f32 v18, -v10, v14, 1.0
	v_fmac_f32_e32 v14, v18, v14
	v_div_scale_f32 v18, vcc, 1.0, v23, 1.0
	v_mul_f32_e32 v24, v18, v14
	v_fma_f32 v25, -v10, v24, v18
	v_fmac_f32_e32 v24, v25, v14
	v_fma_f32 v10, -v10, v24, v18
	v_div_fmas_f32 v10, v10, v14, v24
	v_div_scale_f32 v14, s[0:1], v22, v22, 1.0
	v_rcp_f32_e32 v18, v14
	v_div_fixup_f32 v10, v10, v23, 1.0
	v_fma_f32 v23, -v14, v18, 1.0
	v_fmac_f32_e32 v18, v23, v18
	v_div_scale_f32 v23, vcc, 1.0, v22, 1.0
	v_mul_f32_e32 v24, v23, v18
	v_fma_f32 v25, -v14, v24, v23
	v_fmac_f32_e32 v24, v25, v18
	v_fma_f32 v14, -v14, v24, v23
	v_div_fmas_f32 v14, v14, v18, v24
	v_div_fixup_f32 v14, v14, v22, 1.0
	v_sub_f32_e32 v18, 1.0, v14
	v_fmac_f32_e32 v14, v10, v18
	v_cmp_gt_f32_e32 vcc, s11, v14
	s_nop 1
	v_cndmask_b32_e64 v10, 0, 32, vcc
	v_ldexp_f32 v10, v14, v10
	v_log_f32_e32 v10, v10
	s_nop 0
	v_mul_f32_e32 v14, 0x3f317217, v10
	v_fma_f32 v14, v10, s37, -v14
	v_fmac_f32_e32 v14, 0x3377d1cf, v10
	v_fmac_f32_e32 v14, 0x3f317217, v10
	v_cmp_lt_f32_e64 s[42:43], |v10|, s10
	s_nop 1
	v_cndmask_b32_e64 v10, v10, v14, s[42:43]
	v_cndmask_b32_e32 v14, 0, v225, vcc
	v_sub_f32_e32 v10, v10, v14
	v_sub_f32_e32 v14, v15, v19
	v_mul_f32_e32 v14, 0xbfb8aa3b, v14
	v_exp_f32_e32 v14, v14
	v_exp_f32_e32 v15, v11
	s_nop 0
	v_pk_add_f32 v[14:15], v[14:15], 1.0 op_sel_hi:[1,0]
	s_nop 0
	v_div_scale_f32 v11, s[0:1], v15, v15, 1.0
	v_rcp_f32_e32 v18, v11
	s_nop 0
	v_fma_f32 v19, -v11, v18, 1.0
	v_fmac_f32_e32 v18, v19, v18
	v_div_scale_f32 v19, vcc, 1.0, v15, 1.0
	v_mul_f32_e32 v22, v19, v18
	v_fma_f32 v23, -v11, v22, v19
	v_fmac_f32_e32 v22, v23, v18
	v_fma_f32 v11, -v11, v22, v19
	v_div_fmas_f32 v11, v11, v18, v22
	v_div_fixup_f32 v11, v11, v15, 1.0
	v_div_scale_f32 v15, s[0:1], v14, v14, 1.0
	v_rcp_f32_e32 v18, v15
	s_nop 0
	v_fma_f32 v19, -v15, v18, 1.0
	v_fmac_f32_e32 v18, v19, v18
	v_div_scale_f32 v19, vcc, 1.0, v14, 1.0
	v_mul_f32_e32 v22, v19, v18
	v_fma_f32 v23, -v15, v22, v19
	v_fmac_f32_e32 v22, v23, v18
	v_fma_f32 v15, -v15, v22, v19
	v_div_fmas_f32 v15, v15, v18, v22
	v_div_fixup_f32 v14, v15, v14, 1.0
	v_sub_f32_e32 v15, 1.0, v14
	v_fmac_f32_e32 v14, v11, v15
	v_cmp_gt_f32_e32 vcc, s11, v14
	v_exp_f32_e32 v15, v12
	s_nop 0
	v_cndmask_b32_e64 v11, 0, 32, vcc
	v_ldexp_f32 v11, v14, v11
	v_log_f32_e32 v11, v11
	s_nop 0
	v_mul_f32_e32 v14, 0x3f317217, v11
	v_fma_f32 v14, v11, s37, -v14
	v_fmac_f32_e32 v14, 0x3377d1cf, v11
	v_fmac_f32_e32 v14, 0x3f317217, v11
	v_cmp_lt_f32_e64 s[42:43], |v11|, s10
	s_nop 1
	v_cndmask_b32_e64 v11, v11, v14, s[42:43]
	v_cndmask_b32_e32 v14, 0, v225, vcc
	v_sub_f32_e32 v11, v11, v14
	v_sub_f32_e32 v14, v16, v20
	v_mul_f32_e32 v14, 0xbfb8aa3b, v14
	v_exp_f32_e32 v14, v14
	s_nop 0
	v_pk_add_f32 v[14:15], v[14:15], 1.0 op_sel_hi:[1,0]
	s_nop 0
	v_div_scale_f32 v12, s[0:1], v15, v15, 1.0
	v_rcp_f32_e32 v16, v12
	s_nop 0
	v_fma_f32 v18, -v12, v16, 1.0
	v_fmac_f32_e32 v16, v18, v16
	v_div_scale_f32 v18, vcc, 1.0, v15, 1.0
	v_mul_f32_e32 v19, v18, v16
	v_fma_f32 v20, -v12, v19, v18
	v_fmac_f32_e32 v19, v20, v16
	v_fma_f32 v12, -v12, v19, v18
	v_div_fmas_f32 v12, v12, v16, v19
	v_div_fixup_f32 v12, v12, v15, 1.0
	v_div_scale_f32 v15, s[0:1], v14, v14, 1.0
	v_rcp_f32_e32 v16, v15
	s_nop 0
	v_fma_f32 v18, -v15, v16, 1.0
	v_fmac_f32_e32 v16, v18, v16
	v_div_scale_f32 v18, vcc, 1.0, v14, 1.0
	v_mul_f32_e32 v19, v18, v16
	v_fma_f32 v20, -v15, v19, v18
	v_fmac_f32_e32 v19, v20, v16
	v_fma_f32 v15, -v15, v19, v18
	v_div_fmas_f32 v15, v15, v16, v19
	v_div_fixup_f32 v14, v15, v14, 1.0
	v_sub_f32_e32 v15, 1.0, v14
	v_fmac_f32_e32 v14, v12, v15
	v_cmp_gt_f32_e32 vcc, s11, v14
	v_exp_f32_e32 v15, v13
	s_nop 0
	v_cndmask_b32_e64 v12, 0, 32, vcc
	v_ldexp_f32 v12, v14, v12
	v_log_f32_e32 v12, v12
	s_nop 0
	v_mul_f32_e32 v14, 0x3f317217, v12
	v_fma_f32 v14, v12, s37, -v14
	v_fmac_f32_e32 v14, 0x3377d1cf, v12
	v_fmac_f32_e32 v14, 0x3f317217, v12
	v_cmp_lt_f32_e64 s[42:43], |v12|, s10
	s_nop 1
	v_cndmask_b32_e64 v12, v12, v14, s[42:43]
	v_cndmask_b32_e32 v14, 0, v225, vcc
	v_sub_f32_e32 v12, v12, v14
	v_sub_f32_e32 v14, v17, v21
	v_mul_f32_e32 v14, 0xbfb8aa3b, v14
	v_exp_f32_e32 v14, v14
	s_nop 0
	v_pk_add_f32 v[14:15], v[14:15], 1.0 op_sel_hi:[1,0]
	s_nop 0
	v_div_scale_f32 v13, s[0:1], v15, v15, 1.0
	v_rcp_f32_e32 v16, v13
	s_nop 0
	v_fma_f32 v17, -v13, v16, 1.0
	v_fmac_f32_e32 v16, v17, v16
	v_div_scale_f32 v17, vcc, 1.0, v15, 1.0
	v_mul_f32_e32 v18, v17, v16
	v_fma_f32 v19, -v13, v18, v17
	v_fmac_f32_e32 v18, v19, v16
	v_fma_f32 v13, -v13, v18, v17
	v_div_fmas_f32 v13, v13, v16, v18
	v_div_fixup_f32 v13, v13, v15, 1.0
	v_div_scale_f32 v15, s[0:1], v14, v14, 1.0
	v_rcp_f32_e32 v16, v15
	s_nop 0
	v_fma_f32 v17, -v15, v16, 1.0
	v_fmac_f32_e32 v16, v17, v16
	v_div_scale_f32 v17, vcc, 1.0, v14, 1.0
	v_mul_f32_e32 v18, v17, v16
	v_fma_f32 v19, -v15, v18, v17
	v_fmac_f32_e32 v18, v19, v16
	v_fma_f32 v15, -v15, v18, v17
	v_div_fmas_f32 v15, v15, v16, v18
	v_div_fixup_f32 v14, v15, v14, 1.0
	v_sub_f32_e32 v15, 1.0, v14
	v_fmac_f32_e32 v14, v13, v15
	v_cmp_gt_f32_e32 vcc, s11, v14
	s_nop 1
	v_cndmask_b32_e64 v13, 0, 32, vcc
	v_ldexp_f32 v13, v14, v13
	v_log_f32_e32 v13, v13
	s_nop 0
	v_mul_f32_e32 v14, 0x3f317217, v13
	v_fma_f32 v14, v13, s37, -v14
	v_fmac_f32_e32 v14, 0x3377d1cf, v13
	v_fmac_f32_e32 v14, 0x3f317217, v13
	v_cmp_lt_f32_e64 s[42:43], |v13|, s10
	s_nop 1
	v_cndmask_b32_e64 v13, v13, v14, s[42:43]
	v_cndmask_b32_e32 v14, 0, v225, vcc
	v_sub_f32_e32 v13, v13, v14

; DEV float sigm(float x) { return 1.f / (1.f + __expf(-x)); }
;   DEV void operator()(int m, int n, f32x4 v) {
;     ...
;     if (seg == 1 || seg == 2) {
;       const int dir = seg - 1;
; #pragma unroll
;       for (int r = 0; r < 4; r++) {
;         float lb = sigm(lbp[(2 + dir) * 1024 + c + r] - lbp[dir * 1024 + c + r]);
;         float ff = lb + (1.f - lb) * sigm(v[r]);
;         v[r] = __logf(ff);
.LBB0_582:
	s_andn2_b64 vcc, exec, s[0:1]
	s_cbranch_vccnz .LBB0_584
	v_mul_f32_e32 v6, 0xbfb8aa3b, v6
	v_exp_f32_e32 v19, v6
	s_mov_b32 s11, 0x800000
	s_mov_b32 s10, 0x7f800000
	v_mul_f32_e32 v7, 0xbfb8aa3b, v7
	v_mul_f32_e32 v8, 0xbfb8aa3b, v8
	v_mul_f32_e32 v9, 0xbfb8aa3b, v9
	v_mov_b32_e32 v10, v84
	v_mov_b32_e32 v11, v85
	v_mov_b32_e32 v12, v86
	v_mov_b32_e32 v13, v87
	v_mov_b32_e32 v14, v88
	v_mov_b32_e32 v15, v89
	v_mov_b32_e32 v16, v90
	v_mov_b32_e32 v17, v91
	v_sub_f32_e32 v10, v10, v14
	v_mul_f32_e32 v10, 0xbfb8aa3b, v10
	v_exp_f32_e32 v18, v10
	s_nop 0
	v_pk_add_f32 v[18:19], v[18:19], 1.0 op_sel_hi:[1,0]
	s_nop 0
	v_div_scale_f32 v6, s[0:1], v19, v19, 1.0
	v_rcp_f32_e32 v10, v6
	s_nop 0
	v_fma_f32 v14, -v6, v10, 1.0
	v_fmac_f32_e32 v10, v14, v10
	v_div_scale_f32 v14, vcc, 1.0, v19, 1.0
	v_mul_f32_e32 v20, v14, v10
	v_fma_f32 v21, -v6, v20, v14
	v_fmac_f32_e32 v20, v21, v10
	v_fma_f32 v6, -v6, v20, v14
	v_div_fmas_f32 v6, v6, v10, v20
	v_div_scale_f32 v10, s[0:1], v18, v18, 1.0
	v_rcp_f32_e32 v14, v10
	v_div_fixup_f32 v6, v6, v19, 1.0
	v_fma_f32 v19, -v10, v14, 1.0
	v_fmac_f32_e32 v14, v19, v14
	v_div_scale_f32 v19, vcc, 1.0, v18, 1.0
	v_mul_f32_e32 v20, v19, v14
	v_fma_f32 v21, -v10, v20, v19
	v_fmac_f32_e32 v20, v21, v14
	v_fma_f32 v10, -v10, v20, v19
	v_div_fmas_f32 v10, v10, v14, v20
	v_div_fixup_f32 v10, v10, v18, 1.0
	v_sub_f32_e32 v14, 1.0, v10
	v_fmac_f32_e32 v10, v6, v14
	v_cmp_gt_f32_e32 vcc, s11, v10
	s_nop 1
	v_cndmask_b32_e64 v6, 0, 32, vcc
	v_ldexp_f32 v6, v10, v6
	v_log_f32_e32 v6, v6
	s_nop 0
	v_mul_f32_e32 v10, 0x3f317217, v6
	v_fma_f32 v10, v6, s37, -v10
	v_fmac_f32_e32 v10, 0x3377d1cf, v6
	v_fmac_f32_e32 v10, 0x3f317217, v6
	v_cmp_lt_f32_e64 s[42:43], |v6|, s10
	s_nop 1
	v_cndmask_b32_e64 v6, v6, v10, s[42:43]
	v_cndmask_b32_e32 v10, 0, v225, vcc
	v_sub_f32_e32 v6, v6, v10
	v_sub_f32_e32 v10, v11, v15
	v_mul_f32_e32 v10, 0xbfb8aa3b, v10
	v_exp_f32_e32 v10, v10
	v_exp_f32_e32 v11, v7
	s_nop 0
	v_pk_add_f32 v[10:11], v[10:11], 1.0 op_sel_hi:[1,0]
	s_nop 0
	v_div_scale_f32 v7, s[0:1], v11, v11, 1.0
	v_rcp_f32_e32 v14, v7
	s_nop 0
	v_fma_f32 v15, -v7, v14, 1.0
	v_fmac_f32_e32 v14, v15, v14
	v_div_scale_f32 v15, vcc, 1.0, v11, 1.0
	v_mul_f32_e32 v18, v15, v14
	v_fma_f32 v19, -v7, v18, v15
	v_fmac_f32_e32 v18, v19, v14
	v_fma_f32 v7, -v7, v18, v15
	v_div_fmas_f32 v7, v7, v14, v18
	v_div_fixup_f32 v7, v7, v11, 1.0
	v_div_scale_f32 v11, s[0:1], v10, v10, 1.0
	v_rcp_f32_e32 v14, v11
	s_nop 0
	v_fma_f32 v15, -v11, v14, 1.0
	v_fmac_f32_e32 v14, v15, v14
	v_div_scale_f32 v15, vcc, 1.0, v10, 1.0
	v_mul_f32_e32 v18, v15, v14
	v_fma_f32 v19, -v11, v18, v15
	v_fmac_f32_e32 v18, v19, v14
	v_fma_f32 v11, -v11, v18, v15
	v_div_fmas_f32 v11, v11, v14, v18
	v_div_fixup_f32 v10, v11, v10, 1.0
	v_sub_f32_e32 v11, 1.0, v10
	v_fmac_f32_e32 v10, v7, v11
	v_cmp_gt_f32_e32 vcc, s11, v10
	v_exp_f32_e32 v11, v8
	s_nop 0
	v_cndmask_b32_e64 v7, 0, 32, vcc
	v_ldexp_f32 v7, v10, v7
	v_log_f32_e32 v7, v7
	s_nop 0
	v_mul_f32_e32 v10, 0x3f317217, v7
	v_fma_f32 v10, v7, s37, -v10
	v_fmac_f32_e32 v10, 0x3377d1cf, v7
	v_fmac_f32_e32 v10, 0x3f317217, v7
	v_cmp_lt_f32_e64 s[42:43], |v7|, s10
	s_nop 1
	v_cndmask_b32_e64 v7, v7, v10, s[42:43]
	v_cndmask_b32_e32 v10, 0, v225, vcc
	v_sub_f32_e32 v7, v7, v10
	v_sub_f32_e32 v10, v12, v16
	v_mul_f32_e32 v10, 0xbfb8aa3b, v10
	v_exp_f32_e32 v10, v10
	s_nop 0
	v_pk_add_f32 v[10:11], v[10:11], 1.0 op_sel_hi:[1,0]
	s_nop 0
	v_div_scale_f32 v8, s[0:1], v11, v11, 1.0
	v_rcp_f32_e32 v12, v8
	s_nop 0
	v_fma_f32 v14, -v8, v12, 1.0
	v_fmac_f32_e32 v12, v14, v12
	v_div_scale_f32 v14, vcc, 1.0, v11, 1.0
	v_mul_f32_e32 v15, v14, v12
	v_fma_f32 v16, -v8, v15, v14
	v_fmac_f32_e32 v15, v16, v12
	v_fma_f32 v8, -v8, v15, v14
	v_div_fmas_f32 v8, v8, v12, v15
	v_div_fixup_f32 v8, v8, v11, 1.0
	v_div_scale_f32 v11, s[0:1], v10, v10, 1.0
	v_rcp_f32_e32 v12, v11
	s_nop 0
	v_fma_f32 v14, -v11, v12, 1.0
	v_fmac_f32_e32 v12, v14, v12
	v_div_scale_f32 v14, vcc, 1.0, v10, 1.0
	v_mul_f32_e32 v15, v14, v12
	v_fma_f32 v16, -v11, v15, v14
	v_fmac_f32_e32 v15, v16, v12
	v_fma_f32 v11, -v11, v15, v14
	v_div_fmas_f32 v11, v11, v12, v15
	v_div_fixup_f32 v10, v11, v10, 1.0
	v_sub_f32_e32 v11, 1.0, v10
	v_fmac_f32_e32 v10, v8, v11
	v_cmp_gt_f32_e32 vcc, s11, v10
	v_exp_f32_e32 v11, v9
	s_nop 0
	v_cndmask_b32_e64 v8, 0, 32, vcc
	v_ldexp_f32 v8, v10, v8
	v_log_f32_e32 v8, v8
	s_nop 0
	v_mul_f32_e32 v10, 0x3f317217, v8
	v_fma_f32 v10, v8, s37, -v10
	v_fmac_f32_e32 v10, 0x3377d1cf, v8
	v_fmac_f32_e32 v10, 0x3f317217, v8
	v_cmp_lt_f32_e64 s[42:43], |v8|, s10
	s_nop 1
	v_cndmask_b32_e64 v8, v8, v10, s[42:43]
	v_cndmask_b32_e32 v10, 0, v225, vcc
	v_sub_f32_e32 v8, v8, v10
	v_sub_f32_e32 v10, v13, v17
	v_mul_f32_e32 v10, 0xbfb8aa3b, v10
	v_exp_f32_e32 v10, v10
	s_nop 0
	v_pk_add_f32 v[10:11], v[10:11], 1.0 op_sel_hi:[1,0]
	s_nop 0
	v_div_scale_f32 v9, s[0:1], v11, v11, 1.0
	v_rcp_f32_e32 v12, v9
	s_nop 0
	v_fma_f32 v13, -v9, v12, 1.0
	v_fmac_f32_e32 v12, v13, v12
	v_div_scale_f32 v13, vcc, 1.0, v11, 1.0
	v_mul_f32_e32 v14, v13, v12
	v_fma_f32 v15, -v9, v14, v13
	v_fmac_f32_e32 v14, v15, v12
	v_fma_f32 v9, -v9, v14, v13
	v_div_fmas_f32 v9, v9, v12, v14
	v_div_fixup_f32 v9, v9, v11, 1.0
	v_div_scale_f32 v11, s[0:1], v10, v10, 1.0
	v_rcp_f32_e32 v12, v11
	s_nop 0
	v_fma_f32 v13, -v11, v12, 1.0
	v_fmac_f32_e32 v12, v13, v12
	v_div_scale_f32 v13, vcc, 1.0, v10, 1.0
	v_mul_f32_e32 v14, v13, v12
	v_fma_f32 v15, -v11, v14, v13
	v_fmac_f32_e32 v14, v15, v12
	v_fma_f32 v11, -v11, v14, v13
	v_div_fmas_f32 v11, v11, v12, v14
	v_div_fixup_f32 v10, v11, v10, 1.0
	v_sub_f32_e32 v11, 1.0, v10
	v_fmac_f32_e32 v10, v9, v11
	v_cmp_gt_f32_e32 vcc, s11, v10
	s_nop 1
	v_cndmask_b32_e64 v9, 0, 32, vcc
	v_ldexp_f32 v9, v10, v9
	v_log_f32_e32 v9, v9
	s_nop 0
	v_mul_f32_e32 v10, 0x3f317217, v9
	v_fma_f32 v10, v9, s37, -v10
	v_fmac_f32_e32 v10, 0x3377d1cf, v9
	v_fmac_f32_e32 v10, 0x3f317217, v9
	v_cmp_lt_f32_e64 s[42:43], |v9|, s10
	s_nop 1
	v_cndmask_b32_e64 v9, v9, v10, s[42:43]
	v_cndmask_b32_e32 v10, 0, v225, vcc
	v_sub_f32_e32 v9, v9, v10

; DEV float sigm(float x) { return 1.f / (1.f + __expf(-x)); }
;   DEV void operator()(int m, int n, f32x4 v) {
;     ...
;     if (seg == 1 || seg == 2) {
;       const int dir = seg - 1;
; #pragma unroll
;       for (int r = 0; r < 4; r++) {
;         float lb = sigm(lbp[(2 + dir) * 1024 + c + r] - lbp[dir * 1024 + c + r]);
;         float ff = lb + (1.f - lb) * sigm(v[r]);
;         v[r] = __logf(ff);
.LBB0_599:
	s_andn2_b64 vcc, exec, s[0:1]
	s_cbranch_vccnz .LBB0_322
	v_mul_f32_e32 v2, 0xbfb8aa3b, v2
	v_exp_f32_e32 v15, v2
	s_mov_b32 s11, 0x800000
	s_mov_b32 s10, 0x7f800000
	v_mul_f32_e32 v3, 0xbfb8aa3b, v3
	v_mul_f32_e32 v4, 0xbfb8aa3b, v4
	v_mul_f32_e32 v5, 0xbfb8aa3b, v5
	v_mov_b32_e32 v6, v84
	v_mov_b32_e32 v7, v85
	v_mov_b32_e32 v8, v86
	v_mov_b32_e32 v9, v87
	v_mov_b32_e32 v10, v88
	v_mov_b32_e32 v11, v89
	v_mov_b32_e32 v12, v90
	v_mov_b32_e32 v13, v91
	v_sub_f32_e32 v6, v6, v10
	v_mul_f32_e32 v6, 0xbfb8aa3b, v6
	v_exp_f32_e32 v14, v6
	s_nop 0
	v_pk_add_f32 v[14:15], v[14:15], 1.0 op_sel_hi:[1,0]
	s_nop 0
	v_div_scale_f32 v2, s[0:1], v15, v15, 1.0
	v_rcp_f32_e32 v6, v2
	s_nop 0
	v_fma_f32 v10, -v2, v6, 1.0
	v_fmac_f32_e32 v6, v10, v6
	v_div_scale_f32 v10, vcc, 1.0, v15, 1.0
	v_mul_f32_e32 v16, v10, v6
	v_fma_f32 v17, -v2, v16, v10
	v_fmac_f32_e32 v16, v17, v6
	v_fma_f32 v2, -v2, v16, v10
	v_div_fmas_f32 v2, v2, v6, v16
	v_div_scale_f32 v6, s[0:1], v14, v14, 1.0
	v_rcp_f32_e32 v10, v6
	v_div_fixup_f32 v2, v2, v15, 1.0
	v_fma_f32 v15, -v6, v10, 1.0
	v_fmac_f32_e32 v10, v15, v10
	v_div_scale_f32 v15, vcc, 1.0, v14, 1.0
	v_mul_f32_e32 v16, v15, v10
	v_fma_f32 v17, -v6, v16, v15
	v_fmac_f32_e32 v16, v17, v10
	v_fma_f32 v6, -v6, v16, v15
	v_div_fmas_f32 v6, v6, v10, v16
	v_div_fixup_f32 v6, v6, v14, 1.0
	v_sub_f32_e32 v10, 1.0, v6
	v_fmac_f32_e32 v6, v2, v10
	v_cmp_gt_f32_e32 vcc, s11, v6
	s_nop 1
	v_cndmask_b32_e64 v2, 0, 32, vcc
	v_ldexp_f32 v2, v6, v2
	v_log_f32_e32 v2, v2
	s_nop 0
	v_mul_f32_e32 v6, 0x3f317217, v2
	v_fma_f32 v6, v2, s37, -v6
	v_fmac_f32_e32 v6, 0x3377d1cf, v2
	v_fmac_f32_e32 v6, 0x3f317217, v2
	v_cmp_lt_f32_e64 s[38:39], |v2|, s10
	s_nop 1
	v_cndmask_b32_e64 v2, v2, v6, s[38:39]
	v_cndmask_b32_e32 v6, 0, v225, vcc
	v_sub_f32_e32 v2, v2, v6
	v_sub_f32_e32 v6, v7, v11
	v_mul_f32_e32 v6, 0xbfb8aa3b, v6
	v_exp_f32_e32 v6, v6
	v_exp_f32_e32 v7, v3
	s_nop 0
	v_pk_add_f32 v[6:7], v[6:7], 1.0 op_sel_hi:[1,0]
	s_nop 0
	v_div_scale_f32 v3, s[0:1], v7, v7, 1.0
	v_rcp_f32_e32 v10, v3
	s_nop 0
	v_fma_f32 v11, -v3, v10, 1.0
	v_fmac_f32_e32 v10, v11, v10
	v_div_scale_f32 v11, vcc, 1.0, v7, 1.0
	v_mul_f32_e32 v14, v11, v10
	v_fma_f32 v15, -v3, v14, v11
	v_fmac_f32_e32 v14, v15, v10
	v_fma_f32 v3, -v3, v14, v11
	v_div_fmas_f32 v3, v3, v10, v14
	v_div_fixup_f32 v3, v3, v7, 1.0
	v_div_scale_f32 v7, s[0:1], v6, v6, 1.0
	v_rcp_f32_e32 v10, v7
	s_nop 0
	v_fma_f32 v11, -v7, v10, 1.0
	v_fmac_f32_e32 v10, v11, v10
	v_div_scale_f32 v11, vcc, 1.0, v6, 1.0
	v_mul_f32_e32 v14, v11, v10
	v_fma_f32 v15, -v7, v14, v11
	v_fmac_f32_e32 v14, v15, v10
	v_fma_f32 v7, -v7, v14, v11
	v_div_fmas_f32 v7, v7, v10, v14
	v_div_fixup_f32 v6, v7, v6, 1.0
	v_sub_f32_e32 v7, 1.0, v6
	v_fmac_f32_e32 v6, v3, v7
	v_cmp_gt_f32_e32 vcc, s11, v6
	v_exp_f32_e32 v7, v4
	s_nop 0
	v_cndmask_b32_e64 v3, 0, 32, vcc
	v_ldexp_f32 v3, v6, v3
	v_log_f32_e32 v3, v3
	s_nop 0
	v_mul_f32_e32 v6, 0x3f317217, v3
	v_fma_f32 v6, v3, s37, -v6
	v_fmac_f32_e32 v6, 0x3377d1cf, v3
	v_fmac_f32_e32 v6, 0x3f317217, v3
	v_cmp_lt_f32_e64 s[38:39], |v3|, s10
	s_nop 1
	v_cndmask_b32_e64 v3, v3, v6, s[38:39]
	v_cndmask_b32_e32 v6, 0, v225, vcc
	v_sub_f32_e32 v3, v3, v6
	v_sub_f32_e32 v6, v8, v12
	v_mul_f32_e32 v6, 0xbfb8aa3b, v6
	v_exp_f32_e32 v6, v6
	s_nop 0
	v_pk_add_f32 v[6:7], v[6:7], 1.0 op_sel_hi:[1,0]
	s_nop 0
	v_div_scale_f32 v4, s[0:1], v7, v7, 1.0
	v_rcp_f32_e32 v8, v4
	s_nop 0
	v_fma_f32 v10, -v4, v8, 1.0
	v_fmac_f32_e32 v8, v10, v8
	v_div_scale_f32 v10, vcc, 1.0, v7, 1.0
	v_mul_f32_e32 v11, v10, v8
	v_fma_f32 v12, -v4, v11, v10
	v_fmac_f32_e32 v11, v12, v8
	v_fma_f32 v4, -v4, v11, v10
	v_div_fmas_f32 v4, v4, v8, v11
	v_div_fixup_f32 v4, v4, v7, 1.0
	v_div_scale_f32 v7, s[0:1], v6, v6, 1.0
	v_rcp_f32_e32 v8, v7
	s_nop 0
	v_fma_f32 v10, -v7, v8, 1.0
	v_fmac_f32_e32 v8, v10, v8
	v_div_scale_f32 v10, vcc, 1.0, v6, 1.0
	v_mul_f32_e32 v11, v10, v8
	v_fma_f32 v12, -v7, v11, v10
	v_fmac_f32_e32 v11, v12, v8
	v_fma_f32 v7, -v7, v11, v10
	v_div_fmas_f32 v7, v7, v8, v11
	v_div_fixup_f32 v6, v7, v6, 1.0
	v_sub_f32_e32 v7, 1.0, v6
	v_fmac_f32_e32 v6, v4, v7
	v_cmp_gt_f32_e32 vcc, s11, v6
	v_exp_f32_e32 v7, v5
	s_nop 0
	v_cndmask_b32_e64 v4, 0, 32, vcc
	v_ldexp_f32 v4, v6, v4
	v_log_f32_e32 v4, v4
	s_nop 0
	v_mul_f32_e32 v6, 0x3f317217, v4
	v_fma_f32 v6, v4, s37, -v6
	v_fmac_f32_e32 v6, 0x3377d1cf, v4
	v_fmac_f32_e32 v6, 0x3f317217, v4
	v_cmp_lt_f32_e64 s[38:39], |v4|, s10
	s_nop 1
	v_cndmask_b32_e64 v4, v4, v6, s[38:39]
	v_cndmask_b32_e32 v6, 0, v225, vcc
	v_sub_f32_e32 v4, v4, v6
	v_sub_f32_e32 v6, v9, v13
	v_mul_f32_e32 v6, 0xbfb8aa3b, v6
	v_exp_f32_e32 v6, v6
	s_nop 0
	v_pk_add_f32 v[6:7], v[6:7], 1.0 op_sel_hi:[1,0]
	s_nop 0
	v_div_scale_f32 v5, s[0:1], v7, v7, 1.0
	v_rcp_f32_e32 v8, v5
	s_nop 0
	v_fma_f32 v9, -v5, v8, 1.0
	v_fmac_f32_e32 v8, v9, v8
	v_div_scale_f32 v9, vcc, 1.0, v7, 1.0
	v_mul_f32_e32 v10, v9, v8
	v_fma_f32 v11, -v5, v10, v9
	v_fmac_f32_e32 v10, v11, v8
	v_fma_f32 v5, -v5, v10, v9
	v_div_fmas_f32 v5, v5, v8, v10
	v_div_fixup_f32 v5, v5, v7, 1.0
	v_div_scale_f32 v7, s[0:1], v6, v6, 1.0
	v_rcp_f32_e32 v8, v7
	s_nop 0
	v_fma_f32 v9, -v7, v8, 1.0
	v_fmac_f32_e32 v8, v9, v8
	v_div_scale_f32 v9, vcc, 1.0, v6, 1.0
	v_mul_f32_e32 v10, v9, v8
	v_fma_f32 v11, -v7, v10, v9
	v_fmac_f32_e32 v10, v11, v8
	v_fma_f32 v7, -v7, v10, v9
	v_div_fmas_f32 v7, v7, v8, v10
	v_div_fixup_f32 v6, v7, v6, 1.0
	v_sub_f32_e32 v7, 1.0, v6
	v_fmac_f32_e32 v6, v5, v7
	v_cmp_gt_f32_e32 vcc, s11, v6
	s_nop 1
	v_cndmask_b32_e64 v5, 0, 32, vcc
	v_ldexp_f32 v5, v6, v5
	v_log_f32_e32 v5, v5
	s_nop 0
	v_mul_f32_e32 v6, 0x3f317217, v5
	v_fma_f32 v6, v5, s37, -v6
	v_fmac_f32_e32 v6, 0x3377d1cf, v5
	v_fmac_f32_e32 v6, 0x3f317217, v5
	v_cmp_lt_f32_e64 s[38:39], |v5|, s10
	s_nop 1
	v_cndmask_b32_e64 v5, v5, v6, s[38:39]
	v_cndmask_b32_e32 v6, 0, v225, vcc
	v_sub_f32_e32 v5, v5, v6
	s_branch .LBB0_322

; DEV void phase_peer_expert(const Params& p, int layer, int M, bool final_, int part, char* smem) {
;     ...
;       float d0 = da.x + da.y, d1 = db.x + db.y;
;       d0 += __shfl_xor(d0, 1); d1 += __shfl_xor(d1, 1);
;       d0 += __shfl_xor(d0, 2); d1 += __shfl_xor(d1, 2);
;       d0 += __shfl_xor(d0, 4); d1 += __shfl_xor(d1, 4);
;       d0 += __shfl_xor(d0, 8); d1 += __shfl_xor(d1, 8);
;       const int s0 = st * 8 + g, s1 = s0 + 4;
;       d0 *= su[s0]; d1 *= su[s1];
;       const float a0 = 0.5f * d0 * (1.f + erff(d0 * 0.70710678118f));
;       const float a1 = 0.5f * d1 * (1.f + erff(d1 * 0.70710678118f));
;       if (l16 == 0) { COEF[(size_t)m * 128 + s0] = sg[s0] * a0; COEF[(size_t)m * 128 + s1] = sg[s1] * a1; }
.Lu_nx_ok:
	s_mul_i32 s29, s22, 0x2200
	s_lshl_b32 s40, s28, 8
	s_add_u32 s29, s29, s40
	s_lshl_b32 s40, s28, 21
	s_add_u32 s38, s14, s40
	s_addc_u32 s39, s15, 0
	s_lshl_b32 s32, s22, 9
	s_sub_u32 s37, s37, 1
	s_cmp_lg_u32 s37, 0
	s_cbranch_scc1 .Lu_loop
	s_waitcnt vmcnt(0) lgkmcnt(0)
	s_add_u32 s40, s9, 0
	s_lshl_b32 s40, s40, 9
	v_add_u32_e32 v100, s40, v165
	global_load_dword v2, v100, s[16:17] offset:0
	global_load_dword v3, v100, s[16:17] offset:256
	v_add_u32_e32 v173, 0x840000, v100
	global_load_dword v4, v173, s[16:17] offset:0
	global_load_dword v5, v173, s[16:17] offset:256
	ds_read_b32 v6, v161 offset:0
	ds_read_b32 v7, v161 offset:256
	s_add_u32 s40, s9, 4
	s_lshl_b32 s40, s40, 9
	v_add_u32_e32 v101, s40, v165
	global_load_dword v8, v101, s[16:17] offset:0
	global_load_dword v9, v101, s[16:17] offset:256
	v_add_u32_e32 v173, 0x840000, v101
	global_load_dword v10, v173, s[16:17] offset:0
	global_load_dword v11, v173, s[16:17] offset:256
	ds_read_b32 v12, v161 offset:512
	ds_read_b32 v13, v161 offset:768
	s_add_u32 s40, s9, 8
	s_lshl_b32 s40, s40, 9
	v_add_u32_e32 v102, s40, v165
	global_load_dword v14, v102, s[16:17] offset:0
	global_load_dword v15, v102, s[16:17] offset:256
	v_add_u32_e32 v173, 0x840000, v102
	global_load_dword v16, v173, s[16:17] offset:0
	global_load_dword v17, v173, s[16:17] offset:256
	ds_read_b32 v18, v161 offset:1024
	ds_read_b32 v19, v161 offset:1280
	s_add_u32 s40, s9, 12
	s_lshl_b32 s40, s40, 9
	v_add_u32_e32 v103, s40, v165
	global_load_dword v20, v103, s[16:17] offset:0
	global_load_dword v21, v103, s[16:17] offset:256
	v_add_u32_e32 v173, 0x840000, v103
	global_load_dword v22, v173, s[16:17] offset:0
	global_load_dword v23, v173, s[16:17] offset:256
	ds_read_b32 v24, v161 offset:1536
	ds_read_b32 v25, v161 offset:1792
	s_add_u32 s40, s9, 16
	s_lshl_b32 s40, s40, 9
	v_add_u32_e32 v104, s40, v165
	global_load_dword v26, v104, s[16:17] offset:0
	global_load_dword v27, v104, s[16:17] offset:256
	v_add_u32_e32 v173, 0x840000, v104
	global_load_dword v28, v173, s[16:17] offset:0
	global_load_dword v29, v173, s[16:17] offset:256
	ds_read_b32 v30, v161 offset:2048
	ds_read_b32 v31, v161 offset:2304
	s_add_u32 s40, s9, 20
	s_lshl_b32 s40, s40, 9
	v_add_u32_e32 v105, s40, v165
	global_load_dword v32, v105, s[16:17] offset:0
	global_load_dword v33, v105, s[16:17] offset:256
	v_add_u32_e32 v173, 0x840000, v105
	global_load_dword v34, v173, s[16:17] offset:0
	global_load_dword v35, v173, s[16:17] offset:256
	ds_read_b32 v36, v161 offset:2560
	ds_read_b32 v37, v161 offset:2816
	s_add_u32 s40, s9, 24
	s_lshl_b32 s40, s40, 9
	v_add_u32_e32 v106, s40, v165
	global_load_dword v38, v106, s[16:17] offset:0
	global_load_dword v39, v106, s[16:17] offset:256
	v_add_u32_e32 v173, 0x840000, v106
	global_load_dword v40, v173, s[16:17] offset:0
	global_load_dword v41, v173, s[16:17] offset:256
	ds_read_b32 v42, v161 offset:3072
	ds_read_b32 v43, v161 offset:3328
	s_add_u32 s40, s9, 28
	s_lshl_b32 s40, s40, 9
	v_add_u32_e32 v107, s40, v165
	global_load_dword v44, v107, s[16:17] offset:0
	global_load_dword v45, v107, s[16:17] offset:256
	v_add_u32_e32 v173, 0x840000, v107
	global_load_dword v46, v173, s[16:17] offset:0
	global_load_dword v47, v173, s[16:17] offset:256
	ds_read_b32 v48, v161 offset:3584
	ds_read_b32 v49, v161 offset:3840
	s_add_u32 s40, s9, 32
	s_lshl_b32 s40, s40, 9
	v_add_u32_e32 v108, s40, v165
	global_load_dword v50, v108, s[16:17] offset:0
	global_load_dword v51, v108, s[16:17] offset:256
	v_add_u32_e32 v173, 0x840000, v108
	global_load_dword v52, v173, s[16:17] offset:0
	global_load_dword v53, v173, s[16:17] offset:256
	ds_read_b32 v54, v161 offset:4096
	ds_read_b32 v55, v161 offset:4352
	s_waitcnt vmcnt(32) lgkmcnt(0)
	v_mul_f32_e32 v6, v6, v4
	v_mul_f32_e32 v7, v7, v5
	v_mul_f32_e32 v110, 0x3f3504f3, v6
	v_fma_f32 v111, |v110|, s33, v222
	v_fma_f32 v111, |v110|, v111, s26
	v_fma_f32 v111, |v110|, v111, s27
	v_fma_f32 v111, |v110|, v111, s4
	v_fma_f32 v111, |v110|, v111, s5
	v_fma_f32 v111, |v110|, v111, s96
	v_fma_f32 v111, |v110|, v111, |v110|
	v_mul_f32_e32 v112, 0xbfb8aa3b, v111
	v_fma_f32 v113, v111, s97, -v112
	v_rndne_f32_e32 v114, v112
	v_fmac_f32_e32 v113, 0xb2a5705f, v111
	v_sub_f32_e32 v112, v112, v114
	v_add_f32_e32 v112, v112, v113
	v_cvt_i32_f32_e32 v113, v114
	v_exp_f32_e32 v112, v112
	v_cmp_nlt_f32_e32 vcc, s24, v111
	v_ldexp_f32 v112, v112, v113
	s_nop 0
	v_cndmask_b32_e32 v112, 0, v112, vcc
	v_cmp_ngt_f32_e32 vcc, s25, v111
	s_nop 1
	v_cndmask_b32_e32 v111, v223, v112, vcc
	v_sub_f32_e32 v111, 1.0, v111
	v_mul_f32_e32 v114, v110, v110
	v_fmamk_f32 v115, v114, 0xba1345e1, v196
	v_fmaak_f32 v115, v114, v115, 0xbcdac9b8
	v_fmaak_f32 v115, v114, v115, 0x3de703be
	v_fmaak_f32 v115, v114, v115, 0xbec09330
	v_fmaak_f32 v115, v114, v115, 0x3e0375d0
	v_fma_f32 v115, |v110|, v115, |v110|
	v_cmp_nlt_f32_e64 vcc, |v110|, 1.0
	s_nop 1
	v_cndmask_b32_e32 v111, v115, v111, vcc
	v_bfi_b32 v111, s50, v111, v110
	v_add_f32_e32 v111, 1.0, v111
	v_mul_f32_e32 v112, 0.5, v6
	v_mul_f32_e32 v111, v112, v111
	v_mul_f32_e32 v116, v111, v2
	v_mul_f32_e32 v110, 0x3f3504f3, v7
	v_fma_f32 v111, |v110|, s33, v222
	v_fma_f32 v111, |v110|, v111, s26
	v_fma_f32 v111, |v110|, v111, s27
	v_fma_f32 v111, |v110|, v111, s4
	v_fma_f32 v111, |v110|, v111, s5
	v_fma_f32 v111, |v110|, v111, s96
	v_fma_f32 v111, |v110|, v111, |v110|
	v_mul_f32_e32 v112, 0xbfb8aa3b, v111
	v_fma_f32 v113, v111, s97, -v112
	v_rndne_f32_e32 v114, v112
	v_fmac_f32_e32 v113, 0xb2a5705f, v111
	v_sub_f32_e32 v112, v112, v114
	v_add_f32_e32 v112, v112, v113
	v_cvt_i32_f32_e32 v113, v114
	v_exp_f32_e32 v112, v112
	v_cmp_nlt_f32_e32 vcc, s24, v111
	v_ldexp_f32 v112, v112, v113
	s_nop 0
	v_cndmask_b32_e32 v112, 0, v112, vcc
	v_cmp_ngt_f32_e32 vcc, s25, v111
	s_nop 1
	v_cndmask_b32_e32 v111, v223, v112, vcc
	v_sub_f32_e32 v111, 1.0, v111
	v_mul_f32_e32 v114, v110, v110
	v_fmamk_f32 v115, v114, 0xba1345e1, v196
	v_fmaak_f32 v115, v114, v115, 0xbcdac9b8
	v_fmaak_f32 v115, v114, v115, 0x3de703be
	v_fmaak_f32 v115, v114, v115, 0xbec09330
	v_fmaak_f32 v115, v114, v115, 0x3e0375d0
	v_fma_f32 v115, |v110|, v115, |v110|
	v_cmp_nlt_f32_e64 vcc, |v110|, 1.0
	s_nop 1
	v_cndmask_b32_e32 v111, v115, v111, vcc
	v_bfi_b32 v111, s50, v111, v110
	v_add_f32_e32 v111, 1.0, v111
	v_mul_f32_e32 v112, 0.5, v7
	v_mul_f32_e32 v111, v112, v111
	v_mul_f32_e32 v117, v111, v3
	global_store_dword v100, v116, s[2:3]
	global_store_dword v100, v117, s[2:3] offset:256
	s_waitcnt vmcnt(30) lgkmcnt(0)
; DEV void phase_peer_expert(const Params& p, int layer, int M, bool final_, int part, char* smem) {
;     ...
;       d0 *= su[s0]; d1 *= su[s1];
;       const float a0 = 0.5f * d0 * (1.f + erff(d0 * 0.70710678118f));
;       const float a1 = 0.5f * d1 * (1.f + erff(d1 * 0.70710678118f));
;       if (l16 == 0) { COEF[(size_t)m * 128 + s0] = sg[s0] * a0; COEF[(size_t)m * 128 + s1] = sg[s1] * a1; }
	v_mul_f32_e32 v12, v12, v10
	v_mul_f32_e32 v13, v13, v11
	v_mul_f32_e32 v110, 0x3f3504f3, v12
	v_fma_f32 v111, |v110|, s33, v222
	v_fma_f32 v111, |v110|, v111, s26
	v_fma_f32 v111, |v110|, v111, s27
	v_fma_f32 v111, |v110|, v111, s4
	v_fma_f32 v111, |v110|, v111, s5
	v_fma_f32 v111, |v110|, v111, s96
	v_fma_f32 v111, |v110|, v111, |v110|
	v_mul_f32_e32 v112, 0xbfb8aa3b, v111
	v_fma_f32 v113, v111, s97, -v112
	v_rndne_f32_e32 v114, v112
	v_fmac_f32_e32 v113, 0xb2a5705f, v111
	v_sub_f32_e32 v112, v112, v114
	v_add_f32_e32 v112, v112, v113
	v_cvt_i32_f32_e32 v113, v114
	v_exp_f32_e32 v112, v112
	v_cmp_nlt_f32_e32 vcc, s24, v111
	v_ldexp_f32 v112, v112, v113
	s_nop 0
	v_cndmask_b32_e32 v112, 0, v112, vcc
	v_cmp_ngt_f32_e32 vcc, s25, v111
	s_nop 1
	v_cndmask_b32_e32 v111, v223, v112, vcc
	v_sub_f32_e32 v111, 1.0, v111
	v_mul_f32_e32 v114, v110, v110
	v_fmamk_f32 v115, v114, 0xba1345e1, v196
	v_fmaak_f32 v115, v114, v115, 0xbcdac9b8
	v_fmaak_f32 v115, v114, v115, 0x3de703be
	v_fmaak_f32 v115, v114, v115, 0xbec09330
	v_fmaak_f32 v115, v114, v115, 0x3e0375d0
	v_fma_f32 v115, |v110|, v115, |v110|
	v_cmp_nlt_f32_e64 vcc, |v110|, 1.0
	s_nop 1
	v_cndmask_b32_e32 v111, v115, v111, vcc
	v_bfi_b32 v111, s50, v111, v110
	v_add_f32_e32 v111, 1.0, v111
	v_mul_f32_e32 v112, 0.5, v12
	v_mul_f32_e32 v111, v112, v111
	v_mul_f32_e32 v116, v111, v8
	v_mul_f32_e32 v110, 0x3f3504f3, v13
	v_fma_f32 v111, |v110|, s33, v222
	v_fma_f32 v111, |v110|, v111, s26
	v_fma_f32 v111, |v110|, v111, s27
	v_fma_f32 v111, |v110|, v111, s4
	v_fma_f32 v111, |v110|, v111, s5
	v_fma_f32 v111, |v110|, v111, s96
	v_fma_f32 v111, |v110|, v111, |v110|
	v_mul_f32_e32 v112, 0xbfb8aa3b, v111
	v_fma_f32 v113, v111, s97, -v112
	v_rndne_f32_e32 v114, v112
	v_fmac_f32_e32 v113, 0xb2a5705f, v111
	v_sub_f32_e32 v112, v112, v114
	v_add_f32_e32 v112, v112, v113
	v_cvt_i32_f32_e32 v113, v114
	v_exp_f32_e32 v112, v112
	v_cmp_nlt_f32_e32 vcc, s24, v111
	v_ldexp_f32 v112, v112, v113
	s_nop 0
	v_cndmask_b32_e32 v112, 0, v112, vcc
	v_cmp_ngt_f32_e32 vcc, s25, v111
	s_nop 1
	v_cndmask_b32_e32 v111, v223, v112, vcc
	v_sub_f32_e32 v111, 1.0, v111
	v_mul_f32_e32 v114, v110, v110
	v_fmamk_f32 v115, v114, 0xba1345e1, v196
	v_fmaak_f32 v115, v114, v115, 0xbcdac9b8
	v_fmaak_f32 v115, v114, v115, 0x3de703be
	v_fmaak_f32 v115, v114, v115, 0xbec09330
	v_fmaak_f32 v115, v114, v115, 0x3e0375d0
	v_fma_f32 v115, |v110|, v115, |v110|
	v_cmp_nlt_f32_e64 vcc, |v110|, 1.0
	s_nop 1
	v_cndmask_b32_e32 v111, v115, v111, vcc
	v_bfi_b32 v111, s50, v111, v110
	v_add_f32_e32 v111, 1.0, v111
	v_mul_f32_e32 v112, 0.5, v13
	v_mul_f32_e32 v111, v112, v111
	v_mul_f32_e32 v117, v111, v9
	global_store_dword v101, v116, s[2:3]
	global_store_dword v101, v117, s[2:3] offset:256
	s_waitcnt vmcnt(28) lgkmcnt(0)
	v_mul_f32_e32 v18, v18, v16
	v_mul_f32_e32 v19, v19, v17
	v_mul_f32_e32 v110, 0x3f3504f3, v18
	v_fma_f32 v111, |v110|, s33, v222
	v_fma_f32 v111, |v110|, v111, s26
	v_fma_f32 v111, |v110|, v111, s27
	v_fma_f32 v111, |v110|, v111, s4
	v_fma_f32 v111, |v110|, v111, s5
	v_fma_f32 v111, |v110|, v111, s96
	v_fma_f32 v111, |v110|, v111, |v110|
	v_mul_f32_e32 v112, 0xbfb8aa3b, v111
	v_fma_f32 v113, v111, s97, -v112
	v_rndne_f32_e32 v114, v112
	v_fmac_f32_e32 v113, 0xb2a5705f, v111
	v_sub_f32_e32 v112, v112, v114
	v_add_f32_e32 v112, v112, v113
	v_cvt_i32_f32_e32 v113, v114
	v_exp_f32_e32 v112, v112
	v_cmp_nlt_f32_e32 vcc, s24, v111
	v_ldexp_f32 v112, v112, v113
	s_nop 0
	v_cndmask_b32_e32 v112, 0, v112, vcc
	v_cmp_ngt_f32_e32 vcc, s25, v111
	s_nop 1
	v_cndmask_b32_e32 v111, v223, v112, vcc
	v_sub_f32_e32 v111, 1.0, v111
	v_mul_f32_e32 v114, v110, v110
	v_fmamk_f32 v115, v114, 0xba1345e1, v196
	v_fmaak_f32 v115, v114, v115, 0xbcdac9b8
	v_fmaak_f32 v115, v114, v115, 0x3de703be
	v_fmaak_f32 v115, v114, v115, 0xbec09330
	v_fmaak_f32 v115, v114, v115, 0x3e0375d0
	v_fma_f32 v115, |v110|, v115, |v110|
	v_cmp_nlt_f32_e64 vcc, |v110|, 1.0
	s_nop 1
	v_cndmask_b32_e32 v111, v115, v111, vcc
	v_bfi_b32 v111, s50, v111, v110
	v_add_f32_e32 v111, 1.0, v111
	v_mul_f32_e32 v112, 0.5, v18
	v_mul_f32_e32 v111, v112, v111
	v_mul_f32_e32 v116, v111, v14
	v_mul_f32_e32 v110, 0x3f3504f3, v19
	v_fma_f32 v111, |v110|, s33, v222
	v_fma_f32 v111, |v110|, v111, s26
	v_fma_f32 v111, |v110|, v111, s27
	v_fma_f32 v111, |v110|, v111, s4
	v_fma_f32 v111, |v110|, v111, s5
	v_fma_f32 v111, |v110|, v111, s96
	v_fma_f32 v111, |v110|, v111, |v110|
	v_mul_f32_e32 v112, 0xbfb8aa3b, v111
	v_fma_f32 v113, v111, s97, -v112
	v_rndne_f32_e32 v114, v112
	v_fmac_f32_e32 v113, 0xb2a5705f, v111
	v_sub_f32_e32 v112, v112, v114
	v_add_f32_e32 v112, v112, v113
	v_cvt_i32_f32_e32 v113, v114
	v_exp_f32_e32 v112, v112
	v_cmp_nlt_f32_e32 vcc, s24, v111
	v_ldexp_f32 v112, v112, v113
	s_nop 0
	v_cndmask_b32_e32 v112, 0, v112, vcc
	v_cmp_ngt_f32_e32 vcc, s25, v111
	s_nop 1
	v_cndmask_b32_e32 v111, v223, v112, vcc
	v_sub_f32_e32 v111, 1.0, v111
	v_mul_f32_e32 v114, v110, v110
	v_fmamk_f32 v115, v114, 0xba1345e1, v196
	v_fmaak_f32 v115, v114, v115, 0xbcdac9b8
	v_fmaak_f32 v115, v114, v115, 0x3de703be
	v_fmaak_f32 v115, v114, v115, 0xbec09330
	v_fmaak_f32 v115, v114, v115, 0x3e0375d0
	v_fma_f32 v115, |v110|, v115, |v110|
	v_cmp_nlt_f32_e64 vcc, |v110|, 1.0
	s_nop 1
	v_cndmask_b32_e32 v111, v115, v111, vcc
	v_bfi_b32 v111, s50, v111, v110
	v_add_f32_e32 v111, 1.0, v111
	v_mul_f32_e32 v112, 0.5, v19
	v_mul_f32_e32 v111, v112, v111
	v_mul_f32_e32 v117, v111, v15
	global_store_dword v102, v116, s[2:3]
	global_store_dword v102, v117, s[2:3] offset:256
	s_waitcnt vmcnt(26) lgkmcnt(0)
; DEV void phase_peer_expert(const Params& p, int layer, int M, bool final_, int part, char* smem) {
;     ...
;       d0 *= su[s0]; d1 *= su[s1];
;       const float a0 = 0.5f * d0 * (1.f + erff(d0 * 0.70710678118f));
;       const float a1 = 0.5f * d1 * (1.f + erff(d1 * 0.70710678118f));
;       if (l16 == 0) { COEF[(size_t)m * 128 + s0] = sg[s0] * a0; COEF[(size_t)m * 128 + s1] = sg[s1] * a1; }
	v_mul_f32_e32 v24, v24, v22
	v_mul_f32_e32 v25, v25, v23
	v_mul_f32_e32 v110, 0x3f3504f3, v24
	v_fma_f32 v111, |v110|, s33, v222
	v_fma_f32 v111, |v110|, v111, s26
	v_fma_f32 v111, |v110|, v111, s27
	v_fma_f32 v111, |v110|, v111, s4
	v_fma_f32 v111, |v110|, v111, s5
	v_fma_f32 v111, |v110|, v111, s96
	v_fma_f32 v111, |v110|, v111, |v110|
	v_mul_f32_e32 v112, 0xbfb8aa3b, v111
	v_fma_f32 v113, v111, s97, -v112
	v_rndne_f32_e32 v114, v112
	v_fmac_f32_e32 v113, 0xb2a5705f, v111
	v_sub_f32_e32 v112, v112, v114
	v_add_f32_e32 v112, v112, v113
	v_cvt_i32_f32_e32 v113, v114
	v_exp_f32_e32 v112, v112
	v_cmp_nlt_f32_e32 vcc, s24, v111
	v_ldexp_f32 v112, v112, v113
	s_nop 0
	v_cndmask_b32_e32 v112, 0, v112, vcc
	v_cmp_ngt_f32_e32 vcc, s25, v111
	s_nop 1
	v_cndmask_b32_e32 v111, v223, v112, vcc
	v_sub_f32_e32 v111, 1.0, v111
	v_mul_f32_e32 v114, v110, v110
	v_fmamk_f32 v115, v114, 0xba1345e1, v196
	v_fmaak_f32 v115, v114, v115, 0xbcdac9b8
	v_fmaak_f32 v115, v114, v115, 0x3de703be
	v_fmaak_f32 v115, v114, v115, 0xbec09330
	v_fmaak_f32 v115, v114, v115, 0x3e0375d0
	v_fma_f32 v115, |v110|, v115, |v110|
	v_cmp_nlt_f32_e64 vcc, |v110|, 1.0
	s_nop 1
	v_cndmask_b32_e32 v111, v115, v111, vcc
	v_bfi_b32 v111, s50, v111, v110
	v_add_f32_e32 v111, 1.0, v111
	v_mul_f32_e32 v112, 0.5, v24
	v_mul_f32_e32 v111, v112, v111
	v_mul_f32_e32 v116, v111, v20
	v_mul_f32_e32 v110, 0x3f3504f3, v25
	v_fma_f32 v111, |v110|, s33, v222
	v_fma_f32 v111, |v110|, v111, s26
	v_fma_f32 v111, |v110|, v111, s27
	v_fma_f32 v111, |v110|, v111, s4
	v_fma_f32 v111, |v110|, v111, s5
	v_fma_f32 v111, |v110|, v111, s96
	v_fma_f32 v111, |v110|, v111, |v110|
	v_mul_f32_e32 v112, 0xbfb8aa3b, v111
	v_fma_f32 v113, v111, s97, -v112
	v_rndne_f32_e32 v114, v112
	v_fmac_f32_e32 v113, 0xb2a5705f, v111
	v_sub_f32_e32 v112, v112, v114
	v_add_f32_e32 v112, v112, v113
	v_cvt_i32_f32_e32 v113, v114
	v_exp_f32_e32 v112, v112
	v_cmp_nlt_f32_e32 vcc, s24, v111
	v_ldexp_f32 v112, v112, v113
	s_nop 0
	v_cndmask_b32_e32 v112, 0, v112, vcc
	v_cmp_ngt_f32_e32 vcc, s25, v111
	s_nop 1
	v_cndmask_b32_e32 v111, v223, v112, vcc
	v_sub_f32_e32 v111, 1.0, v111
	v_mul_f32_e32 v114, v110, v110
	v_fmamk_f32 v115, v114, 0xba1345e1, v196
	v_fmaak_f32 v115, v114, v115, 0xbcdac9b8
	v_fmaak_f32 v115, v114, v115, 0x3de703be
	v_fmaak_f32 v115, v114, v115, 0xbec09330
	v_fmaak_f32 v115, v114, v115, 0x3e0375d0
	v_fma_f32 v115, |v110|, v115, |v110|
	v_cmp_nlt_f32_e64 vcc, |v110|, 1.0
	s_nop 1
	v_cndmask_b32_e32 v111, v115, v111, vcc
	v_bfi_b32 v111, s50, v111, v110
	v_add_f32_e32 v111, 1.0, v111
	v_mul_f32_e32 v112, 0.5, v25
	v_mul_f32_e32 v111, v112, v111
	v_mul_f32_e32 v117, v111, v21
	global_store_dword v103, v116, s[2:3]
	global_store_dword v103, v117, s[2:3] offset:256
	s_waitcnt vmcnt(24) lgkmcnt(0)
	v_mul_f32_e32 v30, v30, v28
	v_mul_f32_e32 v31, v31, v29
	v_mul_f32_e32 v110, 0x3f3504f3, v30
	v_fma_f32 v111, |v110|, s33, v222
	v_fma_f32 v111, |v110|, v111, s26
	v_fma_f32 v111, |v110|, v111, s27
	v_fma_f32 v111, |v110|, v111, s4
	v_fma_f32 v111, |v110|, v111, s5
	v_fma_f32 v111, |v110|, v111, s96
	v_fma_f32 v111, |v110|, v111, |v110|
	v_mul_f32_e32 v112, 0xbfb8aa3b, v111
	v_fma_f32 v113, v111, s97, -v112
	v_rndne_f32_e32 v114, v112
	v_fmac_f32_e32 v113, 0xb2a5705f, v111
	v_sub_f32_e32 v112, v112, v114
	v_add_f32_e32 v112, v112, v113
	v_cvt_i32_f32_e32 v113, v114
	v_exp_f32_e32 v112, v112
	v_cmp_nlt_f32_e32 vcc, s24, v111
	v_ldexp_f32 v112, v112, v113
	s_nop 0
	v_cndmask_b32_e32 v112, 0, v112, vcc
	v_cmp_ngt_f32_e32 vcc, s25, v111
	s_nop 1
	v_cndmask_b32_e32 v111, v223, v112, vcc
	v_sub_f32_e32 v111, 1.0, v111
	v_mul_f32_e32 v114, v110, v110
	v_fmamk_f32 v115, v114, 0xba1345e1, v196
	v_fmaak_f32 v115, v114, v115, 0xbcdac9b8
	v_fmaak_f32 v115, v114, v115, 0x3de703be
	v_fmaak_f32 v115, v114, v115, 0xbec09330
	v_fmaak_f32 v115, v114, v115, 0x3e0375d0
	v_fma_f32 v115, |v110|, v115, |v110|
	v_cmp_nlt_f32_e64 vcc, |v110|, 1.0
	s_nop 1
	v_cndmask_b32_e32 v111, v115, v111, vcc
	v_bfi_b32 v111, s50, v111, v110
	v_add_f32_e32 v111, 1.0, v111
	v_mul_f32_e32 v112, 0.5, v30
	v_mul_f32_e32 v111, v112, v111
	v_mul_f32_e32 v116, v111, v26
	v_mul_f32_e32 v110, 0x3f3504f3, v31
	v_fma_f32 v111, |v110|, s33, v222
	v_fma_f32 v111, |v110|, v111, s26
	v_fma_f32 v111, |v110|, v111, s27
	v_fma_f32 v111, |v110|, v111, s4
	v_fma_f32 v111, |v110|, v111, s5
	v_fma_f32 v111, |v110|, v111, s96
	v_fma_f32 v111, |v110|, v111, |v110|
	v_mul_f32_e32 v112, 0xbfb8aa3b, v111
	v_fma_f32 v113, v111, s97, -v112
	v_rndne_f32_e32 v114, v112
	v_fmac_f32_e32 v113, 0xb2a5705f, v111
	v_sub_f32_e32 v112, v112, v114
	v_add_f32_e32 v112, v112, v113
	v_cvt_i32_f32_e32 v113, v114
	v_exp_f32_e32 v112, v112
	v_cmp_nlt_f32_e32 vcc, s24, v111
	v_ldexp_f32 v112, v112, v113
	s_nop 0
	v_cndmask_b32_e32 v112, 0, v112, vcc
	v_cmp_ngt_f32_e32 vcc, s25, v111
	s_nop 1
	v_cndmask_b32_e32 v111, v223, v112, vcc
	v_sub_f32_e32 v111, 1.0, v111
	v_mul_f32_e32 v114, v110, v110
	v_fmamk_f32 v115, v114, 0xba1345e1, v196
	v_fmaak_f32 v115, v114, v115, 0xbcdac9b8
	v_fmaak_f32 v115, v114, v115, 0x3de703be
	v_fmaak_f32 v115, v114, v115, 0xbec09330
	v_fmaak_f32 v115, v114, v115, 0x3e0375d0
	v_fma_f32 v115, |v110|, v115, |v110|
	v_cmp_nlt_f32_e64 vcc, |v110|, 1.0
	s_nop 1
	v_cndmask_b32_e32 v111, v115, v111, vcc
	v_bfi_b32 v111, s50, v111, v110
	v_add_f32_e32 v111, 1.0, v111
	v_mul_f32_e32 v112, 0.5, v31
	v_mul_f32_e32 v111, v112, v111
	v_mul_f32_e32 v117, v111, v27
	global_store_dword v104, v116, s[2:3]
	global_store_dword v104, v117, s[2:3] offset:256
	s_waitcnt vmcnt(22) lgkmcnt(0)
; DEV void phase_peer_expert(const Params& p, int layer, int M, bool final_, int part, char* smem) {
;     ...
;       const int s0 = st * 8 + g, s1 = s0 + 4;
;       d0 *= su[s0]; d1 *= su[s1];
;       const float a0 = 0.5f * d0 * (1.f + erff(d0 * 0.70710678118f));
;       const float a1 = 0.5f * d1 * (1.f + erff(d1 * 0.70710678118f));
;       if (l16 == 0) { COEF[(size_t)m * 128 + s0] = sg[s0] * a0; COEF[(size_t)m * 128 + s1] = sg[s1] * a1; }
	v_mul_f32_e32 v36, v36, v34
	v_mul_f32_e32 v37, v37, v35
	v_mul_f32_e32 v110, 0x3f3504f3, v36
	v_fma_f32 v111, |v110|, s33, v222
	v_fma_f32 v111, |v110|, v111, s26
	v_fma_f32 v111, |v110|, v111, s27
	v_fma_f32 v111, |v110|, v111, s4
	v_fma_f32 v111, |v110|, v111, s5
	v_fma_f32 v111, |v110|, v111, s96
	v_fma_f32 v111, |v110|, v111, |v110|
	v_mul_f32_e32 v112, 0xbfb8aa3b, v111
	v_fma_f32 v113, v111, s97, -v112
	v_rndne_f32_e32 v114, v112
	v_fmac_f32_e32 v113, 0xb2a5705f, v111
	v_sub_f32_e32 v112, v112, v114
	v_add_f32_e32 v112, v112, v113
	v_cvt_i32_f32_e32 v113, v114
	v_exp_f32_e32 v112, v112
	v_cmp_nlt_f32_e32 vcc, s24, v111
	v_ldexp_f32 v112, v112, v113
	s_nop 0
	v_cndmask_b32_e32 v112, 0, v112, vcc
	v_cmp_ngt_f32_e32 vcc, s25, v111
	s_nop 1
	v_cndmask_b32_e32 v111, v223, v112, vcc
	v_sub_f32_e32 v111, 1.0, v111
	v_mul_f32_e32 v114, v110, v110
	v_fmamk_f32 v115, v114, 0xba1345e1, v196
	v_fmaak_f32 v115, v114, v115, 0xbcdac9b8
	v_fmaak_f32 v115, v114, v115, 0x3de703be
	v_fmaak_f32 v115, v114, v115, 0xbec09330
	v_fmaak_f32 v115, v114, v115, 0x3e0375d0
	v_fma_f32 v115, |v110|, v115, |v110|
	v_cmp_nlt_f32_e64 vcc, |v110|, 1.0
	s_nop 1
	v_cndmask_b32_e32 v111, v115, v111, vcc
	v_bfi_b32 v111, s50, v111, v110
	v_add_f32_e32 v111, 1.0, v111
	v_mul_f32_e32 v112, 0.5, v36
	v_mul_f32_e32 v111, v112, v111
	v_mul_f32_e32 v116, v111, v32
	v_mul_f32_e32 v110, 0x3f3504f3, v37
	v_fma_f32 v111, |v110|, s33, v222
	v_fma_f32 v111, |v110|, v111, s26
	v_fma_f32 v111, |v110|, v111, s27
	v_fma_f32 v111, |v110|, v111, s4
	v_fma_f32 v111, |v110|, v111, s5
	v_fma_f32 v111, |v110|, v111, s96
	v_fma_f32 v111, |v110|, v111, |v110|
	v_mul_f32_e32 v112, 0xbfb8aa3b, v111
	v_fma_f32 v113, v111, s97, -v112
	v_rndne_f32_e32 v114, v112
	v_fmac_f32_e32 v113, 0xb2a5705f, v111
	v_sub_f32_e32 v112, v112, v114
	v_add_f32_e32 v112, v112, v113
	v_cvt_i32_f32_e32 v113, v114
	v_exp_f32_e32 v112, v112
	v_cmp_nlt_f32_e32 vcc, s24, v111
	v_ldexp_f32 v112, v112, v113
	s_nop 0
	v_cndmask_b32_e32 v112, 0, v112, vcc
	v_cmp_ngt_f32_e32 vcc, s25, v111
	s_nop 1
	v_cndmask_b32_e32 v111, v223, v112, vcc
	v_sub_f32_e32 v111, 1.0, v111
	v_mul_f32_e32 v114, v110, v110
	v_fmamk_f32 v115, v114, 0xba1345e1, v196
	v_fmaak_f32 v115, v114, v115, 0xbcdac9b8
	v_fmaak_f32 v115, v114, v115, 0x3de703be
	v_fmaak_f32 v115, v114, v115, 0xbec09330
	v_fmaak_f32 v115, v114, v115, 0x3e0375d0
	v_fma_f32 v115, |v110|, v115, |v110|
	v_cmp_nlt_f32_e64 vcc, |v110|, 1.0
	s_nop 1
	v_cndmask_b32_e32 v111, v115, v111, vcc
	v_bfi_b32 v111, s50, v111, v110
	v_add_f32_e32 v111, 1.0, v111
	v_mul_f32_e32 v112, 0.5, v37
	v_mul_f32_e32 v111, v112, v111
	v_mul_f32_e32 v117, v111, v33
	global_store_dword v105, v116, s[2:3]
	global_store_dword v105, v117, s[2:3] offset:256
	s_waitcnt vmcnt(20) lgkmcnt(0)
	v_mul_f32_e32 v42, v42, v40
	v_mul_f32_e32 v43, v43, v41
	v_mul_f32_e32 v110, 0x3f3504f3, v42
	v_fma_f32 v111, |v110|, s33, v222
	v_fma_f32 v111, |v110|, v111, s26
	v_fma_f32 v111, |v110|, v111, s27
	v_fma_f32 v111, |v110|, v111, s4
	v_fma_f32 v111, |v110|, v111, s5
	v_fma_f32 v111, |v110|, v111, s96
	v_fma_f32 v111, |v110|, v111, |v110|
	v_mul_f32_e32 v112, 0xbfb8aa3b, v111
	v_fma_f32 v113, v111, s97, -v112
	v_rndne_f32_e32 v114, v112
	v_fmac_f32_e32 v113, 0xb2a5705f, v111
	v_sub_f32_e32 v112, v112, v114
	v_add_f32_e32 v112, v112, v113
	v_cvt_i32_f32_e32 v113, v114
	v_exp_f32_e32 v112, v112
	v_cmp_nlt_f32_e32 vcc, s24, v111
	v_ldexp_f32 v112, v112, v113
	s_nop 0
	v_cndmask_b32_e32 v112, 0, v112, vcc
	v_cmp_ngt_f32_e32 vcc, s25, v111
	s_nop 1
	v_cndmask_b32_e32 v111, v223, v112, vcc
	v_sub_f32_e32 v111, 1.0, v111
	v_mul_f32_e32 v114, v110, v110
	v_fmamk_f32 v115, v114, 0xba1345e1, v196
	v_fmaak_f32 v115, v114, v115, 0xbcdac9b8
	v_fmaak_f32 v115, v114, v115, 0x3de703be
	v_fmaak_f32 v115, v114, v115, 0xbec09330
	v_fmaak_f32 v115, v114, v115, 0x3e0375d0
	v_fma_f32 v115, |v110|, v115, |v110|
	v_cmp_nlt_f32_e64 vcc, |v110|, 1.0
	s_nop 1
	v_cndmask_b32_e32 v111, v115, v111, vcc
	v_bfi_b32 v111, s50, v111, v110
	v_add_f32_e32 v111, 1.0, v111
	v_mul_f32_e32 v112, 0.5, v42
	v_mul_f32_e32 v111, v112, v111
	v_mul_f32_e32 v116, v111, v38
	v_mul_f32_e32 v110, 0x3f3504f3, v43
	v_fma_f32 v111, |v110|, s33, v222
	v_fma_f32 v111, |v110|, v111, s26
	v_fma_f32 v111, |v110|, v111, s27
	v_fma_f32 v111, |v110|, v111, s4
	v_fma_f32 v111, |v110|, v111, s5
	v_fma_f32 v111, |v110|, v111, s96
	v_fma_f32 v111, |v110|, v111, |v110|
	v_mul_f32_e32 v112, 0xbfb8aa3b, v111
	v_fma_f32 v113, v111, s97, -v112
	v_rndne_f32_e32 v114, v112
	v_fmac_f32_e32 v113, 0xb2a5705f, v111
	v_sub_f32_e32 v112, v112, v114
	v_add_f32_e32 v112, v112, v113
	v_cvt_i32_f32_e32 v113, v114
	v_exp_f32_e32 v112, v112
	v_cmp_nlt_f32_e32 vcc, s24, v111
	v_ldexp_f32 v112, v112, v113
	s_nop 0
	v_cndmask_b32_e32 v112, 0, v112, vcc
	v_cmp_ngt_f32_e32 vcc, s25, v111
	s_nop 1
	v_cndmask_b32_e32 v111, v223, v112, vcc
	v_sub_f32_e32 v111, 1.0, v111
	v_mul_f32_e32 v114, v110, v110
	v_fmamk_f32 v115, v114, 0xba1345e1, v196
	v_fmaak_f32 v115, v114, v115, 0xbcdac9b8
	v_fmaak_f32 v115, v114, v115, 0x3de703be
	v_fmaak_f32 v115, v114, v115, 0xbec09330
	v_fmaak_f32 v115, v114, v115, 0x3e0375d0
	v_fma_f32 v115, |v110|, v115, |v110|
	v_cmp_nlt_f32_e64 vcc, |v110|, 1.0
	s_nop 1
	v_cndmask_b32_e32 v111, v115, v111, vcc
	v_bfi_b32 v111, s50, v111, v110
	v_add_f32_e32 v111, 1.0, v111
	v_mul_f32_e32 v112, 0.5, v43
	v_mul_f32_e32 v111, v112, v111
	v_mul_f32_e32 v117, v111, v39
	global_store_dword v106, v116, s[2:3]
	global_store_dword v106, v117, s[2:3] offset:256
	s_waitcnt vmcnt(18) lgkmcnt(0)
; DEV void phase_peer_expert(const Params& p, int layer, int M, bool final_, int part, char* smem) {
;     ...
;       const int s0 = st * 8 + g, s1 = s0 + 4;
;       d0 *= su[s0]; d1 *= su[s1];
;       const float a0 = 0.5f * d0 * (1.f + erff(d0 * 0.70710678118f));
;       const float a1 = 0.5f * d1 * (1.f + erff(d1 * 0.70710678118f));
;       if (l16 == 0) { COEF[(size_t)m * 128 + s0] = sg[s0] * a0; COEF[(size_t)m * 128 + s1] = sg[s1] * a1; }
	v_mul_f32_e32 v48, v48, v46
	v_mul_f32_e32 v49, v49, v47
	v_mul_f32_e32 v110, 0x3f3504f3, v48
	v_fma_f32 v111, |v110|, s33, v222
	v_fma_f32 v111, |v110|, v111, s26
	v_fma_f32 v111, |v110|, v111, s27
	v_fma_f32 v111, |v110|, v111, s4
	v_fma_f32 v111, |v110|, v111, s5
	v_fma_f32 v111, |v110|, v111, s96
	v_fma_f32 v111, |v110|, v111, |v110|
	v_mul_f32_e32 v112, 0xbfb8aa3b, v111
	v_fma_f32 v113, v111, s97, -v112
	v_rndne_f32_e32 v114, v112
	v_fmac_f32_e32 v113, 0xb2a5705f, v111
	v_sub_f32_e32 v112, v112, v114
	v_add_f32_e32 v112, v112, v113
	v_cvt_i32_f32_e32 v113, v114
	v_exp_f32_e32 v112, v112
	v_cmp_nlt_f32_e32 vcc, s24, v111
	v_ldexp_f32 v112, v112, v113
	s_nop 0
	v_cndmask_b32_e32 v112, 0, v112, vcc
	v_cmp_ngt_f32_e32 vcc, s25, v111
	s_nop 1
	v_cndmask_b32_e32 v111, v223, v112, vcc
	v_sub_f32_e32 v111, 1.0, v111
	v_mul_f32_e32 v114, v110, v110
	v_fmamk_f32 v115, v114, 0xba1345e1, v196
	v_fmaak_f32 v115, v114, v115, 0xbcdac9b8
	v_fmaak_f32 v115, v114, v115, 0x3de703be
	v_fmaak_f32 v115, v114, v115, 0xbec09330
	v_fmaak_f32 v115, v114, v115, 0x3e0375d0
	v_fma_f32 v115, |v110|, v115, |v110|
	v_cmp_nlt_f32_e64 vcc, |v110|, 1.0
	s_nop 1
	v_cndmask_b32_e32 v111, v115, v111, vcc
	v_bfi_b32 v111, s50, v111, v110
	v_add_f32_e32 v111, 1.0, v111
	v_mul_f32_e32 v112, 0.5, v48
	v_mul_f32_e32 v111, v112, v111
	v_mul_f32_e32 v116, v111, v44
	v_mul_f32_e32 v110, 0x3f3504f3, v49
	v_fma_f32 v111, |v110|, s33, v222
	v_fma_f32 v111, |v110|, v111, s26
	v_fma_f32 v111, |v110|, v111, s27
	v_fma_f32 v111, |v110|, v111, s4
	v_fma_f32 v111, |v110|, v111, s5
	v_fma_f32 v111, |v110|, v111, s96
	v_fma_f32 v111, |v110|, v111, |v110|
	v_mul_f32_e32 v112, 0xbfb8aa3b, v111
	v_fma_f32 v113, v111, s97, -v112
	v_rndne_f32_e32 v114, v112
	v_fmac_f32_e32 v113, 0xb2a5705f, v111
	v_sub_f32_e32 v112, v112, v114
	v_add_f32_e32 v112, v112, v113
	v_cvt_i32_f32_e32 v113, v114
	v_exp_f32_e32 v112, v112
	v_cmp_nlt_f32_e32 vcc, s24, v111
	v_ldexp_f32 v112, v112, v113
	s_nop 0
	v_cndmask_b32_e32 v112, 0, v112, vcc
	v_cmp_ngt_f32_e32 vcc, s25, v111
	s_nop 1
	v_cndmask_b32_e32 v111, v223, v112, vcc
	v_sub_f32_e32 v111, 1.0, v111
	v_mul_f32_e32 v114, v110, v110
	v_fmamk_f32 v115, v114, 0xba1345e1, v196
	v_fmaak_f32 v115, v114, v115, 0xbcdac9b8
	v_fmaak_f32 v115, v114, v115, 0x3de703be
	v_fmaak_f32 v115, v114, v115, 0xbec09330
	v_fmaak_f32 v115, v114, v115, 0x3e0375d0
	v_fma_f32 v115, |v110|, v115, |v110|
	v_cmp_nlt_f32_e64 vcc, |v110|, 1.0
	s_nop 1
	v_cndmask_b32_e32 v111, v115, v111, vcc
	v_bfi_b32 v111, s50, v111, v110
	v_add_f32_e32 v111, 1.0, v111
	v_mul_f32_e32 v112, 0.5, v49
	v_mul_f32_e32 v111, v112, v111
	v_mul_f32_e32 v117, v111, v45
	global_store_dword v107, v116, s[2:3]
	global_store_dword v107, v117, s[2:3] offset:256
	s_cmp_lt_u32 s8, 9
	s_cbranch_scc1 .Lu_tail_done
	s_waitcnt vmcnt(16) lgkmcnt(0)
	v_mul_f32_e32 v54, v54, v52
	v_mul_f32_e32 v55, v55, v53
	v_mul_f32_e32 v110, 0x3f3504f3, v54
	v_fma_f32 v111, |v110|, s33, v222
	v_fma_f32 v111, |v110|, v111, s26
	v_fma_f32 v111, |v110|, v111, s27
	v_fma_f32 v111, |v110|, v111, s4
	v_fma_f32 v111, |v110|, v111, s5
	v_fma_f32 v111, |v110|, v111, s96
	v_fma_f32 v111, |v110|, v111, |v110|
	v_mul_f32_e32 v112, 0xbfb8aa3b, v111
	v_fma_f32 v113, v111, s97, -v112
	v_rndne_f32_e32 v114, v112
	v_fmac_f32_e32 v113, 0xb2a5705f, v111
	v_sub_f32_e32 v112, v112, v114
	v_add_f32_e32 v112, v112, v113
	v_cvt_i32_f32_e32 v113, v114
	v_exp_f32_e32 v112, v112
	v_cmp_nlt_f32_e32 vcc, s24, v111
	v_ldexp_f32 v112, v112, v113
	s_nop 0
	v_cndmask_b32_e32 v112, 0, v112, vcc
	v_cmp_ngt_f32_e32 vcc, s25, v111
	s_nop 1
	v_cndmask_b32_e32 v111, v223, v112, vcc
	v_sub_f32_e32 v111, 1.0, v111
	v_mul_f32_e32 v114, v110, v110
	v_fmamk_f32 v115, v114, 0xba1345e1, v196
	v_fmaak_f32 v115, v114, v115, 0xbcdac9b8
	v_fmaak_f32 v115, v114, v115, 0x3de703be
	v_fmaak_f32 v115, v114, v115, 0xbec09330
	v_fmaak_f32 v115, v114, v115, 0x3e0375d0
	v_fma_f32 v115, |v110|, v115, |v110|
	v_cmp_nlt_f32_e64 vcc, |v110|, 1.0
	s_nop 1
	v_cndmask_b32_e32 v111, v115, v111, vcc
	v_bfi_b32 v111, s50, v111, v110
	v_add_f32_e32 v111, 1.0, v111
	v_mul_f32_e32 v112, 0.5, v54
	v_mul_f32_e32 v111, v112, v111
	v_mul_f32_e32 v116, v111, v50
	v_mul_f32_e32 v110, 0x3f3504f3, v55
	v_fma_f32 v111, |v110|, s33, v222
	v_fma_f32 v111, |v110|, v111, s26
	v_fma_f32 v111, |v110|, v111, s27
	v_fma_f32 v111, |v110|, v111, s4
	v_fma_f32 v111, |v110|, v111, s5
	v_fma_f32 v111, |v110|, v111, s96
	v_fma_f32 v111, |v110|, v111, |v110|
	v_mul_f32_e32 v112, 0xbfb8aa3b, v111
	v_fma_f32 v113, v111, s97, -v112
	v_rndne_f32_e32 v114, v112
	v_fmac_f32_e32 v113, 0xb2a5705f, v111
	v_sub_f32_e32 v112, v112, v114
	v_add_f32_e32 v112, v112, v113
	v_cvt_i32_f32_e32 v113, v114
	v_exp_f32_e32 v112, v112
	v_cmp_nlt_f32_e32 vcc, s24, v111
	v_ldexp_f32 v112, v112, v113
	s_nop 0
	v_cndmask_b32_e32 v112, 0, v112, vcc
	v_cmp_ngt_f32_e32 vcc, s25, v111
	s_nop 1
	v_cndmask_b32_e32 v111, v223, v112, vcc
	v_sub_f32_e32 v111, 1.0, v111
	v_mul_f32_e32 v114, v110, v110
	v_fmamk_f32 v115, v114, 0xba1345e1, v196
	v_fmaak_f32 v115, v114, v115, 0xbcdac9b8
	v_fmaak_f32 v115, v114, v115, 0x3de703be
	v_fmaak_f32 v115, v114, v115, 0xbec09330
	v_fmaak_f32 v115, v114, v115, 0x3e0375d0
	v_fma_f32 v115, |v110|, v115, |v110|
	v_cmp_nlt_f32_e64 vcc, |v110|, 1.0
	s_nop 1
	v_cndmask_b32_e32 v111, v115, v111, vcc
	v_bfi_b32 v111, s50, v111, v110
	v_add_f32_e32 v111, 1.0, v111
	v_mul_f32_e32 v112, 0.5, v55
	v_mul_f32_e32 v111, v112, v111
	v_mul_f32_e32 v117, v111, v51
	global_store_dword v108, v116, s[2:3]
	global_store_dword v108, v117, s[2:3] offset:256
; DEV void phase_peer_expert(const Params& p, int layer, int M, bool final_, int part, char* smem) {
;     ...
;   for (int m = blockIdx.x * 4 + w; m < M; m += gridDim.x * 4) {
;     {
;       int2 e2 = *(const int2*)(EIDX + (size_t)m * 128 + lane * 2);
;       float2 c2 = *(const float2*)(COEF + (size_t)m * 128 + lane * 2);
;       *(int2*)(se + lane * 2) = e2; *(float2*)(coefs + lane * 2) = c2;
;     }
;     u32x4 cur[8], nxt[8];
;     __syncthreads();
;     f32x2 acc[32];
; #pragma unroll
;     for (int i = 0; i < 32; i++) acc[i] = (f32x2){0.f, 0.f};
;     {
;       const unsigned char* r0p = V + (size_t)se[g] * 1024 + l16 * 16;
;       const unsigned char* r1p = V + (size_t)se[4 + g] * 1024 + l16 * 16;
; #pragma unroll
;       for (int c = 0; c < 4; c++) { cur[c] = *(const u32x4*)(r0p + c * 256); cur[4 + c] = *(const u32x4*)(r1p + c * 256); }
;     }
.Lu_tail_done:
	s_branch .Lpeer_grid_barrier
.Lpeer_v:
	s_add_u32 s14, s0, s45
	s_addc_u32 s15, s1, 0
	s_add_u32 s16, s0, s52
	s_addc_u32 s17, s1, 0
	s_add_u32 s12, s0, s43
	s_addc_u32 s13, s1, 0
	v_add_u32_e32 v177, 0x4800, v167
	v_add_u32_e32 v159, 0, v166
	global_load_dwordx2 v[2:3], v159, s[12:13]
	v_add_u32_e32 v159, 2048, v166
	global_load_dwordx2 v[4:5], v159, s[12:13]
	v_add_u32_e32 v159, 4096, v166
	global_load_dwordx2 v[6:7], v159, s[12:13]
	v_add_u32_e32 v159, 6144, v166
	global_load_dwordx2 v[8:9], v159, s[12:13]
	v_add_u32_e32 v159, 8192, v166
	global_load_dwordx2 v[10:11], v159, s[12:13]
	v_add_u32_e32 v159, 10240, v166
	global_load_dwordx2 v[12:13], v159, s[12:13]
	v_add_u32_e32 v159, 12288, v166
	global_load_dwordx2 v[14:15], v159, s[12:13]
	v_add_u32_e32 v159, 14336, v166
	global_load_dwordx2 v[16:17], v159, s[12:13]
	v_add_u32_e32 v159, 16384, v166
	global_load_dwordx2 v[18:19], v159, s[12:13]
	s_waitcnt vmcnt(0)
	ds_write_b32 v177, v2 offset:0
	ds_write_b32 v177, v3 offset:64
	ds_write_b32 v177, v4 offset:512
	ds_write_b32 v177, v5 offset:576
	ds_write_b32 v177, v6 offset:1024
	ds_write_b32 v177, v7 offset:1088
	ds_write_b32 v177, v8 offset:1536
	ds_write_b32 v177, v9 offset:1600
	ds_write_b32 v177, v10 offset:2048
	ds_write_b32 v177, v11 offset:2112
	ds_write_b32 v177, v12 offset:2560
	ds_write_b32 v177, v13 offset:2624
	ds_write_b32 v177, v14 offset:3072
	ds_write_b32 v177, v15 offset:3136
	ds_write_b32 v177, v16 offset:3584
	ds_write_b32 v177, v17 offset:3648
	ds_write_b32 v177, v18 offset:4096
	ds_write_b32 v177, v19 offset:4160
	v_add_u32_e32 v172, 0x4800, v157
	s_lshl_b32 s40, s6, 12
	s_add_u32 s40, s40, 0x9000
	v_lshl_add_u32 v169, v164, 9, s40
	v_add_u32_e32 v169, v169, v156
	v_lshl_add_u32 v170, v162, 3, s40
	s_mul_i32 s40, s6, 0x900
	s_add_u32 s40, s40, 0xd000
	v_lshl_add_u32 v171, v162, 2, s40
	v_bfe_u32 v159, v162, 1, 3
	v_lshlrev_b32_e32 v159, 4, v159
	v_lshrrev_b32_e32 v160, 4, v162
	v_lshl_add_u32 v159, v160, 2, v159
	v_and_b32_e32 v160, 1, v162
	v_lshl_add_u32 v159, v160, 1, v159
	v_lshlrev_b32_e32 v168, 2, v159
	v_xor_b32_e32 v175, 16, v162
	v_lshlrev_b32_e32 v175, 2, v175
	v_xor_b32_e32 v176, 32, v162
	v_lshlrev_b32_e32 v176, 2, v176
	v_mov_b32_e32 v160, 0
	ds_write_b32 v171, v160 offset:0
	ds_write_b32 v171, v160 offset:256
	ds_write_b32 v171, v160 offset:512
	ds_write_b32 v171, v160 offset:768
	ds_write_b32 v171, v160 offset:1024
	ds_write_b32 v171, v160 offset:1280
	ds_write_b32 v171, v160 offset:1536
	ds_write_b32 v171, v160 offset:1792
	ds_write_b32 v171, v160 offset:2048
	s_waitcnt lgkmcnt(0)
	s_mov_b32 s18, 0
	s_mov_b32 s20, 0
	ds_read_b128 v[66:69], v157 offset:0
	ds_read_b128 v[70:73], v157 offset:16
	ds_read_b128 v[74:77], v157 offset:32
	ds_read_b128 v[78:81], v157 offset:48
	s_waitcnt lgkmcnt(0)
	v_add_u32_e32 v159, v66, v156
	global_load_dwordx4 v[2:5], v159, s[14:15]
	v_add_u32_e32 v159, v67, v156
	global_load_dwordx4 v[6:9], v159, s[14:15]
	v_add_u32_e32 v159, v68, v156
	global_load_dwordx4 v[10:13], v159, s[14:15]
	v_add_u32_e32 v159, v69, v156
	global_load_dwordx4 v[14:17], v159, s[14:15]
	v_add_u32_e32 v159, v70, v156
	global_load_dwordx4 v[18:21], v159, s[14:15]
	v_add_u32_e32 v159, v71, v156
	global_load_dwordx4 v[22:25], v159, s[14:15]
	v_add_u32_e32 v159, v72, v156
	global_load_dwordx4 v[26:29], v159, s[14:15]
	v_add_u32_e32 v159, v73, v156
	global_load_dwordx4 v[30:33], v159, s[14:15]
	v_add_u32_e32 v159, v74, v156
	global_load_dwordx4 v[34:37], v159, s[14:15]
	v_add_u32_e32 v159, v75, v156
	global_load_dwordx4 v[38:41], v159, s[14:15]
	v_add_u32_e32 v159, v76, v156
	global_load_dwordx4 v[42:45], v159, s[14:15]
	v_add_u32_e32 v159, v77, v156
	global_load_dwordx4 v[46:49], v159, s[14:15]
	v_add_u32_e32 v159, v78, v156
	global_load_dwordx4 v[50:53], v159, s[14:15]
	v_add_u32_e32 v159, v79, v156
	global_load_dwordx4 v[54:57], v159, s[14:15]
	v_add_u32_e32 v159, v80, v156
	global_load_dwordx4 v[58:61], v159, s[14:15]
	v_add_u32_e32 v159, v81, v156
	global_load_dwordx4 v[62:65], v159, s[14:15]
	global_load_dword v178, v168, s[0:1]
	s_lshl_b32 s40, s18, 2
	s_add_u32 s40, s40, s9
	s_lshr_b32 s42, s40, 13
	s_min_u32 s42, s42, 2
	s_mul_i32 s42, s42, 0x6000
	s_lshl_b32 s41, s40, 12
	s_lshl_b32 s43, s20, 9
	s_add_u32 s41, s41, s43
	s_add_u32 s42, s42, s43
	v_add_u32_e32 v173, s41, v168
	global_load_dwordx2 v[122:123], v173, s[0:1]
	v_add_u32_e32 v174, s42, v168
	global_load_dwordx2 v[124:125], v174, s[16:17]
	s_mov_b32 s22, 1
	s_mov_b32 s28, 0
	s_lshl_b32 s40, s28, 21
	s_add_u32 s38, s14, s40
	s_addc_u32 s39, s15, 0
	s_lshl_b32 s32, s22, 9
	ds_read_b128 v[82:85], v172 offset:0
	ds_read_b128 v[86:89], v172 offset:16
	ds_read_b128 v[90:93], v172 offset:32
	ds_read_b128 v[94:97], v172 offset:48
	v_add_u32_e32 v160, s32, v157
	ds_read_b128 v[66:69], v160 offset:0
	ds_read_b128 v[70:73], v160 offset:16
	ds_read_b128 v[74:77], v160 offset:32
	ds_read_b128 v[78:81], v160 offset:48
	s_lshl_b32 s37, s8, 3

; DEV unsigned pack2(float a, float b) { f32x2 v = {a, b}; return __builtin_bit_cast(unsigned, __builtin_convertvector(v, bf2_t)); }
; DEV void phase_peer_expert(const Params& p, int layer, int M, bool final_, int part, char* smem) {
;     ...
;     for (int st = 0; st < 16; st++) {
;       if (st + 1 < 16) {
;         const unsigned char* r0p = V + (size_t)se[(st + 1) * 8 + g] * 1024 + l16 * 16;
;         const unsigned char* r1p = V + (size_t)se[(st + 1) * 8 + 4 + g] * 1024 + l16 * 16;
; #pragma unroll
;         for (int c = 0; c < 4; c++) { nxt[c] = *(const u32x4*)(r0p + c * 256); nxt[4 + c] = *(const u32x4*)(r1p + c * 256); }
;       }
;     ...
;     if (!final_) {
; #pragma unroll
;       for (int q = 0; q < 4; q++)
;         *(float4*)(X + (size_t)m * 1024 + col + q * 4) = make_float4(xn[q * 4 + 0], xn[q * 4 + 1], xn[q * 4 + 2], xn[q * 4 + 3]);
;       ss = wave_sum(ss);
;       const float rinv = rsqrtf(ss * (1.f / 1024.f) + 1e-6f);
;       const float* ng = p.in[I_N1G] + (layer + 1) * 1024;
;       const float* nmod = WSP(float, S_MOD) + (size_t)(layer + 1) * 3 * 6144 + (size_t)mr * 6144;
;       unsigned hv[8];
; #pragma unroll
;       for (int q = 0; q < 4; q++) {
;         float4 g4 = *(const float4*)(ng + col + q * 4), sh = *(const float4*)(nmod + col + q * 4), sc = *(const float4*)(nmod + 1024 + col + q * 4);
;         hv[q * 2 + 0] = pack2(xn[q * 4 + 0] * rinv * g4.x * (1.f + sc.x) + sh.x, xn[q * 4 + 1] * rinv * g4.y * (1.f + sc.y) + sh.y);
;         hv[q * 2 + 1] = pack2(xn[q * 4 + 2] * rinv * g4.z * (1.f + sc.z) + sh.z, xn[q * 4 + 3] * rinv * g4.w * (1.f + sc.w) + sh.w);
;       }
;       bf16_t* hw = WSP(bf16_t, OFF_H) + (size_t)m * LDH + col;
;       *(uint4*)(hw) = make_uint4(hv[0], hv[1], hv[2], hv[3]);
;       *(uint4*)(hw + 8) = make_uint4(hv[4], hv[5], hv[6], hv[7]);
.Lv_nx_ok:
	s_lshl_b32 s40, s28, 21
	s_add_u32 s38, s14, s40
	s_addc_u32 s39, s15, 0
	s_lshl_b32 s32, s22, 9
	s_lshl_b32 s40, s18, 2
	s_add_u32 s40, s40, s9
	s_lshr_b32 s42, s40, 13
	s_min_u32 s42, s42, 2
	s_mul_i32 s42, s42, 0x6000
	s_lshl_b32 s41, s40, 12
	s_lshl_b32 s43, s20, 9
	s_add_u32 s41, s41, s43
	s_add_u32 s42, s42, s43
	v_add_u32_e32 v173, s41, v168
	global_load_dwordx2 v[122:123], v173, s[0:1]
	v_add_u32_e32 v174, s42, v168
	global_load_dwordx2 v[124:125], v174, s[16:17]
	v_add_u32_e32 v160, s32, v157
	ds_read_b128 v[66:69], v160 offset:0
	ds_read_b128 v[70:73], v160 offset:16
	ds_read_b128 v[74:77], v160 offset:32
	ds_read_b128 v[78:81], v160 offset:48
	s_sub_u32 s37, s37, 1
	s_cmp_lg_u32 s37, 0
	s_cbranch_scc1 .Lv_loop
	s_waitcnt vmcnt(0) lgkmcnt(0)
	v_mov_b32_e32 v2, 0x13b30
	ds_read_b64 v[2:3], v2
	v_mov_b32_e32 v4, 0x13bd0
	ds_read_b128 v[4:7], v4
	v_mov_b32_e32 v8, 0x13be0
	ds_read_b64 v[8:9], v8
	s_waitcnt lgkmcnt(0)
	v_readfirstlane_b32 s10, v2
	v_readfirstlane_b32 s11, v3
	v_readfirstlane_b32 s12, v4
	v_readfirstlane_b32 s13, v5
	v_readfirstlane_b32 s2, v8
	v_readfirstlane_b32 s3, v9
	s_add_u32 s10, s10, 0x1000
	s_addc_u32 s11, s11, 0
	s_add_u32 s16, s0, 0xbf52000
	s_addc_u32 s17, s1, 0
	s_add_u32 s14, s0, 0x4200000
	s_addc_u32 s15, s1, 0
	v_lshlrev_b32_e32 v173, 6, v162
	s_cmp_eq_u32 s57, 20
	s_cbranch_scc1 .Lv_tail_final
	global_load_dwordx4 v[178:181], v173, s[10:11] offset:0
	global_load_dwordx4 v[182:185], v173, s[10:11] offset:16
	global_load_dwordx4 v[186:189], v173, s[10:11] offset:32
	global_load_dwordx4 v[190:193], v173, s[10:11] offset:48
	s_add_u32 s40, s9, 0
	s_lshl_b32 s41, s40, 12
	v_add_u32_e32 v150, s41, v173
	global_load_dwordx4 v[2:5], v150, s[0:1] offset:0
	global_load_dwordx4 v[6:9], v150, s[0:1] offset:16
	global_load_dwordx4 v[10:13], v150, s[0:1] offset:32
	global_load_dwordx4 v[14:17], v150, s[0:1] offset:48
	s_lshr_b32 s42, s40, 13
	s_min_u32 s42, s42, 2
	s_mul_i32 s42, s42, 0x6000
	v_add_u32_e32 v160, s42, v173
	global_load_dwordx4 v[18:21], v160, s[16:17] offset:0
	global_load_dwordx4 v[22:25], v160, s[16:17] offset:16
	global_load_dwordx4 v[26:29], v160, s[16:17] offset:32
	global_load_dwordx4 v[30:33], v160, s[16:17] offset:48
	v_add_u32_e32 v159, 0x1000, v160
	global_load_dwordx4 v[34:37], v159, s[16:17] offset:0
	global_load_dwordx4 v[38:41], v159, s[16:17] offset:16
	global_load_dwordx4 v[42:45], v159, s[16:17] offset:32
	global_load_dwordx4 v[46:49], v159, s[16:17] offset:48
	ds_read_b32 v146, v171 offset:0
	s_add_u32 s40, s9, 4
	s_lshl_b32 s41, s40, 12
	v_add_u32_e32 v151, s41, v173
	global_load_dwordx4 v[50:53], v151, s[0:1] offset:0
	global_load_dwordx4 v[54:57], v151, s[0:1] offset:16
	global_load_dwordx4 v[58:61], v151, s[0:1] offset:32
	global_load_dwordx4 v[62:65], v151, s[0:1] offset:48
	s_lshr_b32 s42, s40, 13
	s_min_u32 s42, s42, 2
	s_mul_i32 s42, s42, 0x6000
	v_add_u32_e32 v160, s42, v173
	global_load_dwordx4 v[66:69], v160, s[16:17] offset:0
	global_load_dwordx4 v[70:73], v160, s[16:17] offset:16
	global_load_dwordx4 v[74:77], v160, s[16:17] offset:32
	global_load_dwordx4 v[78:81], v160, s[16:17] offset:48
	v_add_u32_e32 v159, 0x1000, v160
	global_load_dwordx4 v[82:85], v159, s[16:17] offset:0
	global_load_dwordx4 v[86:89], v159, s[16:17] offset:16
	global_load_dwordx4 v[90:93], v159, s[16:17] offset:32
	global_load_dwordx4 v[94:97], v159, s[16:17] offset:48
	ds_read_b32 v147, v171 offset:256
	s_add_u32 s40, s9, 8
	s_lshl_b32 s41, s40, 12
	v_add_u32_e32 v152, s41, v173
	global_load_dwordx4 v[98:101], v152, s[0:1] offset:0
	global_load_dwordx4 v[102:105], v152, s[0:1] offset:16
	global_load_dwordx4 v[106:109], v152, s[0:1] offset:32
	global_load_dwordx4 v[110:113], v152, s[0:1] offset:48
	s_lshr_b32 s42, s40, 13
	s_min_u32 s42, s42, 2
	s_mul_i32 s42, s42, 0x6000
	v_add_u32_e32 v160, s42, v173
	global_load_dwordx4 v[114:117], v160, s[16:17] offset:0
	global_load_dwordx4 v[118:121], v160, s[16:17] offset:16
	global_load_dwordx4 v[122:125], v160, s[16:17] offset:32
	global_load_dwordx4 v[126:129], v160, s[16:17] offset:48
	v_add_u32_e32 v159, 0x1000, v160
	global_load_dwordx4 v[130:133], v159, s[16:17] offset:0
	global_load_dwordx4 v[134:137], v159, s[16:17] offset:16
	global_load_dwordx4 v[138:141], v159, s[16:17] offset:32
	global_load_dwordx4 v[142:145], v159, s[16:17] offset:48
	ds_read_b32 v148, v171 offset:512
	s_waitcnt lgkmcnt(0)
	s_nop 1
	v_add_f32_dpp v146, v146, v146 quad_perm:[1,0,3,2] row_mask:0xf bank_mask:0xf
	s_nop 1
	v_add_f32_dpp v146, v146, v146 quad_perm:[2,3,0,1] row_mask:0xf bank_mask:0xf
	s_nop 1
	v_add_f32_dpp v146, v146, v146 row_half_mirror row_mask:0xf bank_mask:0xf
	s_nop 1
	v_add_f32_dpp v146, v146, v146 row_mirror row_mask:0xf bank_mask:0xf
	ds_bpermute_b32 v153, v175, v146
	s_waitcnt lgkmcnt(0)
	v_add_f32_e32 v146, v146, v153
	ds_bpermute_b32 v153, v176, v146
	s_waitcnt lgkmcnt(0)
	v_add_f32_e32 v146, v146, v153
	v_fmamk_f32 v146, v146, 0x3a800000, v211
	s_nop 0
	v_rsq_f32_e32 v146, v146
	s_waitcnt vmcnt(24)
; DEV unsigned pack2(float a, float b) { f32x2 v = {a, b}; return __builtin_bit_cast(unsigned, __builtin_convertvector(v, bf2_t)); }
; DEV void phase_peer_expert(const Params& p, int layer, int M, bool final_, int part, char* smem) {
;     ...
;       ss = wave_sum(ss);
;       const float rinv = rsqrtf(ss * (1.f / 1024.f) + 1e-6f);
;       const float* ng = p.in[I_N1G] + (layer + 1) * 1024;
;       const float* nmod = WSP(float, S_MOD) + (size_t)(layer + 1) * 3 * 6144 + (size_t)mr * 6144;
;       unsigned hv[8];
; #pragma unroll
;       for (int q = 0; q < 4; q++) {
;         float4 g4 = *(const float4*)(ng + col + q * 4), sh = *(const float4*)(nmod + col + q * 4), sc = *(const float4*)(nmod + 1024 + col + q * 4);
;         hv[q * 2 + 0] = pack2(xn[q * 4 + 0] * rinv * g4.x * (1.f + sc.x) + sh.x, xn[q * 4 + 1] * rinv * g4.y * (1.f + sc.y) + sh.y);
;         hv[q * 2 + 1] = pack2(xn[q * 4 + 2] * rinv * g4.z * (1.f + sc.z) + sh.z, xn[q * 4 + 3] * rinv * g4.w * (1.f + sc.w) + sh.w);
;       }
;       bf16_t* hw = WSP(bf16_t, OFF_H) + (size_t)m * LDH + col;
;       *(uint4*)(hw) = make_uint4(hv[0], hv[1], hv[2], hv[3]);
;       *(uint4*)(hw + 8) = make_uint4(hv[4], hv[5], hv[6], hv[7]);
	v_mul_f32_e32 v2, v2, v146
	v_mul_f32_e32 v3, v3, v146
	v_mul_f32_e32 v4, v4, v146
	v_mul_f32_e32 v5, v5, v146
	v_mul_f32_e32 v6, v6, v146
	v_mul_f32_e32 v7, v7, v146
	v_mul_f32_e32 v8, v8, v146
	v_mul_f32_e32 v9, v9, v146
	v_mul_f32_e32 v10, v10, v146
	v_mul_f32_e32 v11, v11, v146
	v_mul_f32_e32 v12, v12, v146
	v_mul_f32_e32 v13, v13, v146
	v_mul_f32_e32 v14, v14, v146
	v_mul_f32_e32 v15, v15, v146
	v_mul_f32_e32 v16, v16, v146
	v_mul_f32_e32 v17, v17, v146
	v_mul_f32_e32 v2, v2, v178
	v_mul_f32_e32 v3, v3, v179
	v_mul_f32_e32 v4, v4, v180
	v_mul_f32_e32 v5, v5, v181
	v_mul_f32_e32 v6, v6, v182
	v_mul_f32_e32 v7, v7, v183
	v_mul_f32_e32 v8, v8, v184
	v_mul_f32_e32 v9, v9, v185
	v_mul_f32_e32 v10, v10, v186
	v_mul_f32_e32 v11, v11, v187
	v_mul_f32_e32 v12, v12, v188
	v_mul_f32_e32 v13, v13, v189
	v_mul_f32_e32 v14, v14, v190
	v_mul_f32_e32 v15, v15, v191
	v_mul_f32_e32 v16, v16, v192
	v_mul_f32_e32 v17, v17, v193
	v_add_f32_e32 v34, 1.0, v34
	v_add_f32_e32 v35, 1.0, v35
	v_add_f32_e32 v36, 1.0, v36
	v_add_f32_e32 v37, 1.0, v37
	v_add_f32_e32 v38, 1.0, v38
	v_add_f32_e32 v39, 1.0, v39
	v_add_f32_e32 v40, 1.0, v40
	v_add_f32_e32 v41, 1.0, v41
	v_add_f32_e32 v42, 1.0, v42
	v_add_f32_e32 v43, 1.0, v43
	v_add_f32_e32 v44, 1.0, v44
	v_add_f32_e32 v45, 1.0, v45
	v_add_f32_e32 v46, 1.0, v46
	v_add_f32_e32 v47, 1.0, v47
	v_add_f32_e32 v48, 1.0, v48
	v_add_f32_e32 v49, 1.0, v49
	v_fma_f32 v2, v2, v34, v18
	v_fma_f32 v3, v3, v35, v19
	v_fma_f32 v4, v4, v36, v20
	v_fma_f32 v5, v5, v37, v21
	v_fma_f32 v6, v6, v38, v22
	v_fma_f32 v7, v7, v39, v23
	v_fma_f32 v8, v8, v40, v24
	v_fma_f32 v9, v9, v41, v25
	v_fma_f32 v10, v10, v42, v26
	v_fma_f32 v11, v11, v43, v27
	v_fma_f32 v12, v12, v44, v28
	v_fma_f32 v13, v13, v45, v29
	v_fma_f32 v14, v14, v46, v30
	v_fma_f32 v15, v15, v47, v31
	v_fma_f32 v16, v16, v48, v32
	v_fma_f32 v17, v17, v49, v33
	v_cvt_pk_bf16_f32 v18, v2, v3
	v_cvt_pk_bf16_f32 v19, v4, v5
	v_cvt_pk_bf16_f32 v20, v6, v7
	v_cvt_pk_bf16_f32 v21, v8, v9
	v_cvt_pk_bf16_f32 v22, v10, v11
	v_cvt_pk_bf16_f32 v23, v12, v13
	v_cvt_pk_bf16_f32 v24, v14, v15
	v_cvt_pk_bf16_f32 v25, v16, v17
	s_add_u32 s40, s9, 0
	s_mul_i32 s42, s40, 0x880
	v_lshl_add_u32 v160, v162, 5, s42
	global_store_dwordx4 v160, v[18:21], s[14:15]
	global_store_dwordx4 v160, v[22:25], s[14:15] offset:16
	s_waitcnt lgkmcnt(0)
	s_nop 1
	v_add_f32_dpp v147, v147, v147 quad_perm:[1,0,3,2] row_mask:0xf bank_mask:0xf
	s_nop 1
	v_add_f32_dpp v147, v147, v147 quad_perm:[2,3,0,1] row_mask:0xf bank_mask:0xf
	s_nop 1
	v_add_f32_dpp v147, v147, v147 row_half_mirror row_mask:0xf bank_mask:0xf
	s_nop 1
	v_add_f32_dpp v147, v147, v147 row_mirror row_mask:0xf bank_mask:0xf
	ds_bpermute_b32 v153, v175, v147
	s_waitcnt lgkmcnt(0)
	v_add_f32_e32 v147, v147, v153
	ds_bpermute_b32 v153, v176, v147
	s_waitcnt lgkmcnt(0)
	v_add_f32_e32 v147, v147, v153
	v_fmamk_f32 v147, v147, 0x3a800000, v211
	s_nop 0
	v_rsq_f32_e32 v147, v147
	s_waitcnt vmcnt(14)
	v_mul_f32_e32 v50, v50, v147
	v_mul_f32_e32 v51, v51, v147
	v_mul_f32_e32 v52, v52, v147
	v_mul_f32_e32 v53, v53, v147
	v_mul_f32_e32 v54, v54, v147
	v_mul_f32_e32 v55, v55, v147
	v_mul_f32_e32 v56, v56, v147
	v_mul_f32_e32 v57, v57, v147
	v_mul_f32_e32 v58, v58, v147
	v_mul_f32_e32 v59, v59, v147
	v_mul_f32_e32 v60, v60, v147
	v_mul_f32_e32 v61, v61, v147
	v_mul_f32_e32 v62, v62, v147
	v_mul_f32_e32 v63, v63, v147
	v_mul_f32_e32 v64, v64, v147
	v_mul_f32_e32 v65, v65, v147
	v_mul_f32_e32 v50, v50, v178
	v_mul_f32_e32 v51, v51, v179
	v_mul_f32_e32 v52, v52, v180
	v_mul_f32_e32 v53, v53, v181
	v_mul_f32_e32 v54, v54, v182
	v_mul_f32_e32 v55, v55, v183
	v_mul_f32_e32 v56, v56, v184
	v_mul_f32_e32 v57, v57, v185
	v_mul_f32_e32 v58, v58, v186
	v_mul_f32_e32 v59, v59, v187
	v_mul_f32_e32 v60, v60, v188
	v_mul_f32_e32 v61, v61, v189
	v_mul_f32_e32 v62, v62, v190
	v_mul_f32_e32 v63, v63, v191
	v_mul_f32_e32 v64, v64, v192
	v_mul_f32_e32 v65, v65, v193
	v_add_f32_e32 v82, 1.0, v82
	v_add_f32_e32 v83, 1.0, v83
	v_add_f32_e32 v84, 1.0, v84
	v_add_f32_e32 v85, 1.0, v85
	v_add_f32_e32 v86, 1.0, v86
	v_add_f32_e32 v87, 1.0, v87
	v_add_f32_e32 v88, 1.0, v88
	v_add_f32_e32 v89, 1.0, v89
	v_add_f32_e32 v90, 1.0, v90
	v_add_f32_e32 v91, 1.0, v91
	v_add_f32_e32 v92, 1.0, v92
	v_add_f32_e32 v93, 1.0, v93
	v_add_f32_e32 v94, 1.0, v94
	v_add_f32_e32 v95, 1.0, v95
	v_add_f32_e32 v96, 1.0, v96
	v_add_f32_e32 v97, 1.0, v97
	v_fma_f32 v50, v50, v82, v66
	v_fma_f32 v51, v51, v83, v67
	v_fma_f32 v52, v52, v84, v68
	v_fma_f32 v53, v53, v85, v69
	v_fma_f32 v54, v54, v86, v70
	v_fma_f32 v55, v55, v87, v71
	v_fma_f32 v56, v56, v88, v72
	v_fma_f32 v57, v57, v89, v73
	v_fma_f32 v58, v58, v90, v74
	v_fma_f32 v59, v59, v91, v75
	v_fma_f32 v60, v60, v92, v76
	v_fma_f32 v61, v61, v93, v77
	v_fma_f32 v62, v62, v94, v78
	v_fma_f32 v63, v63, v95, v79
	v_fma_f32 v64, v64, v96, v80
	v_fma_f32 v65, v65, v97, v81
	v_cvt_pk_bf16_f32 v66, v50, v51
	v_cvt_pk_bf16_f32 v67, v52, v53
	v_cvt_pk_bf16_f32 v68, v54, v55
	v_cvt_pk_bf16_f32 v69, v56, v57
	v_cvt_pk_bf16_f32 v70, v58, v59
	v_cvt_pk_bf16_f32 v71, v60, v61
	v_cvt_pk_bf16_f32 v72, v62, v63
	v_cvt_pk_bf16_f32 v73, v64, v65
	s_add_u32 s40, s9, 4
	s_mul_i32 s42, s40, 0x880
	v_lshl_add_u32 v160, v162, 5, s42
	global_store_dwordx4 v160, v[66:69], s[14:15]
	global_store_dwordx4 v160, v[70:73], s[14:15] offset:16
	s_waitcnt lgkmcnt(0)
	s_nop 1
	v_add_f32_dpp v148, v148, v148 quad_perm:[1,0,3,2] row_mask:0xf bank_mask:0xf
	s_nop 1
	v_add_f32_dpp v148, v148, v148 quad_perm:[2,3,0,1] row_mask:0xf bank_mask:0xf
	s_nop 1
	v_add_f32_dpp v148, v148, v148 row_half_mirror row_mask:0xf bank_mask:0xf
	s_nop 1
	v_add_f32_dpp v148, v148, v148 row_mirror row_mask:0xf bank_mask:0xf
	ds_bpermute_b32 v153, v175, v148
	s_waitcnt lgkmcnt(0)
; DEV unsigned pack2(float a, float b) { f32x2 v = {a, b}; return __builtin_bit_cast(unsigned, __builtin_convertvector(v, bf2_t)); }
; DEV void phase_peer_expert(const Params& p, int layer, int M, bool final_, int part, char* smem) {
;     ...
;       ss = wave_sum(ss);
;       const float rinv = rsqrtf(ss * (1.f / 1024.f) + 1e-6f);
;       const float* ng = p.in[I_N1G] + (layer + 1) * 1024;
;       const float* nmod = WSP(float, S_MOD) + (size_t)(layer + 1) * 3 * 6144 + (size_t)mr * 6144;
;       unsigned hv[8];
; #pragma unroll
;       for (int q = 0; q < 4; q++) {
;         float4 g4 = *(const float4*)(ng + col + q * 4), sh = *(const float4*)(nmod + col + q * 4), sc = *(const float4*)(nmod + 1024 + col + q * 4);
;         hv[q * 2 + 0] = pack2(xn[q * 4 + 0] * rinv * g4.x * (1.f + sc.x) + sh.x, xn[q * 4 + 1] * rinv * g4.y * (1.f + sc.y) + sh.y);
;         hv[q * 2 + 1] = pack2(xn[q * 4 + 2] * rinv * g4.z * (1.f + sc.z) + sh.z, xn[q * 4 + 3] * rinv * g4.w * (1.f + sc.w) + sh.w);
;       }
;       bf16_t* hw = WSP(bf16_t, OFF_H) + (size_t)m * LDH + col;
;       *(uint4*)(hw) = make_uint4(hv[0], hv[1], hv[2], hv[3]);
;       *(uint4*)(hw + 8) = make_uint4(hv[4], hv[5], hv[6], hv[7]);
	v_add_f32_e32 v148, v148, v153
	ds_bpermute_b32 v153, v176, v148
	s_waitcnt lgkmcnt(0)
	v_add_f32_e32 v148, v148, v153
	v_fmamk_f32 v148, v148, 0x3a800000, v211
	s_nop 0
	v_rsq_f32_e32 v148, v148
	s_waitcnt vmcnt(4)
	v_mul_f32_e32 v98, v98, v148
	v_mul_f32_e32 v99, v99, v148
	v_mul_f32_e32 v100, v100, v148
	v_mul_f32_e32 v101, v101, v148
	v_mul_f32_e32 v102, v102, v148
	v_mul_f32_e32 v103, v103, v148
	v_mul_f32_e32 v104, v104, v148
	v_mul_f32_e32 v105, v105, v148
	v_mul_f32_e32 v106, v106, v148
	v_mul_f32_e32 v107, v107, v148
	v_mul_f32_e32 v108, v108, v148
	v_mul_f32_e32 v109, v109, v148
	v_mul_f32_e32 v110, v110, v148
	v_mul_f32_e32 v111, v111, v148
	v_mul_f32_e32 v112, v112, v148
	v_mul_f32_e32 v113, v113, v148
	v_mul_f32_e32 v98, v98, v178
	v_mul_f32_e32 v99, v99, v179
	v_mul_f32_e32 v100, v100, v180
	v_mul_f32_e32 v101, v101, v181
	v_mul_f32_e32 v102, v102, v182
	v_mul_f32_e32 v103, v103, v183
	v_mul_f32_e32 v104, v104, v184
	v_mul_f32_e32 v105, v105, v185
	v_mul_f32_e32 v106, v106, v186
	v_mul_f32_e32 v107, v107, v187
	v_mul_f32_e32 v108, v108, v188
	v_mul_f32_e32 v109, v109, v189
	v_mul_f32_e32 v110, v110, v190
	v_mul_f32_e32 v111, v111, v191
	v_mul_f32_e32 v112, v112, v192
	v_mul_f32_e32 v113, v113, v193
	v_add_f32_e32 v130, 1.0, v130
	v_add_f32_e32 v131, 1.0, v131
	v_add_f32_e32 v132, 1.0, v132
	v_add_f32_e32 v133, 1.0, v133
	v_add_f32_e32 v134, 1.0, v134
	v_add_f32_e32 v135, 1.0, v135
	v_add_f32_e32 v136, 1.0, v136
	v_add_f32_e32 v137, 1.0, v137
	v_add_f32_e32 v138, 1.0, v138
	v_add_f32_e32 v139, 1.0, v139
	v_add_f32_e32 v140, 1.0, v140
	v_add_f32_e32 v141, 1.0, v141
	v_add_f32_e32 v142, 1.0, v142
	v_add_f32_e32 v143, 1.0, v143
	v_add_f32_e32 v144, 1.0, v144
	v_add_f32_e32 v145, 1.0, v145
	v_fma_f32 v98, v98, v130, v114
	v_fma_f32 v99, v99, v131, v115
	v_fma_f32 v100, v100, v132, v116
	v_fma_f32 v101, v101, v133, v117
	v_fma_f32 v102, v102, v134, v118
	v_fma_f32 v103, v103, v135, v119
	v_fma_f32 v104, v104, v136, v120
	v_fma_f32 v105, v105, v137, v121
	v_fma_f32 v106, v106, v138, v122
	v_fma_f32 v107, v107, v139, v123
	v_fma_f32 v108, v108, v140, v124
	v_fma_f32 v109, v109, v141, v125
	v_fma_f32 v110, v110, v142, v126
	v_fma_f32 v111, v111, v143, v127
	v_fma_f32 v112, v112, v144, v128
	v_fma_f32 v113, v113, v145, v129
	v_cvt_pk_bf16_f32 v114, v98, v99
	v_cvt_pk_bf16_f32 v115, v100, v101
	v_cvt_pk_bf16_f32 v116, v102, v103
	v_cvt_pk_bf16_f32 v117, v104, v105
	v_cvt_pk_bf16_f32 v118, v106, v107
	v_cvt_pk_bf16_f32 v119, v108, v109
	v_cvt_pk_bf16_f32 v120, v110, v111
	v_cvt_pk_bf16_f32 v121, v112, v113
	s_add_u32 s40, s9, 8
	s_mul_i32 s42, s40, 0x880
	v_lshl_add_u32 v160, v162, 5, s42
	global_store_dwordx4 v160, v[114:117], s[14:15]
	global_store_dwordx4 v160, v[118:121], s[14:15] offset:16
	s_add_u32 s40, s9, 12
	s_lshl_b32 s41, s40, 12
	v_add_u32_e32 v150, s41, v173
	global_load_dwordx4 v[2:5], v150, s[0:1] offset:0
	global_load_dwordx4 v[6:9], v150, s[0:1] offset:16
	global_load_dwordx4 v[10:13], v150, s[0:1] offset:32
	global_load_dwordx4 v[14:17], v150, s[0:1] offset:48
	s_lshr_b32 s42, s40, 13
	s_min_u32 s42, s42, 2
	s_mul_i32 s42, s42, 0x6000
	v_add_u32_e32 v160, s42, v173
	global_load_dwordx4 v[18:21], v160, s[16:17] offset:0
	global_load_dwordx4 v[22:25], v160, s[16:17] offset:16
	global_load_dwordx4 v[26:29], v160, s[16:17] offset:32
	global_load_dwordx4 v[30:33], v160, s[16:17] offset:48
	v_add_u32_e32 v159, 0x1000, v160
	global_load_dwordx4 v[34:37], v159, s[16:17] offset:0
	global_load_dwordx4 v[38:41], v159, s[16:17] offset:16
	global_load_dwordx4 v[42:45], v159, s[16:17] offset:32
	global_load_dwordx4 v[46:49], v159, s[16:17] offset:48
	ds_read_b32 v146, v171 offset:768
	s_add_u32 s40, s9, 16
	s_lshl_b32 s41, s40, 12
	v_add_u32_e32 v151, s41, v173
	global_load_dwordx4 v[50:53], v151, s[0:1] offset:0
	global_load_dwordx4 v[54:57], v151, s[0:1] offset:16
	global_load_dwordx4 v[58:61], v151, s[0:1] offset:32
	global_load_dwordx4 v[62:65], v151, s[0:1] offset:48
	s_lshr_b32 s42, s40, 13
	s_min_u32 s42, s42, 2
	s_mul_i32 s42, s42, 0x6000
	v_add_u32_e32 v160, s42, v173
	global_load_dwordx4 v[66:69], v160, s[16:17] offset:0
	global_load_dwordx4 v[70:73], v160, s[16:17] offset:16
	global_load_dwordx4 v[74:77], v160, s[16:17] offset:32
	global_load_dwordx4 v[78:81], v160, s[16:17] offset:48
	v_add_u32_e32 v159, 0x1000, v160
	global_load_dwordx4 v[82:85], v159, s[16:17] offset:0
	global_load_dwordx4 v[86:89], v159, s[16:17] offset:16
	global_load_dwordx4 v[90:93], v159, s[16:17] offset:32
	global_load_dwordx4 v[94:97], v159, s[16:17] offset:48
	ds_read_b32 v147, v171 offset:1024
	s_add_u32 s40, s9, 20
	s_lshl_b32 s41, s40, 12
	v_add_u32_e32 v152, s41, v173
	global_load_dwordx4 v[98:101], v152, s[0:1] offset:0
	global_load_dwordx4 v[102:105], v152, s[0:1] offset:16
	global_load_dwordx4 v[106:109], v152, s[0:1] offset:32
	global_load_dwordx4 v[110:113], v152, s[0:1] offset:48
	s_lshr_b32 s42, s40, 13
	s_min_u32 s42, s42, 2
	s_mul_i32 s42, s42, 0x6000
	v_add_u32_e32 v160, s42, v173
	global_load_dwordx4 v[114:117], v160, s[16:17] offset:0
	global_load_dwordx4 v[118:121], v160, s[16:17] offset:16
	global_load_dwordx4 v[122:125], v160, s[16:17] offset:32
	global_load_dwordx4 v[126:129], v160, s[16:17] offset:48
	v_add_u32_e32 v159, 0x1000, v160
	global_load_dwordx4 v[130:133], v159, s[16:17] offset:0
	global_load_dwordx4 v[134:137], v159, s[16:17] offset:16
	global_load_dwordx4 v[138:141], v159, s[16:17] offset:32
	global_load_dwordx4 v[142:145], v159, s[16:17] offset:48
	ds_read_b32 v148, v171 offset:1280
	s_waitcnt lgkmcnt(0)
; DEV unsigned pack2(float a, float b) { f32x2 v = {a, b}; return __builtin_bit_cast(unsigned, __builtin_convertvector(v, bf2_t)); }
; DEV void phase_peer_expert(const Params& p, int layer, int M, bool final_, int part, char* smem) {
;     ...
;       ss = wave_sum(ss);
;       const float rinv = rsqrtf(ss * (1.f / 1024.f) + 1e-6f);
;       const float* ng = p.in[I_N1G] + (layer + 1) * 1024;
;       const float* nmod = WSP(float, S_MOD) + (size_t)(layer + 1) * 3 * 6144 + (size_t)mr * 6144;
;       unsigned hv[8];
; #pragma unroll
;       for (int q = 0; q < 4; q++) {
;         float4 g4 = *(const float4*)(ng + col + q * 4), sh = *(const float4*)(nmod + col + q * 4), sc = *(const float4*)(nmod + 1024 + col + q * 4);
;         hv[q * 2 + 0] = pack2(xn[q * 4 + 0] * rinv * g4.x * (1.f + sc.x) + sh.x, xn[q * 4 + 1] * rinv * g4.y * (1.f + sc.y) + sh.y);
;         hv[q * 2 + 1] = pack2(xn[q * 4 + 2] * rinv * g4.z * (1.f + sc.z) + sh.z, xn[q * 4 + 3] * rinv * g4.w * (1.f + sc.w) + sh.w);
;       }
;       bf16_t* hw = WSP(bf16_t, OFF_H) + (size_t)m * LDH + col;
;       *(uint4*)(hw) = make_uint4(hv[0], hv[1], hv[2], hv[3]);
;       *(uint4*)(hw + 8) = make_uint4(hv[4], hv[5], hv[6], hv[7]);
	s_nop 1
	v_add_f32_dpp v146, v146, v146 quad_perm:[1,0,3,2] row_mask:0xf bank_mask:0xf
	s_nop 1
	v_add_f32_dpp v146, v146, v146 quad_perm:[2,3,0,1] row_mask:0xf bank_mask:0xf
	s_nop 1
	v_add_f32_dpp v146, v146, v146 row_half_mirror row_mask:0xf bank_mask:0xf
	s_nop 1
	v_add_f32_dpp v146, v146, v146 row_mirror row_mask:0xf bank_mask:0xf
	ds_bpermute_b32 v153, v175, v146
	s_waitcnt lgkmcnt(0)
	v_add_f32_e32 v146, v146, v153
	ds_bpermute_b32 v153, v176, v146
	s_waitcnt lgkmcnt(0)
	v_add_f32_e32 v146, v146, v153
	v_fmamk_f32 v146, v146, 0x3a800000, v211
	s_nop 0
	v_rsq_f32_e32 v146, v146
	s_waitcnt vmcnt(24)
	v_mul_f32_e32 v2, v2, v146
	v_mul_f32_e32 v3, v3, v146
	v_mul_f32_e32 v4, v4, v146
	v_mul_f32_e32 v5, v5, v146
	v_mul_f32_e32 v6, v6, v146
	v_mul_f32_e32 v7, v7, v146
	v_mul_f32_e32 v8, v8, v146
	v_mul_f32_e32 v9, v9, v146
	v_mul_f32_e32 v10, v10, v146
	v_mul_f32_e32 v11, v11, v146
	v_mul_f32_e32 v12, v12, v146
	v_mul_f32_e32 v13, v13, v146
	v_mul_f32_e32 v14, v14, v146
	v_mul_f32_e32 v15, v15, v146
	v_mul_f32_e32 v16, v16, v146
	v_mul_f32_e32 v17, v17, v146
	v_mul_f32_e32 v2, v2, v178
	v_mul_f32_e32 v3, v3, v179
	v_mul_f32_e32 v4, v4, v180
	v_mul_f32_e32 v5, v5, v181
	v_mul_f32_e32 v6, v6, v182
	v_mul_f32_e32 v7, v7, v183
	v_mul_f32_e32 v8, v8, v184
	v_mul_f32_e32 v9, v9, v185
	v_mul_f32_e32 v10, v10, v186
	v_mul_f32_e32 v11, v11, v187
	v_mul_f32_e32 v12, v12, v188
	v_mul_f32_e32 v13, v13, v189
	v_mul_f32_e32 v14, v14, v190
	v_mul_f32_e32 v15, v15, v191
	v_mul_f32_e32 v16, v16, v192
	v_mul_f32_e32 v17, v17, v193
	v_add_f32_e32 v34, 1.0, v34
	v_add_f32_e32 v35, 1.0, v35
	v_add_f32_e32 v36, 1.0, v36
	v_add_f32_e32 v37, 1.0, v37
	v_add_f32_e32 v38, 1.0, v38
	v_add_f32_e32 v39, 1.0, v39
	v_add_f32_e32 v40, 1.0, v40
	v_add_f32_e32 v41, 1.0, v41
	v_add_f32_e32 v42, 1.0, v42
	v_add_f32_e32 v43, 1.0, v43
	v_add_f32_e32 v44, 1.0, v44
	v_add_f32_e32 v45, 1.0, v45
	v_add_f32_e32 v46, 1.0, v46
	v_add_f32_e32 v47, 1.0, v47
	v_add_f32_e32 v48, 1.0, v48
	v_add_f32_e32 v49, 1.0, v49
	v_fma_f32 v2, v2, v34, v18
	v_fma_f32 v3, v3, v35, v19
	v_fma_f32 v4, v4, v36, v20
	v_fma_f32 v5, v5, v37, v21
	v_fma_f32 v6, v6, v38, v22
	v_fma_f32 v7, v7, v39, v23
	v_fma_f32 v8, v8, v40, v24
	v_fma_f32 v9, v9, v41, v25
	v_fma_f32 v10, v10, v42, v26
	v_fma_f32 v11, v11, v43, v27
	v_fma_f32 v12, v12, v44, v28
	v_fma_f32 v13, v13, v45, v29
	v_fma_f32 v14, v14, v46, v30
	v_fma_f32 v15, v15, v47, v31
	v_fma_f32 v16, v16, v48, v32
	v_fma_f32 v17, v17, v49, v33
	v_cvt_pk_bf16_f32 v18, v2, v3
	v_cvt_pk_bf16_f32 v19, v4, v5
	v_cvt_pk_bf16_f32 v20, v6, v7
	v_cvt_pk_bf16_f32 v21, v8, v9
	v_cvt_pk_bf16_f32 v22, v10, v11
	v_cvt_pk_bf16_f32 v23, v12, v13
	v_cvt_pk_bf16_f32 v24, v14, v15
	v_cvt_pk_bf16_f32 v25, v16, v17
	s_add_u32 s40, s9, 12
	s_mul_i32 s42, s40, 0x880
	v_lshl_add_u32 v160, v162, 5, s42
	global_store_dwordx4 v160, v[18:21], s[14:15]
	global_store_dwordx4 v160, v[22:25], s[14:15] offset:16
	s_waitcnt lgkmcnt(0)
	s_nop 1
	v_add_f32_dpp v147, v147, v147 quad_perm:[1,0,3,2] row_mask:0xf bank_mask:0xf
	s_nop 1
	v_add_f32_dpp v147, v147, v147 quad_perm:[2,3,0,1] row_mask:0xf bank_mask:0xf
	s_nop 1
	v_add_f32_dpp v147, v147, v147 row_half_mirror row_mask:0xf bank_mask:0xf
	s_nop 1
	v_add_f32_dpp v147, v147, v147 row_mirror row_mask:0xf bank_mask:0xf
	ds_bpermute_b32 v153, v175, v147
	s_waitcnt lgkmcnt(0)
	v_add_f32_e32 v147, v147, v153
	ds_bpermute_b32 v153, v176, v147
	s_waitcnt lgkmcnt(0)
	v_add_f32_e32 v147, v147, v153
	v_fmamk_f32 v147, v147, 0x3a800000, v211
	s_nop 0
	v_rsq_f32_e32 v147, v147
	s_waitcnt vmcnt(14)
	v_mul_f32_e32 v50, v50, v147
	v_mul_f32_e32 v51, v51, v147
	v_mul_f32_e32 v52, v52, v147
	v_mul_f32_e32 v53, v53, v147
	v_mul_f32_e32 v54, v54, v147
	v_mul_f32_e32 v55, v55, v147
	v_mul_f32_e32 v56, v56, v147
	v_mul_f32_e32 v57, v57, v147
	v_mul_f32_e32 v58, v58, v147
	v_mul_f32_e32 v59, v59, v147
	v_mul_f32_e32 v60, v60, v147
	v_mul_f32_e32 v61, v61, v147
	v_mul_f32_e32 v62, v62, v147
	v_mul_f32_e32 v63, v63, v147
	v_mul_f32_e32 v64, v64, v147
	v_mul_f32_e32 v65, v65, v147
	v_mul_f32_e32 v50, v50, v178
	v_mul_f32_e32 v51, v51, v179
	v_mul_f32_e32 v52, v52, v180
	v_mul_f32_e32 v53, v53, v181
	v_mul_f32_e32 v54, v54, v182
	v_mul_f32_e32 v55, v55, v183
	v_mul_f32_e32 v56, v56, v184
	v_mul_f32_e32 v57, v57, v185
	v_mul_f32_e32 v58, v58, v186
	v_mul_f32_e32 v59, v59, v187
	v_mul_f32_e32 v60, v60, v188
	v_mul_f32_e32 v61, v61, v189
	v_mul_f32_e32 v62, v62, v190
	v_mul_f32_e32 v63, v63, v191
	v_mul_f32_e32 v64, v64, v192
	v_mul_f32_e32 v65, v65, v193
	v_add_f32_e32 v82, 1.0, v82
	v_add_f32_e32 v83, 1.0, v83
	v_add_f32_e32 v84, 1.0, v84
	v_add_f32_e32 v85, 1.0, v85
	v_add_f32_e32 v86, 1.0, v86
	v_add_f32_e32 v87, 1.0, v87
	v_add_f32_e32 v88, 1.0, v88
	v_add_f32_e32 v89, 1.0, v89
	v_add_f32_e32 v90, 1.0, v90
	v_add_f32_e32 v91, 1.0, v91
	v_add_f32_e32 v92, 1.0, v92
	v_add_f32_e32 v93, 1.0, v93
	v_add_f32_e32 v94, 1.0, v94
	v_add_f32_e32 v95, 1.0, v95
	v_add_f32_e32 v96, 1.0, v96
	v_add_f32_e32 v97, 1.0, v97
	v_fma_f32 v50, v50, v82, v66
	v_fma_f32 v51, v51, v83, v67
	v_fma_f32 v52, v52, v84, v68
	v_fma_f32 v53, v53, v85, v69
	v_fma_f32 v54, v54, v86, v70
	v_fma_f32 v55, v55, v87, v71
	v_fma_f32 v56, v56, v88, v72
	v_fma_f32 v57, v57, v89, v73
	v_fma_f32 v58, v58, v90, v74
	v_fma_f32 v59, v59, v91, v75
	v_fma_f32 v60, v60, v92, v76
	v_fma_f32 v61, v61, v93, v77
	v_fma_f32 v62, v62, v94, v78
	v_fma_f32 v63, v63, v95, v79
	v_fma_f32 v64, v64, v96, v80
	v_fma_f32 v65, v65, v97, v81
	v_cvt_pk_bf16_f32 v66, v50, v51
	v_cvt_pk_bf16_f32 v67, v52, v53
	v_cvt_pk_bf16_f32 v68, v54, v55
	v_cvt_pk_bf16_f32 v69, v56, v57
	v_cvt_pk_bf16_f32 v70, v58, v59
	v_cvt_pk_bf16_f32 v71, v60, v61
	v_cvt_pk_bf16_f32 v72, v62, v63
	v_cvt_pk_bf16_f32 v73, v64, v65
	s_add_u32 s40, s9, 16
	s_mul_i32 s42, s40, 0x880
	v_lshl_add_u32 v160, v162, 5, s42
	global_store_dwordx4 v160, v[66:69], s[14:15]
	global_store_dwordx4 v160, v[70:73], s[14:15] offset:16
	s_waitcnt lgkmcnt(0)
; DEV unsigned pack2(float a, float b) { f32x2 v = {a, b}; return __builtin_bit_cast(unsigned, __builtin_convertvector(v, bf2_t)); }
; DEV void phase_peer_expert(const Params& p, int layer, int M, bool final_, int part, char* smem) {
;     ...
;       ss = wave_sum(ss);
;       const float rinv = rsqrtf(ss * (1.f / 1024.f) + 1e-6f);
;       const float* ng = p.in[I_N1G] + (layer + 1) * 1024;
;       const float* nmod = WSP(float, S_MOD) + (size_t)(layer + 1) * 3 * 6144 + (size_t)mr * 6144;
;       unsigned hv[8];
; #pragma unroll
;       for (int q = 0; q < 4; q++) {
;         float4 g4 = *(const float4*)(ng + col + q * 4), sh = *(const float4*)(nmod + col + q * 4), sc = *(const float4*)(nmod + 1024 + col + q * 4);
;         hv[q * 2 + 0] = pack2(xn[q * 4 + 0] * rinv * g4.x * (1.f + sc.x) + sh.x, xn[q * 4 + 1] * rinv * g4.y * (1.f + sc.y) + sh.y);
;         hv[q * 2 + 1] = pack2(xn[q * 4 + 2] * rinv * g4.z * (1.f + sc.z) + sh.z, xn[q * 4 + 3] * rinv * g4.w * (1.f + sc.w) + sh.w);
;       }
;       bf16_t* hw = WSP(bf16_t, OFF_H) + (size_t)m * LDH + col;
;       *(uint4*)(hw) = make_uint4(hv[0], hv[1], hv[2], hv[3]);
;       *(uint4*)(hw + 8) = make_uint4(hv[4], hv[5], hv[6], hv[7]);
	s_nop 1
	v_add_f32_dpp v148, v148, v148 quad_perm:[1,0,3,2] row_mask:0xf bank_mask:0xf
	s_nop 1
	v_add_f32_dpp v148, v148, v148 quad_perm:[2,3,0,1] row_mask:0xf bank_mask:0xf
	s_nop 1
	v_add_f32_dpp v148, v148, v148 row_half_mirror row_mask:0xf bank_mask:0xf
	s_nop 1
	v_add_f32_dpp v148, v148, v148 row_mirror row_mask:0xf bank_mask:0xf
	ds_bpermute_b32 v153, v175, v148
	s_waitcnt lgkmcnt(0)
	v_add_f32_e32 v148, v148, v153
	ds_bpermute_b32 v153, v176, v148
	s_waitcnt lgkmcnt(0)
	v_add_f32_e32 v148, v148, v153
	v_fmamk_f32 v148, v148, 0x3a800000, v211
	s_nop 0
	v_rsq_f32_e32 v148, v148
	s_waitcnt vmcnt(4)
	v_mul_f32_e32 v98, v98, v148
	v_mul_f32_e32 v99, v99, v148
	v_mul_f32_e32 v100, v100, v148
	v_mul_f32_e32 v101, v101, v148
	v_mul_f32_e32 v102, v102, v148
	v_mul_f32_e32 v103, v103, v148
	v_mul_f32_e32 v104, v104, v148
	v_mul_f32_e32 v105, v105, v148
	v_mul_f32_e32 v106, v106, v148
	v_mul_f32_e32 v107, v107, v148
	v_mul_f32_e32 v108, v108, v148
	v_mul_f32_e32 v109, v109, v148
	v_mul_f32_e32 v110, v110, v148
	v_mul_f32_e32 v111, v111, v148
	v_mul_f32_e32 v112, v112, v148
	v_mul_f32_e32 v113, v113, v148
	v_mul_f32_e32 v98, v98, v178
	v_mul_f32_e32 v99, v99, v179
	v_mul_f32_e32 v100, v100, v180
	v_mul_f32_e32 v101, v101, v181
	v_mul_f32_e32 v102, v102, v182
	v_mul_f32_e32 v103, v103, v183
	v_mul_f32_e32 v104, v104, v184
	v_mul_f32_e32 v105, v105, v185
	v_mul_f32_e32 v106, v106, v186
	v_mul_f32_e32 v107, v107, v187
	v_mul_f32_e32 v108, v108, v188
	v_mul_f32_e32 v109, v109, v189
	v_mul_f32_e32 v110, v110, v190
	v_mul_f32_e32 v111, v111, v191
	v_mul_f32_e32 v112, v112, v192
	v_mul_f32_e32 v113, v113, v193
	v_add_f32_e32 v130, 1.0, v130
	v_add_f32_e32 v131, 1.0, v131
	v_add_f32_e32 v132, 1.0, v132
	v_add_f32_e32 v133, 1.0, v133
	v_add_f32_e32 v134, 1.0, v134
	v_add_f32_e32 v135, 1.0, v135
	v_add_f32_e32 v136, 1.0, v136
	v_add_f32_e32 v137, 1.0, v137
	v_add_f32_e32 v138, 1.0, v138
	v_add_f32_e32 v139, 1.0, v139
	v_add_f32_e32 v140, 1.0, v140
	v_add_f32_e32 v141, 1.0, v141
	v_add_f32_e32 v142, 1.0, v142
	v_add_f32_e32 v143, 1.0, v143
	v_add_f32_e32 v144, 1.0, v144
	v_add_f32_e32 v145, 1.0, v145
	v_fma_f32 v98, v98, v130, v114
	v_fma_f32 v99, v99, v131, v115
	v_fma_f32 v100, v100, v132, v116
	v_fma_f32 v101, v101, v133, v117
	v_fma_f32 v102, v102, v134, v118
	v_fma_f32 v103, v103, v135, v119
	v_fma_f32 v104, v104, v136, v120
	v_fma_f32 v105, v105, v137, v121
	v_fma_f32 v106, v106, v138, v122
	v_fma_f32 v107, v107, v139, v123
	v_fma_f32 v108, v108, v140, v124
	v_fma_f32 v109, v109, v141, v125
	v_fma_f32 v110, v110, v142, v126
	v_fma_f32 v111, v111, v143, v127
	v_fma_f32 v112, v112, v144, v128
	v_fma_f32 v113, v113, v145, v129
	v_cvt_pk_bf16_f32 v114, v98, v99
	v_cvt_pk_bf16_f32 v115, v100, v101
	v_cvt_pk_bf16_f32 v116, v102, v103
	v_cvt_pk_bf16_f32 v117, v104, v105
	v_cvt_pk_bf16_f32 v118, v106, v107
	v_cvt_pk_bf16_f32 v119, v108, v109
	v_cvt_pk_bf16_f32 v120, v110, v111
	v_cvt_pk_bf16_f32 v121, v112, v113
	s_add_u32 s40, s9, 20
	s_mul_i32 s42, s40, 0x880
	v_lshl_add_u32 v160, v162, 5, s42
	global_store_dwordx4 v160, v[114:117], s[14:15]
	global_store_dwordx4 v160, v[118:121], s[14:15] offset:16
	s_add_u32 s40, s9, 24
	s_lshl_b32 s41, s40, 12
	v_add_u32_e32 v150, s41, v173
	global_load_dwordx4 v[2:5], v150, s[0:1] offset:0
	global_load_dwordx4 v[6:9], v150, s[0:1] offset:16
	global_load_dwordx4 v[10:13], v150, s[0:1] offset:32
	global_load_dwordx4 v[14:17], v150, s[0:1] offset:48
	s_lshr_b32 s42, s40, 13
	s_min_u32 s42, s42, 2
	s_mul_i32 s42, s42, 0x6000
	v_add_u32_e32 v160, s42, v173
	global_load_dwordx4 v[18:21], v160, s[16:17] offset:0
	global_load_dwordx4 v[22:25], v160, s[16:17] offset:16
	global_load_dwordx4 v[26:29], v160, s[16:17] offset:32
	global_load_dwordx4 v[30:33], v160, s[16:17] offset:48
	v_add_u32_e32 v159, 0x1000, v160
	global_load_dwordx4 v[34:37], v159, s[16:17] offset:0
	global_load_dwordx4 v[38:41], v159, s[16:17] offset:16
	global_load_dwordx4 v[42:45], v159, s[16:17] offset:32
	global_load_dwordx4 v[46:49], v159, s[16:17] offset:48
	ds_read_b32 v146, v171 offset:1536
	s_add_u32 s40, s9, 28
	s_lshl_b32 s41, s40, 12
	v_add_u32_e32 v151, s41, v173
	global_load_dwordx4 v[50:53], v151, s[0:1] offset:0
	global_load_dwordx4 v[54:57], v151, s[0:1] offset:16
	global_load_dwordx4 v[58:61], v151, s[0:1] offset:32
	global_load_dwordx4 v[62:65], v151, s[0:1] offset:48
	s_lshr_b32 s42, s40, 13
	s_min_u32 s42, s42, 2
	s_mul_i32 s42, s42, 0x6000
	v_add_u32_e32 v160, s42, v173
	global_load_dwordx4 v[66:69], v160, s[16:17] offset:0
	global_load_dwordx4 v[70:73], v160, s[16:17] offset:16
	global_load_dwordx4 v[74:77], v160, s[16:17] offset:32
	global_load_dwordx4 v[78:81], v160, s[16:17] offset:48
	v_add_u32_e32 v159, 0x1000, v160
	global_load_dwordx4 v[82:85], v159, s[16:17] offset:0
	global_load_dwordx4 v[86:89], v159, s[16:17] offset:16
	global_load_dwordx4 v[90:93], v159, s[16:17] offset:32
	global_load_dwordx4 v[94:97], v159, s[16:17] offset:48
	ds_read_b32 v147, v171 offset:1792
	s_add_u32 s40, s9, 32
	s_lshl_b32 s41, s40, 12
	v_add_u32_e32 v152, s41, v173
	global_load_dwordx4 v[98:101], v152, s[0:1] offset:0
	global_load_dwordx4 v[102:105], v152, s[0:1] offset:16
	global_load_dwordx4 v[106:109], v152, s[0:1] offset:32
	global_load_dwordx4 v[110:113], v152, s[0:1] offset:48
	s_lshr_b32 s42, s40, 13
	s_min_u32 s42, s42, 2
	s_mul_i32 s42, s42, 0x6000
	v_add_u32_e32 v160, s42, v173
	global_load_dwordx4 v[114:117], v160, s[16:17] offset:0
	global_load_dwordx4 v[118:121], v160, s[16:17] offset:16
	global_load_dwordx4 v[122:125], v160, s[16:17] offset:32
	global_load_dwordx4 v[126:129], v160, s[16:17] offset:48
	v_add_u32_e32 v159, 0x1000, v160
	global_load_dwordx4 v[130:133], v159, s[16:17] offset:0
	global_load_dwordx4 v[134:137], v159, s[16:17] offset:16
	global_load_dwordx4 v[138:141], v159, s[16:17] offset:32
	global_load_dwordx4 v[142:145], v159, s[16:17] offset:48
	ds_read_b32 v148, v171 offset:2048
	s_waitcnt lgkmcnt(0)
; DEV unsigned pack2(float a, float b) { f32x2 v = {a, b}; return __builtin_bit_cast(unsigned, __builtin_convertvector(v, bf2_t)); }
; DEV void phase_peer_expert(const Params& p, int layer, int M, bool final_, int part, char* smem) {
;     ...
;       ss = wave_sum(ss);
;       const float rinv = rsqrtf(ss * (1.f / 1024.f) + 1e-6f);
;       const float* ng = p.in[I_N1G] + (layer + 1) * 1024;
;       const float* nmod = WSP(float, S_MOD) + (size_t)(layer + 1) * 3 * 6144 + (size_t)mr * 6144;
;       unsigned hv[8];
; #pragma unroll
;       for (int q = 0; q < 4; q++) {
;         float4 g4 = *(const float4*)(ng + col + q * 4), sh = *(const float4*)(nmod + col + q * 4), sc = *(const float4*)(nmod + 1024 + col + q * 4);
;         hv[q * 2 + 0] = pack2(xn[q * 4 + 0] * rinv * g4.x * (1.f + sc.x) + sh.x, xn[q * 4 + 1] * rinv * g4.y * (1.f + sc.y) + sh.y);
;         hv[q * 2 + 1] = pack2(xn[q * 4 + 2] * rinv * g4.z * (1.f + sc.z) + sh.z, xn[q * 4 + 3] * rinv * g4.w * (1.f + sc.w) + sh.w);
;       }
;       bf16_t* hw = WSP(bf16_t, OFF_H) + (size_t)m * LDH + col;
;       *(uint4*)(hw) = make_uint4(hv[0], hv[1], hv[2], hv[3]);
;       *(uint4*)(hw + 8) = make_uint4(hv[4], hv[5], hv[6], hv[7]);
	s_nop 1
	v_add_f32_dpp v146, v146, v146 quad_perm:[1,0,3,2] row_mask:0xf bank_mask:0xf
	s_nop 1
	v_add_f32_dpp v146, v146, v146 quad_perm:[2,3,0,1] row_mask:0xf bank_mask:0xf
	s_nop 1
	v_add_f32_dpp v146, v146, v146 row_half_mirror row_mask:0xf bank_mask:0xf
	s_nop 1
	v_add_f32_dpp v146, v146, v146 row_mirror row_mask:0xf bank_mask:0xf
	ds_bpermute_b32 v153, v175, v146
	s_waitcnt lgkmcnt(0)
	v_add_f32_e32 v146, v146, v153
	ds_bpermute_b32 v153, v176, v146
	s_waitcnt lgkmcnt(0)
	v_add_f32_e32 v146, v146, v153
	v_fmamk_f32 v146, v146, 0x3a800000, v211
	s_nop 0
	v_rsq_f32_e32 v146, v146
	s_waitcnt vmcnt(24)
	v_mul_f32_e32 v2, v2, v146
	v_mul_f32_e32 v3, v3, v146
	v_mul_f32_e32 v4, v4, v146
	v_mul_f32_e32 v5, v5, v146
	v_mul_f32_e32 v6, v6, v146
	v_mul_f32_e32 v7, v7, v146
	v_mul_f32_e32 v8, v8, v146
	v_mul_f32_e32 v9, v9, v146
	v_mul_f32_e32 v10, v10, v146
	v_mul_f32_e32 v11, v11, v146
	v_mul_f32_e32 v12, v12, v146
	v_mul_f32_e32 v13, v13, v146
	v_mul_f32_e32 v14, v14, v146
	v_mul_f32_e32 v15, v15, v146
	v_mul_f32_e32 v16, v16, v146
	v_mul_f32_e32 v17, v17, v146
	v_mul_f32_e32 v2, v2, v178
	v_mul_f32_e32 v3, v3, v179
	v_mul_f32_e32 v4, v4, v180
	v_mul_f32_e32 v5, v5, v181
	v_mul_f32_e32 v6, v6, v182
	v_mul_f32_e32 v7, v7, v183
	v_mul_f32_e32 v8, v8, v184
	v_mul_f32_e32 v9, v9, v185
	v_mul_f32_e32 v10, v10, v186
	v_mul_f32_e32 v11, v11, v187
	v_mul_f32_e32 v12, v12, v188
	v_mul_f32_e32 v13, v13, v189
	v_mul_f32_e32 v14, v14, v190
	v_mul_f32_e32 v15, v15, v191
	v_mul_f32_e32 v16, v16, v192
	v_mul_f32_e32 v17, v17, v193
	v_add_f32_e32 v34, 1.0, v34
	v_add_f32_e32 v35, 1.0, v35
	v_add_f32_e32 v36, 1.0, v36
	v_add_f32_e32 v37, 1.0, v37
	v_add_f32_e32 v38, 1.0, v38
	v_add_f32_e32 v39, 1.0, v39
	v_add_f32_e32 v40, 1.0, v40
	v_add_f32_e32 v41, 1.0, v41
	v_add_f32_e32 v42, 1.0, v42
	v_add_f32_e32 v43, 1.0, v43
	v_add_f32_e32 v44, 1.0, v44
	v_add_f32_e32 v45, 1.0, v45
	v_add_f32_e32 v46, 1.0, v46
	v_add_f32_e32 v47, 1.0, v47
	v_add_f32_e32 v48, 1.0, v48
	v_add_f32_e32 v49, 1.0, v49
	v_fma_f32 v2, v2, v34, v18
	v_fma_f32 v3, v3, v35, v19
	v_fma_f32 v4, v4, v36, v20
	v_fma_f32 v5, v5, v37, v21
	v_fma_f32 v6, v6, v38, v22
	v_fma_f32 v7, v7, v39, v23
	v_fma_f32 v8, v8, v40, v24
	v_fma_f32 v9, v9, v41, v25
	v_fma_f32 v10, v10, v42, v26
	v_fma_f32 v11, v11, v43, v27
	v_fma_f32 v12, v12, v44, v28
	v_fma_f32 v13, v13, v45, v29
	v_fma_f32 v14, v14, v46, v30
	v_fma_f32 v15, v15, v47, v31
	v_fma_f32 v16, v16, v48, v32
	v_fma_f32 v17, v17, v49, v33
	v_cvt_pk_bf16_f32 v18, v2, v3
	v_cvt_pk_bf16_f32 v19, v4, v5
	v_cvt_pk_bf16_f32 v20, v6, v7
	v_cvt_pk_bf16_f32 v21, v8, v9
	v_cvt_pk_bf16_f32 v22, v10, v11
	v_cvt_pk_bf16_f32 v23, v12, v13
	v_cvt_pk_bf16_f32 v24, v14, v15
	v_cvt_pk_bf16_f32 v25, v16, v17
	s_add_u32 s40, s9, 24
	s_mul_i32 s42, s40, 0x880
	v_lshl_add_u32 v160, v162, 5, s42
	global_store_dwordx4 v160, v[18:21], s[14:15]
	global_store_dwordx4 v160, v[22:25], s[14:15] offset:16
	s_waitcnt lgkmcnt(0)
	s_nop 1
	v_add_f32_dpp v147, v147, v147 quad_perm:[1,0,3,2] row_mask:0xf bank_mask:0xf
	s_nop 1
	v_add_f32_dpp v147, v147, v147 quad_perm:[2,3,0,1] row_mask:0xf bank_mask:0xf
	s_nop 1
	v_add_f32_dpp v147, v147, v147 row_half_mirror row_mask:0xf bank_mask:0xf
	s_nop 1
	v_add_f32_dpp v147, v147, v147 row_mirror row_mask:0xf bank_mask:0xf
	ds_bpermute_b32 v153, v175, v147
	s_waitcnt lgkmcnt(0)
	v_add_f32_e32 v147, v147, v153
	ds_bpermute_b32 v153, v176, v147
	s_waitcnt lgkmcnt(0)
	v_add_f32_e32 v147, v147, v153
	v_fmamk_f32 v147, v147, 0x3a800000, v211
	s_nop 0
	v_rsq_f32_e32 v147, v147
	s_waitcnt vmcnt(14)
	v_mul_f32_e32 v50, v50, v147
	v_mul_f32_e32 v51, v51, v147
	v_mul_f32_e32 v52, v52, v147
	v_mul_f32_e32 v53, v53, v147
	v_mul_f32_e32 v54, v54, v147
	v_mul_f32_e32 v55, v55, v147
	v_mul_f32_e32 v56, v56, v147
	v_mul_f32_e32 v57, v57, v147
	v_mul_f32_e32 v58, v58, v147
	v_mul_f32_e32 v59, v59, v147
	v_mul_f32_e32 v60, v60, v147
	v_mul_f32_e32 v61, v61, v147
	v_mul_f32_e32 v62, v62, v147
	v_mul_f32_e32 v63, v63, v147
	v_mul_f32_e32 v64, v64, v147
	v_mul_f32_e32 v65, v65, v147
	v_mul_f32_e32 v50, v50, v178
	v_mul_f32_e32 v51, v51, v179
	v_mul_f32_e32 v52, v52, v180
	v_mul_f32_e32 v53, v53, v181
	v_mul_f32_e32 v54, v54, v182
	v_mul_f32_e32 v55, v55, v183
	v_mul_f32_e32 v56, v56, v184
	v_mul_f32_e32 v57, v57, v185
	v_mul_f32_e32 v58, v58, v186
	v_mul_f32_e32 v59, v59, v187
	v_mul_f32_e32 v60, v60, v188
	v_mul_f32_e32 v61, v61, v189
	v_mul_f32_e32 v62, v62, v190
	v_mul_f32_e32 v63, v63, v191
	v_mul_f32_e32 v64, v64, v192
	v_mul_f32_e32 v65, v65, v193
	v_add_f32_e32 v82, 1.0, v82
	v_add_f32_e32 v83, 1.0, v83
	v_add_f32_e32 v84, 1.0, v84
	v_add_f32_e32 v85, 1.0, v85
	v_add_f32_e32 v86, 1.0, v86
	v_add_f32_e32 v87, 1.0, v87
	v_add_f32_e32 v88, 1.0, v88
	v_add_f32_e32 v89, 1.0, v89
	v_add_f32_e32 v90, 1.0, v90
	v_add_f32_e32 v91, 1.0, v91
	v_add_f32_e32 v92, 1.0, v92
	v_add_f32_e32 v93, 1.0, v93
	v_add_f32_e32 v94, 1.0, v94
	v_add_f32_e32 v95, 1.0, v95
	v_add_f32_e32 v96, 1.0, v96
	v_add_f32_e32 v97, 1.0, v97
	v_fma_f32 v50, v50, v82, v66
	v_fma_f32 v51, v51, v83, v67
	v_fma_f32 v52, v52, v84, v68
	v_fma_f32 v53, v53, v85, v69
	v_fma_f32 v54, v54, v86, v70
	v_fma_f32 v55, v55, v87, v71
	v_fma_f32 v56, v56, v88, v72
	v_fma_f32 v57, v57, v89, v73
	v_fma_f32 v58, v58, v90, v74
	v_fma_f32 v59, v59, v91, v75
	v_fma_f32 v60, v60, v92, v76
	v_fma_f32 v61, v61, v93, v77
	v_fma_f32 v62, v62, v94, v78
	v_fma_f32 v63, v63, v95, v79
	v_fma_f32 v64, v64, v96, v80
	v_fma_f32 v65, v65, v97, v81
	v_cvt_pk_bf16_f32 v66, v50, v51
	v_cvt_pk_bf16_f32 v67, v52, v53
	v_cvt_pk_bf16_f32 v68, v54, v55
	v_cvt_pk_bf16_f32 v69, v56, v57
	v_cvt_pk_bf16_f32 v70, v58, v59
	v_cvt_pk_bf16_f32 v71, v60, v61
	v_cvt_pk_bf16_f32 v72, v62, v63
	v_cvt_pk_bf16_f32 v73, v64, v65
	s_add_u32 s40, s9, 28
	s_mul_i32 s42, s40, 0x880
	v_lshl_add_u32 v160, v162, 5, s42
	global_store_dwordx4 v160, v[66:69], s[14:15]
	global_store_dwordx4 v160, v[70:73], s[14:15] offset:16
	s_cmp_lt_u32 s8, 9
	s_cbranch_scc1 .Lv_tail_done
; DEV unsigned pack2(float a, float b) { f32x2 v = {a, b}; return __builtin_bit_cast(unsigned, __builtin_convertvector(v, bf2_t)); }
; DEV void phase_peer_expert(const Params& p, int layer, int M, bool final_, int part, char* smem) {
;     ...
;       ss = wave_sum(ss);
;       const float rinv = rsqrtf(ss * (1.f / 1024.f) + 1e-6f);
;       const float* ng = p.in[I_N1G] + (layer + 1) * 1024;
;       const float* nmod = WSP(float, S_MOD) + (size_t)(layer + 1) * 3 * 6144 + (size_t)mr * 6144;
;       unsigned hv[8];
; #pragma unroll
;       for (int q = 0; q < 4; q++) {
;         float4 g4 = *(const float4*)(ng + col + q * 4), sh = *(const float4*)(nmod + col + q * 4), sc = *(const float4*)(nmod + 1024 + col + q * 4);
;         hv[q * 2 + 0] = pack2(xn[q * 4 + 0] * rinv * g4.x * (1.f + sc.x) + sh.x, xn[q * 4 + 1] * rinv * g4.y * (1.f + sc.y) + sh.y);
;         hv[q * 2 + 1] = pack2(xn[q * 4 + 2] * rinv * g4.z * (1.f + sc.z) + sh.z, xn[q * 4 + 3] * rinv * g4.w * (1.f + sc.w) + sh.w);
;       }
;       bf16_t* hw = WSP(bf16_t, OFF_H) + (size_t)m * LDH + col;
;       *(uint4*)(hw) = make_uint4(hv[0], hv[1], hv[2], hv[3]);
;       *(uint4*)(hw + 8) = make_uint4(hv[4], hv[5], hv[6], hv[7]);
;     } else {
;       ss = wave_sum(ss);
;       const float rinv = rsqrtf(ss * (1.f / 1024.f) + 1e-6f);
;       const float* fg = p.in[I_FNG];
; #pragma unroll
;       for (int q = 0; q < 4; q++) {
;         float4 g4 = *(const float4*)(fg + col + q * 4);
;         *(float4*)(p.out + (size_t)m * 1024 + col + q * 4) = make_float4(xn[q * 4 + 0] * rinv * g4.x, xn[q * 4 + 1] * rinv * g4.y, xn[q * 4 + 2] * rinv * g4.z, xn[q * 4 + 3] * rinv * g4.w);
;       }
	s_waitcnt lgkmcnt(0)
	s_nop 1
	v_add_f32_dpp v148, v148, v148 quad_perm:[1,0,3,2] row_mask:0xf bank_mask:0xf
	s_nop 1
	v_add_f32_dpp v148, v148, v148 quad_perm:[2,3,0,1] row_mask:0xf bank_mask:0xf
	s_nop 1
	v_add_f32_dpp v148, v148, v148 row_half_mirror row_mask:0xf bank_mask:0xf
	s_nop 1
	v_add_f32_dpp v148, v148, v148 row_mirror row_mask:0xf bank_mask:0xf
	ds_bpermute_b32 v153, v175, v148
	s_waitcnt lgkmcnt(0)
	v_add_f32_e32 v148, v148, v153
	ds_bpermute_b32 v153, v176, v148
	s_waitcnt lgkmcnt(0)
	v_add_f32_e32 v148, v148, v153
	v_fmamk_f32 v148, v148, 0x3a800000, v211
	s_nop 0
	v_rsq_f32_e32 v148, v148
	s_waitcnt vmcnt(4)
	v_mul_f32_e32 v98, v98, v148
	v_mul_f32_e32 v99, v99, v148
	v_mul_f32_e32 v100, v100, v148
	v_mul_f32_e32 v101, v101, v148
	v_mul_f32_e32 v102, v102, v148
	v_mul_f32_e32 v103, v103, v148
	v_mul_f32_e32 v104, v104, v148
	v_mul_f32_e32 v105, v105, v148
	v_mul_f32_e32 v106, v106, v148
	v_mul_f32_e32 v107, v107, v148
	v_mul_f32_e32 v108, v108, v148
	v_mul_f32_e32 v109, v109, v148
	v_mul_f32_e32 v110, v110, v148
	v_mul_f32_e32 v111, v111, v148
	v_mul_f32_e32 v112, v112, v148
	v_mul_f32_e32 v113, v113, v148
	v_mul_f32_e32 v98, v98, v178
	v_mul_f32_e32 v99, v99, v179
	v_mul_f32_e32 v100, v100, v180
	v_mul_f32_e32 v101, v101, v181
	v_mul_f32_e32 v102, v102, v182
	v_mul_f32_e32 v103, v103, v183
	v_mul_f32_e32 v104, v104, v184
	v_mul_f32_e32 v105, v105, v185
	v_mul_f32_e32 v106, v106, v186
	v_mul_f32_e32 v107, v107, v187
	v_mul_f32_e32 v108, v108, v188
	v_mul_f32_e32 v109, v109, v189
	v_mul_f32_e32 v110, v110, v190
	v_mul_f32_e32 v111, v111, v191
	v_mul_f32_e32 v112, v112, v192
	v_mul_f32_e32 v113, v113, v193
	v_add_f32_e32 v130, 1.0, v130
	v_add_f32_e32 v131, 1.0, v131
	v_add_f32_e32 v132, 1.0, v132
	v_add_f32_e32 v133, 1.0, v133
	v_add_f32_e32 v134, 1.0, v134
	v_add_f32_e32 v135, 1.0, v135
	v_add_f32_e32 v136, 1.0, v136
	v_add_f32_e32 v137, 1.0, v137
	v_add_f32_e32 v138, 1.0, v138
	v_add_f32_e32 v139, 1.0, v139
	v_add_f32_e32 v140, 1.0, v140
	v_add_f32_e32 v141, 1.0, v141
	v_add_f32_e32 v142, 1.0, v142
	v_add_f32_e32 v143, 1.0, v143
	v_add_f32_e32 v144, 1.0, v144
	v_add_f32_e32 v145, 1.0, v145
	v_fma_f32 v98, v98, v130, v114
	v_fma_f32 v99, v99, v131, v115
	v_fma_f32 v100, v100, v132, v116
	v_fma_f32 v101, v101, v133, v117
	v_fma_f32 v102, v102, v134, v118
	v_fma_f32 v103, v103, v135, v119
	v_fma_f32 v104, v104, v136, v120
	v_fma_f32 v105, v105, v137, v121
	v_fma_f32 v106, v106, v138, v122
	v_fma_f32 v107, v107, v139, v123
	v_fma_f32 v108, v108, v140, v124
	v_fma_f32 v109, v109, v141, v125
	v_fma_f32 v110, v110, v142, v126
	v_fma_f32 v111, v111, v143, v127
	v_fma_f32 v112, v112, v144, v128
	v_fma_f32 v113, v113, v145, v129
	v_cvt_pk_bf16_f32 v114, v98, v99
	v_cvt_pk_bf16_f32 v115, v100, v101
	v_cvt_pk_bf16_f32 v116, v102, v103
	v_cvt_pk_bf16_f32 v117, v104, v105
	v_cvt_pk_bf16_f32 v118, v106, v107
	v_cvt_pk_bf16_f32 v119, v108, v109
	v_cvt_pk_bf16_f32 v120, v110, v111
	v_cvt_pk_bf16_f32 v121, v112, v113
	s_add_u32 s40, s9, 32
	s_mul_i32 s42, s40, 0x880
	v_lshl_add_u32 v160, v162, 5, s42
	global_store_dwordx4 v160, v[114:117], s[14:15]
	global_store_dwordx4 v160, v[118:121], s[14:15] offset:16
	s_branch .Lv_tail_done
.Lv_tail_final:
	global_load_dwordx4 v[178:181], v173, s[12:13] offset:0
	global_load_dwordx4 v[182:185], v173, s[12:13] offset:16
	global_load_dwordx4 v[186:189], v173, s[12:13] offset:32
	global_load_dwordx4 v[190:193], v173, s[12:13] offset:48
	s_add_u32 s40, s9, 0
	s_lshl_b32 s41, s40, 12
	v_add_u32_e32 v150, s41, v173
	global_load_dwordx4 v[2:5], v150, s[0:1] offset:0
	global_load_dwordx4 v[6:9], v150, s[0:1] offset:16
	global_load_dwordx4 v[10:13], v150, s[0:1] offset:32
	global_load_dwordx4 v[14:17], v150, s[0:1] offset:48
	ds_read_b32 v146, v171 offset:0
	s_add_u32 s40, s9, 4
	s_lshl_b32 s41, s40, 12
	v_add_u32_e32 v151, s41, v173
	global_load_dwordx4 v[50:53], v151, s[0:1] offset:0
	global_load_dwordx4 v[54:57], v151, s[0:1] offset:16
	global_load_dwordx4 v[58:61], v151, s[0:1] offset:32
	global_load_dwordx4 v[62:65], v151, s[0:1] offset:48
	ds_read_b32 v147, v171 offset:256
	s_add_u32 s40, s9, 8
	s_lshl_b32 s41, s40, 12
	v_add_u32_e32 v152, s41, v173
	global_load_dwordx4 v[98:101], v152, s[0:1] offset:0
	global_load_dwordx4 v[102:105], v152, s[0:1] offset:16
	global_load_dwordx4 v[106:109], v152, s[0:1] offset:32
	global_load_dwordx4 v[110:113], v152, s[0:1] offset:48
	ds_read_b32 v148, v171 offset:512
	s_waitcnt lgkmcnt(0)
	s_nop 1
	v_add_f32_dpp v146, v146, v146 quad_perm:[1,0,3,2] row_mask:0xf bank_mask:0xf
	s_nop 1
	v_add_f32_dpp v146, v146, v146 quad_perm:[2,3,0,1] row_mask:0xf bank_mask:0xf
	s_nop 1
	v_add_f32_dpp v146, v146, v146 row_half_mirror row_mask:0xf bank_mask:0xf
	s_nop 1
	v_add_f32_dpp v146, v146, v146 row_mirror row_mask:0xf bank_mask:0xf
	ds_bpermute_b32 v153, v175, v146
	s_waitcnt lgkmcnt(0)
	v_add_f32_e32 v146, v146, v153
	ds_bpermute_b32 v153, v176, v146
	s_waitcnt lgkmcnt(0)
	v_add_f32_e32 v146, v146, v153
	v_fmamk_f32 v146, v146, 0x3a800000, v211
	s_nop 0
	v_rsq_f32_e32 v146, v146
	s_waitcnt vmcnt(8)
	v_mul_f32_e32 v2, v2, v146
	v_mul_f32_e32 v3, v3, v146
	v_mul_f32_e32 v4, v4, v146
	v_mul_f32_e32 v5, v5, v146
	v_mul_f32_e32 v6, v6, v146
	v_mul_f32_e32 v7, v7, v146
	v_mul_f32_e32 v8, v8, v146
	v_mul_f32_e32 v9, v9, v146
	v_mul_f32_e32 v10, v10, v146
	v_mul_f32_e32 v11, v11, v146
	v_mul_f32_e32 v12, v12, v146
	v_mul_f32_e32 v13, v13, v146
	v_mul_f32_e32 v14, v14, v146
	v_mul_f32_e32 v15, v15, v146
	v_mul_f32_e32 v16, v16, v146
	v_mul_f32_e32 v17, v17, v146
	v_mul_f32_e32 v2, v2, v178
	v_mul_f32_e32 v3, v3, v179
	v_mul_f32_e32 v4, v4, v180
	v_mul_f32_e32 v5, v5, v181
	v_mul_f32_e32 v6, v6, v182
	v_mul_f32_e32 v7, v7, v183
	v_mul_f32_e32 v8, v8, v184
	v_mul_f32_e32 v9, v9, v185
	v_mul_f32_e32 v10, v10, v186
	v_mul_f32_e32 v11, v11, v187
	v_mul_f32_e32 v12, v12, v188
	v_mul_f32_e32 v13, v13, v189
	v_mul_f32_e32 v14, v14, v190
	v_mul_f32_e32 v15, v15, v191
	v_mul_f32_e32 v16, v16, v192
	v_mul_f32_e32 v17, v17, v193
	global_store_dwordx4 v150, v[2:5], s[2:3] offset:0
	global_store_dwordx4 v150, v[6:9], s[2:3] offset:16
	global_store_dwordx4 v150, v[10:13], s[2:3] offset:32
	global_store_dwordx4 v150, v[14:17], s[2:3] offset:48
	s_waitcnt lgkmcnt(0)
; DEV void phase_peer_expert(const Params& p, int layer, int M, bool final_, int part, char* smem) {
;     ...
;     } else {
;       ss = wave_sum(ss);
;       const float rinv = rsqrtf(ss * (1.f / 1024.f) + 1e-6f);
;       const float* fg = p.in[I_FNG];
; #pragma unroll
;       for (int q = 0; q < 4; q++) {
;         float4 g4 = *(const float4*)(fg + col + q * 4);
;         *(float4*)(p.out + (size_t)m * 1024 + col + q * 4) = make_float4(xn[q * 4 + 0] * rinv * g4.x, xn[q * 4 + 1] * rinv * g4.y, xn[q * 4 + 2] * rinv * g4.z, xn[q * 4 + 3] * rinv * g4.w);
;       }
	s_nop 1
	v_add_f32_dpp v147, v147, v147 quad_perm:[1,0,3,2] row_mask:0xf bank_mask:0xf
	s_nop 1
	v_add_f32_dpp v147, v147, v147 quad_perm:[2,3,0,1] row_mask:0xf bank_mask:0xf
	s_nop 1
	v_add_f32_dpp v147, v147, v147 row_half_mirror row_mask:0xf bank_mask:0xf
	s_nop 1
	v_add_f32_dpp v147, v147, v147 row_mirror row_mask:0xf bank_mask:0xf
	ds_bpermute_b32 v153, v175, v147
	s_waitcnt lgkmcnt(0)
	v_add_f32_e32 v147, v147, v153
	ds_bpermute_b32 v153, v176, v147
	s_waitcnt lgkmcnt(0)
	v_add_f32_e32 v147, v147, v153
	v_fmamk_f32 v147, v147, 0x3a800000, v211
	s_nop 0
	v_rsq_f32_e32 v147, v147
	s_waitcnt vmcnt(8)
	v_mul_f32_e32 v50, v50, v147
	v_mul_f32_e32 v51, v51, v147
	v_mul_f32_e32 v52, v52, v147
	v_mul_f32_e32 v53, v53, v147
	v_mul_f32_e32 v54, v54, v147
	v_mul_f32_e32 v55, v55, v147
	v_mul_f32_e32 v56, v56, v147
	v_mul_f32_e32 v57, v57, v147
	v_mul_f32_e32 v58, v58, v147
	v_mul_f32_e32 v59, v59, v147
	v_mul_f32_e32 v60, v60, v147
	v_mul_f32_e32 v61, v61, v147
	v_mul_f32_e32 v62, v62, v147
	v_mul_f32_e32 v63, v63, v147
	v_mul_f32_e32 v64, v64, v147
	v_mul_f32_e32 v65, v65, v147
	v_mul_f32_e32 v50, v50, v178
	v_mul_f32_e32 v51, v51, v179
	v_mul_f32_e32 v52, v52, v180
	v_mul_f32_e32 v53, v53, v181
	v_mul_f32_e32 v54, v54, v182
	v_mul_f32_e32 v55, v55, v183
	v_mul_f32_e32 v56, v56, v184
	v_mul_f32_e32 v57, v57, v185
	v_mul_f32_e32 v58, v58, v186
	v_mul_f32_e32 v59, v59, v187
	v_mul_f32_e32 v60, v60, v188
	v_mul_f32_e32 v61, v61, v189
	v_mul_f32_e32 v62, v62, v190
	v_mul_f32_e32 v63, v63, v191
	v_mul_f32_e32 v64, v64, v192
	v_mul_f32_e32 v65, v65, v193
	global_store_dwordx4 v151, v[50:53], s[2:3] offset:0
	global_store_dwordx4 v151, v[54:57], s[2:3] offset:16
	global_store_dwordx4 v151, v[58:61], s[2:3] offset:32
	global_store_dwordx4 v151, v[62:65], s[2:3] offset:48
	s_waitcnt lgkmcnt(0)
	s_nop 1
	v_add_f32_dpp v148, v148, v148 quad_perm:[1,0,3,2] row_mask:0xf bank_mask:0xf
	s_nop 1
	v_add_f32_dpp v148, v148, v148 quad_perm:[2,3,0,1] row_mask:0xf bank_mask:0xf
	s_nop 1
	v_add_f32_dpp v148, v148, v148 row_half_mirror row_mask:0xf bank_mask:0xf
	s_nop 1
	v_add_f32_dpp v148, v148, v148 row_mirror row_mask:0xf bank_mask:0xf
	ds_bpermute_b32 v153, v175, v148
	s_waitcnt lgkmcnt(0)
	v_add_f32_e32 v148, v148, v153
	ds_bpermute_b32 v153, v176, v148
	s_waitcnt lgkmcnt(0)
	v_add_f32_e32 v148, v148, v153
	v_fmamk_f32 v148, v148, 0x3a800000, v211
	s_nop 0
	v_rsq_f32_e32 v148, v148
	s_waitcnt vmcnt(8)
	v_mul_f32_e32 v98, v98, v148
	v_mul_f32_e32 v99, v99, v148
	v_mul_f32_e32 v100, v100, v148
	v_mul_f32_e32 v101, v101, v148
	v_mul_f32_e32 v102, v102, v148
	v_mul_f32_e32 v103, v103, v148
	v_mul_f32_e32 v104, v104, v148
	v_mul_f32_e32 v105, v105, v148
	v_mul_f32_e32 v106, v106, v148
	v_mul_f32_e32 v107, v107, v148
	v_mul_f32_e32 v108, v108, v148
	v_mul_f32_e32 v109, v109, v148
	v_mul_f32_e32 v110, v110, v148
	v_mul_f32_e32 v111, v111, v148
	v_mul_f32_e32 v112, v112, v148
	v_mul_f32_e32 v113, v113, v148
	v_mul_f32_e32 v98, v98, v178
	v_mul_f32_e32 v99, v99, v179
	v_mul_f32_e32 v100, v100, v180
	v_mul_f32_e32 v101, v101, v181
	v_mul_f32_e32 v102, v102, v182
	v_mul_f32_e32 v103, v103, v183
	v_mul_f32_e32 v104, v104, v184
	v_mul_f32_e32 v105, v105, v185
	v_mul_f32_e32 v106, v106, v186
	v_mul_f32_e32 v107, v107, v187
	v_mul_f32_e32 v108, v108, v188
	v_mul_f32_e32 v109, v109, v189
	v_mul_f32_e32 v110, v110, v190
	v_mul_f32_e32 v111, v111, v191
	v_mul_f32_e32 v112, v112, v192
	v_mul_f32_e32 v113, v113, v193
	global_store_dwordx4 v152, v[98:101], s[2:3] offset:0
	global_store_dwordx4 v152, v[102:105], s[2:3] offset:16
	global_store_dwordx4 v152, v[106:109], s[2:3] offset:32
	global_store_dwordx4 v152, v[110:113], s[2:3] offset:48
	s_add_u32 s40, s9, 12
	s_lshl_b32 s41, s40, 12
	v_add_u32_e32 v150, s41, v173
	global_load_dwordx4 v[2:5], v150, s[0:1] offset:0
	global_load_dwordx4 v[6:9], v150, s[0:1] offset:16
	global_load_dwordx4 v[10:13], v150, s[0:1] offset:32
	global_load_dwordx4 v[14:17], v150, s[0:1] offset:48
	ds_read_b32 v146, v171 offset:768
	s_add_u32 s40, s9, 16
	s_lshl_b32 s41, s40, 12
	v_add_u32_e32 v151, s41, v173
	global_load_dwordx4 v[50:53], v151, s[0:1] offset:0
	global_load_dwordx4 v[54:57], v151, s[0:1] offset:16
	global_load_dwordx4 v[58:61], v151, s[0:1] offset:32
	global_load_dwordx4 v[62:65], v151, s[0:1] offset:48
	ds_read_b32 v147, v171 offset:1024
	s_add_u32 s40, s9, 20
	s_lshl_b32 s41, s40, 12
	v_add_u32_e32 v152, s41, v173
	global_load_dwordx4 v[98:101], v152, s[0:1] offset:0
	global_load_dwordx4 v[102:105], v152, s[0:1] offset:16
	global_load_dwordx4 v[106:109], v152, s[0:1] offset:32
	global_load_dwordx4 v[110:113], v152, s[0:1] offset:48
	ds_read_b32 v148, v171 offset:1280
	s_waitcnt lgkmcnt(0)
	s_nop 1
	v_add_f32_dpp v146, v146, v146 quad_perm:[1,0,3,2] row_mask:0xf bank_mask:0xf
	s_nop 1
	v_add_f32_dpp v146, v146, v146 quad_perm:[2,3,0,1] row_mask:0xf bank_mask:0xf
	s_nop 1
	v_add_f32_dpp v146, v146, v146 row_half_mirror row_mask:0xf bank_mask:0xf
	s_nop 1
	v_add_f32_dpp v146, v146, v146 row_mirror row_mask:0xf bank_mask:0xf
	ds_bpermute_b32 v153, v175, v146
	s_waitcnt lgkmcnt(0)
	v_add_f32_e32 v146, v146, v153
	ds_bpermute_b32 v153, v176, v146
	s_waitcnt lgkmcnt(0)
	v_add_f32_e32 v146, v146, v153
	v_fmamk_f32 v146, v146, 0x3a800000, v211
	s_nop 0
	v_rsq_f32_e32 v146, v146
	s_waitcnt vmcnt(8)
; DEV void phase_peer_expert(const Params& p, int layer, int M, bool final_, int part, char* smem) {
;     ...
;     } else {
;       ss = wave_sum(ss);
;       const float rinv = rsqrtf(ss * (1.f / 1024.f) + 1e-6f);
;       const float* fg = p.in[I_FNG];
; #pragma unroll
;       for (int q = 0; q < 4; q++) {
;         float4 g4 = *(const float4*)(fg + col + q * 4);
;         *(float4*)(p.out + (size_t)m * 1024 + col + q * 4) = make_float4(xn[q * 4 + 0] * rinv * g4.x, xn[q * 4 + 1] * rinv * g4.y, xn[q * 4 + 2] * rinv * g4.z, xn[q * 4 + 3] * rinv * g4.w);
;       }
	v_mul_f32_e32 v2, v2, v146
	v_mul_f32_e32 v3, v3, v146
	v_mul_f32_e32 v4, v4, v146
	v_mul_f32_e32 v5, v5, v146
	v_mul_f32_e32 v6, v6, v146
	v_mul_f32_e32 v7, v7, v146
	v_mul_f32_e32 v8, v8, v146
	v_mul_f32_e32 v9, v9, v146
	v_mul_f32_e32 v10, v10, v146
	v_mul_f32_e32 v11, v11, v146
	v_mul_f32_e32 v12, v12, v146
	v_mul_f32_e32 v13, v13, v146
	v_mul_f32_e32 v14, v14, v146
	v_mul_f32_e32 v15, v15, v146
	v_mul_f32_e32 v16, v16, v146
	v_mul_f32_e32 v17, v17, v146
	v_mul_f32_e32 v2, v2, v178
	v_mul_f32_e32 v3, v3, v179
	v_mul_f32_e32 v4, v4, v180
	v_mul_f32_e32 v5, v5, v181
	v_mul_f32_e32 v6, v6, v182
	v_mul_f32_e32 v7, v7, v183
	v_mul_f32_e32 v8, v8, v184
	v_mul_f32_e32 v9, v9, v185
	v_mul_f32_e32 v10, v10, v186
	v_mul_f32_e32 v11, v11, v187
	v_mul_f32_e32 v12, v12, v188
	v_mul_f32_e32 v13, v13, v189
	v_mul_f32_e32 v14, v14, v190
	v_mul_f32_e32 v15, v15, v191
	v_mul_f32_e32 v16, v16, v192
	v_mul_f32_e32 v17, v17, v193
	global_store_dwordx4 v150, v[2:5], s[2:3] offset:0
	global_store_dwordx4 v150, v[6:9], s[2:3] offset:16
	global_store_dwordx4 v150, v[10:13], s[2:3] offset:32
	global_store_dwordx4 v150, v[14:17], s[2:3] offset:48
	s_waitcnt lgkmcnt(0)
	s_nop 1
	v_add_f32_dpp v147, v147, v147 quad_perm:[1,0,3,2] row_mask:0xf bank_mask:0xf
	s_nop 1
	v_add_f32_dpp v147, v147, v147 quad_perm:[2,3,0,1] row_mask:0xf bank_mask:0xf
	s_nop 1
	v_add_f32_dpp v147, v147, v147 row_half_mirror row_mask:0xf bank_mask:0xf
	s_nop 1
	v_add_f32_dpp v147, v147, v147 row_mirror row_mask:0xf bank_mask:0xf
	ds_bpermute_b32 v153, v175, v147
	s_waitcnt lgkmcnt(0)
	v_add_f32_e32 v147, v147, v153
	ds_bpermute_b32 v153, v176, v147
	s_waitcnt lgkmcnt(0)
	v_add_f32_e32 v147, v147, v153
	v_fmamk_f32 v147, v147, 0x3a800000, v211
	s_nop 0
	v_rsq_f32_e32 v147, v147
	s_waitcnt vmcnt(8)
	v_mul_f32_e32 v50, v50, v147
	v_mul_f32_e32 v51, v51, v147
	v_mul_f32_e32 v52, v52, v147
	v_mul_f32_e32 v53, v53, v147
	v_mul_f32_e32 v54, v54, v147
	v_mul_f32_e32 v55, v55, v147
	v_mul_f32_e32 v56, v56, v147
	v_mul_f32_e32 v57, v57, v147
	v_mul_f32_e32 v58, v58, v147
	v_mul_f32_e32 v59, v59, v147
	v_mul_f32_e32 v60, v60, v147
	v_mul_f32_e32 v61, v61, v147
	v_mul_f32_e32 v62, v62, v147
	v_mul_f32_e32 v63, v63, v147
	v_mul_f32_e32 v64, v64, v147
	v_mul_f32_e32 v65, v65, v147
	v_mul_f32_e32 v50, v50, v178
	v_mul_f32_e32 v51, v51, v179
	v_mul_f32_e32 v52, v52, v180
	v_mul_f32_e32 v53, v53, v181
	v_mul_f32_e32 v54, v54, v182
	v_mul_f32_e32 v55, v55, v183
	v_mul_f32_e32 v56, v56, v184
	v_mul_f32_e32 v57, v57, v185
	v_mul_f32_e32 v58, v58, v186
	v_mul_f32_e32 v59, v59, v187
	v_mul_f32_e32 v60, v60, v188
	v_mul_f32_e32 v61, v61, v189
	v_mul_f32_e32 v62, v62, v190
	v_mul_f32_e32 v63, v63, v191
	v_mul_f32_e32 v64, v64, v192
	v_mul_f32_e32 v65, v65, v193
	global_store_dwordx4 v151, v[50:53], s[2:3] offset:0
	global_store_dwordx4 v151, v[54:57], s[2:3] offset:16
	global_store_dwordx4 v151, v[58:61], s[2:3] offset:32
	global_store_dwordx4 v151, v[62:65], s[2:3] offset:48
	s_waitcnt lgkmcnt(0)
	s_nop 1
	v_add_f32_dpp v148, v148, v148 quad_perm:[1,0,3,2] row_mask:0xf bank_mask:0xf
	s_nop 1
	v_add_f32_dpp v148, v148, v148 quad_perm:[2,3,0,1] row_mask:0xf bank_mask:0xf
	s_nop 1
	v_add_f32_dpp v148, v148, v148 row_half_mirror row_mask:0xf bank_mask:0xf
	s_nop 1
	v_add_f32_dpp v148, v148, v148 row_mirror row_mask:0xf bank_mask:0xf
	ds_bpermute_b32 v153, v175, v148
	s_waitcnt lgkmcnt(0)
	v_add_f32_e32 v148, v148, v153
	ds_bpermute_b32 v153, v176, v148
	s_waitcnt lgkmcnt(0)
	v_add_f32_e32 v148, v148, v153
	v_fmamk_f32 v148, v148, 0x3a800000, v211
	s_nop 0
	v_rsq_f32_e32 v148, v148
	s_waitcnt vmcnt(8)
	v_mul_f32_e32 v98, v98, v148
	v_mul_f32_e32 v99, v99, v148
	v_mul_f32_e32 v100, v100, v148
	v_mul_f32_e32 v101, v101, v148
	v_mul_f32_e32 v102, v102, v148
	v_mul_f32_e32 v103, v103, v148
	v_mul_f32_e32 v104, v104, v148
	v_mul_f32_e32 v105, v105, v148
	v_mul_f32_e32 v106, v106, v148
	v_mul_f32_e32 v107, v107, v148
	v_mul_f32_e32 v108, v108, v148
	v_mul_f32_e32 v109, v109, v148
	v_mul_f32_e32 v110, v110, v148
	v_mul_f32_e32 v111, v111, v148
	v_mul_f32_e32 v112, v112, v148
	v_mul_f32_e32 v113, v113, v148
	v_mul_f32_e32 v98, v98, v178
	v_mul_f32_e32 v99, v99, v179
	v_mul_f32_e32 v100, v100, v180
	v_mul_f32_e32 v101, v101, v181
	v_mul_f32_e32 v102, v102, v182
	v_mul_f32_e32 v103, v103, v183
	v_mul_f32_e32 v104, v104, v184
	v_mul_f32_e32 v105, v105, v185
	v_mul_f32_e32 v106, v106, v186
	v_mul_f32_e32 v107, v107, v187
	v_mul_f32_e32 v108, v108, v188
	v_mul_f32_e32 v109, v109, v189
	v_mul_f32_e32 v110, v110, v190
	v_mul_f32_e32 v111, v111, v191
	v_mul_f32_e32 v112, v112, v192
	v_mul_f32_e32 v113, v113, v193
	global_store_dwordx4 v152, v[98:101], s[2:3] offset:0
	global_store_dwordx4 v152, v[102:105], s[2:3] offset:16
	global_store_dwordx4 v152, v[106:109], s[2:3] offset:32
	global_store_dwordx4 v152, v[110:113], s[2:3] offset:48
	s_add_u32 s40, s9, 24
	s_lshl_b32 s41, s40, 12
	v_add_u32_e32 v150, s41, v173
	global_load_dwordx4 v[2:5], v150, s[0:1] offset:0
	global_load_dwordx4 v[6:9], v150, s[0:1] offset:16
	global_load_dwordx4 v[10:13], v150, s[0:1] offset:32
	global_load_dwordx4 v[14:17], v150, s[0:1] offset:48
	ds_read_b32 v146, v171 offset:1536
	s_add_u32 s40, s9, 28
	s_lshl_b32 s41, s40, 12
	v_add_u32_e32 v151, s41, v173
	global_load_dwordx4 v[50:53], v151, s[0:1] offset:0
	global_load_dwordx4 v[54:57], v151, s[0:1] offset:16
	global_load_dwordx4 v[58:61], v151, s[0:1] offset:32
	global_load_dwordx4 v[62:65], v151, s[0:1] offset:48
	ds_read_b32 v147, v171 offset:1792
	s_add_u32 s40, s9, 32
	s_lshl_b32 s41, s40, 12
	v_add_u32_e32 v152, s41, v173
	global_load_dwordx4 v[98:101], v152, s[0:1] offset:0
	global_load_dwordx4 v[102:105], v152, s[0:1] offset:16
	global_load_dwordx4 v[106:109], v152, s[0:1] offset:32
	global_load_dwordx4 v[110:113], v152, s[0:1] offset:48
	ds_read_b32 v148, v171 offset:2048
	s_waitcnt lgkmcnt(0)
; DEV void phase_peer_expert(const Params& p, int layer, int M, bool final_, int part, char* smem) {
;     ...
;     } else {
;       ss = wave_sum(ss);
;       const float rinv = rsqrtf(ss * (1.f / 1024.f) + 1e-6f);
;       const float* fg = p.in[I_FNG];
; #pragma unroll
;       for (int q = 0; q < 4; q++) {
;         float4 g4 = *(const float4*)(fg + col + q * 4);
;         *(float4*)(p.out + (size_t)m * 1024 + col + q * 4) = make_float4(xn[q * 4 + 0] * rinv * g4.x, xn[q * 4 + 1] * rinv * g4.y, xn[q * 4 + 2] * rinv * g4.z, xn[q * 4 + 3] * rinv * g4.w);
;       }
	s_nop 1
	v_add_f32_dpp v146, v146, v146 quad_perm:[1,0,3,2] row_mask:0xf bank_mask:0xf
	s_nop 1
	v_add_f32_dpp v146, v146, v146 quad_perm:[2,3,0,1] row_mask:0xf bank_mask:0xf
	s_nop 1
	v_add_f32_dpp v146, v146, v146 row_half_mirror row_mask:0xf bank_mask:0xf
	s_nop 1
	v_add_f32_dpp v146, v146, v146 row_mirror row_mask:0xf bank_mask:0xf
	ds_bpermute_b32 v153, v175, v146
	s_waitcnt lgkmcnt(0)
	v_add_f32_e32 v146, v146, v153
	ds_bpermute_b32 v153, v176, v146
	s_waitcnt lgkmcnt(0)
	v_add_f32_e32 v146, v146, v153
	v_fmamk_f32 v146, v146, 0x3a800000, v211
	s_nop 0
	v_rsq_f32_e32 v146, v146
	s_waitcnt vmcnt(8)
	v_mul_f32_e32 v2, v2, v146
	v_mul_f32_e32 v3, v3, v146
	v_mul_f32_e32 v4, v4, v146
	v_mul_f32_e32 v5, v5, v146
	v_mul_f32_e32 v6, v6, v146
	v_mul_f32_e32 v7, v7, v146
	v_mul_f32_e32 v8, v8, v146
	v_mul_f32_e32 v9, v9, v146
	v_mul_f32_e32 v10, v10, v146
	v_mul_f32_e32 v11, v11, v146
	v_mul_f32_e32 v12, v12, v146
	v_mul_f32_e32 v13, v13, v146
	v_mul_f32_e32 v14, v14, v146
	v_mul_f32_e32 v15, v15, v146
	v_mul_f32_e32 v16, v16, v146
	v_mul_f32_e32 v17, v17, v146
	v_mul_f32_e32 v2, v2, v178
	v_mul_f32_e32 v3, v3, v179
	v_mul_f32_e32 v4, v4, v180
	v_mul_f32_e32 v5, v5, v181
	v_mul_f32_e32 v6, v6, v182
	v_mul_f32_e32 v7, v7, v183
	v_mul_f32_e32 v8, v8, v184
	v_mul_f32_e32 v9, v9, v185
	v_mul_f32_e32 v10, v10, v186
	v_mul_f32_e32 v11, v11, v187
	v_mul_f32_e32 v12, v12, v188
	v_mul_f32_e32 v13, v13, v189
	v_mul_f32_e32 v14, v14, v190
	v_mul_f32_e32 v15, v15, v191
	v_mul_f32_e32 v16, v16, v192
	v_mul_f32_e32 v17, v17, v193
	global_store_dwordx4 v150, v[2:5], s[2:3] offset:0
	global_store_dwordx4 v150, v[6:9], s[2:3] offset:16
	global_store_dwordx4 v150, v[10:13], s[2:3] offset:32
	global_store_dwordx4 v150, v[14:17], s[2:3] offset:48
	s_waitcnt lgkmcnt(0)
	s_nop 1
	v_add_f32_dpp v147, v147, v147 quad_perm:[1,0,3,2] row_mask:0xf bank_mask:0xf
	s_nop 1
	v_add_f32_dpp v147, v147, v147 quad_perm:[2,3,0,1] row_mask:0xf bank_mask:0xf
	s_nop 1
	v_add_f32_dpp v147, v147, v147 row_half_mirror row_mask:0xf bank_mask:0xf
	s_nop 1
	v_add_f32_dpp v147, v147, v147 row_mirror row_mask:0xf bank_mask:0xf
	ds_bpermute_b32 v153, v175, v147
	s_waitcnt lgkmcnt(0)
	v_add_f32_e32 v147, v147, v153
	ds_bpermute_b32 v153, v176, v147
	s_waitcnt lgkmcnt(0)
	v_add_f32_e32 v147, v147, v153
	v_fmamk_f32 v147, v147, 0x3a800000, v211
	s_nop 0
	v_rsq_f32_e32 v147, v147
	s_waitcnt vmcnt(8)
	v_mul_f32_e32 v50, v50, v147
	v_mul_f32_e32 v51, v51, v147
	v_mul_f32_e32 v52, v52, v147
	v_mul_f32_e32 v53, v53, v147
	v_mul_f32_e32 v54, v54, v147
	v_mul_f32_e32 v55, v55, v147
	v_mul_f32_e32 v56, v56, v147
	v_mul_f32_e32 v57, v57, v147
	v_mul_f32_e32 v58, v58, v147
	v_mul_f32_e32 v59, v59, v147
	v_mul_f32_e32 v60, v60, v147
	v_mul_f32_e32 v61, v61, v147
	v_mul_f32_e32 v62, v62, v147
	v_mul_f32_e32 v63, v63, v147
	v_mul_f32_e32 v64, v64, v147
	v_mul_f32_e32 v65, v65, v147
	v_mul_f32_e32 v50, v50, v178
	v_mul_f32_e32 v51, v51, v179
	v_mul_f32_e32 v52, v52, v180
	v_mul_f32_e32 v53, v53, v181
	v_mul_f32_e32 v54, v54, v182
	v_mul_f32_e32 v55, v55, v183
	v_mul_f32_e32 v56, v56, v184
	v_mul_f32_e32 v57, v57, v185
	v_mul_f32_e32 v58, v58, v186
	v_mul_f32_e32 v59, v59, v187
	v_mul_f32_e32 v60, v60, v188
	v_mul_f32_e32 v61, v61, v189
	v_mul_f32_e32 v62, v62, v190
	v_mul_f32_e32 v63, v63, v191
	v_mul_f32_e32 v64, v64, v192
	v_mul_f32_e32 v65, v65, v193
	global_store_dwordx4 v151, v[50:53], s[2:3] offset:0
	global_store_dwordx4 v151, v[54:57], s[2:3] offset:16
	global_store_dwordx4 v151, v[58:61], s[2:3] offset:32
	global_store_dwordx4 v151, v[62:65], s[2:3] offset:48
	s_cmp_lt_u32 s8, 9
	s_cbranch_scc1 .Lv_tail_done
	s_waitcnt lgkmcnt(0)
	s_nop 1
	v_add_f32_dpp v148, v148, v148 quad_perm:[1,0,3,2] row_mask:0xf bank_mask:0xf
	s_nop 1
	v_add_f32_dpp v148, v148, v148 quad_perm:[2,3,0,1] row_mask:0xf bank_mask:0xf
	s_nop 1
	v_add_f32_dpp v148, v148, v148 row_half_mirror row_mask:0xf bank_mask:0xf
	s_nop 1
	v_add_f32_dpp v148, v148, v148 row_mirror row_mask:0xf bank_mask:0xf
	ds_bpermute_b32 v153, v175, v148
	s_waitcnt lgkmcnt(0)
	v_add_f32_e32 v148, v148, v153
	ds_bpermute_b32 v153, v176, v148
	s_waitcnt lgkmcnt(0)
	v_add_f32_e32 v148, v148, v153
	v_fmamk_f32 v148, v148, 0x3a800000, v211
	s_nop 0
	v_rsq_f32_e32 v148, v148
	s_waitcnt vmcnt(8)
	v_mul_f32_e32 v98, v98, v148
	v_mul_f32_e32 v99, v99, v148
	v_mul_f32_e32 v100, v100, v148
	v_mul_f32_e32 v101, v101, v148
	v_mul_f32_e32 v102, v102, v148
	v_mul_f32_e32 v103, v103, v148
	v_mul_f32_e32 v104, v104, v148
	v_mul_f32_e32 v105, v105, v148
	v_mul_f32_e32 v106, v106, v148
	v_mul_f32_e32 v107, v107, v148
	v_mul_f32_e32 v108, v108, v148
	v_mul_f32_e32 v109, v109, v148
	v_mul_f32_e32 v110, v110, v148
	v_mul_f32_e32 v111, v111, v148
	v_mul_f32_e32 v112, v112, v148
	v_mul_f32_e32 v113, v113, v148
	v_mul_f32_e32 v98, v98, v178
	v_mul_f32_e32 v99, v99, v179
	v_mul_f32_e32 v100, v100, v180
	v_mul_f32_e32 v101, v101, v181
	v_mul_f32_e32 v102, v102, v182
	v_mul_f32_e32 v103, v103, v183
	v_mul_f32_e32 v104, v104, v184
	v_mul_f32_e32 v105, v105, v185
	v_mul_f32_e32 v106, v106, v186
	v_mul_f32_e32 v107, v107, v187
	v_mul_f32_e32 v108, v108, v188
	v_mul_f32_e32 v109, v109, v189
	v_mul_f32_e32 v110, v110, v190
	v_mul_f32_e32 v111, v111, v191
	v_mul_f32_e32 v112, v112, v192
	v_mul_f32_e32 v113, v113, v193
	global_store_dwordx4 v152, v[98:101], s[2:3] offset:0
	global_store_dwordx4 v152, v[102:105], s[2:3] offset:16
	global_store_dwordx4 v152, v[106:109], s[2:3] offset:32
	global_store_dwordx4 v152, v[110:113], s[2:3] offset:48
.Lv_tail_done:
	s_waitcnt vmcnt(0)
	s_cmp_eq_u32 s57, 20
	s_cbranch_scc1 .Lpeer_to_next
	s_branch .Lpeer_grid_barrier

; DEV int tidx() { int t = threadIdx.x; asm volatile("" : "+v"(t)); return t; }
; #define G_LOAD(RA, RB, KT) { _Pragma("unroll") for (int i = 0; i < 4; i++) { \
;       RA[i] = *(const u32x4*)(Ap + (size_t)(i * 32) * lda + (KT) * 64); RB[i] = *(const u32x4*)(Bp + (size_t)(i * 32) * ldb + (KT) * 64); } }
; template <class Epi>
; DEV void gemm_tile(const bf16_t* __restrict__ A, int lda, const bf16_t* __restrict__ Bt, int ldb, int K, int m0, int n0,
;                    Epi& epi, char* smem) {
;     ...
;   const int tid = tidx(), lane = tid & 63, w = tid >> 6, wm = w >> 1, wn = w & 1;
;   const int l15 = lane & 15, quad = lane >> 4;
;   f32x4 acc[4][4];
; #pragma unroll
;   for (int i = 0; i < 4; i++)
; #pragma unroll
;     for (int j = 0; j < 4; j++) acc[i][j] = (f32x4){0.f, 0.f, 0.f, 0.f};
;   u32x4 ra0[4], rb0[4], ra1[4], rb1[4];
;   const int nk = K >> 6;
;   const int lrow = tid >> 3, lcc = tid & 7;
;   const bf16_t* Ap = A + (size_t)(m0 + lrow) * lda + lcc * 8;
;   const bf16_t* Bp = Bt + (size_t)(n0 + lrow) * ldb + lcc * 8;
;     ...
;   G_LOAD(ra0, rb0, 0);
;   G_LOAD(ra1, rb1, 1);
.LBB0_644:
	s_ashr_i32 s9, s11, 6
	s_and_b32 s8, s11, 7
	s_and_b32 s12, s9, -8
	s_or_b32 s12, s12, s8
	s_lshr_b32 s8, s11, 31
	s_add_i32 s8, s12, s8
	s_ashr_i32 s8, s8, 1
	s_lshl_b32 s13, s8, 3
	s_bfe_u32 s14, s11, 0x30006
	s_or_b32 s13, s13, s14
	s_cmpk_gt_i32 s13, 0x83
	s_cbranch_scc1 .LBB0_643
	v_mov_b32_e32 v145, v195
	s_lshr_b32 s14, s11, 6
	s_lshl_b32 s12, s12, 3
	s_lshl_b32 s18, s8, 4
	s_lshl_b32 s13, s13, 7
	s_and_b32 s15, s10, 7
	v_ashrrev_i32_e32 v66, 3, v145
	s_and_b32 s14, s14, 7
	s_sub_i32 s12, s12, s18
	s_movk_i32 s20, 0x880
	s_bfe_u32 s19, s11, 0x30003
	v_add_u32_e32 v0, s13, v66
	v_mov_b64_e32 v[2:3], s[6:7]
	s_lshl_b32 s16, s15, 3
	s_lshl_b32 s17, s14, 7
	s_or_b32 s12, s12, s19
	v_mad_i64_i32 v[2:3], s[14:15], v0, s20, v[2:3]
	v_lshlrev_b32_e32 v0, 4, v145
	s_lshl_b32 s12, s12, 7
	v_and_b32_e32 v0, 0x70, v0
	v_lshl_add_u64 v[6:7], v[2:3], 0, v[0:1]
	v_add_u32_e32 v4, s12, v66
	v_mov_b64_e32 v[2:3], s[2:3]
	v_mad_i64_i32 v[2:3], s[14:15], v4, s20, v[2:3]
	s_mov_b32 s14, 0x11000
	s_waitcnt vmcnt(21)
	v_add_co_u32_e32 v22, vcc, s14, v6
	v_lshl_add_u64 v[14:15], v[2:3], 0, v[0:1]
	s_nop 0
	v_addc_co_u32_e32 v23, vcc, 0, v7, vcc
	s_waitcnt vmcnt(20)
	v_add_co_u32_e32 v30, vcc, s14, v14
	s_mov_b32 s14, 0x22000
	s_nop 0
	v_addc_co_u32_e32 v31, vcc, 0, v15, vcc
	s_waitcnt vmcnt(19)
	v_add_co_u32_e32 v38, vcc, s14, v6
	s_lshl_b32 s9, s9, 3
	s_nop 0
	v_addc_co_u32_e32 v39, vcc, 0, v7, vcc
	s_waitcnt vmcnt(18)
	v_add_co_u32_e32 v46, vcc, s14, v14
	s_mov_b32 s14, 0x33000
	s_nop 0
	v_addc_co_u32_e32 v47, vcc, 0, v15, vcc
	s_waitcnt vmcnt(17)
	v_add_co_u32_e32 v54, vcc, s14, v6
	s_and_b32 s9, s9, 0x1ffffc0
	s_nop 0
	v_addc_co_u32_e32 v55, vcc, 0, v7, vcc
	s_waitcnt vmcnt(16)
	v_add_co_u32_e32 v62, vcc, s14, v14
	s_or_b32 s9, s9, s16
	s_nop 0
	v_addc_co_u32_e32 v63, vcc, 0, v15, vcc
	global_load_dwordx4 v[2:5], v[6:7], off
	s_nop 0
	global_load_dwordx4 v[10:13], v[14:15], off
	s_nop 0
	global_load_dwordx4 v[18:21], v[22:23], off
	s_nop 0
	global_load_dwordx4 v[26:29], v[30:31], off
	s_nop 0
	global_load_dwordx4 v[34:37], v[38:39], off
	s_nop 0
	global_load_dwordx4 v[42:45], v[46:47], off
	s_nop 0
	global_load_dwordx4 v[50:53], v[54:55], off
	s_nop 0
	global_load_dwordx4 v[58:61], v[62:63], off
	s_nop 0
	global_load_dwordx4 v[6:9], v[6:7], off offset:128
	s_nop 0
	global_load_dwordx4 v[14:17], v[14:15], off offset:128
	s_nop 0
	global_load_dwordx4 v[22:25], v[22:23], off offset:128
	s_nop 0
	global_load_dwordx4 v[30:33], v[30:31], off offset:128
	s_nop 0
	global_load_dwordx4 v[38:41], v[38:39], off offset:128
	s_nop 0
	global_load_dwordx4 v[46:49], v[46:47], off offset:128
	s_nop 0
	global_load_dwordx4 v[54:57], v[54:55], off offset:128
	s_nop 0
	global_load_dwordx4 v[62:65], v[62:63], off offset:128
	s_or_b32 s9, s9, s19
	v_mad_u64_u32 v[134:135], s[14:15], v66, s36, v[0:1]
	s_sub_i32 s9, s9, s18
	v_ashrrev_i32_e32 v67, 1, v145
	s_lshl_b32 s14, s9, 7
	v_and_b32_e32 v146, 0xffffffc0, v67
	v_ashrrev_i32_e32 v67, 31, v66
	s_ashr_i32 s15, s14, 31
	s_lshl_b32 s8, s8, 10
	s_movk_i32 s19, 0x880
	v_lshl_add_u64 v[68:69], v[66:67], 0, s[14:15]
	v_mov_b64_e32 v[70:71], s[28:29]
	s_or_b32 s8, s17, s8
	v_and_b32_e32 v0, 7, v145
	v_mad_u64_u32 v[136:137], s[14:15], v68, s19, v[70:71]
	v_add_u32_e32 v66, s8, v66
	v_mov_b32_e32 v118, 0
	v_and_b32_e32 v144, 64, v145
	v_lshlrev_b32_e32 v0, 4, v0
	v_mad_i32_i24 v137, v69, s19, v137
	v_mad_i64_i32 v[138:139], s[8:9], v66, s19, v[70:71]
	s_mov_b32 s14, -2
	v_mov_b32_e32 v119, v118
	v_mov_b32_e32 v120, v118
	v_mov_b32_e32 v121, v118
	v_mov_b32_e32 v126, v118
	v_mov_b32_e32 v127, v118
	v_mov_b32_e32 v128, v118
	v_mov_b32_e32 v129, v118
	v_mov_b32_e32 v90, v118
	v_mov_b32_e32 v91, v118
	v_mov_b32_e32 v92, v118
	v_mov_b32_e32 v93, v118
	v_mov_b32_e32 v98, v118
	v_mov_b32_e32 v99, v118
	v_mov_b32_e32 v100, v118
	v_mov_b32_e32 v101, v118
	v_mov_b32_e32 v66, v118
	v_mov_b32_e32 v67, v118
	v_mov_b32_e32 v68, v118
	v_mov_b32_e32 v69, v118
	v_mov_b32_e32 v70, v118
	v_mov_b32_e32 v71, v118
	v_mov_b32_e32 v72, v118
	v_mov_b32_e32 v73, v118
	v_mov_b32_e32 v74, v118
	v_mov_b32_e32 v75, v118
	v_mov_b32_e32 v76, v118
	v_mov_b32_e32 v77, v118
	v_mov_b32_e32 v82, v118
	v_mov_b32_e32 v83, v118
	v_mov_b32_e32 v84, v118
	v_mov_b32_e32 v85, v118
	v_mov_b32_e32 v78, v118
	v_mov_b32_e32 v79, v118
	v_mov_b32_e32 v80, v118
	v_mov_b32_e32 v81, v118
	v_mov_b32_e32 v86, v118
	v_mov_b32_e32 v87, v118
	v_mov_b32_e32 v88, v118
	v_mov_b32_e32 v89, v118
	v_mov_b32_e32 v94, v118
	v_mov_b32_e32 v95, v118
	v_mov_b32_e32 v96, v118
	v_mov_b32_e32 v97, v118
	v_mov_b32_e32 v102, v118
	v_mov_b32_e32 v103, v118
	v_mov_b32_e32 v104, v118
	v_mov_b32_e32 v105, v118
	v_mov_b32_e32 v110, v118
	v_mov_b32_e32 v111, v118
	v_mov_b32_e32 v112, v118
	v_mov_b32_e32 v113, v118
	v_mov_b32_e32 v114, v118
	v_mov_b32_e32 v115, v118
	v_mov_b32_e32 v116, v118
	v_mov_b32_e32 v117, v118
	v_mov_b32_e32 v122, v118
	v_mov_b32_e32 v123, v118
	v_mov_b32_e32 v124, v118
	v_mov_b32_e32 v125, v118
	v_mov_b32_e32 v106, v118
	v_mov_b32_e32 v107, v118
	v_mov_b32_e32 v108, v118
	v_mov_b32_e32 v109, v118
	s_branch .LBB0_647

; #define G_LOAD(RA, RB, KT) { _Pragma("unroll") for (int i = 0; i < 4; i++) { \
;       RA[i] = *(const u32x4*)(Ap + (size_t)(i * 32) * lda + (KT) * 64); RB[i] = *(const u32x4*)(Bp + (size_t)(i * 32) * ldb + (KT) * 64); } }
; #define G_STORE(RA, RB) { _Pragma("unroll") for (int i = 0; i < 4; i++) { \
;       *(u32x4*)(As + (lrow + i * 32) * GLD + lcc * 8) = RA[i]; *(u32x4*)(Bs + (lrow + i * 32) * GLD + lcc * 8) = RB[i]; } }
; template <class Epi>
; DEV void gemm_tile(const bf16_t* __restrict__ A, int lda, const bf16_t* __restrict__ Bt, int ldb, int K, int m0, int n0,
;                    Epi& epi, char* smem) {
;     ...
;   for (int kt = 0; kt < nk; kt += 2) {
;     __syncthreads();
;     G_STORE(ra0, rb0);
;     __syncthreads();
;     if (kt + 2 < nk) G_LOAD(ra0, rb0, kt + 2);
.LBB0_647:
	s_add_i32 s14, s14, 2
	s_cmp_gt_u32 s14, 13
	s_cselect_b64 s[8:9], -1, 0
	s_and_b64 vcc, exec, s[8:9]
	v_lshl_add_u64 v[142:143], v[138:139], 0, v[0:1]
	v_lshl_add_u64 v[140:141], v[136:137], 0, v[0:1]
	s_waitcnt lgkmcnt(0)
	s_barrier
	s_waitcnt vmcnt(8)
	ds_write_b128 v134, v[2:5]
	ds_write_b128 v134, v[10:13] offset:20480
	ds_write_b128 v134, v[18:21] offset:5120
	ds_write_b128 v134, v[26:29] offset:25600
	ds_write_b128 v134, v[34:37] offset:10240
	ds_write_b128 v134, v[42:45] offset:30720
	ds_write_b128 v134, v[50:53] offset:15360
	ds_write_b128 v134, v[58:61] offset:35840
	s_waitcnt lgkmcnt(0)
	s_barrier
	s_cbranch_vccnz .Lgw_skip_3
	v_add_co_u32_e32 v2, vcc, 0x4200000, v142
	s_nop 1
	v_addc_co_u32_e32 v3, vcc, 0, v143, vcc
	v_add_co_u32_e32 v10, vcc, 0xb5c0000, v140
	global_load_dwordx4 v[2:5], v[2:3], off offset:256
	s_nop 0
	v_addc_co_u32_e32 v11, vcc, 0, v141, vcc
	v_add_co_u32_e32 v18, vcc, 0x4211000, v142
	global_load_dwordx4 v[10:13], v[10:11], off offset:256
	s_nop 0
	v_addc_co_u32_e32 v19, vcc, 0, v143, vcc
	v_add_co_u32_e32 v26, vcc, 0xb5d1000, v140
	global_load_dwordx4 v[18:21], v[18:19], off offset:256
	s_nop 0
	v_addc_co_u32_e32 v27, vcc, 0, v141, vcc
	v_add_co_u32_e32 v34, vcc, 0x4222000, v142
	global_load_dwordx4 v[26:29], v[26:27], off offset:256
	s_nop 0
	v_addc_co_u32_e32 v35, vcc, 0, v143, vcc
	v_add_co_u32_e32 v42, vcc, 0xb5e2000, v140
	global_load_dwordx4 v[34:37], v[34:35], off offset:256
	s_nop 0
	v_addc_co_u32_e32 v43, vcc, 0, v141, vcc
	v_add_co_u32_e32 v50, vcc, 0x4233000, v142
	global_load_dwordx4 v[42:45], v[42:43], off offset:256
	s_nop 0
	v_addc_co_u32_e32 v51, vcc, 0, v143, vcc
	v_add_co_u32_e32 v58, vcc, 0xb5f3000, v140
	global_load_dwordx4 v[50:53], v[50:51], off offset:256
	s_nop 0
	v_addc_co_u32_e32 v59, vcc, 0, v141, vcc
	global_load_dwordx4 v[58:61], v[58:59], off offset:256
; DEV int tidx() { int t = threadIdx.x; asm volatile("" : "+v"(t)); return t; }
; DEV f32x4 mfma16(bf16x8 a, bf16x8 b, f32x4 c) { return __builtin_amdgcn_mfma_f32_16x16x32_bf16(a, b, c, 0, 0, 0); }
; #define G_LOAD(RA, RB, KT) { _Pragma("unroll") for (int i = 0; i < 4; i++) { \
;       RA[i] = *(const u32x4*)(Ap + (size_t)(i * 32) * lda + (KT) * 64); RB[i] = *(const u32x4*)(Bp + (size_t)(i * 32) * ldb + (KT) * 64); } }
; #define G_STORE(RA, RB) { _Pragma("unroll") for (int i = 0; i < 4; i++) { \
;       *(u32x4*)(As + (lrow + i * 32) * GLD + lcc * 8) = RA[i]; *(u32x4*)(Bs + (lrow + i * 32) * GLD + lcc * 8) = RB[i]; } }
; template <int TI, int TJ, int KS>
; DEV void mfma_lds(const bf16_t* Arows, int lda, const bf16_t* Brows, int ldb, int i0, int j0, f32x4 (&acc)[TI][TJ]) {
;   const int lane = tidx() & 63, l15 = lane & 15, quad = lane >> 4;
; #pragma unroll
;   for (int ks = 0; ks < KS; ks++) {
;     bf16x8 af[TI], bfr[TJ];
; #pragma unroll
;     for (int i = 0; i < TI; i++) af[i] = *(const bf16x8*)(Arows + (i0 + i * 16 + l15) * lda + ks * 32 + quad * 8);
; #pragma unroll
;     for (int j = 0; j < TJ; j++) bfr[j] = *(const bf16x8*)(Brows + (j0 + j * 16 + l15) * ldb + ks * 32 + quad * 8);
; #pragma unroll
;     for (int i = 0; i < TI; i++)
; #pragma unroll
;       for (int j = 0; j < TJ; j++) acc[i][j] = mfma16(af[i], bfr[j], acc[i][j]);
;   }
; template <class Epi>
; DEV void gemm_tile(const bf16_t* __restrict__ A, int lda, const bf16_t* __restrict__ Bt, int ldb, int K, int m0, int n0,
;                    Epi& epi, char* smem) {
;     ...
;     mfma_lds<4, 4, 2>(Bs, GLD, As, GLD, wn * 64, wm * 64, acc);
;     __syncthreads();
;     G_STORE(ra1, rb1);
;     __syncthreads();
;     if (kt + 3 < nk) G_LOAD(ra1, rb1, kt + 3);
.LBB0_649:
	v_mov_b32_e32 v130, v195
	s_cmp_gt_u32 s14, 12
	v_and_b32_e32 v135, 15, v130
	v_or_b32_e32 v131, v135, v144
	v_and_b32_e32 v148, 48, v130
	v_mul_u32_u24_e32 v130, 0x50, v131
	v_lshl_add_u32 v147, v130, 1, v148
	ds_read_b128 v[130:133], v147 offset:20480
	v_or_b32_e32 v135, v135, v146
	v_mad_u64_u32 v[184:185], s[16:17], v135, s36, v[148:149]
	ds_read_b128 v[148:151], v184
	ds_read_b128 v[152:155], v184 offset:2560
	ds_read_b128 v[156:159], v184 offset:5120
	ds_read_b128 v[160:163], v184 offset:7680
	s_waitcnt lgkmcnt(3)
	v_mfma_f32_16x16x32_bf16 v[106:109], v[130:133], v[148:151], v[106:109]
	s_waitcnt lgkmcnt(2)
	v_mfma_f32_16x16x32_bf16 v[122:125], v[130:133], v[152:155], v[122:125]
	s_waitcnt lgkmcnt(1)
	v_mfma_f32_16x16x32_bf16 v[114:117], v[130:133], v[156:159], v[114:117]
	s_waitcnt lgkmcnt(0)
	v_mfma_f32_16x16x32_bf16 v[110:113], v[130:133], v[160:163], v[110:113]
	ds_read_b128 v[130:133], v147 offset:23040
	s_waitcnt lgkmcnt(0)
	v_mfma_f32_16x16x32_bf16 v[102:105], v[130:133], v[148:151], v[102:105]
	v_mfma_f32_16x16x32_bf16 v[94:97], v[130:133], v[152:155], v[94:97]
	v_mfma_f32_16x16x32_bf16 v[164:167], v[130:133], v[156:159], v[86:89]
	v_mfma_f32_16x16x32_bf16 v[130:133], v[130:133], v[160:163], v[78:81]
	s_nop 2
	ds_read_b128 v[78:81], v147 offset:25600
	s_waitcnt lgkmcnt(0)
	v_mfma_f32_16x16x32_bf16 v[180:183], v[78:81], v[160:163], v[66:69]
	s_nop 2
	ds_read_b128 v[66:69], v147 offset:28160
	v_mfma_f32_16x16x32_bf16 v[168:171], v[78:81], v[148:151], v[82:85]
	v_mfma_f32_16x16x32_bf16 v[172:175], v[78:81], v[152:155], v[74:77]
	v_mfma_f32_16x16x32_bf16 v[176:179], v[78:81], v[156:159], v[70:73]
	ds_read_b128 v[78:81], v147 offset:20544
	s_waitcnt lgkmcnt(1)
	v_mfma_f32_16x16x32_bf16 v[126:129], v[66:69], v[156:159], v[126:129]
	v_mfma_f32_16x16x32_bf16 v[156:159], v[66:69], v[160:163], v[118:121]
	ds_read_b128 v[160:163], v184 offset:2624
	s_nop 1
	ds_read_b128 v[118:121], v184 offset:64
	v_mfma_f32_16x16x32_bf16 v[148:151], v[66:69], v[148:151], v[98:101]
	s_nop 2
	ds_read_b128 v[98:101], v147 offset:23104
	s_waitcnt lgkmcnt(2)
	v_mfma_f32_16x16x32_bf16 v[70:73], v[78:81], v[160:163], v[122:125]
	s_nop 2
	ds_read_b128 v[122:125], v184 offset:5184
	ds_read_b128 v[184:187], v184 offset:7744
	v_mfma_f32_16x16x32_bf16 v[152:155], v[66:69], v[152:155], v[90:93]
	s_waitcnt lgkmcnt(3)
	v_mfma_f32_16x16x32_bf16 v[66:69], v[78:81], v[118:121], v[106:109]
	s_waitcnt lgkmcnt(1)
	v_mfma_f32_16x16x32_bf16 v[74:77], v[78:81], v[122:125], v[114:117]
	s_waitcnt lgkmcnt(0)
	v_mfma_f32_16x16x32_bf16 v[78:81], v[78:81], v[184:187], v[110:113]
	v_mfma_f32_16x16x32_bf16 v[86:89], v[98:101], v[160:163], v[94:97]
	s_nop 1
	ds_read_b128 v[110:113], v147 offset:25664
	v_mfma_f32_16x16x32_bf16 v[94:97], v[98:101], v[184:187], v[130:133]
	s_nop 2
	ds_read_b128 v[130:133], v147 offset:28224
	v_mfma_f32_16x16x32_bf16 v[82:85], v[98:101], v[118:121], v[102:105]
	s_waitcnt lgkmcnt(0)
	s_barrier
	v_mfma_f32_16x16x32_bf16 v[90:93], v[98:101], v[122:125], v[164:167]
	s_waitcnt vmcnt(8)
	ds_write_b128 v134, v[6:9]
	ds_write_b128 v134, v[14:17] offset:20480
	ds_write_b128 v134, v[22:25] offset:5120
	ds_write_b128 v134, v[30:33] offset:25600
	ds_write_b128 v134, v[38:41] offset:10240
	ds_write_b128 v134, v[46:49] offset:30720
	ds_write_b128 v134, v[54:57] offset:15360
	ds_write_b128 v134, v[62:65] offset:35840
	v_mfma_f32_16x16x32_bf16 v[98:101], v[110:113], v[118:121], v[168:171]
	s_waitcnt lgkmcnt(0)
	s_barrier
	v_mfma_f32_16x16x32_bf16 v[102:105], v[110:113], v[160:163], v[172:175]
	v_mfma_f32_16x16x32_bf16 v[106:109], v[110:113], v[122:125], v[176:179]
	v_mfma_f32_16x16x32_bf16 v[110:113], v[110:113], v[184:187], v[180:183]
	v_mfma_f32_16x16x32_bf16 v[114:117], v[130:133], v[118:121], v[148:151]
	v_mfma_f32_16x16x32_bf16 v[118:121], v[130:133], v[160:163], v[152:155]
	v_mfma_f32_16x16x32_bf16 v[122:125], v[130:133], v[122:125], v[126:129]
	v_mfma_f32_16x16x32_bf16 v[130:133], v[130:133], v[184:187], v[156:159]
	s_cbranch_scc1 .LBB0_646
	v_add_co_u32_e32 v6, vcc, 0x4200000, v142
	s_nop 1
	v_addc_co_u32_e32 v7, vcc, 0, v143, vcc
	v_add_co_u32_e32 v14, vcc, 0xb5c0000, v140
	global_load_dwordx4 v[6:9], v[6:7], off offset:384
	s_nop 0
	v_addc_co_u32_e32 v15, vcc, 0, v141, vcc
	v_add_co_u32_e32 v22, vcc, 0x4211000, v142
	global_load_dwordx4 v[14:17], v[14:15], off offset:384
	s_nop 0
	v_addc_co_u32_e32 v23, vcc, 0, v143, vcc
	v_add_co_u32_e32 v30, vcc, 0xb5d1000, v140
	global_load_dwordx4 v[22:25], v[22:23], off offset:384
	s_nop 0
	v_addc_co_u32_e32 v31, vcc, 0, v141, vcc
	v_add_co_u32_e32 v38, vcc, 0x4222000, v142
	global_load_dwordx4 v[30:33], v[30:31], off offset:384
	s_nop 0
	v_addc_co_u32_e32 v39, vcc, 0, v143, vcc
	v_add_co_u32_e32 v46, vcc, 0xb5e2000, v140
	global_load_dwordx4 v[38:41], v[38:39], off offset:384
	s_nop 0
	v_addc_co_u32_e32 v47, vcc, 0, v141, vcc
	v_add_co_u32_e32 v54, vcc, 0x4233000, v142
	global_load_dwordx4 v[46:49], v[46:47], off offset:384
	s_nop 0
	v_addc_co_u32_e32 v55, vcc, 0, v143, vcc
	v_add_co_u32_e32 v62, vcc, 0xb5f3000, v140
	global_load_dwordx4 v[54:57], v[54:55], off offset:384
	s_nop 0
	v_addc_co_u32_e32 v63, vcc, 0, v141, vcc
	global_load_dwordx4 v[62:65], v[62:63], off offset:384
	s_branch .LBB0_646

; DEV int tidx() { int t = threadIdx.x; asm volatile("" : "+v"(t)); return t; }
; #define G_LOAD(RA, RB, KT) { _Pragma("unroll") for (int i = 0; i < 4; i++) { \
;       RA[i] = *(const u32x4*)(Ap + (size_t)(i * 32) * lda + (KT) * 64); RB[i] = *(const u32x4*)(Bp + (size_t)(i * 32) * ldb + (KT) * 64); } }
; template <class Epi>
; DEV void gemm_tile(const bf16_t* __restrict__ A, int lda, const bf16_t* __restrict__ Bt, int ldb, int K, int m0, int n0,
;                    Epi& epi, char* smem) {
;     ...
;   const int tid = tidx(), lane = tid & 63, w = tid >> 6, wm = w >> 1, wn = w & 1;
;   const int l15 = lane & 15, quad = lane >> 4;
;   f32x4 acc[4][4];
; #pragma unroll
;   for (int i = 0; i < 4; i++)
; #pragma unroll
;     for (int j = 0; j < 4; j++) acc[i][j] = (f32x4){0.f, 0.f, 0.f, 0.f};
;   u32x4 ra0[4], rb0[4], ra1[4], rb1[4];
;   const int nk = K >> 6;
;   const int lrow = tid >> 3, lcc = tid & 7;
;   const bf16_t* Ap = A + (size_t)(m0 + lrow) * lda + lcc * 8;
;   const bf16_t* Bp = Bt + (size_t)(n0 + lrow) * ldb + lcc * 8;
;     ...
;   G_LOAD(ra0, rb0, 0);
;   G_LOAD(ra1, rb1, 1);
.LBB0_668:
	s_ashr_i32 s8, s12, 6
	s_and_b32 s9, s12, 7
	s_and_b32 s13, s8, 0x1ffffff8
	s_or_b32 s9, s13, s9
	s_lshl_b32 s9, s9, 3
	s_bfe_u32 s13, s12, 0x30006
	s_or_b32 s9, s9, s13
	s_cmpk_gt_i32 s9, 0x83
	s_cbranch_scc1 .LBB0_667
	s_bfe_u32 s14, s11, 0x30007
	s_mul_i32 s15, s14, 0x44000
	s_and_b32 s14, s10, 7
	v_mov_b32_e32 v141, v195
	s_lshl_b32 s18, s14, 3
	s_lshl_b32 s14, s9, 7
	s_movk_i32 s20, 0x880
	v_ashrrev_i32_e32 v2, 3, v141
	v_add_u32_e32 v0, s14, v2
	v_mov_b64_e32 v[4:5], s[6:7]
	s_lshr_b32 s13, s12, 6
	s_lshl_b32 s9, s12, 4
	v_mad_i64_i32 v[4:5], s[16:17], v0, s20, v[4:5]
	v_lshlrev_b32_e32 v0, 4, v141
	s_and_b32 s19, s13, 7
	s_and_b32 s13, s9, 0x380
	v_and_b32_e32 v0, 0x70, v0
	v_lshl_add_u64 v[4:5], v[4:5], 0, v[0:1]
	v_add_u32_e32 v3, s13, v2
	v_mov_b64_e32 v[6:7], s[2:3]
	s_mov_b32 s9, 0x11000
	v_mad_i64_i32 v[6:7], s[16:17], v3, s20, v[6:7]
	v_add_co_u32_e32 v8, vcc, s9, v4
	v_lshl_add_u64 v[6:7], v[6:7], 0, v[0:1]
	s_nop 0
	v_addc_co_u32_e32 v9, vcc, 0, v5, vcc
	v_add_co_u32_e32 v10, vcc, s9, v6
	s_mov_b32 s9, 0x22000
	s_nop 0
	v_addc_co_u32_e32 v11, vcc, 0, v7, vcc
	v_add_co_u32_e32 v12, vcc, s9, v4
	v_mad_u64_u32 v[130:131], s[16:17], v2, s36, v[0:1]
	s_nop 0
	v_addc_co_u32_e32 v13, vcc, 0, v5, vcc
	s_waitcnt vmcnt(22)
	v_add_co_u32_e32 v14, vcc, s9, v6
	s_mov_b32 s9, 0x33000
	s_nop 0
	v_addc_co_u32_e32 v15, vcc, 0, v7, vcc
	v_add_co_u32_e32 v16, vcc, s9, v4
	s_add_u32 s16, s28, s15
	s_nop 0
	v_addc_co_u32_e32 v17, vcc, 0, v5, vcc
	v_add_co_u32_e32 v18, vcc, s9, v6
	s_addc_u32 s17, s29, 0
	s_nop 0
	v_addc_co_u32_e32 v19, vcc, 0, v7, vcc
	global_load_dwordx4 v[42:45], v[4:5], off
	global_load_dwordx4 v[50:53], v[6:7], off
	global_load_dwordx4 v[62:65], v[8:9], off
	global_load_dwordx4 v[70:73], v[10:11], off
	global_load_dwordx4 v[78:81], v[12:13], off
	global_load_dwordx4 v[86:89], v[14:15], off
	global_load_dwordx4 v[94:97], v[16:17], off
	global_load_dwordx4 v[102:105], v[18:19], off
	global_load_dwordx4 v[46:49], v[4:5], off offset:128
	global_load_dwordx4 v[54:57], v[6:7], off offset:128
	global_load_dwordx4 v[66:69], v[8:9], off offset:128
	global_load_dwordx4 v[74:77], v[10:11], off offset:128
	global_load_dwordx4 v[82:85], v[12:13], off offset:128
	global_load_dwordx4 v[90:93], v[14:15], off offset:128
	global_load_dwordx4 v[98:101], v[16:17], off offset:128
	global_load_dwordx4 v[106:109], v[18:19], off offset:128
	s_lshl_b32 s8, s8, 3
	s_and_b32 s8, s8, 0x1ffffc0
	s_or_b32 s8, s8, s18
	s_or_b32 s8, s8, s19
	v_ashrrev_i32_e32 v3, 1, v141
	s_lshl_b32 s8, s8, 7
	v_and_b32_e32 v142, 0xffffffc0, v3
	v_ashrrev_i32_e32 v3, 31, v2
	v_mov_b64_e32 v[4:5], s[16:17]
	s_ashr_i32 s9, s8, 31
	v_mad_i64_i32 v[132:133], s[16:17], v2, s20, v[4:5]
	s_movk_i32 s19, 0x880
	v_lshl_add_u64 v[2:3], v[2:3], 0, s[8:9]
	v_mov_b64_e32 v[4:5], s[28:29]
	v_and_b32_e32 v0, 7, v141
	v_mad_u64_u32 v[134:135], s[8:9], v2, s19, v[4:5]
	v_mov_b32_e32 v2, 0
	v_and_b32_e32 v140, 64, v141
	v_lshlrev_b32_e32 v0, 4, v0
	v_mad_i32_i24 v135, v3, s19, v135
	s_mov_b32 s15, -2
	v_mov_b32_e32 v3, v2
	v_mov_b32_e32 v4, v2
	v_mov_b32_e32 v5, v2
	v_mov_b32_e32 v6, v2
	v_mov_b32_e32 v7, v2
	v_mov_b32_e32 v8, v2
	v_mov_b32_e32 v9, v2
	v_mov_b32_e32 v10, v2
	v_mov_b32_e32 v11, v2
	v_mov_b32_e32 v12, v2
	v_mov_b32_e32 v13, v2
	v_mov_b32_e32 v14, v2
	v_mov_b32_e32 v15, v2
	v_mov_b32_e32 v16, v2
	v_mov_b32_e32 v17, v2
	v_mov_b32_e32 v18, v2
	v_mov_b32_e32 v19, v2
	v_mov_b32_e32 v20, v2
	v_mov_b32_e32 v21, v2
	s_waitcnt vmcnt(37)
	v_mov_b32_e32 v22, v2
	v_mov_b32_e32 v23, v2
	v_mov_b32_e32 v24, v2
	v_mov_b32_e32 v25, v2
	v_mov_b32_e32 v26, v2
	v_mov_b32_e32 v27, v2
	v_mov_b32_e32 v28, v2
	v_mov_b32_e32 v29, v2
	s_waitcnt vmcnt(36)
	v_mov_b32_e32 v30, v2
	v_mov_b32_e32 v31, v2
	v_mov_b32_e32 v32, v2
	v_mov_b32_e32 v33, v2
	v_mov_b32_e32 v34, v2
	v_mov_b32_e32 v35, v2
	v_mov_b32_e32 v36, v2
	v_mov_b32_e32 v37, v2
	s_waitcnt vmcnt(35)
	v_mov_b32_e32 v38, v2
	v_mov_b32_e32 v39, v2
	v_mov_b32_e32 v40, v2
	v_mov_b32_e32 v41, v2
	v_mov_b32_e32 v58, v2
	v_mov_b32_e32 v59, v2
	v_mov_b32_e32 v60, v2
	v_mov_b32_e32 v61, v2
	s_waitcnt vmcnt(34)
	v_mov_b32_e32 v110, v2
	v_mov_b32_e32 v111, v2
	v_mov_b32_e32 v112, v2
	v_mov_b32_e32 v113, v2
	v_mov_b32_e32 v114, v2
	v_mov_b32_e32 v115, v2
	v_mov_b32_e32 v116, v2
	v_mov_b32_e32 v117, v2
	s_waitcnt vmcnt(33)
	v_mov_b32_e32 v118, v2
	v_mov_b32_e32 v119, v2
	v_mov_b32_e32 v120, v2
	v_mov_b32_e32 v121, v2
	v_mov_b32_e32 v122, v2
	v_mov_b32_e32 v123, v2
	v_mov_b32_e32 v124, v2
	v_mov_b32_e32 v125, v2
	s_waitcnt vmcnt(32)
	v_mov_b32_e32 v126, v2
	v_mov_b32_e32 v127, v2
	v_mov_b32_e32 v128, v2
	v_mov_b32_e32 v129, v2
	s_branch .LBB0_671

; #define G_LOAD(RA, RB, KT) { _Pragma("unroll") for (int i = 0; i < 4; i++) { \
;       RA[i] = *(const u32x4*)(Ap + (size_t)(i * 32) * lda + (KT) * 64); RB[i] = *(const u32x4*)(Bp + (size_t)(i * 32) * ldb + (KT) * 64); } }
; #define G_STORE(RA, RB) { _Pragma("unroll") for (int i = 0; i < 4; i++) { \
;       *(u32x4*)(As + (lrow + i * 32) * GLD + lcc * 8) = RA[i]; *(u32x4*)(Bs + (lrow + i * 32) * GLD + lcc * 8) = RB[i]; } }
; template <class Epi>
; DEV void gemm_tile(const bf16_t* __restrict__ A, int lda, const bf16_t* __restrict__ Bt, int ldb, int K, int m0, int n0,
;                    Epi& epi, char* smem) {
;     ...
;   for (int kt = 0; kt < nk; kt += 2) {
;     __syncthreads();
;     G_STORE(ra0, rb0);
;     __syncthreads();
;     if (kt + 2 < nk) G_LOAD(ra0, rb0, kt + 2);
.LBB0_671:
	s_add_i32 s15, s15, 2
	s_cmp_gt_u32 s15, 13
	s_cselect_b64 s[8:9], -1, 0
	s_and_b64 vcc, exec, s[8:9]
	v_lshl_add_u64 v[138:139], v[134:135], 0, v[0:1]
	v_lshl_add_u64 v[136:137], v[132:133], 0, v[0:1]
	s_waitcnt lgkmcnt(0)
	s_barrier
	s_waitcnt vmcnt(8)
	ds_write_b128 v130, v[42:45]
	ds_write_b128 v130, v[50:53] offset:20480
	ds_write_b128 v130, v[62:65] offset:5120
	ds_write_b128 v130, v[70:73] offset:25600
	ds_write_b128 v130, v[78:81] offset:10240
	ds_write_b128 v130, v[86:89] offset:30720
	ds_write_b128 v130, v[94:97] offset:15360
	ds_write_b128 v130, v[102:105] offset:35840
	s_waitcnt lgkmcnt(0)
	s_barrier
	s_cbranch_vccnz .Lgw_skip_4
	v_add_co_u32_e32 v42, vcc, 0x19700000, v138
	s_nop 1
	v_addc_co_u32_e32 v43, vcc, 0, v139, vcc
	v_add_co_u32_e32 v50, vcc, 0xa6e0000, v136
	global_load_dwordx4 v[42:45], v[42:43], off offset:256
	s_nop 0
	v_addc_co_u32_e32 v51, vcc, 0, v137, vcc
	v_add_co_u32_e32 v62, vcc, 0x19711000, v138
	global_load_dwordx4 v[50:53], v[50:51], off offset:256
	s_nop 0
	v_addc_co_u32_e32 v63, vcc, 0, v139, vcc
	v_add_co_u32_e32 v70, vcc, 0xa6f1000, v136
	global_load_dwordx4 v[62:65], v[62:63], off offset:256
	s_nop 0
	v_addc_co_u32_e32 v71, vcc, 0, v137, vcc
	v_add_co_u32_e32 v78, vcc, 0x19722000, v138
	global_load_dwordx4 v[70:73], v[70:71], off offset:256
	s_nop 0
	v_addc_co_u32_e32 v79, vcc, 0, v139, vcc
	v_add_co_u32_e32 v86, vcc, 0xa702000, v136
	global_load_dwordx4 v[78:81], v[78:79], off offset:256
	s_nop 0
	v_addc_co_u32_e32 v87, vcc, 0, v137, vcc
	v_add_co_u32_e32 v94, vcc, 0x19733000, v138
	global_load_dwordx4 v[86:89], v[86:87], off offset:256
	s_nop 0
	v_addc_co_u32_e32 v95, vcc, 0, v139, vcc
	v_add_co_u32_e32 v102, vcc, 0xa713000, v136
	global_load_dwordx4 v[94:97], v[94:95], off offset:256
	s_nop 0
	v_addc_co_u32_e32 v103, vcc, 0, v137, vcc
	global_load_dwordx4 v[102:105], v[102:103], off offset:256
; DEV int tidx() { int t = threadIdx.x; asm volatile("" : "+v"(t)); return t; }
; DEV f32x4 mfma16(bf16x8 a, bf16x8 b, f32x4 c) { return __builtin_amdgcn_mfma_f32_16x16x32_bf16(a, b, c, 0, 0, 0); }
; #define G_LOAD(RA, RB, KT) { _Pragma("unroll") for (int i = 0; i < 4; i++) { \
;       RA[i] = *(const u32x4*)(Ap + (size_t)(i * 32) * lda + (KT) * 64); RB[i] = *(const u32x4*)(Bp + (size_t)(i * 32) * ldb + (KT) * 64); } }
; #define G_STORE(RA, RB) { _Pragma("unroll") for (int i = 0; i < 4; i++) { \
;       *(u32x4*)(As + (lrow + i * 32) * GLD + lcc * 8) = RA[i]; *(u32x4*)(Bs + (lrow + i * 32) * GLD + lcc * 8) = RB[i]; } }
; template <int TI, int TJ, int KS>
; DEV void mfma_lds(const bf16_t* Arows, int lda, const bf16_t* Brows, int ldb, int i0, int j0, f32x4 (&acc)[TI][TJ]) {
;   const int lane = tidx() & 63, l15 = lane & 15, quad = lane >> 4;
; #pragma unroll
;   for (int ks = 0; ks < KS; ks++) {
;     bf16x8 af[TI], bfr[TJ];
; #pragma unroll
;     for (int i = 0; i < TI; i++) af[i] = *(const bf16x8*)(Arows + (i0 + i * 16 + l15) * lda + ks * 32 + quad * 8);
; #pragma unroll
;     for (int j = 0; j < TJ; j++) bfr[j] = *(const bf16x8*)(Brows + (j0 + j * 16 + l15) * ldb + ks * 32 + quad * 8);
; #pragma unroll
;     for (int i = 0; i < TI; i++)
; #pragma unroll
;       for (int j = 0; j < TJ; j++) acc[i][j] = mfma16(af[i], bfr[j], acc[i][j]);
;   }
; template <class Epi>
; DEV void gemm_tile(const bf16_t* __restrict__ A, int lda, const bf16_t* __restrict__ Bt, int ldb, int K, int m0, int n0,
;                    Epi& epi, char* smem) {
;     ...
;     mfma_lds<4, 4, 2>(Bs, GLD, As, GLD, wn * 64, wm * 64, acc);
;     __syncthreads();
;     G_STORE(ra1, rb1);
;     __syncthreads();
;     if (kt + 3 < nk) G_LOAD(ra1, rb1, kt + 3);
.LBB0_673:
	v_mov_b32_e32 v131, v195
	s_cmp_gt_u32 s15, 12
	v_and_b32_e32 v143, 15, v131
	v_or_b32_e32 v144, v143, v140
	v_and_b32_e32 v148, 48, v131
	v_mul_u32_u24_e32 v131, 0x50, v144
	v_lshl_add_u32 v131, v131, 1, v148
	ds_read_b128 v[144:147], v131 offset:20480
	v_or_b32_e32 v143, v143, v142
	v_mad_u64_u32 v[180:181], s[16:17], v143, s36, v[148:149]
	ds_read_b128 v[148:151], v180
	ds_read_b128 v[152:155], v180 offset:2560
	ds_read_b128 v[156:159], v180 offset:5120
	ds_read_b128 v[160:163], v180 offset:7680
	s_waitcnt lgkmcnt(3)
	v_mfma_f32_16x16x32_bf16 v[126:129], v[144:147], v[148:151], v[126:129]
	ds_read_b128 v[176:179], v180 offset:64
	s_waitcnt lgkmcnt(3)
	v_mfma_f32_16x16x32_bf16 v[122:125], v[144:147], v[152:155], v[122:125]
	s_waitcnt lgkmcnt(2)
	v_mfma_f32_16x16x32_bf16 v[118:121], v[144:147], v[156:159], v[118:121]
	s_waitcnt lgkmcnt(1)
	v_mfma_f32_16x16x32_bf16 v[114:117], v[144:147], v[160:163], v[114:117]
	ds_read_b128 v[144:147], v131 offset:23040
	s_waitcnt lgkmcnt(0)
	v_mfma_f32_16x16x32_bf16 v[110:113], v[144:147], v[148:151], v[110:113]
	v_mfma_f32_16x16x32_bf16 v[58:61], v[144:147], v[152:155], v[58:61]
	v_mfma_f32_16x16x32_bf16 v[38:41], v[144:147], v[156:159], v[38:41]
	v_mfma_f32_16x16x32_bf16 v[34:37], v[144:147], v[160:163], v[34:37]
	ds_read_b128 v[144:147], v131 offset:25600
	s_waitcnt lgkmcnt(0)
	v_mfma_f32_16x16x32_bf16 v[164:167], v[144:147], v[148:151], v[30:33]
	s_nop 2
	ds_read_b128 v[30:33], v131 offset:23104
	v_mfma_f32_16x16x32_bf16 v[168:171], v[144:147], v[152:155], v[26:29]
	v_mfma_f32_16x16x32_bf16 v[172:175], v[144:147], v[156:159], v[22:25]
	v_mfma_f32_16x16x32_bf16 v[144:147], v[144:147], v[160:163], v[18:21]
	s_nop 2
	ds_read_b128 v[18:21], v131 offset:28160
	s_waitcnt lgkmcnt(0)
	v_mfma_f32_16x16x32_bf16 v[148:151], v[18:21], v[148:151], v[14:17]
	s_nop 2
	ds_read_b128 v[14:17], v131 offset:20544
	v_mfma_f32_16x16x32_bf16 v[160:163], v[18:21], v[160:163], v[2:5]
	s_waitcnt lgkmcnt(0)
	v_mfma_f32_16x16x32_bf16 v[2:5], v[14:17], v[176:179], v[126:129]
	s_nop 2
	ds_read_b128 v[126:129], v180 offset:2624
	v_mfma_f32_16x16x32_bf16 v[152:155], v[18:21], v[152:155], v[10:13]
	v_mfma_f32_16x16x32_bf16 v[156:159], v[18:21], v[156:159], v[6:9]
	v_mfma_f32_16x16x32_bf16 v[18:21], v[30:33], v[176:179], v[110:113]
	s_nop 2
	ds_read_b128 v[110:113], v131 offset:25664
	s_waitcnt lgkmcnt(1)
	v_mfma_f32_16x16x32_bf16 v[6:9], v[14:17], v[126:129], v[122:125]
	s_nop 2
	ds_read_b128 v[122:125], v180 offset:5184
	ds_read_b128 v[180:183], v180 offset:7744
	v_mfma_f32_16x16x32_bf16 v[22:25], v[30:33], v[126:129], v[58:61]
	s_waitcnt lgkmcnt(1)
	v_mfma_f32_16x16x32_bf16 v[26:29], v[30:33], v[122:125], v[38:41]
	s_waitcnt lgkmcnt(0)
	v_mfma_f32_16x16x32_bf16 v[30:33], v[30:33], v[180:183], v[34:37]
	v_mfma_f32_16x16x32_bf16 v[34:37], v[110:113], v[176:179], v[164:167]
	s_nop 2
	ds_read_b128 v[164:167], v131 offset:28224
	v_mfma_f32_16x16x32_bf16 v[10:13], v[14:17], v[122:125], v[118:121]
	s_waitcnt lgkmcnt(0)
	s_barrier
	v_mfma_f32_16x16x32_bf16 v[14:17], v[14:17], v[180:183], v[114:117]
	s_waitcnt vmcnt(8)
	ds_write_b128 v130, v[46:49]
	ds_write_b128 v130, v[54:57] offset:20480
	ds_write_b128 v130, v[66:69] offset:5120
	ds_write_b128 v130, v[74:77] offset:25600
	ds_write_b128 v130, v[82:85] offset:10240
	ds_write_b128 v130, v[90:93] offset:30720
	ds_write_b128 v130, v[98:101] offset:15360
	ds_write_b128 v130, v[106:109] offset:35840
	v_mfma_f32_16x16x32_bf16 v[38:41], v[110:113], v[126:129], v[168:171]
	s_waitcnt lgkmcnt(0)
	s_barrier
	v_mfma_f32_16x16x32_bf16 v[58:61], v[110:113], v[122:125], v[172:175]
	v_mfma_f32_16x16x32_bf16 v[110:113], v[110:113], v[180:183], v[144:147]
	v_mfma_f32_16x16x32_bf16 v[114:117], v[164:167], v[176:179], v[148:151]
	v_mfma_f32_16x16x32_bf16 v[118:121], v[164:167], v[126:129], v[152:155]
	v_mfma_f32_16x16x32_bf16 v[122:125], v[164:167], v[122:125], v[156:159]
	v_mfma_f32_16x16x32_bf16 v[126:129], v[164:167], v[180:183], v[160:163]
	s_cbranch_scc1 .LBB0_670
	v_add_co_u32_e32 v46, vcc, 0x19700000, v138
	s_nop 1
	v_addc_co_u32_e32 v47, vcc, 0, v139, vcc
	v_add_co_u32_e32 v54, vcc, 0xa6e0000, v136
	global_load_dwordx4 v[46:49], v[46:47], off offset:384
	s_nop 0
	v_addc_co_u32_e32 v55, vcc, 0, v137, vcc
	v_add_co_u32_e32 v66, vcc, 0x19711000, v138
	global_load_dwordx4 v[54:57], v[54:55], off offset:384
	s_nop 0
	v_addc_co_u32_e32 v67, vcc, 0, v139, vcc
	v_add_co_u32_e32 v74, vcc, 0xa6f1000, v136
	global_load_dwordx4 v[66:69], v[66:67], off offset:384
	s_nop 0
	v_addc_co_u32_e32 v75, vcc, 0, v137, vcc
	v_add_co_u32_e32 v82, vcc, 0x19722000, v138
	global_load_dwordx4 v[74:77], v[74:75], off offset:384
	s_nop 0
	v_addc_co_u32_e32 v83, vcc, 0, v139, vcc
	v_add_co_u32_e32 v90, vcc, 0xa702000, v136
	global_load_dwordx4 v[82:85], v[82:83], off offset:384
	s_nop 0
	v_addc_co_u32_e32 v91, vcc, 0, v137, vcc
	v_add_co_u32_e32 v98, vcc, 0x19733000, v138
	global_load_dwordx4 v[90:93], v[90:91], off offset:384
	s_nop 0
	v_addc_co_u32_e32 v99, vcc, 0, v139, vcc
	v_add_co_u32_e32 v106, vcc, 0xa713000, v136
	global_load_dwordx4 v[98:101], v[98:99], off offset:384
	s_nop 0
	v_addc_co_u32_e32 v107, vcc, 0, v137, vcc
	global_load_dwordx4 v[106:109], v[106:107], off offset:384
	s_branch .LBB0_670

; DEV int tidx() { int t = threadIdx.x; asm volatile("" : "+v"(t)); return t; }
; #define G_LOAD(RA, RB, KT) { _Pragma("unroll") for (int i = 0; i < 4; i++) { \
;       RA[i] = *(const u32x4*)(Ap + (size_t)(i * 32) * lda + (KT) * 64); RB[i] = *(const u32x4*)(Bp + (size_t)(i * 32) * ldb + (KT) * 64); } }
; template <class Epi>
; DEV void gemm_tile(const bf16_t* __restrict__ A, int lda, const bf16_t* __restrict__ Bt, int ldb, int K, int m0, int n0,
;                    Epi& epi, char* smem) {
;     ...
;   const int tid = tidx(), lane = tid & 63, w = tid >> 6, wm = w >> 1, wn = w & 1;
;   const int l15 = lane & 15, quad = lane >> 4;
;   f32x4 acc[4][4];
; #pragma unroll
;   for (int i = 0; i < 4; i++)
; #pragma unroll
;     for (int j = 0; j < 4; j++) acc[i][j] = (f32x4){0.f, 0.f, 0.f, 0.f};
;   u32x4 ra0[4], rb0[4], ra1[4], rb1[4];
;   const int nk = K >> 6;
;   const int lrow = tid >> 3, lcc = tid & 7;
;   const bf16_t* Ap = A + (size_t)(m0 + lrow) * lda + lcc * 8;
;   const bf16_t* Bp = Bt + (size_t)(n0 + lrow) * ldb + lcc * 8;
;     ...
;   G_LOAD(ra0, rb0, 0);
;   G_LOAD(ra1, rb1, 1);
; DEV void phase_gemm_win(const Params& p, char* smem) {
;   EpiP0 epi{WSP(bf16_t, R_P0)};
;   const int NTL = 12, items = (MT / 128) * NTL;
;   for (int item = blockIdx.x; item < items; item += gridDim.x) {
;     int mt = item / NTL, nt = item - mt * NTL;
;     gemm_tile(WSP(bf16_t, OFF_H), LDH, WSP(bf16_t, S_WIN0), LDH, 1024, mt * 128, nt * 128, epi, smem);
.LBB0_1037:
	s_mul_hi_i32 s8, s11, 0x2aaaaaab
	s_lshr_b32 s9, s8, 31
	s_ashr_i32 s8, s8, 1
	s_add_i32 s14, s8, s9
	v_mov_b32_e32 v140, v195
	s_mul_i32 s8, s14, -12
	s_lshl_b32 s12, s14, 7
	s_add_i32 s8, s8, s11
	v_ashrrev_i32_e32 v66, 3, v140
	v_add_u32_e32 v68, s12, v66
	v_mov_b64_e32 v[2:3], s[2:3]
	v_lshlrev_b32_e32 v0, 4, v140
	s_lshl_b32 s13, s8, 7
	v_mad_i64_i32 v[2:3], s[8:9], v68, s19, v[2:3]
	v_and_b32_e32 v0, 0x70, v0
	v_lshl_add_u64 v[6:7], v[2:3], 0, v[0:1]
	v_add_u32_e32 v4, s13, v66
	v_mov_b64_e32 v[2:3], s[6:7]
	v_mad_i64_i32 v[2:3], s[8:9], v4, s19, v[2:3]
	s_mov_b32 s8, 0x11000
	s_waitcnt vmcnt(5)
	v_add_co_u32_e32 v22, vcc, s8, v6
	v_lshl_add_u64 v[14:15], v[2:3], 0, v[0:1]
	s_nop 0
	v_addc_co_u32_e32 v23, vcc, 0, v7, vcc
	s_waitcnt vmcnt(4)
	v_add_co_u32_e32 v30, vcc, s8, v14
	s_mov_b32 s8, 0x22000
	s_nop 0
	v_addc_co_u32_e32 v31, vcc, 0, v15, vcc
	s_waitcnt vmcnt(3)
	v_add_co_u32_e32 v38, vcc, s8, v6
	v_ashrrev_i32_e32 v67, 1, v140
	s_nop 0
	v_addc_co_u32_e32 v39, vcc, 0, v7, vcc
	s_waitcnt vmcnt(2)
	v_add_co_u32_e32 v46, vcc, s8, v14
	s_mov_b32 s8, 0x33000
	s_nop 0
	v_addc_co_u32_e32 v47, vcc, 0, v15, vcc
	s_waitcnt vmcnt(1)
	v_add_co_u32_e32 v54, vcc, s8, v6
	s_mulk_i32 s14, 0x600
	s_nop 0
	v_addc_co_u32_e32 v55, vcc, 0, v7, vcc
	s_waitcnt vmcnt(0)
	v_add_co_u32_e32 v62, vcc, s8, v14
	v_mad_u64_u32 v[130:131], s[8:9], v66, s36, v[0:1]
	s_nop 0
	v_addc_co_u32_e32 v63, vcc, 0, v15, vcc
	global_load_dwordx4 v[2:5], v[6:7], off
	s_nop 0
	global_load_dwordx4 v[10:13], v[14:15], off
	s_nop 0
	global_load_dwordx4 v[18:21], v[22:23], off
	s_nop 0
	global_load_dwordx4 v[26:29], v[30:31], off
	s_nop 0
	global_load_dwordx4 v[34:37], v[38:39], off
	s_nop 0
	global_load_dwordx4 v[42:45], v[46:47], off
	s_nop 0
	global_load_dwordx4 v[50:53], v[54:55], off
	s_nop 0
	global_load_dwordx4 v[58:61], v[62:63], off
	s_nop 0
	global_load_dwordx4 v[6:9], v[6:7], off offset:128
	s_nop 0
	global_load_dwordx4 v[14:17], v[14:15], off offset:128
	s_nop 0
	global_load_dwordx4 v[22:25], v[22:23], off offset:128
	s_nop 0
	global_load_dwordx4 v[30:33], v[30:31], off offset:128
	s_nop 0
	global_load_dwordx4 v[38:41], v[38:39], off offset:128
	s_nop 0
	global_load_dwordx4 v[46:49], v[46:47], off offset:128
	s_nop 0
	global_load_dwordx4 v[54:57], v[54:55], off offset:128
	s_nop 0
	global_load_dwordx4 v[62:65], v[62:63], off offset:128
	v_add_u32_e32 v66, s10, v66
	v_and_b32_e32 v142, 0xffffffc0, v67
	v_and_b32_e32 v0, 7, v140
	v_subrev_u32_e32 v69, s14, v66
	v_mov_b64_e32 v[66:67], s[28:29]
	v_mov_b32_e32 v90, 0
	v_and_b32_e32 v141, 64, v140
	v_lshlrev_b32_e32 v0, 4, v0
	v_mad_i64_i32 v[132:133], s[8:9], v69, s19, v[66:67]
	v_mad_i64_i32 v[134:135], s[8:9], v68, s19, v[66:67]
	s_mov_b32 s14, -2
	v_mov_b32_e32 v91, v90
	v_mov_b32_e32 v92, v90
	v_mov_b32_e32 v93, v90
	v_mov_b32_e32 v66, v90
	v_mov_b32_e32 v67, v90
	v_mov_b32_e32 v68, v90
	v_mov_b32_e32 v69, v90
	v_mov_b32_e32 v74, v90
	v_mov_b32_e32 v75, v90
	v_mov_b32_e32 v76, v90
	v_mov_b32_e32 v77, v90
	v_mov_b32_e32 v86, v90
	v_mov_b32_e32 v87, v90
	v_mov_b32_e32 v88, v90
	v_mov_b32_e32 v89, v90
	v_mov_b32_e32 v70, v90
	v_mov_b32_e32 v71, v90
	v_mov_b32_e32 v72, v90
	v_mov_b32_e32 v73, v90
	v_mov_b32_e32 v78, v90
	v_mov_b32_e32 v79, v90
	v_mov_b32_e32 v80, v90
	v_mov_b32_e32 v81, v90
	v_mov_b32_e32 v82, v90
	v_mov_b32_e32 v83, v90
	v_mov_b32_e32 v84, v90
	v_mov_b32_e32 v85, v90
	v_mov_b32_e32 v94, v90
	v_mov_b32_e32 v95, v90
	v_mov_b32_e32 v96, v90
	v_mov_b32_e32 v97, v90
	v_mov_b32_e32 v98, v90
	v_mov_b32_e32 v99, v90
	v_mov_b32_e32 v100, v90
	v_mov_b32_e32 v101, v90
	v_mov_b32_e32 v102, v90
	v_mov_b32_e32 v103, v90
	v_mov_b32_e32 v104, v90
	v_mov_b32_e32 v105, v90
	v_mov_b32_e32 v106, v90
	v_mov_b32_e32 v107, v90
	v_mov_b32_e32 v108, v90
	v_mov_b32_e32 v109, v90
	v_mov_b32_e32 v110, v90
	v_mov_b32_e32 v111, v90
	v_mov_b32_e32 v112, v90
	v_mov_b32_e32 v113, v90
	v_mov_b32_e32 v118, v90
	v_mov_b32_e32 v119, v90
	v_mov_b32_e32 v120, v90
	v_mov_b32_e32 v121, v90
	v_mov_b32_e32 v122, v90
	v_mov_b32_e32 v123, v90
	v_mov_b32_e32 v124, v90
	v_mov_b32_e32 v125, v90
	v_mov_b32_e32 v126, v90
	v_mov_b32_e32 v127, v90
	v_mov_b32_e32 v128, v90
	v_mov_b32_e32 v129, v90
	v_mov_b32_e32 v114, v90
	v_mov_b32_e32 v115, v90
	v_mov_b32_e32 v116, v90
	v_mov_b32_e32 v117, v90
	s_branch .LBB0_1039

; #define G_LOAD(RA, RB, KT) { _Pragma("unroll") for (int i = 0; i < 4; i++) { \
;       RA[i] = *(const u32x4*)(Ap + (size_t)(i * 32) * lda + (KT) * 64); RB[i] = *(const u32x4*)(Bp + (size_t)(i * 32) * ldb + (KT) * 64); } }
; #define G_STORE(RA, RB) { _Pragma("unroll") for (int i = 0; i < 4; i++) { \
;       *(u32x4*)(As + (lrow + i * 32) * GLD + lcc * 8) = RA[i]; *(u32x4*)(Bs + (lrow + i * 32) * GLD + lcc * 8) = RB[i]; } }
; template <class Epi>
; DEV void gemm_tile(const bf16_t* __restrict__ A, int lda, const bf16_t* __restrict__ Bt, int ldb, int K, int m0, int n0,
;                    Epi& epi, char* smem) {
;     ...
;   for (int kt = 0; kt < nk; kt += 2) {
;     __syncthreads();
;     G_STORE(ra0, rb0);
;     __syncthreads();
;     if (kt + 2 < nk) G_LOAD(ra0, rb0, kt + 2);
.LBB0_1039:
	s_add_i32 s14, s14, 2
	s_cmp_gt_u32 s14, 13
	s_cselect_b64 s[8:9], -1, 0
	s_and_b64 vcc, exec, s[8:9]
	v_lshl_add_u64 v[138:139], v[134:135], 0, v[0:1]
	v_lshl_add_u64 v[136:137], v[132:133], 0, v[0:1]
	s_waitcnt lgkmcnt(0)
	s_barrier
	s_waitcnt vmcnt(8)
	ds_write_b128 v130, v[2:5]
	ds_write_b128 v130, v[10:13] offset:20480
	ds_write_b128 v130, v[18:21] offset:5120
	ds_write_b128 v130, v[26:29] offset:25600
	ds_write_b128 v130, v[34:37] offset:10240
	ds_write_b128 v130, v[42:45] offset:30720
	ds_write_b128 v130, v[50:53] offset:15360
	ds_write_b128 v130, v[58:61] offset:35840
	s_waitcnt lgkmcnt(0)
	s_barrier
	s_cbranch_vccnz .Lgw_skip_5
	v_add_co_u32_e32 v2, vcc, 0x4200000, v138
	s_nop 1
	v_addc_co_u32_e32 v3, vcc, 0, v139, vcc
	v_add_co_u32_e32 v10, vcc, 0xa300000, v136
	global_load_dwordx4 v[2:5], v[2:3], off offset:256
	s_nop 0
	v_addc_co_u32_e32 v11, vcc, 0, v137, vcc
	v_add_co_u32_e32 v18, vcc, 0x4211000, v138
	global_load_dwordx4 v[10:13], v[10:11], off offset:256
	s_nop 0
	v_addc_co_u32_e32 v19, vcc, 0, v139, vcc
	v_add_co_u32_e32 v26, vcc, 0xa311000, v136
	global_load_dwordx4 v[18:21], v[18:19], off offset:256
	s_nop 0
	v_addc_co_u32_e32 v27, vcc, 0, v137, vcc
	v_add_co_u32_e32 v34, vcc, 0x4222000, v138
	global_load_dwordx4 v[26:29], v[26:27], off offset:256
	s_nop 0
	v_addc_co_u32_e32 v35, vcc, 0, v139, vcc
	v_add_co_u32_e32 v42, vcc, 0xa322000, v136
	global_load_dwordx4 v[34:37], v[34:35], off offset:256
	s_nop 0
	v_addc_co_u32_e32 v43, vcc, 0, v137, vcc
	v_add_co_u32_e32 v50, vcc, 0x4233000, v138
	global_load_dwordx4 v[42:45], v[42:43], off offset:256
	s_nop 0
	v_addc_co_u32_e32 v51, vcc, 0, v139, vcc
	v_add_co_u32_e32 v58, vcc, 0xa333000, v136
	global_load_dwordx4 v[50:53], v[50:51], off offset:256
	s_nop 0
	v_addc_co_u32_e32 v59, vcc, 0, v137, vcc
	global_load_dwordx4 v[58:61], v[58:59], off offset:256
; DEV int tidx() { int t = threadIdx.x; asm volatile("" : "+v"(t)); return t; }
; DEV f32x4 mfma16(bf16x8 a, bf16x8 b, f32x4 c) { return __builtin_amdgcn_mfma_f32_16x16x32_bf16(a, b, c, 0, 0, 0); }
; #define G_LOAD(RA, RB, KT) { _Pragma("unroll") for (int i = 0; i < 4; i++) { \
;       RA[i] = *(const u32x4*)(Ap + (size_t)(i * 32) * lda + (KT) * 64); RB[i] = *(const u32x4*)(Bp + (size_t)(i * 32) * ldb + (KT) * 64); } }
; #define G_STORE(RA, RB) { _Pragma("unroll") for (int i = 0; i < 4; i++) { \
;       *(u32x4*)(As + (lrow + i * 32) * GLD + lcc * 8) = RA[i]; *(u32x4*)(Bs + (lrow + i * 32) * GLD + lcc * 8) = RB[i]; } }
; template <int TI, int TJ, int KS>
; DEV void mfma_lds(const bf16_t* Arows, int lda, const bf16_t* Brows, int ldb, int i0, int j0, f32x4 (&acc)[TI][TJ]) {
;   const int lane = tidx() & 63, l15 = lane & 15, quad = lane >> 4;
; #pragma unroll
;   for (int ks = 0; ks < KS; ks++) {
;     bf16x8 af[TI], bfr[TJ];
; #pragma unroll
;     for (int i = 0; i < TI; i++) af[i] = *(const bf16x8*)(Arows + (i0 + i * 16 + l15) * lda + ks * 32 + quad * 8);
; #pragma unroll
;     for (int j = 0; j < TJ; j++) bfr[j] = *(const bf16x8*)(Brows + (j0 + j * 16 + l15) * ldb + ks * 32 + quad * 8);
; #pragma unroll
;     for (int i = 0; i < TI; i++)
; #pragma unroll
;       for (int j = 0; j < TJ; j++) acc[i][j] = mfma16(af[i], bfr[j], acc[i][j]);
;   }
; template <class Epi>
; DEV void gemm_tile(const bf16_t* __restrict__ A, int lda, const bf16_t* __restrict__ Bt, int ldb, int K, int m0, int n0,
;                    Epi& epi, char* smem) {
;     ...
;     mfma_lds<4, 4, 2>(Bs, GLD, As, GLD, wn * 64, wm * 64, acc);
;     __syncthreads();
;     G_STORE(ra1, rb1);
;     __syncthreads();
;     if (kt + 3 < nk) G_LOAD(ra1, rb1, kt + 3);
.LBB0_1041:
	v_mov_b32_e32 v131, v195
	s_cmp_gt_u32 s14, 12
	v_and_b32_e32 v143, 15, v131
	v_or_b32_e32 v144, v143, v141
	v_and_b32_e32 v148, 48, v131
	v_mul_u32_u24_e32 v131, 0x50, v144
	v_lshl_add_u32 v131, v131, 1, v148
	ds_read_b128 v[144:147], v131 offset:20480
	v_or_b32_e32 v143, v143, v142
	v_mad_u64_u32 v[184:185], s[16:17], v143, s36, v[148:149]
	ds_read_b128 v[148:151], v184
	ds_read_b128 v[152:155], v184 offset:2560
	ds_read_b128 v[156:159], v184 offset:5120
	ds_read_b128 v[160:163], v184 offset:7680
	s_waitcnt lgkmcnt(3)
	v_mfma_f32_16x16x32_bf16 v[114:117], v[144:147], v[148:151], v[114:117]
	ds_read_b128 v[176:179], v184 offset:64
	ds_read_b128 v[180:183], v184 offset:2624
	s_waitcnt lgkmcnt(4)
	v_mfma_f32_16x16x32_bf16 v[126:129], v[144:147], v[152:155], v[126:129]
	s_waitcnt lgkmcnt(3)
	v_mfma_f32_16x16x32_bf16 v[122:125], v[144:147], v[156:159], v[122:125]
	s_waitcnt lgkmcnt(2)
	v_mfma_f32_16x16x32_bf16 v[118:121], v[144:147], v[160:163], v[118:121]
	ds_read_b128 v[144:147], v131 offset:23040
	s_waitcnt lgkmcnt(0)
	v_mfma_f32_16x16x32_bf16 v[110:113], v[144:147], v[148:151], v[110:113]
	v_mfma_f32_16x16x32_bf16 v[106:109], v[144:147], v[152:155], v[106:109]
	v_mfma_f32_16x16x32_bf16 v[102:105], v[144:147], v[156:159], v[102:105]
	v_mfma_f32_16x16x32_bf16 v[98:101], v[144:147], v[160:163], v[98:101]
	ds_read_b128 v[144:147], v131 offset:25600
	s_waitcnt lgkmcnt(0)
	v_mfma_f32_16x16x32_bf16 v[164:167], v[144:147], v[148:151], v[94:97]
	s_nop 2
	ds_read_b128 v[94:97], v131 offset:23104
	v_mfma_f32_16x16x32_bf16 v[172:175], v[144:147], v[156:159], v[78:81]
	s_nop 2
	ds_read_b128 v[78:81], v131 offset:20544
	v_mfma_f32_16x16x32_bf16 v[168:171], v[144:147], v[152:155], v[82:85]
	v_mfma_f32_16x16x32_bf16 v[144:147], v[144:147], v[160:163], v[70:73]
	s_nop 2
	ds_read_b128 v[70:73], v131 offset:28160
	s_waitcnt lgkmcnt(2)
	v_mfma_f32_16x16x32_bf16 v[82:85], v[94:97], v[176:179], v[110:113]
	s_nop 2
	ds_read_b128 v[110:113], v131 offset:25664
	s_waitcnt lgkmcnt(1)
	v_mfma_f32_16x16x32_bf16 v[148:151], v[70:73], v[148:151], v[86:89]
	v_mfma_f32_16x16x32_bf16 v[152:155], v[70:73], v[152:155], v[74:77]
	v_mfma_f32_16x16x32_bf16 v[156:159], v[70:73], v[156:159], v[66:69]
	v_mfma_f32_16x16x32_bf16 v[160:163], v[70:73], v[160:163], v[90:93]
	v_mfma_f32_16x16x32_bf16 v[70:73], v[78:81], v[180:183], v[126:129]
	s_nop 2
	ds_read_b128 v[126:129], v184 offset:5184
	ds_read_b128 v[184:187], v184 offset:7744
	v_mfma_f32_16x16x32_bf16 v[86:89], v[94:97], v[180:183], v[106:109]
	s_waitcnt lgkmcnt(1)
	v_mfma_f32_16x16x32_bf16 v[90:93], v[94:97], v[126:129], v[102:105]
	s_waitcnt lgkmcnt(0)
	v_mfma_f32_16x16x32_bf16 v[94:97], v[94:97], v[184:187], v[98:101]
	v_mfma_f32_16x16x32_bf16 v[98:101], v[110:113], v[176:179], v[164:167]
	s_nop 2
	ds_read_b128 v[164:167], v131 offset:28224
	v_mfma_f32_16x16x32_bf16 v[66:69], v[78:81], v[176:179], v[114:117]
	s_waitcnt lgkmcnt(0)
	s_barrier
	v_mfma_f32_16x16x32_bf16 v[74:77], v[78:81], v[126:129], v[122:125]
	s_waitcnt vmcnt(8)
	ds_write_b128 v130, v[6:9]
	ds_write_b128 v130, v[14:17] offset:20480
	ds_write_b128 v130, v[22:25] offset:5120
	ds_write_b128 v130, v[30:33] offset:25600
	ds_write_b128 v130, v[38:41] offset:10240
	ds_write_b128 v130, v[46:49] offset:30720
	ds_write_b128 v130, v[54:57] offset:15360
	ds_write_b128 v130, v[62:65] offset:35840
	v_mfma_f32_16x16x32_bf16 v[78:81], v[78:81], v[184:187], v[118:121]
	s_waitcnt lgkmcnt(0)
	s_barrier
	v_mfma_f32_16x16x32_bf16 v[102:105], v[110:113], v[180:183], v[168:171]
	v_mfma_f32_16x16x32_bf16 v[106:109], v[110:113], v[126:129], v[172:175]
	v_mfma_f32_16x16x32_bf16 v[110:113], v[110:113], v[184:187], v[144:147]
	v_mfma_f32_16x16x32_bf16 v[114:117], v[164:167], v[176:179], v[148:151]
	v_mfma_f32_16x16x32_bf16 v[118:121], v[164:167], v[180:183], v[152:155]
	v_mfma_f32_16x16x32_bf16 v[122:125], v[164:167], v[126:129], v[156:159]
	v_mfma_f32_16x16x32_bf16 v[126:129], v[164:167], v[184:187], v[160:163]
	s_cbranch_scc1 .LBB0_1038
	v_add_co_u32_e32 v6, vcc, 0x4200000, v138
	s_nop 1
	v_addc_co_u32_e32 v7, vcc, 0, v139, vcc
	v_add_co_u32_e32 v14, vcc, 0xa300000, v136
	global_load_dwordx4 v[6:9], v[6:7], off offset:384
	s_nop 0
	v_addc_co_u32_e32 v15, vcc, 0, v137, vcc
	v_add_co_u32_e32 v22, vcc, 0x4211000, v138
	global_load_dwordx4 v[14:17], v[14:15], off offset:384
	s_nop 0
	v_addc_co_u32_e32 v23, vcc, 0, v139, vcc
	v_add_co_u32_e32 v30, vcc, 0xa311000, v136
	global_load_dwordx4 v[22:25], v[22:23], off offset:384
	s_nop 0
	v_addc_co_u32_e32 v31, vcc, 0, v137, vcc
	v_add_co_u32_e32 v38, vcc, 0x4222000, v138
	global_load_dwordx4 v[30:33], v[30:31], off offset:384
	s_nop 0
	v_addc_co_u32_e32 v39, vcc, 0, v139, vcc
	v_add_co_u32_e32 v46, vcc, 0xa322000, v136
	global_load_dwordx4 v[38:41], v[38:39], off offset:384
	s_nop 0
	v_addc_co_u32_e32 v47, vcc, 0, v137, vcc
	v_add_co_u32_e32 v54, vcc, 0x4233000, v138
	global_load_dwordx4 v[46:49], v[46:47], off offset:384
	s_nop 0
	v_addc_co_u32_e32 v55, vcc, 0, v139, vcc
	v_add_co_u32_e32 v62, vcc, 0xa333000, v136
	global_load_dwordx4 v[54:57], v[54:55], off offset:384
	s_nop 0
	v_addc_co_u32_e32 v63, vcc, 0, v137, vcc
	global_load_dwordx4 v[62:65], v[62:63], off offset:384
	s_branch .LBB0_1038
